# epilogue row reductions: ds_bpermute lane^16/lane^32 replaced by v_permlane16/32_swap in all GEMM epilogues (224 sites)
# speedup vs baseline: 1.0026x; 1.0026x over previous
.LBB0_181:
	v_lshl_add_u32 v150, s14, 8, v154
	v_ashrrev_i32_e32 v151, 31, v150
	v_lshlrev_b64 v[148:149], 7, v[150:151]
	v_lshl_add_u64 v[148:149], v[138:139], 0, v[148:149]
	global_load_dwordx4 v[164:167], v[148:149], off
	global_load_dwordx4 v[168:171], v[148:149], off offset:16
	v_and_b32_e32 v149, 64, v160
	v_xor_b32_e32 v137, 16, v160
	v_add_u32_e32 v149, 64, v149
	v_cmp_lt_i32_e32 vcc, v137, v149
	v_lshl_or_b32 v148, s12, 8, v156
	s_cmp_gt_i32 s12, 7
	v_cndmask_b32_e32 v137, v160, v137, vcc
	v_lshlrev_b32_e32 v162, 2, v137
	s_cselect_b64 s[46:47], -1, 0
	s_and_b64 s[46:47], s[4:5], s[46:47]
	s_waitcnt vmcnt(0)
	v_mov_b32_e32 v152, v164
	v_mov_b32_e32 v153, v168
	v_mov_b32_e32 v168, v165
	v_mov_b32_e32 v164, v166
	v_mov_b32_e32 v165, v170
	v_mov_b32_e32 v170, v167
	v_pk_add_f32 v[152:153], v[152:153], v[168:169]
	v_pk_add_f32 v[164:165], v[164:165], v[170:171]
	s_nop 0
	v_pk_add_f32 v[152:153], v[152:153], v[164:165]
	s_nop 0
	v_add_f32_e32 v137, 0, v152
	v_add_f32_e32 v137, v137, v153
	v_mov_b32_e32 v152, v137
	s_nop 1
	v_permlane16_swap_b32_e32 v152, v137
	v_xor_b32_e32 v153, 32, v160
	v_cmp_lt_i32_e32 vcc, v153, v149
	s_waitcnt lgkmcnt(0)
	v_add_f32_e32 v137, v137, v152
	v_cndmask_b32_e32 v149, v160, v153, vcc
	v_lshlrev_b32_e32 v163, 2, v149
	v_mov_b32_e32 v152, v137
	s_nop 1
	v_permlane32_swap_b32_e32 v152, v137
	v_ashrrev_i32_e32 v149, 31, v148
	s_waitcnt lgkmcnt(0)
	v_add_f32_e32 v137, v137, v152
	v_fmamk_f32 v137, v137, 0x3a000000, v161
	v_mul_f32_e32 v152, 0x4b800000, v137
	v_cmp_gt_f32_e32 vcc, s64, v137
	s_nop 1
	v_cndmask_b32_e32 v137, v137, v152, vcc
	v_rsq_f32_e32 v137, v137
	v_lshlrev_b64 v[152:153], 13, v[150:151]
	v_lshl_add_u64 v[152:153], s[18:19], 0, v[152:153]
	v_lshl_add_u64 v[152:153], v[148:149], 1, v[152:153]
	v_mul_f32_e32 v164, 0x45800000, v137
	v_cndmask_b32_e32 v164, v137, v164, vcc
	v_pk_mul_f32 v[124:125], v[124:125], v[164:165] op_sel_hi:[1,0]
	v_pk_mul_f32 v[120:121], v[120:121], v[164:165] op_sel_hi:[1,0]
	v_pk_mul_f32 v[126:127], v[126:127], v[164:165] op_sel_hi:[1,0]
	v_pk_mul_f32 v[122:123], v[122:123], v[164:165] op_sel_hi:[1,0]
	v_pk_mul_f32 v[118:119], v[118:119], v[164:165] op_sel_hi:[1,0]
	v_pk_mul_f32 v[116:117], v[116:117], v[164:165] op_sel_hi:[1,0]
	v_pk_mul_f32 v[166:167], v[112:113], v[164:165] op_sel_hi:[1,0]
	v_mul_f32_e32 v137, 0x3d122279, v124
	v_mul_f32_e32 v165, 0x3d122279, v120
	v_mul_f32_e32 v168, 0x3d122279, v125
	v_mul_f32_e32 v169, 0x3d122279, v121
	v_mul_f32_e32 v170, 0x3d122279, v126
	v_mul_f32_e32 v171, 0x3d122279, v122
	v_fmaak_f32 v137, v124, v137, 0x3f4c422a
	v_fmaak_f32 v165, v120, v165, 0x3f4c422a
	v_mov_b32_e32 v112, v124
	v_mov_b32_e32 v113, v120
	v_fmaak_f32 v168, v125, v168, 0x3f4c422a
	v_fmaak_f32 v169, v121, v169, 0x3f4c422a
	v_fmaak_f32 v170, v126, v170, 0x3f4c422a
	v_fmaak_f32 v171, v122, v171, 0x3f4c422a
	v_mul_f32_e32 v124, v124, v137
	v_mul_f32_e32 v120, v120, v165
	v_mul_f32_e32 v137, v125, v168
	v_mul_f32_e32 v165, v121, v169
	v_mul_f32_e32 v168, v126, v170
	v_mul_f32_e32 v169, v122, v171
	v_add_f32_e32 v124, v124, v124
	v_add_f32_e32 v120, v120, v120
	v_mul_f32_e32 v172, 0x3d122279, v127
	v_mul_f32_e32 v173, 0x3d122279, v123
	v_add_f32_e32 v168, v168, v168
	v_add_f32_e32 v169, v169, v169
	v_mul_f32_e32 v124, 0xbfb8aa3b, v124
	v_mul_f32_e32 v120, 0xbfb8aa3b, v120
	v_fmaak_f32 v172, v127, v172, 0x3f4c422a
	v_fmaak_f32 v173, v123, v173, 0x3f4c422a
	v_add_f32_e32 v165, v165, v165
	v_mul_f32_e32 v168, 0xbfb8aa3b, v168
	v_mul_f32_e32 v169, 0xbfb8aa3b, v169
	v_exp_f32_e32 v124, v124
	v_exp_f32_e32 v120, v120
	v_mul_f32_e32 v170, v127, v172
	v_mul_f32_e32 v171, v123, v173
	v_mul_f32_e32 v165, 0xbfb8aa3b, v165
	v_exp_f32_e32 v168, v168
	v_exp_f32_e32 v169, v169
	v_mul_f32_e32 v174, 0x3d122279, v116
	v_add_f32_e32 v137, v137, v137
	v_add_f32_e32 v170, v170, v170
	v_add_f32_e32 v171, v171, v171
	v_exp_f32_e32 v165, v165
	v_fmaak_f32 v174, v116, v174, 0x3f4c422a
	v_mul_f32_e32 v137, 0xbfb8aa3b, v137
	v_mul_f32_e32 v170, 0xbfb8aa3b, v170
	v_mul_f32_e32 v171, 0xbfb8aa3b, v171
	v_mul_f32_e32 v172, v116, v174
	v_exp_f32_e32 v137, v137
	v_exp_f32_e32 v170, v170
	v_exp_f32_e32 v171, v171
	v_add_f32_e32 v124, 1.0, v124
	v_add_f32_e32 v120, 1.0, v120
	v_add_f32_e32 v172, v172, v172
	v_add_f32_e32 v173, 1.0, v168
	v_add_f32_e32 v174, 1.0, v169
	v_rcp_f32_e32 v168, v124
	v_rcp_f32_e32 v169, v120
	v_mul_f32_e32 v172, 0xbfb8aa3b, v172
	v_add_f32_e32 v165, 1.0, v165
	v_exp_f32_e32 v172, v172
	v_rcp_f32_e32 v120, v165
	v_rcp_f32_e32 v165, v174
	v_add_f32_e32 v137, 1.0, v137
	v_add_f32_e32 v170, 1.0, v170
	v_add_f32_e32 v171, 1.0, v171
	v_rcp_f32_e32 v124, v137
	v_rcp_f32_e32 v137, v173
	v_rcp_f32_e32 v173, v170
	v_rcp_f32_e32 v174, v171
	v_pk_mul_f32 v[170:171], v[112:113], v[168:169]
	v_pk_mul_f32 v[114:115], v[114:115], v[164:165] op_sel_hi:[1,0]
	v_pk_fma_f32 v[112:113], v[112:113], v[168:169], v[170:171] op_sel:[0,0,1] op_sel_hi:[1,1,0]
	v_add_f32_e32 v164, 1.0, v172
	v_mul_f32_e32 v113, 0x3d122279, v166
	v_fmaak_f32 v113, v166, v113, 0x3f4c422a
	v_rcp_f32_e32 v178, v164
	v_mul_f32_e32 v164, 0x3d122279, v117
	v_mul_f32_e32 v113, v166, v113
	v_fmaak_f32 v164, v117, v164, 0x3f4c422a
	v_mul_f32_e32 v168, 0x3d122279, v167
	v_add_f32_e32 v113, v113, v113
	v_mul_f32_e32 v164, v117, v164
	v_fmaak_f32 v168, v167, v168, 0x3f4c422a
	v_mul_f32_e32 v113, 0xbfb8aa3b, v113
	v_add_f32_e32 v164, v164, v164
	v_mul_f32_e32 v168, v167, v168
	v_exp_f32_e32 v113, v113
	v_mul_f32_e32 v164, 0xbfb8aa3b, v164
	v_add_f32_e32 v168, v168, v168
	v_exp_f32_e32 v164, v164
	v_mul_f32_e32 v168, 0xbfb8aa3b, v168
	v_exp_f32_e32 v168, v168
	v_add_f32_e32 v113, 1.0, v113
	v_rcp_f32_e32 v179, v113
	v_add_f32_e32 v113, 1.0, v164
	v_mul_f32_e32 v164, 0x3d122279, v118
	v_rcp_f32_e32 v180, v113
	v_add_f32_e32 v113, 1.0, v168
	v_fmaak_f32 v164, v118, v164, 0x3f4c422a
	v_mul_f32_e32 v168, 0x3d122279, v114
	v_mul_f32_e32 v164, v118, v164
	v_fmaak_f32 v168, v114, v168, 0x3f4c422a
	v_add_f32_e32 v164, v164, v164
	v_mul_f32_e32 v168, v114, v168
	v_mul_f32_e32 v164, 0xbfb8aa3b, v164
	v_add_f32_e32 v168, v168, v168
	v_exp_f32_e32 v164, v164
	v_mul_f32_e32 v168, 0xbfb8aa3b, v168
	v_exp_f32_e32 v168, v168
	v_rcp_f32_e32 v181, v113
	v_add_f32_e32 v113, 1.0, v164
	v_mul_f32_e32 v164, 0x3d122279, v119
	v_rcp_f32_e32 v182, v113
	v_add_f32_e32 v113, 1.0, v168
	v_fmaak_f32 v164, v119, v164, 0x3f4c422a
	v_mul_f32_e32 v168, 0x3d122279, v115
	v_mul_f32_e32 v164, v119, v164
	v_fmaak_f32 v168, v115, v168, 0x3f4c422a
	v_add_f32_e32 v164, v164, v164
	v_mul_f32_e32 v168, v115, v168
	v_mul_f32_e32 v164, 0xbfb8aa3b, v164
	v_add_f32_e32 v168, v168, v168
	v_exp_f32_e32 v164, v164
	v_mul_f32_e32 v168, 0xbfb8aa3b, v168
	v_exp_f32_e32 v168, v168
	v_rcp_f32_e32 v183, v113
	v_add_f32_e32 v113, 1.0, v164
	v_mul_f32_e32 v164, v127, v173
	v_mov_b32_e32 v172, v125
	v_mov_b32_e32 v173, v170
	v_mov_b32_e32 v125, v170
	v_mov_b32_e32 v176, v121
	v_mov_b32_e32 v177, v171
	v_mov_b32_e32 v121, v171
	v_rcp_f32_e32 v184, v113
	v_add_f32_e32 v113, 1.0, v168
	v_mul_f32_e32 v168, v123, v174
	v_pk_mul_f32 v[174:175], v[172:173], v[124:125]
	v_pk_mul_f32 v[120:121], v[176:177], v[120:121]
	v_rcp_f32_e32 v185, v113
	v_pk_fma_f32 v[124:125], v[172:173], v[124:125], v[120:121]
	v_pk_mul_f32 v[172:173], v[174:175], v[174:175]
	v_pk_mul_f32 v[176:177], v[120:121], v[120:121]
	v_mul_f32_e32 v126, v126, v137
	v_mul_f32_e32 v122, v122, v165
	v_mov_b32_e32 v113, v172
	v_mov_b32_e32 v137, v176
	v_pk_add_f32 v[112:113], v[112:113], v[136:137]
	v_mul_f32_e32 v127, v126, v126
	v_mul_f32_e32 v123, v122, v122
	v_pk_add_f32 v[112:113], v[124:125], v[112:113]
	v_pk_add_f32 v[124:125], v[126:127], v[122:123]
	v_mul_f32_e32 v165, v164, v164
	v_mul_f32_e32 v169, v168, v168
	v_pk_add_f32 v[112:113], v[124:125], v[112:113]
	v_pk_add_f32 v[124:125], v[164:165], v[168:169]
	v_mul_f32_e32 v116, v116, v178
	v_pk_add_f32 v[124:125], v[124:125], v[112:113]
	v_cvt_pk_bf16_f32 v112, v170, v174
	v_cvt_pk_bf16_f32 v113, v126, v164
	v_mul_f32_e32 v126, v166, v179
	v_mul_f32_e32 v164, v117, v180
	v_mul_f32_e32 v166, v167, v181
	v_mul_f32_e32 v117, v116, v116
	v_mul_f32_e32 v127, v126, v126
	v_mul_f32_e32 v118, v118, v182
	v_mul_f32_e32 v172, v114, v183
	v_mul_f32_e32 v176, v115, v185
	v_pk_add_f32 v[114:115], v[116:117], v[126:127]
	v_mul_f32_e32 v165, v164, v164
	v_mul_f32_e32 v167, v166, v166
	v_mul_f32_e32 v174, v119, v184
	v_pk_add_f32 v[114:115], v[114:115], v[124:125]
	v_pk_add_f32 v[124:125], v[164:165], v[166:167]
	v_mul_f32_e32 v119, v118, v118
	v_mul_f32_e32 v173, v172, v172
	v_pk_add_f32 v[114:115], v[124:125], v[114:115]
	v_pk_add_f32 v[124:125], v[118:119], v[172:173]
	v_mul_f32_e32 v175, v174, v174
	v_mul_f32_e32 v177, v176, v176
	v_pk_add_f32 v[114:115], v[124:125], v[114:115]
	v_pk_add_f32 v[124:125], v[174:175], v[176:177]
	s_nop 0
	v_pk_add_f32 v[124:125], v[124:125], v[114:115]
	v_mov_b32_e32 v178, v124
	s_nop 1
	v_permlane16_swap_b32_e32 v178, v124
	v_mov_b32_e32 v179, v125
	s_nop 1
	v_permlane16_swap_b32_e32 v179, v125
	v_cvt_pk_bf16_f32 v114, v171, v120
	v_cvt_pk_bf16_f32 v115, v122, v168
	global_store_dwordx4 v[152:153], v[112:115], off
	v_cvt_pk_bf16_f32 v116, v116, v164
	v_cvt_pk_bf16_f32 v117, v118, v174
	v_cvt_pk_bf16_f32 v118, v126, v166
	v_cvt_pk_bf16_f32 v119, v172, v176
	global_store_dwordx4 v[152:153], v[116:119], off offset:256
	s_waitcnt lgkmcnt(0)
	v_pk_add_f32 v[112:113], v[124:125], v[178:179]
	v_mov_b32_e32 v114, v112
	s_nop 1
	v_permlane32_swap_b32_e32 v114, v112
	v_mov_b32_e32 v115, v113
	s_nop 1
	v_permlane32_swap_b32_e32 v115, v113
	s_and_saveexec_b64 s[48:49], s[46:47]
	s_cbranch_execz .LBB0_183
	s_lshl_b32 s14, s12, 2
	v_lshlrev_b64 v[116:117], 5, v[150:151]
	s_sub_i32 s14, s14, 32
	v_lshl_add_u64 v[116:117], v[116:117], 0, s[14:15]
	v_or_b32_e32 v116, s56, v116
	v_lshl_add_u64 v[116:117], v[116:117], 3, s[20:21]
	s_waitcnt lgkmcnt(0)
	v_pk_add_f32 v[112:113], v[112:113], v[114:115]
	global_store_dwordx2 v[116:117], v[112:113], off
.LBB0_183:
	s_or_b64 exec, exec, s[48:49]
	v_or_b32_e32 v112, 16, v150
	v_ashrrev_i32_e32 v113, 31, v112
	s_waitcnt lgkmcnt(0)
	v_lshlrev_b64 v[114:115], 7, v[112:113]
	v_lshl_add_u64 v[118:119], v[138:139], 0, v[114:115]
	global_load_dwordx4 v[114:117], v[118:119], off
	s_nop 0
	global_load_dwordx4 v[118:121], v[118:119], off offset:16
	s_waitcnt vmcnt(1)
	v_mov_b32_e32 v122, v114
	s_waitcnt vmcnt(0)
	v_mov_b32_e32 v123, v118
	v_mov_b32_e32 v118, v115
	v_mov_b32_e32 v114, v116
	v_mov_b32_e32 v115, v120
	v_mov_b32_e32 v120, v117
	v_pk_add_f32 v[116:117], v[122:123], v[118:119]
	v_pk_add_f32 v[114:115], v[114:115], v[120:121]
	s_nop 0
	v_pk_add_f32 v[114:115], v[116:117], v[114:115]
	s_nop 0
	v_add_f32_e32 v114, 0, v114
	v_add_f32_e32 v114, v114, v115
	v_mov_b32_e32 v115, v114
	s_nop 1
	v_permlane16_swap_b32_e32 v115, v114
	s_waitcnt lgkmcnt(0)
	v_add_f32_e32 v114, v114, v115
	v_mov_b32_e32 v115, v114
	s_nop 1
	v_permlane32_swap_b32_e32 v115, v114
	s_waitcnt lgkmcnt(0)
	v_add_f32_e32 v114, v114, v115
	v_fmamk_f32 v114, v114, 0x3a000000, v161
	v_mul_f32_e32 v115, 0x4b800000, v114
	v_cmp_gt_f32_e32 vcc, s64, v114
	s_nop 1
	v_cndmask_b32_e32 v114, v114, v115, vcc
	v_rsq_f32_e32 v116, v114
	v_lshlrev_b64 v[114:115], 13, v[112:113]
	v_lshl_add_u64 v[114:115], s[18:19], 0, v[114:115]
	v_lshl_add_u64 v[114:115], v[148:149], 1, v[114:115]
	v_mul_f32_e32 v117, 0x45800000, v116
	v_cndmask_b32_e32 v116, v116, v117, vcc
	v_pk_mul_f32 v[108:109], v[108:109], v[116:117] op_sel_hi:[1,0]
	v_pk_mul_f32 v[104:105], v[104:105], v[116:117] op_sel_hi:[1,0]
	v_mul_f32_e32 v118, 0x3d122279, v108
	v_mul_f32_e32 v119, 0x3d122279, v104
	v_mul_f32_e32 v120, 0x3d122279, v109
	v_mul_f32_e32 v121, 0x3d122279, v105
	v_fmaak_f32 v118, v108, v118, 0x3f4c422a
	v_fmaak_f32 v119, v104, v119, 0x3f4c422a
	v_pk_mul_f32 v[110:111], v[110:111], v[116:117] op_sel_hi:[1,0]
	v_pk_mul_f32 v[106:107], v[106:107], v[116:117] op_sel_hi:[1,0]
	v_pk_mul_f32 v[102:103], v[102:103], v[116:117] op_sel_hi:[1,0]
	v_pk_mul_f32 v[100:101], v[100:101], v[116:117] op_sel_hi:[1,0]
	v_pk_mul_f32 v[98:99], v[98:99], v[116:117] op_sel_hi:[1,0]
	v_pk_mul_f32 v[116:117], v[96:97], v[116:117] op_sel_hi:[1,0]
	v_mov_b32_e32 v96, v108
	v_mov_b32_e32 v97, v104
	v_fmaak_f32 v120, v109, v120, 0x3f4c422a
	v_fmaak_f32 v121, v105, v121, 0x3f4c422a
	v_mul_f32_e32 v108, v108, v118
	v_mul_f32_e32 v104, v104, v119
	v_mul_f32_e32 v118, v109, v120
	v_mul_f32_e32 v119, v105, v121
	v_add_f32_e32 v108, v108, v108
	v_add_f32_e32 v104, v104, v104
	v_mul_f32_e32 v122, 0x3d122279, v110
	v_mul_f32_e32 v123, 0x3d122279, v106
	v_add_f32_e32 v118, v118, v118
	v_add_f32_e32 v119, v119, v119
	v_mul_f32_e32 v108, 0xbfb8aa3b, v108
	v_mul_f32_e32 v104, 0xbfb8aa3b, v104
	v_fmaak_f32 v122, v110, v122, 0x3f4c422a
	v_fmaak_f32 v123, v106, v123, 0x3f4c422a
	v_mul_f32_e32 v118, 0xbfb8aa3b, v118
	v_mul_f32_e32 v119, 0xbfb8aa3b, v119
	v_exp_f32_e32 v108, v108
	v_exp_f32_e32 v104, v104
	v_mul_f32_e32 v120, v110, v122
	v_mul_f32_e32 v121, v106, v123
	v_exp_f32_e32 v118, v118
	v_exp_f32_e32 v119, v119
	v_add_f32_e32 v120, v120, v120
	v_add_f32_e32 v121, v121, v121
	v_mul_f32_e32 v124, 0x3d122279, v111
	v_mul_f32_e32 v125, 0x3d122279, v107
	v_mul_f32_e32 v126, 0x3d122279, v100
	v_mul_f32_e32 v127, 0x3d122279, v116
	v_mul_f32_e32 v137, 0x3d122279, v101
	v_mul_f32_e32 v120, 0xbfb8aa3b, v120
	v_mul_f32_e32 v121, 0xbfb8aa3b, v121
	v_fmaak_f32 v124, v111, v124, 0x3f4c422a
	v_fmaak_f32 v125, v107, v125, 0x3f4c422a
	v_fmaak_f32 v126, v100, v126, 0x3f4c422a
	v_fmaak_f32 v127, v116, v127, 0x3f4c422a
	v_fmaak_f32 v137, v101, v137, 0x3f4c422a
	v_exp_f32_e32 v120, v120
	v_exp_f32_e32 v121, v121
	v_add_f32_e32 v108, 1.0, v108
	v_add_f32_e32 v104, 1.0, v104
	v_mul_f32_e32 v122, v111, v124
	v_mul_f32_e32 v123, v107, v125
	v_mul_f32_e32 v124, v100, v126
	v_mul_f32_e32 v125, v116, v127
	v_mul_f32_e32 v126, v101, v137
	v_add_f32_e32 v127, 1.0, v118
	v_add_f32_e32 v137, 1.0, v119
	v_rcp_f32_e32 v118, v108
	v_rcp_f32_e32 v119, v104
	v_add_f32_e32 v120, 1.0, v120
	v_add_f32_e32 v121, 1.0, v121
	v_rcp_f32_e32 v108, v127
	v_rcp_f32_e32 v104, v137
	v_rcp_f32_e32 v127, v120
	v_rcp_f32_e32 v137, v121
	v_pk_mul_f32 v[120:121], v[96:97], v[118:119]
	v_add_f32_e32 v126, v126, v126
	v_pk_fma_f32 v[96:97], v[96:97], v[118:119], v[120:121] op_sel:[0,0,1] op_sel_hi:[1,1,0]
	v_mul_f32_e32 v118, 0x3d122279, v117
	v_fmaak_f32 v118, v117, v118, 0x3f4c422a
	v_mul_f32_e32 v118, v117, v118
	v_mul_f32_e32 v97, 0xbfb8aa3b, v126
	v_add_f32_e32 v118, v118, v118
	v_exp_f32_e32 v97, v97
	v_mul_f32_e32 v118, 0xbfb8aa3b, v118
	v_exp_f32_e32 v118, v118
	v_mul_f32_e32 v119, 0x3d122279, v98
	v_add_f32_e32 v97, 1.0, v97
	v_rcp_f32_e32 v165, v97
	v_add_f32_e32 v97, 1.0, v118
	v_mul_f32_e32 v118, 0x3d122279, v102
	v_fmaak_f32 v118, v102, v118, 0x3f4c422a
	v_mul_f32_e32 v118, v102, v118
	v_fmaak_f32 v119, v98, v119, 0x3f4c422a
	v_add_f32_e32 v118, v118, v118
	v_mul_f32_e32 v119, v98, v119
	v_mul_f32_e32 v118, 0xbfb8aa3b, v118
	v_add_f32_e32 v119, v119, v119
	v_exp_f32_e32 v118, v118
	v_mul_f32_e32 v119, 0xbfb8aa3b, v119
	v_exp_f32_e32 v119, v119
	v_rcp_f32_e32 v166, v97
	v_add_f32_e32 v97, 1.0, v118
	v_mul_f32_e32 v118, 0x3d122279, v103
	v_add_f32_e32 v122, v122, v122
	v_add_f32_e32 v123, v123, v123
	v_add_f32_e32 v124, v124, v124
	v_add_f32_e32 v125, v125, v125
	v_rcp_f32_e32 v167, v97
	v_add_f32_e32 v97, 1.0, v119
	v_fmaak_f32 v118, v103, v118, 0x3f4c422a
	v_mul_f32_e32 v119, 0x3d122279, v99
	v_mul_f32_e32 v122, 0xbfb8aa3b, v122
	v_mul_f32_e32 v123, 0xbfb8aa3b, v123
	v_mul_f32_e32 v124, 0xbfb8aa3b, v124
	v_mul_f32_e32 v125, 0xbfb8aa3b, v125
	v_mul_f32_e32 v118, v103, v118
	v_fmaak_f32 v119, v99, v119, 0x3f4c422a
	v_exp_f32_e32 v122, v122
	v_exp_f32_e32 v123, v123
	v_exp_f32_e32 v124, v124
	v_exp_f32_e32 v125, v125
	v_add_f32_e32 v118, v118, v118
	v_mul_f32_e32 v119, v99, v119
	v_mul_f32_e32 v118, 0xbfb8aa3b, v118
	v_add_f32_e32 v119, v119, v119
	v_exp_f32_e32 v118, v118
	v_mul_f32_e32 v119, 0xbfb8aa3b, v119
	v_exp_f32_e32 v119, v119
	v_add_f32_e32 v122, 1.0, v122
	v_add_f32_e32 v123, 1.0, v123
	v_add_f32_e32 v124, 1.0, v124
	v_add_f32_e32 v125, 1.0, v125
	v_rcp_f32_e32 v122, v122
	v_rcp_f32_e32 v123, v123
	v_rcp_f32_e32 v151, v124
	v_rcp_f32_e32 v164, v125
	v_mov_b32_e32 v124, v109
	v_mov_b32_e32 v125, v120
	v_mov_b32_e32 v109, v120
	v_mov_b32_e32 v152, v105
	v_mov_b32_e32 v153, v121
	v_mov_b32_e32 v105, v121
	v_rcp_f32_e32 v168, v97
	v_add_f32_e32 v97, 1.0, v118
	v_mul_f32_e32 v110, v110, v127
	v_pk_mul_f32 v[126:127], v[124:125], v[108:109]
	v_pk_mul_f32 v[104:105], v[152:153], v[104:105]
	v_rcp_f32_e32 v169, v97
	v_add_f32_e32 v97, 1.0, v119
	v_pk_fma_f32 v[108:109], v[124:125], v[108:109], v[104:105]
	v_pk_mul_f32 v[124:125], v[126:127], v[126:127]
	v_pk_mul_f32 v[152:153], v[104:105], v[104:105]
	v_rcp_f32_e32 v170, v97
	v_mul_f32_e32 v106, v106, v137
	v_mov_b32_e32 v97, v124
	v_mov_b32_e32 v137, v152
	v_mul_f32_e32 v118, v111, v122
	v_mul_f32_e32 v122, v107, v123
	v_pk_add_f32 v[96:97], v[96:97], v[136:137]
	v_mul_f32_e32 v111, v110, v110
	v_mul_f32_e32 v107, v106, v106
	v_pk_add_f32 v[96:97], v[108:109], v[96:97]
	v_pk_add_f32 v[108:109], v[110:111], v[106:107]
	v_mul_f32_e32 v119, v118, v118
	v_mul_f32_e32 v123, v122, v122
	v_pk_add_f32 v[96:97], v[108:109], v[96:97]
	v_pk_add_f32 v[108:109], v[118:119], v[122:123]
	v_mul_f32_e32 v100, v100, v151
	v_pk_add_f32 v[108:109], v[108:109], v[96:97]
	v_cvt_pk_bf16_f32 v96, v120, v126
	v_cvt_pk_bf16_f32 v97, v110, v118
	v_mul_f32_e32 v110, v116, v164
	v_mul_f32_e32 v116, v101, v165
	v_mul_f32_e32 v118, v117, v166
	v_mul_f32_e32 v101, v100, v100
	v_mul_f32_e32 v111, v110, v110
	v_mul_f32_e32 v102, v102, v167
	v_mul_f32_e32 v124, v98, v168
	v_mul_f32_e32 v152, v99, v170
	v_pk_add_f32 v[98:99], v[100:101], v[110:111]
	v_mul_f32_e32 v117, v116, v116
	v_mul_f32_e32 v119, v118, v118
	v_mul_f32_e32 v126, v103, v169
	v_pk_add_f32 v[98:99], v[98:99], v[108:109]
	v_pk_add_f32 v[108:109], v[116:117], v[118:119]
	v_mul_f32_e32 v103, v102, v102
	v_mul_f32_e32 v125, v124, v124
	v_pk_add_f32 v[98:99], v[108:109], v[98:99]
	v_pk_add_f32 v[108:109], v[102:103], v[124:125]
	v_mul_f32_e32 v127, v126, v126
	v_mul_f32_e32 v153, v152, v152
	v_pk_add_f32 v[98:99], v[108:109], v[98:99]
	v_pk_add_f32 v[108:109], v[126:127], v[152:153]
	s_nop 0
	v_pk_add_f32 v[108:109], v[108:109], v[98:99]
	v_mov_b32_e32 v164, v108
	s_nop 1
	v_permlane16_swap_b32_e32 v164, v108
	v_mov_b32_e32 v165, v109
	s_nop 1
	v_permlane16_swap_b32_e32 v165, v109
	v_cvt_pk_bf16_f32 v98, v121, v104
	v_cvt_pk_bf16_f32 v99, v106, v122
	global_store_dwordx4 v[114:115], v[96:99], off
	v_cvt_pk_bf16_f32 v100, v100, v116
	v_cvt_pk_bf16_f32 v101, v102, v126
	v_cvt_pk_bf16_f32 v102, v110, v118
	v_cvt_pk_bf16_f32 v103, v124, v152
	global_store_dwordx4 v[114:115], v[100:103], off offset:256
	s_waitcnt lgkmcnt(0)
	v_pk_add_f32 v[96:97], v[108:109], v[164:165]
	v_mov_b32_e32 v98, v96
	s_nop 1
	v_permlane32_swap_b32_e32 v98, v96
	v_mov_b32_e32 v99, v97
	s_nop 1
	v_permlane32_swap_b32_e32 v99, v97
	s_and_saveexec_b64 s[48:49], s[46:47]
	s_cbranch_execz .LBB0_185
	s_lshl_b32 s14, s12, 2
	v_lshlrev_b64 v[100:101], 5, v[112:113]
	s_sub_i32 s14, s14, 32
	v_lshl_add_u64 v[100:101], v[100:101], 0, s[14:15]
	v_or_b32_e32 v100, s56, v100
	v_lshl_add_u64 v[100:101], v[100:101], 3, s[20:21]
	s_waitcnt lgkmcnt(0)
	v_pk_add_f32 v[96:97], v[96:97], v[98:99]
	global_store_dwordx2 v[100:101], v[96:97], off
.LBB0_185:
	s_or_b64 exec, exec, s[48:49]
	v_or_b32_e32 v96, 32, v150
	v_ashrrev_i32_e32 v97, 31, v96
	s_waitcnt lgkmcnt(0)
	v_lshlrev_b64 v[98:99], 7, v[96:97]
	v_lshl_add_u64 v[102:103], v[138:139], 0, v[98:99]
	global_load_dwordx4 v[98:101], v[102:103], off
	s_nop 0
	global_load_dwordx4 v[102:105], v[102:103], off offset:16
	s_waitcnt vmcnt(1)
	v_mov_b32_e32 v106, v98
	s_waitcnt vmcnt(0)
	v_mov_b32_e32 v107, v102
	v_mov_b32_e32 v102, v99
	v_mov_b32_e32 v98, v100
	v_mov_b32_e32 v99, v104
	v_mov_b32_e32 v104, v101
	v_pk_add_f32 v[100:101], v[106:107], v[102:103]
	v_pk_add_f32 v[98:99], v[98:99], v[104:105]
	s_nop 0
	v_pk_add_f32 v[98:99], v[100:101], v[98:99]
	s_nop 0
	v_add_f32_e32 v98, 0, v98
	v_add_f32_e32 v98, v98, v99
	v_mov_b32_e32 v99, v98
	s_nop 1
	v_permlane16_swap_b32_e32 v99, v98
	s_waitcnt lgkmcnt(0)
	v_add_f32_e32 v98, v98, v99
	v_mov_b32_e32 v99, v98
	s_nop 1
	v_permlane32_swap_b32_e32 v99, v98
	s_waitcnt lgkmcnt(0)
	v_add_f32_e32 v98, v98, v99
	v_fmamk_f32 v98, v98, 0x3a000000, v161
	v_mul_f32_e32 v99, 0x4b800000, v98
	v_cmp_gt_f32_e32 vcc, s64, v98
	s_nop 1
	v_cndmask_b32_e32 v98, v98, v99, vcc
	v_rsq_f32_e32 v100, v98
	v_lshlrev_b64 v[98:99], 13, v[96:97]
	v_lshl_add_u64 v[98:99], s[18:19], 0, v[98:99]
	v_lshl_add_u64 v[98:99], v[148:149], 1, v[98:99]
	v_mul_f32_e32 v101, 0x45800000, v100
	v_cndmask_b32_e32 v100, v100, v101, vcc
	v_pk_mul_f32 v[92:93], v[92:93], v[100:101] op_sel_hi:[1,0]
	v_pk_mul_f32 v[88:89], v[88:89], v[100:101] op_sel_hi:[1,0]
	v_mul_f32_e32 v102, 0x3d122279, v92
	v_mul_f32_e32 v103, 0x3d122279, v88
	v_mul_f32_e32 v104, 0x3d122279, v93
	v_mul_f32_e32 v105, 0x3d122279, v89
	v_fmaak_f32 v102, v92, v102, 0x3f4c422a
	v_fmaak_f32 v103, v88, v103, 0x3f4c422a
	v_pk_mul_f32 v[94:95], v[94:95], v[100:101] op_sel_hi:[1,0]
	v_pk_mul_f32 v[90:91], v[90:91], v[100:101] op_sel_hi:[1,0]
	v_pk_mul_f32 v[86:87], v[86:87], v[100:101] op_sel_hi:[1,0]
	v_pk_mul_f32 v[84:85], v[84:85], v[100:101] op_sel_hi:[1,0]
	v_pk_mul_f32 v[82:83], v[82:83], v[100:101] op_sel_hi:[1,0]
	v_pk_mul_f32 v[100:101], v[80:81], v[100:101] op_sel_hi:[1,0]
	v_mov_b32_e32 v80, v92
	v_mov_b32_e32 v81, v88
	v_fmaak_f32 v104, v93, v104, 0x3f4c422a
	v_fmaak_f32 v105, v89, v105, 0x3f4c422a
	v_mul_f32_e32 v92, v92, v102
	v_mul_f32_e32 v88, v88, v103
	v_mul_f32_e32 v102, v93, v104
	v_mul_f32_e32 v103, v89, v105
	v_add_f32_e32 v92, v92, v92
	v_add_f32_e32 v88, v88, v88
	v_mul_f32_e32 v106, 0x3d122279, v94
	v_mul_f32_e32 v107, 0x3d122279, v90
	v_add_f32_e32 v102, v102, v102
	v_add_f32_e32 v103, v103, v103
	v_mul_f32_e32 v92, 0xbfb8aa3b, v92
	v_mul_f32_e32 v88, 0xbfb8aa3b, v88
	v_fmaak_f32 v106, v94, v106, 0x3f4c422a
	v_fmaak_f32 v107, v90, v107, 0x3f4c422a
	v_mul_f32_e32 v102, 0xbfb8aa3b, v102
	v_mul_f32_e32 v103, 0xbfb8aa3b, v103
	v_exp_f32_e32 v92, v92
	v_exp_f32_e32 v88, v88
	v_mul_f32_e32 v104, v94, v106
	v_mul_f32_e32 v105, v90, v107
	v_exp_f32_e32 v102, v102
	v_exp_f32_e32 v103, v103
	v_add_f32_e32 v104, v104, v104
	v_add_f32_e32 v105, v105, v105
	v_mul_f32_e32 v108, 0x3d122279, v95
	v_mul_f32_e32 v109, 0x3d122279, v91
	v_mul_f32_e32 v110, 0x3d122279, v84
	v_mul_f32_e32 v111, 0x3d122279, v100
	v_mul_f32_e32 v112, 0x3d122279, v85
	v_mul_f32_e32 v104, 0xbfb8aa3b, v104
	v_mul_f32_e32 v105, 0xbfb8aa3b, v105
	v_fmaak_f32 v108, v95, v108, 0x3f4c422a
	v_fmaak_f32 v109, v91, v109, 0x3f4c422a
	v_fmaak_f32 v110, v84, v110, 0x3f4c422a
	v_fmaak_f32 v111, v100, v111, 0x3f4c422a
	v_fmaak_f32 v112, v85, v112, 0x3f4c422a
	v_exp_f32_e32 v104, v104
	v_exp_f32_e32 v105, v105
	v_add_f32_e32 v92, 1.0, v92
	v_add_f32_e32 v88, 1.0, v88
	v_mul_f32_e32 v106, v95, v108
	v_mul_f32_e32 v107, v91, v109
	v_mul_f32_e32 v108, v84, v110
	v_mul_f32_e32 v109, v100, v111
	v_mul_f32_e32 v110, v85, v112
	v_add_f32_e32 v111, 1.0, v102
	v_add_f32_e32 v112, 1.0, v103
	v_rcp_f32_e32 v102, v92
	v_rcp_f32_e32 v103, v88
	v_add_f32_e32 v104, 1.0, v104
	v_add_f32_e32 v105, 1.0, v105
	v_rcp_f32_e32 v92, v111
	v_rcp_f32_e32 v88, v112
	v_rcp_f32_e32 v111, v104
	v_rcp_f32_e32 v112, v105
	v_pk_mul_f32 v[104:105], v[80:81], v[102:103]
	v_add_f32_e32 v110, v110, v110
	v_pk_fma_f32 v[80:81], v[80:81], v[102:103], v[104:105] op_sel:[0,0,1] op_sel_hi:[1,1,0]
	v_mul_f32_e32 v102, 0x3d122279, v101
	v_fmaak_f32 v102, v101, v102, 0x3f4c422a
	v_mul_f32_e32 v102, v101, v102
	v_mul_f32_e32 v81, 0xbfb8aa3b, v110
	v_add_f32_e32 v102, v102, v102
	v_exp_f32_e32 v81, v81
	v_mul_f32_e32 v102, 0xbfb8aa3b, v102
	v_exp_f32_e32 v102, v102
	v_mul_f32_e32 v103, 0x3d122279, v82
	v_add_f32_e32 v81, 1.0, v81
	v_rcp_f32_e32 v116, v81
	v_add_f32_e32 v81, 1.0, v102
	v_mul_f32_e32 v102, 0x3d122279, v86
	v_fmaak_f32 v102, v86, v102, 0x3f4c422a
	v_mul_f32_e32 v102, v86, v102
	v_fmaak_f32 v103, v82, v103, 0x3f4c422a
	v_add_f32_e32 v102, v102, v102
	v_mul_f32_e32 v103, v82, v103
	v_mul_f32_e32 v102, 0xbfb8aa3b, v102
	v_add_f32_e32 v103, v103, v103
	v_exp_f32_e32 v102, v102
	v_mul_f32_e32 v103, 0xbfb8aa3b, v103
	v_exp_f32_e32 v103, v103
	v_rcp_f32_e32 v117, v81
	v_add_f32_e32 v81, 1.0, v102
	v_mul_f32_e32 v102, 0x3d122279, v87
	v_add_f32_e32 v106, v106, v106
	v_add_f32_e32 v107, v107, v107
	v_add_f32_e32 v108, v108, v108
	v_add_f32_e32 v109, v109, v109
	v_rcp_f32_e32 v118, v81
	v_add_f32_e32 v81, 1.0, v103
	v_fmaak_f32 v102, v87, v102, 0x3f4c422a
	v_mul_f32_e32 v103, 0x3d122279, v83
	v_mul_f32_e32 v106, 0xbfb8aa3b, v106
	v_mul_f32_e32 v107, 0xbfb8aa3b, v107
	v_mul_f32_e32 v108, 0xbfb8aa3b, v108
	v_mul_f32_e32 v109, 0xbfb8aa3b, v109
	v_mul_f32_e32 v102, v87, v102
	v_fmaak_f32 v103, v83, v103, 0x3f4c422a
	v_exp_f32_e32 v106, v106
	v_exp_f32_e32 v107, v107
	v_exp_f32_e32 v108, v108
	v_exp_f32_e32 v109, v109
	v_add_f32_e32 v102, v102, v102
	v_mul_f32_e32 v103, v83, v103
	v_mul_f32_e32 v102, 0xbfb8aa3b, v102
	v_add_f32_e32 v103, v103, v103
	v_exp_f32_e32 v102, v102
	v_mul_f32_e32 v103, 0xbfb8aa3b, v103
	v_exp_f32_e32 v103, v103
	v_add_f32_e32 v106, 1.0, v106
	v_add_f32_e32 v107, 1.0, v107
	v_add_f32_e32 v108, 1.0, v108
	v_add_f32_e32 v109, 1.0, v109
	v_rcp_f32_e32 v106, v106
	v_rcp_f32_e32 v107, v107
	v_rcp_f32_e32 v114, v108
	v_rcp_f32_e32 v115, v109
	v_mul_f32_e32 v90, v90, v112
	v_mov_b32_e32 v108, v93
	v_mov_b32_e32 v109, v104
	v_mov_b32_e32 v93, v104
	v_mov_b32_e32 v112, v89
	v_mov_b32_e32 v113, v105
	v_mov_b32_e32 v89, v105
	v_rcp_f32_e32 v119, v81
	v_add_f32_e32 v81, 1.0, v102
	v_mul_f32_e32 v94, v94, v111
	v_pk_mul_f32 v[110:111], v[108:109], v[92:93]
	v_pk_mul_f32 v[88:89], v[112:113], v[88:89]
	v_rcp_f32_e32 v120, v81
	v_add_f32_e32 v81, 1.0, v103
	v_pk_fma_f32 v[92:93], v[108:109], v[92:93], v[88:89]
	v_pk_mul_f32 v[108:109], v[110:111], v[110:111]
	v_pk_mul_f32 v[112:113], v[88:89], v[88:89]
	v_rcp_f32_e32 v121, v81
	v_mov_b32_e32 v81, v108
	v_mov_b32_e32 v137, v112
	v_mul_f32_e32 v102, v95, v106
	v_mul_f32_e32 v106, v91, v107
	v_pk_add_f32 v[80:81], v[80:81], v[136:137]
	v_mul_f32_e32 v95, v94, v94
	v_mul_f32_e32 v91, v90, v90
	v_pk_add_f32 v[80:81], v[92:93], v[80:81]
	v_pk_add_f32 v[92:93], v[94:95], v[90:91]
	v_mul_f32_e32 v103, v102, v102
	v_mul_f32_e32 v107, v106, v106
	v_pk_add_f32 v[80:81], v[92:93], v[80:81]
	v_pk_add_f32 v[92:93], v[102:103], v[106:107]
	v_mul_f32_e32 v84, v84, v114
	v_pk_add_f32 v[92:93], v[92:93], v[80:81]
	v_cvt_pk_bf16_f32 v80, v104, v110
	v_cvt_pk_bf16_f32 v81, v94, v102
	v_mul_f32_e32 v94, v100, v115
	v_mul_f32_e32 v100, v85, v116
	v_mul_f32_e32 v102, v101, v117
	v_mul_f32_e32 v85, v84, v84
	v_mul_f32_e32 v95, v94, v94
	v_mul_f32_e32 v86, v86, v118
	v_mul_f32_e32 v108, v82, v119
	v_mul_f32_e32 v112, v83, v121
	v_pk_add_f32 v[82:83], v[84:85], v[94:95]
	v_mul_f32_e32 v101, v100, v100
	v_mul_f32_e32 v103, v102, v102
	v_mul_f32_e32 v110, v87, v120
	v_pk_add_f32 v[82:83], v[82:83], v[92:93]
	v_pk_add_f32 v[92:93], v[100:101], v[102:103]
	v_mul_f32_e32 v87, v86, v86
	v_mul_f32_e32 v109, v108, v108
	v_pk_add_f32 v[82:83], v[92:93], v[82:83]
	v_pk_add_f32 v[92:93], v[86:87], v[108:109]
	v_mul_f32_e32 v111, v110, v110
	v_mul_f32_e32 v113, v112, v112
	v_pk_add_f32 v[82:83], v[92:93], v[82:83]
	v_pk_add_f32 v[92:93], v[110:111], v[112:113]
	s_nop 0
	v_pk_add_f32 v[92:93], v[92:93], v[82:83]
	v_mov_b32_e32 v114, v92
	s_nop 1
	v_permlane16_swap_b32_e32 v114, v92
	v_mov_b32_e32 v115, v93
	s_nop 1
	v_permlane16_swap_b32_e32 v115, v93
	v_cvt_pk_bf16_f32 v82, v105, v88
	v_cvt_pk_bf16_f32 v83, v90, v106
	global_store_dwordx4 v[98:99], v[80:83], off
	v_cvt_pk_bf16_f32 v84, v84, v100
	v_cvt_pk_bf16_f32 v85, v86, v110
	v_cvt_pk_bf16_f32 v86, v94, v102
	v_cvt_pk_bf16_f32 v87, v108, v112
	global_store_dwordx4 v[98:99], v[84:87], off offset:256
	s_waitcnt lgkmcnt(0)
	v_pk_add_f32 v[80:81], v[92:93], v[114:115]
	v_mov_b32_e32 v82, v80
	s_nop 1
	v_permlane32_swap_b32_e32 v82, v80
	v_mov_b32_e32 v83, v81
	s_nop 1
	v_permlane32_swap_b32_e32 v83, v81
	s_and_saveexec_b64 s[48:49], s[46:47]
	s_cbranch_execz .LBB0_187
	s_lshl_b32 s14, s12, 2
	v_lshlrev_b64 v[84:85], 5, v[96:97]
	s_sub_i32 s14, s14, 32
	v_lshl_add_u64 v[84:85], v[84:85], 0, s[14:15]
	v_or_b32_e32 v84, s56, v84
	v_lshl_add_u64 v[84:85], v[84:85], 3, s[20:21]
	s_waitcnt lgkmcnt(0)
	v_pk_add_f32 v[80:81], v[80:81], v[82:83]
	global_store_dwordx2 v[84:85], v[80:81], off
.LBB0_187:
	s_or_b64 exec, exec, s[48:49]
	v_or_b32_e32 v80, 48, v150
	v_ashrrev_i32_e32 v81, 31, v80
	s_waitcnt lgkmcnt(0)
	v_lshlrev_b64 v[82:83], 7, v[80:81]
	v_lshl_add_u64 v[86:87], v[138:139], 0, v[82:83]
	global_load_dwordx4 v[82:85], v[86:87], off
	s_nop 0
	global_load_dwordx4 v[86:89], v[86:87], off offset:16
	s_waitcnt vmcnt(1)
	v_mov_b32_e32 v90, v82
	s_waitcnt vmcnt(0)
	v_mov_b32_e32 v91, v86
	v_mov_b32_e32 v86, v83
	v_mov_b32_e32 v82, v84
	v_mov_b32_e32 v83, v88
	v_mov_b32_e32 v88, v85
	v_pk_add_f32 v[84:85], v[90:91], v[86:87]
	v_pk_add_f32 v[82:83], v[82:83], v[88:89]
	s_nop 0
	v_pk_add_f32 v[82:83], v[84:85], v[82:83]
	s_nop 0
	v_add_f32_e32 v82, 0, v82
	v_add_f32_e32 v82, v82, v83
	v_mov_b32_e32 v83, v82
	s_nop 1
	v_permlane16_swap_b32_e32 v83, v82
	s_waitcnt lgkmcnt(0)
	v_add_f32_e32 v82, v82, v83
	v_mov_b32_e32 v83, v82
	s_nop 1
	v_permlane32_swap_b32_e32 v83, v82
	s_waitcnt lgkmcnt(0)
	v_add_f32_e32 v82, v82, v83
	v_fmamk_f32 v82, v82, 0x3a000000, v161
	v_mul_f32_e32 v83, 0x4b800000, v82
	v_cmp_gt_f32_e32 vcc, s64, v82
	s_nop 1
	v_cndmask_b32_e32 v82, v82, v83, vcc
	v_rsq_f32_e32 v84, v82
	v_lshlrev_b64 v[82:83], 13, v[80:81]
	v_lshl_add_u64 v[82:83], s[18:19], 0, v[82:83]
	v_lshl_add_u64 v[82:83], v[148:149], 1, v[82:83]
	v_mul_f32_e32 v85, 0x45800000, v84
	v_cndmask_b32_e32 v84, v84, v85, vcc
	v_pk_mul_f32 v[76:77], v[76:77], v[84:85] op_sel_hi:[1,0]
	v_pk_mul_f32 v[72:73], v[72:73], v[84:85] op_sel_hi:[1,0]
	v_mul_f32_e32 v86, 0x3d122279, v76
	v_mul_f32_e32 v87, 0x3d122279, v72
	v_mul_f32_e32 v88, 0x3d122279, v77
	v_mul_f32_e32 v89, 0x3d122279, v73
	v_fmaak_f32 v86, v76, v86, 0x3f4c422a
	v_fmaak_f32 v87, v72, v87, 0x3f4c422a
	v_pk_mul_f32 v[78:79], v[78:79], v[84:85] op_sel_hi:[1,0]
	v_pk_mul_f32 v[74:75], v[74:75], v[84:85] op_sel_hi:[1,0]
	v_pk_mul_f32 v[70:71], v[70:71], v[84:85] op_sel_hi:[1,0]
	v_pk_mul_f32 v[68:69], v[68:69], v[84:85] op_sel_hi:[1,0]
	v_pk_mul_f32 v[66:67], v[66:67], v[84:85] op_sel_hi:[1,0]
	v_pk_mul_f32 v[84:85], v[64:65], v[84:85] op_sel_hi:[1,0]
	v_mov_b32_e32 v64, v76
	v_mov_b32_e32 v65, v72
	v_fmaak_f32 v88, v77, v88, 0x3f4c422a
	v_fmaak_f32 v89, v73, v89, 0x3f4c422a
	v_mul_f32_e32 v76, v76, v86
	v_mul_f32_e32 v72, v72, v87
	v_mul_f32_e32 v86, v77, v88
	v_mul_f32_e32 v87, v73, v89
	v_add_f32_e32 v76, v76, v76
	v_add_f32_e32 v72, v72, v72
	v_mul_f32_e32 v90, 0x3d122279, v78
	v_mul_f32_e32 v91, 0x3d122279, v74
	v_add_f32_e32 v86, v86, v86
	v_add_f32_e32 v87, v87, v87
	v_mul_f32_e32 v76, 0xbfb8aa3b, v76
	v_mul_f32_e32 v72, 0xbfb8aa3b, v72
	v_fmaak_f32 v90, v78, v90, 0x3f4c422a
	v_fmaak_f32 v91, v74, v91, 0x3f4c422a
	v_mul_f32_e32 v86, 0xbfb8aa3b, v86
	v_mul_f32_e32 v87, 0xbfb8aa3b, v87
	v_exp_f32_e32 v76, v76
	v_exp_f32_e32 v72, v72
	v_mul_f32_e32 v88, v78, v90
	v_mul_f32_e32 v89, v74, v91
	v_exp_f32_e32 v86, v86
	v_exp_f32_e32 v87, v87
	v_add_f32_e32 v88, v88, v88
	v_add_f32_e32 v89, v89, v89
	v_mul_f32_e32 v92, 0x3d122279, v79
	v_mul_f32_e32 v93, 0x3d122279, v75
	v_mul_f32_e32 v94, 0x3d122279, v68
	v_mul_f32_e32 v95, 0x3d122279, v84
	v_mul_f32_e32 v96, 0x3d122279, v69
	v_mul_f32_e32 v88, 0xbfb8aa3b, v88
	v_mul_f32_e32 v89, 0xbfb8aa3b, v89
	v_fmaak_f32 v92, v79, v92, 0x3f4c422a
	v_fmaak_f32 v93, v75, v93, 0x3f4c422a
	v_fmaak_f32 v94, v68, v94, 0x3f4c422a
	v_fmaak_f32 v95, v84, v95, 0x3f4c422a
	v_fmaak_f32 v96, v69, v96, 0x3f4c422a
	v_exp_f32_e32 v88, v88
	v_exp_f32_e32 v89, v89
	v_add_f32_e32 v76, 1.0, v76
	v_add_f32_e32 v72, 1.0, v72
	v_mul_f32_e32 v90, v79, v92
	v_mul_f32_e32 v91, v75, v93
	v_mul_f32_e32 v92, v68, v94
	v_mul_f32_e32 v93, v84, v95
	v_mul_f32_e32 v94, v69, v96
	v_add_f32_e32 v95, 1.0, v86
	v_add_f32_e32 v96, 1.0, v87
	v_rcp_f32_e32 v86, v76
	v_rcp_f32_e32 v87, v72
	v_add_f32_e32 v88, 1.0, v88
	v_add_f32_e32 v89, 1.0, v89
	v_rcp_f32_e32 v76, v95
	v_rcp_f32_e32 v72, v96
	v_rcp_f32_e32 v95, v88
	v_rcp_f32_e32 v96, v89
	v_pk_mul_f32 v[88:89], v[64:65], v[86:87]
	v_add_f32_e32 v94, v94, v94
	v_pk_fma_f32 v[64:65], v[64:65], v[86:87], v[88:89] op_sel:[0,0,1] op_sel_hi:[1,1,0]
	v_mul_f32_e32 v86, 0x3d122279, v85
	v_fmaak_f32 v86, v85, v86, 0x3f4c422a
	v_mul_f32_e32 v86, v85, v86
	v_mul_f32_e32 v65, 0xbfb8aa3b, v94
	v_add_f32_e32 v86, v86, v86
	v_exp_f32_e32 v65, v65
	v_mul_f32_e32 v86, 0xbfb8aa3b, v86
	v_exp_f32_e32 v86, v86
	v_mul_f32_e32 v87, 0x3d122279, v66
	v_add_f32_e32 v65, 1.0, v65
	v_rcp_f32_e32 v100, v65
	v_add_f32_e32 v65, 1.0, v86
	v_mul_f32_e32 v86, 0x3d122279, v70
	v_fmaak_f32 v86, v70, v86, 0x3f4c422a
	v_mul_f32_e32 v86, v70, v86
	v_fmaak_f32 v87, v66, v87, 0x3f4c422a
	v_add_f32_e32 v86, v86, v86
	v_mul_f32_e32 v87, v66, v87
	v_mul_f32_e32 v86, 0xbfb8aa3b, v86
	v_add_f32_e32 v87, v87, v87
	v_exp_f32_e32 v86, v86
	v_mul_f32_e32 v87, 0xbfb8aa3b, v87
	v_exp_f32_e32 v87, v87
	v_rcp_f32_e32 v101, v65
	v_add_f32_e32 v65, 1.0, v86
	v_mul_f32_e32 v86, 0x3d122279, v71
	v_add_f32_e32 v90, v90, v90
	v_add_f32_e32 v91, v91, v91
	v_add_f32_e32 v92, v92, v92
	v_add_f32_e32 v93, v93, v93
	v_rcp_f32_e32 v102, v65
	v_add_f32_e32 v65, 1.0, v87
	v_fmaak_f32 v86, v71, v86, 0x3f4c422a
	v_mul_f32_e32 v87, 0x3d122279, v67
	v_mul_f32_e32 v90, 0xbfb8aa3b, v90
	v_mul_f32_e32 v91, 0xbfb8aa3b, v91
	v_mul_f32_e32 v92, 0xbfb8aa3b, v92
	v_mul_f32_e32 v93, 0xbfb8aa3b, v93
	v_mul_f32_e32 v86, v71, v86
	v_fmaak_f32 v87, v67, v87, 0x3f4c422a
	v_exp_f32_e32 v90, v90
	v_exp_f32_e32 v91, v91
	v_exp_f32_e32 v92, v92
	v_exp_f32_e32 v93, v93
	v_add_f32_e32 v86, v86, v86
	v_mul_f32_e32 v87, v67, v87
	v_mul_f32_e32 v86, 0xbfb8aa3b, v86
	v_add_f32_e32 v87, v87, v87
	v_exp_f32_e32 v86, v86
	v_mul_f32_e32 v87, 0xbfb8aa3b, v87
	v_exp_f32_e32 v87, v87
	v_add_f32_e32 v90, 1.0, v90
	v_add_f32_e32 v91, 1.0, v91
	v_add_f32_e32 v92, 1.0, v92
	v_add_f32_e32 v93, 1.0, v93
	v_rcp_f32_e32 v90, v90
	v_rcp_f32_e32 v91, v91
	v_rcp_f32_e32 v98, v92
	v_rcp_f32_e32 v99, v93
	v_mul_f32_e32 v74, v74, v96
	v_mov_b32_e32 v92, v77
	v_mov_b32_e32 v93, v88
	v_mov_b32_e32 v77, v88
	v_mov_b32_e32 v96, v73
	v_mov_b32_e32 v97, v89
	v_mov_b32_e32 v73, v89
	v_rcp_f32_e32 v103, v65
	v_add_f32_e32 v65, 1.0, v86
	v_mul_f32_e32 v78, v78, v95
	v_pk_mul_f32 v[94:95], v[92:93], v[76:77]
	v_pk_mul_f32 v[72:73], v[96:97], v[72:73]
	v_rcp_f32_e32 v104, v65
	v_add_f32_e32 v65, 1.0, v87
	v_pk_fma_f32 v[76:77], v[92:93], v[76:77], v[72:73]
	v_pk_mul_f32 v[92:93], v[94:95], v[94:95]
	v_pk_mul_f32 v[96:97], v[72:73], v[72:73]
	v_rcp_f32_e32 v105, v65
	v_mov_b32_e32 v65, v92
	v_mov_b32_e32 v137, v96
	v_mul_f32_e32 v86, v79, v90
	v_mul_f32_e32 v90, v75, v91
	v_pk_add_f32 v[64:65], v[64:65], v[136:137]
	v_mul_f32_e32 v79, v78, v78
	v_mul_f32_e32 v75, v74, v74
	v_pk_add_f32 v[64:65], v[76:77], v[64:65]
	v_pk_add_f32 v[76:77], v[78:79], v[74:75]
	v_mul_f32_e32 v87, v86, v86
	v_mul_f32_e32 v91, v90, v90
	v_pk_add_f32 v[64:65], v[76:77], v[64:65]
	v_pk_add_f32 v[76:77], v[86:87], v[90:91]
	v_mul_f32_e32 v68, v68, v98
	v_pk_add_f32 v[76:77], v[76:77], v[64:65]
	v_cvt_pk_bf16_f32 v64, v88, v94
	v_cvt_pk_bf16_f32 v65, v78, v86
	v_mul_f32_e32 v78, v84, v99
	v_mul_f32_e32 v84, v69, v100
	v_mul_f32_e32 v86, v85, v101
	v_mul_f32_e32 v69, v68, v68
	v_mul_f32_e32 v79, v78, v78
	v_mul_f32_e32 v70, v70, v102
	v_mul_f32_e32 v92, v66, v103
	v_mul_f32_e32 v96, v67, v105
	v_pk_add_f32 v[66:67], v[68:69], v[78:79]
	v_mul_f32_e32 v85, v84, v84
	v_mul_f32_e32 v87, v86, v86
	v_mul_f32_e32 v94, v71, v104
	v_pk_add_f32 v[66:67], v[66:67], v[76:77]
	v_pk_add_f32 v[76:77], v[84:85], v[86:87]
	v_mul_f32_e32 v71, v70, v70
	v_mul_f32_e32 v93, v92, v92
	v_pk_add_f32 v[66:67], v[76:77], v[66:67]
	v_pk_add_f32 v[76:77], v[70:71], v[92:93]
	v_mul_f32_e32 v95, v94, v94
	v_mul_f32_e32 v97, v96, v96
	v_pk_add_f32 v[66:67], v[76:77], v[66:67]
	v_pk_add_f32 v[76:77], v[94:95], v[96:97]
	s_nop 0
	v_pk_add_f32 v[76:77], v[76:77], v[66:67]
	v_mov_b32_e32 v98, v76
	s_nop 1
	v_permlane16_swap_b32_e32 v98, v76
	v_mov_b32_e32 v99, v77
	s_nop 1
	v_permlane16_swap_b32_e32 v99, v77
	v_cvt_pk_bf16_f32 v66, v89, v72
	v_cvt_pk_bf16_f32 v67, v74, v90
	global_store_dwordx4 v[82:83], v[64:67], off
	v_cvt_pk_bf16_f32 v68, v68, v84
	v_cvt_pk_bf16_f32 v69, v70, v94
	v_cvt_pk_bf16_f32 v70, v78, v86
	v_cvt_pk_bf16_f32 v71, v92, v96
	global_store_dwordx4 v[82:83], v[68:71], off offset:256
	s_waitcnt lgkmcnt(0)
	v_pk_add_f32 v[64:65], v[76:77], v[98:99]
	v_mov_b32_e32 v66, v64
	s_nop 1
	v_permlane32_swap_b32_e32 v66, v64
	v_mov_b32_e32 v67, v65
	s_nop 1
	v_permlane32_swap_b32_e32 v67, v65
	s_and_saveexec_b64 s[48:49], s[46:47]
	s_cbranch_execz .LBB0_189
	s_lshl_b32 s14, s12, 2
	v_lshlrev_b64 v[68:69], 5, v[80:81]
	s_sub_i32 s14, s14, 32
	v_lshl_add_u64 v[68:69], v[68:69], 0, s[14:15]
	v_or_b32_e32 v68, s56, v68
	v_lshl_add_u64 v[68:69], v[68:69], 3, s[20:21]
	s_waitcnt lgkmcnt(0)
	v_pk_add_f32 v[64:65], v[64:65], v[66:67]
	global_store_dwordx2 v[68:69], v[64:65], off
.LBB0_189:
	s_or_b64 exec, exec, s[48:49]
	v_add_u32_e32 v64, 0x80, v150
	v_ashrrev_i32_e32 v65, 31, v64
	s_waitcnt lgkmcnt(0)
	v_lshlrev_b64 v[66:67], 7, v[64:65]
	v_lshl_add_u64 v[70:71], v[138:139], 0, v[66:67]
	global_load_dwordx4 v[66:69], v[70:71], off
	s_nop 0
	global_load_dwordx4 v[70:73], v[70:71], off offset:16
	s_waitcnt vmcnt(1)
	v_mov_b32_e32 v74, v66
	s_waitcnt vmcnt(0)
	v_mov_b32_e32 v75, v70
	v_mov_b32_e32 v70, v67
	v_mov_b32_e32 v66, v68
	v_mov_b32_e32 v67, v72
	v_mov_b32_e32 v72, v69
	v_pk_add_f32 v[68:69], v[74:75], v[70:71]
	v_pk_add_f32 v[66:67], v[66:67], v[72:73]
	s_nop 0
	v_pk_add_f32 v[66:67], v[68:69], v[66:67]
	s_nop 0
	v_add_f32_e32 v66, 0, v66
	v_add_f32_e32 v66, v66, v67
	v_mov_b32_e32 v67, v66
	s_nop 1
	v_permlane16_swap_b32_e32 v67, v66
	s_waitcnt lgkmcnt(0)
	v_add_f32_e32 v66, v66, v67
	v_mov_b32_e32 v67, v66
	s_nop 1
	v_permlane32_swap_b32_e32 v67, v66
	s_waitcnt lgkmcnt(0)
	v_add_f32_e32 v66, v66, v67
	v_fmamk_f32 v66, v66, 0x3a000000, v161
	v_mul_f32_e32 v67, 0x4b800000, v66
	v_cmp_gt_f32_e32 vcc, s64, v66
	s_nop 1
	v_cndmask_b32_e32 v66, v66, v67, vcc
	v_rsq_f32_e32 v68, v66
	v_lshlrev_b64 v[66:67], 13, v[64:65]
	v_lshl_add_u64 v[66:67], s[18:19], 0, v[66:67]
	v_lshl_add_u64 v[66:67], v[148:149], 1, v[66:67]
	v_mul_f32_e32 v69, 0x45800000, v68
	v_cndmask_b32_e32 v68, v68, v69, vcc
	v_pk_mul_f32 v[60:61], v[60:61], v[68:69] op_sel_hi:[1,0]
	v_pk_mul_f32 v[56:57], v[56:57], v[68:69] op_sel_hi:[1,0]
	v_mul_f32_e32 v70, 0x3d122279, v60
	v_mul_f32_e32 v71, 0x3d122279, v56
	v_mul_f32_e32 v72, 0x3d122279, v61
	v_mul_f32_e32 v73, 0x3d122279, v57
	v_fmaak_f32 v70, v60, v70, 0x3f4c422a
	v_fmaak_f32 v71, v56, v71, 0x3f4c422a
	v_pk_mul_f32 v[62:63], v[62:63], v[68:69] op_sel_hi:[1,0]
	v_pk_mul_f32 v[58:59], v[58:59], v[68:69] op_sel_hi:[1,0]
	v_pk_mul_f32 v[54:55], v[54:55], v[68:69] op_sel_hi:[1,0]
	v_pk_mul_f32 v[52:53], v[52:53], v[68:69] op_sel_hi:[1,0]
	v_pk_mul_f32 v[50:51], v[50:51], v[68:69] op_sel_hi:[1,0]
	v_pk_mul_f32 v[68:69], v[48:49], v[68:69] op_sel_hi:[1,0]
	v_mov_b32_e32 v48, v60
	v_mov_b32_e32 v49, v56
	v_fmaak_f32 v72, v61, v72, 0x3f4c422a
	v_fmaak_f32 v73, v57, v73, 0x3f4c422a
	v_mul_f32_e32 v60, v60, v70
	v_mul_f32_e32 v56, v56, v71
	v_mul_f32_e32 v70, v61, v72
	v_mul_f32_e32 v71, v57, v73
	v_add_f32_e32 v60, v60, v60
	v_add_f32_e32 v56, v56, v56
	v_mul_f32_e32 v74, 0x3d122279, v62
	v_mul_f32_e32 v75, 0x3d122279, v58
	v_add_f32_e32 v70, v70, v70
	v_add_f32_e32 v71, v71, v71
	v_mul_f32_e32 v60, 0xbfb8aa3b, v60
	v_mul_f32_e32 v56, 0xbfb8aa3b, v56
	v_fmaak_f32 v74, v62, v74, 0x3f4c422a
	v_fmaak_f32 v75, v58, v75, 0x3f4c422a
	v_mul_f32_e32 v70, 0xbfb8aa3b, v70
	v_mul_f32_e32 v71, 0xbfb8aa3b, v71
	v_exp_f32_e32 v60, v60
	v_exp_f32_e32 v56, v56
	v_mul_f32_e32 v72, v62, v74
	v_mul_f32_e32 v73, v58, v75
	v_exp_f32_e32 v70, v70
	v_exp_f32_e32 v71, v71
	v_add_f32_e32 v72, v72, v72
	v_add_f32_e32 v73, v73, v73
	v_mul_f32_e32 v76, 0x3d122279, v63
	v_mul_f32_e32 v77, 0x3d122279, v59
	v_mul_f32_e32 v78, 0x3d122279, v52
	v_mul_f32_e32 v79, 0x3d122279, v68
	v_mul_f32_e32 v80, 0x3d122279, v53
	v_mul_f32_e32 v72, 0xbfb8aa3b, v72
	v_mul_f32_e32 v73, 0xbfb8aa3b, v73
	v_fmaak_f32 v76, v63, v76, 0x3f4c422a
	v_fmaak_f32 v77, v59, v77, 0x3f4c422a
	v_fmaak_f32 v78, v52, v78, 0x3f4c422a
	v_fmaak_f32 v79, v68, v79, 0x3f4c422a
	v_fmaak_f32 v80, v53, v80, 0x3f4c422a
	v_exp_f32_e32 v72, v72
	v_exp_f32_e32 v73, v73
	v_add_f32_e32 v60, 1.0, v60
	v_add_f32_e32 v56, 1.0, v56
	v_mul_f32_e32 v74, v63, v76
	v_mul_f32_e32 v75, v59, v77
	v_mul_f32_e32 v76, v52, v78
	v_mul_f32_e32 v77, v68, v79
	v_mul_f32_e32 v78, v53, v80
	v_add_f32_e32 v79, 1.0, v70
	v_add_f32_e32 v80, 1.0, v71
	v_rcp_f32_e32 v70, v60
	v_rcp_f32_e32 v71, v56
	v_add_f32_e32 v72, 1.0, v72
	v_add_f32_e32 v73, 1.0, v73
	v_rcp_f32_e32 v60, v79
	v_rcp_f32_e32 v56, v80
	v_rcp_f32_e32 v79, v72
	v_rcp_f32_e32 v80, v73
	v_pk_mul_f32 v[72:73], v[48:49], v[70:71]
	v_add_f32_e32 v78, v78, v78
	v_pk_fma_f32 v[48:49], v[48:49], v[70:71], v[72:73] op_sel:[0,0,1] op_sel_hi:[1,1,0]
	v_mul_f32_e32 v70, 0x3d122279, v69
	v_fmaak_f32 v70, v69, v70, 0x3f4c422a
	v_mul_f32_e32 v70, v69, v70
	v_mul_f32_e32 v49, 0xbfb8aa3b, v78
	v_add_f32_e32 v70, v70, v70
	v_exp_f32_e32 v49, v49
	v_mul_f32_e32 v70, 0xbfb8aa3b, v70
	v_exp_f32_e32 v70, v70
	v_mul_f32_e32 v71, 0x3d122279, v50
	v_add_f32_e32 v49, 1.0, v49
	v_rcp_f32_e32 v84, v49
	v_add_f32_e32 v49, 1.0, v70
	v_mul_f32_e32 v70, 0x3d122279, v54
	v_fmaak_f32 v70, v54, v70, 0x3f4c422a
	v_mul_f32_e32 v70, v54, v70
	v_fmaak_f32 v71, v50, v71, 0x3f4c422a
	v_add_f32_e32 v70, v70, v70
	v_mul_f32_e32 v71, v50, v71
	v_mul_f32_e32 v70, 0xbfb8aa3b, v70
	v_add_f32_e32 v71, v71, v71
	v_exp_f32_e32 v70, v70
	v_mul_f32_e32 v71, 0xbfb8aa3b, v71
	v_exp_f32_e32 v71, v71
	v_rcp_f32_e32 v85, v49
	v_add_f32_e32 v49, 1.0, v70
	v_mul_f32_e32 v70, 0x3d122279, v55
	v_add_f32_e32 v74, v74, v74
	v_add_f32_e32 v75, v75, v75
	v_add_f32_e32 v76, v76, v76
	v_add_f32_e32 v77, v77, v77
	v_rcp_f32_e32 v86, v49
	v_add_f32_e32 v49, 1.0, v71
	v_fmaak_f32 v70, v55, v70, 0x3f4c422a
	v_mul_f32_e32 v71, 0x3d122279, v51
	v_mul_f32_e32 v74, 0xbfb8aa3b, v74
	v_mul_f32_e32 v75, 0xbfb8aa3b, v75
	v_mul_f32_e32 v76, 0xbfb8aa3b, v76
	v_mul_f32_e32 v77, 0xbfb8aa3b, v77
	v_mul_f32_e32 v70, v55, v70
	v_fmaak_f32 v71, v51, v71, 0x3f4c422a
	v_exp_f32_e32 v74, v74
	v_exp_f32_e32 v75, v75
	v_exp_f32_e32 v76, v76
	v_exp_f32_e32 v77, v77
	v_add_f32_e32 v70, v70, v70
	v_mul_f32_e32 v71, v51, v71
	v_mul_f32_e32 v70, 0xbfb8aa3b, v70
	v_add_f32_e32 v71, v71, v71
	v_exp_f32_e32 v70, v70
	v_mul_f32_e32 v71, 0xbfb8aa3b, v71
	v_exp_f32_e32 v71, v71
	v_add_f32_e32 v74, 1.0, v74
	v_add_f32_e32 v75, 1.0, v75
	v_add_f32_e32 v76, 1.0, v76
	v_add_f32_e32 v77, 1.0, v77
	v_rcp_f32_e32 v74, v74
	v_rcp_f32_e32 v75, v75
	v_rcp_f32_e32 v82, v76
	v_rcp_f32_e32 v83, v77
	v_mul_f32_e32 v58, v58, v80
	v_mov_b32_e32 v76, v61
	v_mov_b32_e32 v77, v72
	v_mov_b32_e32 v61, v72
	v_mov_b32_e32 v80, v57
	v_mov_b32_e32 v81, v73
	v_mov_b32_e32 v57, v73
	v_rcp_f32_e32 v87, v49
	v_add_f32_e32 v49, 1.0, v70
	v_mul_f32_e32 v62, v62, v79
	v_pk_mul_f32 v[78:79], v[76:77], v[60:61]
	v_pk_mul_f32 v[56:57], v[80:81], v[56:57]
	v_rcp_f32_e32 v88, v49
	v_add_f32_e32 v49, 1.0, v71
	v_pk_fma_f32 v[60:61], v[76:77], v[60:61], v[56:57]
	v_pk_mul_f32 v[76:77], v[78:79], v[78:79]
	v_pk_mul_f32 v[80:81], v[56:57], v[56:57]
	v_rcp_f32_e32 v89, v49
	v_mov_b32_e32 v49, v76
	v_mov_b32_e32 v137, v80
	v_mul_f32_e32 v70, v63, v74
	v_mul_f32_e32 v74, v59, v75
	v_pk_add_f32 v[48:49], v[48:49], v[136:137]
	v_mul_f32_e32 v63, v62, v62
	v_mul_f32_e32 v59, v58, v58
	v_pk_add_f32 v[48:49], v[60:61], v[48:49]
	v_pk_add_f32 v[60:61], v[62:63], v[58:59]
	v_mul_f32_e32 v71, v70, v70
	v_mul_f32_e32 v75, v74, v74
	v_pk_add_f32 v[48:49], v[60:61], v[48:49]
	v_pk_add_f32 v[60:61], v[70:71], v[74:75]
	v_mul_f32_e32 v52, v52, v82
	v_pk_add_f32 v[60:61], v[60:61], v[48:49]
	v_cvt_pk_bf16_f32 v48, v72, v78
	v_cvt_pk_bf16_f32 v49, v62, v70
	v_mul_f32_e32 v62, v68, v83
	v_mul_f32_e32 v68, v53, v84
	v_mul_f32_e32 v70, v69, v85
	v_mul_f32_e32 v53, v52, v52
	v_mul_f32_e32 v63, v62, v62
	v_mul_f32_e32 v54, v54, v86
	v_mul_f32_e32 v76, v50, v87
	v_mul_f32_e32 v80, v51, v89
	v_pk_add_f32 v[50:51], v[52:53], v[62:63]
	v_mul_f32_e32 v69, v68, v68
	v_mul_f32_e32 v71, v70, v70
	v_mul_f32_e32 v78, v55, v88
	v_pk_add_f32 v[50:51], v[50:51], v[60:61]
	v_pk_add_f32 v[60:61], v[68:69], v[70:71]
	v_mul_f32_e32 v55, v54, v54
	v_mul_f32_e32 v77, v76, v76
	v_pk_add_f32 v[50:51], v[60:61], v[50:51]
	v_pk_add_f32 v[60:61], v[54:55], v[76:77]
	v_mul_f32_e32 v79, v78, v78
	v_mul_f32_e32 v81, v80, v80
	v_pk_add_f32 v[50:51], v[60:61], v[50:51]
	v_pk_add_f32 v[60:61], v[78:79], v[80:81]
	s_nop 0
	v_pk_add_f32 v[60:61], v[60:61], v[50:51]
	v_mov_b32_e32 v82, v60
	s_nop 1
	v_permlane16_swap_b32_e32 v82, v60
	v_mov_b32_e32 v83, v61
	s_nop 1
	v_permlane16_swap_b32_e32 v83, v61
	v_cvt_pk_bf16_f32 v50, v73, v56
	v_cvt_pk_bf16_f32 v51, v58, v74
	global_store_dwordx4 v[66:67], v[48:51], off
	v_cvt_pk_bf16_f32 v52, v52, v68
	v_cvt_pk_bf16_f32 v53, v54, v78
	v_cvt_pk_bf16_f32 v54, v62, v70
	v_cvt_pk_bf16_f32 v55, v76, v80
	global_store_dwordx4 v[66:67], v[52:55], off offset:256
	s_waitcnt lgkmcnt(0)
	v_pk_add_f32 v[48:49], v[60:61], v[82:83]
	v_mov_b32_e32 v50, v48
	s_nop 1
	v_permlane32_swap_b32_e32 v50, v48
	v_mov_b32_e32 v51, v49
	s_nop 1
	v_permlane32_swap_b32_e32 v51, v49
	s_and_saveexec_b64 s[48:49], s[46:47]
	s_cbranch_execz .LBB0_191
	s_lshl_b32 s14, s12, 2
	v_lshlrev_b64 v[52:53], 5, v[64:65]
	s_sub_i32 s14, s14, 32
	v_lshl_add_u64 v[52:53], v[52:53], 0, s[14:15]
	v_or_b32_e32 v52, s56, v52
	v_lshl_add_u64 v[52:53], v[52:53], 3, s[20:21]
	s_waitcnt lgkmcnt(0)
	v_pk_add_f32 v[48:49], v[48:49], v[50:51]
	global_store_dwordx2 v[52:53], v[48:49], off
.LBB0_191:
	s_or_b64 exec, exec, s[48:49]
	v_add_u32_e32 v48, 0x90, v150
	v_ashrrev_i32_e32 v49, 31, v48
	s_waitcnt lgkmcnt(0)
	v_lshlrev_b64 v[50:51], 7, v[48:49]
	v_lshl_add_u64 v[54:55], v[138:139], 0, v[50:51]
	global_load_dwordx4 v[50:53], v[54:55], off
	s_nop 0
	global_load_dwordx4 v[54:57], v[54:55], off offset:16
	s_waitcnt vmcnt(1)
	v_mov_b32_e32 v58, v50
	s_waitcnt vmcnt(0)
	v_mov_b32_e32 v59, v54
	v_mov_b32_e32 v54, v51
	v_mov_b32_e32 v50, v52
	v_mov_b32_e32 v51, v56
	v_mov_b32_e32 v56, v53
	v_pk_add_f32 v[52:53], v[58:59], v[54:55]
	v_pk_add_f32 v[50:51], v[50:51], v[56:57]
	s_nop 0
	v_pk_add_f32 v[50:51], v[52:53], v[50:51]
	s_nop 0
	v_add_f32_e32 v50, 0, v50
	v_add_f32_e32 v50, v50, v51
	v_mov_b32_e32 v51, v50
	s_nop 1
	v_permlane16_swap_b32_e32 v51, v50
	s_waitcnt lgkmcnt(0)
	v_add_f32_e32 v50, v50, v51
	v_mov_b32_e32 v51, v50
	s_nop 1
	v_permlane32_swap_b32_e32 v51, v50
	s_waitcnt lgkmcnt(0)
	v_add_f32_e32 v50, v50, v51
	v_fmamk_f32 v50, v50, 0x3a000000, v161
	v_mul_f32_e32 v51, 0x4b800000, v50
	v_cmp_gt_f32_e32 vcc, s64, v50
	s_nop 1
	v_cndmask_b32_e32 v50, v50, v51, vcc
	v_rsq_f32_e32 v52, v50
	v_lshlrev_b64 v[50:51], 13, v[48:49]
	v_lshl_add_u64 v[50:51], s[18:19], 0, v[50:51]
	v_lshl_add_u64 v[50:51], v[148:149], 1, v[50:51]
	v_mul_f32_e32 v53, 0x45800000, v52
	v_cndmask_b32_e32 v52, v52, v53, vcc
	v_pk_mul_f32 v[44:45], v[44:45], v[52:53] op_sel_hi:[1,0]
	v_pk_mul_f32 v[40:41], v[40:41], v[52:53] op_sel_hi:[1,0]
	v_mul_f32_e32 v54, 0x3d122279, v44
	v_mul_f32_e32 v55, 0x3d122279, v40
	v_mul_f32_e32 v56, 0x3d122279, v45
	v_mul_f32_e32 v57, 0x3d122279, v41
	v_fmaak_f32 v54, v44, v54, 0x3f4c422a
	v_fmaak_f32 v55, v40, v55, 0x3f4c422a
	v_pk_mul_f32 v[46:47], v[46:47], v[52:53] op_sel_hi:[1,0]
	v_pk_mul_f32 v[42:43], v[42:43], v[52:53] op_sel_hi:[1,0]
	v_pk_mul_f32 v[38:39], v[38:39], v[52:53] op_sel_hi:[1,0]
	v_pk_mul_f32 v[36:37], v[36:37], v[52:53] op_sel_hi:[1,0]
	v_pk_mul_f32 v[34:35], v[34:35], v[52:53] op_sel_hi:[1,0]
	v_pk_mul_f32 v[52:53], v[32:33], v[52:53] op_sel_hi:[1,0]
	v_mov_b32_e32 v32, v44
	v_mov_b32_e32 v33, v40
	v_fmaak_f32 v56, v45, v56, 0x3f4c422a
	v_fmaak_f32 v57, v41, v57, 0x3f4c422a
	v_mul_f32_e32 v44, v44, v54
	v_mul_f32_e32 v40, v40, v55
	v_mul_f32_e32 v54, v45, v56
	v_mul_f32_e32 v55, v41, v57
	v_add_f32_e32 v44, v44, v44
	v_add_f32_e32 v40, v40, v40
	v_mul_f32_e32 v58, 0x3d122279, v46
	v_mul_f32_e32 v59, 0x3d122279, v42
	v_add_f32_e32 v54, v54, v54
	v_add_f32_e32 v55, v55, v55
	v_mul_f32_e32 v44, 0xbfb8aa3b, v44
	v_mul_f32_e32 v40, 0xbfb8aa3b, v40
	v_fmaak_f32 v58, v46, v58, 0x3f4c422a
	v_fmaak_f32 v59, v42, v59, 0x3f4c422a
	v_mul_f32_e32 v54, 0xbfb8aa3b, v54
	v_mul_f32_e32 v55, 0xbfb8aa3b, v55
	v_exp_f32_e32 v44, v44
	v_exp_f32_e32 v40, v40
	v_mul_f32_e32 v56, v46, v58
	v_mul_f32_e32 v57, v42, v59
	v_exp_f32_e32 v54, v54
	v_exp_f32_e32 v55, v55
	v_add_f32_e32 v56, v56, v56
	v_add_f32_e32 v57, v57, v57
	v_mul_f32_e32 v60, 0x3d122279, v47
	v_mul_f32_e32 v61, 0x3d122279, v43
	v_mul_f32_e32 v62, 0x3d122279, v36
	v_mul_f32_e32 v63, 0x3d122279, v52
	v_mul_f32_e32 v64, 0x3d122279, v37
	v_mul_f32_e32 v56, 0xbfb8aa3b, v56
	v_mul_f32_e32 v57, 0xbfb8aa3b, v57
	v_fmaak_f32 v60, v47, v60, 0x3f4c422a
	v_fmaak_f32 v61, v43, v61, 0x3f4c422a
	v_fmaak_f32 v62, v36, v62, 0x3f4c422a
	v_fmaak_f32 v63, v52, v63, 0x3f4c422a
	v_fmaak_f32 v64, v37, v64, 0x3f4c422a
	v_exp_f32_e32 v56, v56
	v_exp_f32_e32 v57, v57
	v_add_f32_e32 v44, 1.0, v44
	v_add_f32_e32 v40, 1.0, v40
	v_mul_f32_e32 v58, v47, v60
	v_mul_f32_e32 v59, v43, v61
	v_mul_f32_e32 v60, v36, v62
	v_mul_f32_e32 v61, v52, v63
	v_mul_f32_e32 v62, v37, v64
	v_add_f32_e32 v63, 1.0, v54
	v_add_f32_e32 v64, 1.0, v55
	v_rcp_f32_e32 v54, v44
	v_rcp_f32_e32 v55, v40
	v_add_f32_e32 v56, 1.0, v56
	v_add_f32_e32 v57, 1.0, v57
	v_rcp_f32_e32 v44, v63
	v_rcp_f32_e32 v40, v64
	v_rcp_f32_e32 v63, v56
	v_rcp_f32_e32 v64, v57
	v_pk_mul_f32 v[56:57], v[32:33], v[54:55]
	v_add_f32_e32 v62, v62, v62
	v_pk_fma_f32 v[32:33], v[32:33], v[54:55], v[56:57] op_sel:[0,0,1] op_sel_hi:[1,1,0]
	v_mul_f32_e32 v54, 0x3d122279, v53
	v_fmaak_f32 v54, v53, v54, 0x3f4c422a
	v_mul_f32_e32 v54, v53, v54
	v_mul_f32_e32 v33, 0xbfb8aa3b, v62
	v_add_f32_e32 v54, v54, v54
	v_exp_f32_e32 v33, v33
	v_mul_f32_e32 v54, 0xbfb8aa3b, v54
	v_exp_f32_e32 v54, v54
	v_mul_f32_e32 v55, 0x3d122279, v34
	v_add_f32_e32 v33, 1.0, v33
	v_rcp_f32_e32 v68, v33
	v_add_f32_e32 v33, 1.0, v54
	v_mul_f32_e32 v54, 0x3d122279, v38
	v_fmaak_f32 v54, v38, v54, 0x3f4c422a
	v_mul_f32_e32 v54, v38, v54
	v_fmaak_f32 v55, v34, v55, 0x3f4c422a
	v_add_f32_e32 v54, v54, v54
	v_mul_f32_e32 v55, v34, v55
	v_mul_f32_e32 v54, 0xbfb8aa3b, v54
	v_add_f32_e32 v55, v55, v55
	v_exp_f32_e32 v54, v54
	v_mul_f32_e32 v55, 0xbfb8aa3b, v55
	v_exp_f32_e32 v55, v55
	v_rcp_f32_e32 v69, v33
	v_add_f32_e32 v33, 1.0, v54
	v_mul_f32_e32 v54, 0x3d122279, v39
	v_add_f32_e32 v58, v58, v58
	v_add_f32_e32 v59, v59, v59
	v_add_f32_e32 v60, v60, v60
	v_add_f32_e32 v61, v61, v61
	v_rcp_f32_e32 v70, v33
	v_add_f32_e32 v33, 1.0, v55
	v_fmaak_f32 v54, v39, v54, 0x3f4c422a
	v_mul_f32_e32 v55, 0x3d122279, v35
	v_mul_f32_e32 v58, 0xbfb8aa3b, v58
	v_mul_f32_e32 v59, 0xbfb8aa3b, v59
	v_mul_f32_e32 v60, 0xbfb8aa3b, v60
	v_mul_f32_e32 v61, 0xbfb8aa3b, v61
	v_mul_f32_e32 v54, v39, v54
	v_fmaak_f32 v55, v35, v55, 0x3f4c422a
	v_exp_f32_e32 v58, v58
	v_exp_f32_e32 v59, v59
	v_exp_f32_e32 v60, v60
	v_exp_f32_e32 v61, v61
	v_add_f32_e32 v54, v54, v54
	v_mul_f32_e32 v55, v35, v55
	v_mul_f32_e32 v54, 0xbfb8aa3b, v54
	v_add_f32_e32 v55, v55, v55
	v_exp_f32_e32 v54, v54
	v_mul_f32_e32 v55, 0xbfb8aa3b, v55
	v_exp_f32_e32 v55, v55
	v_add_f32_e32 v58, 1.0, v58
	v_add_f32_e32 v59, 1.0, v59
	v_add_f32_e32 v60, 1.0, v60
	v_add_f32_e32 v61, 1.0, v61
	v_rcp_f32_e32 v58, v58
	v_rcp_f32_e32 v59, v59
	v_rcp_f32_e32 v66, v60
	v_rcp_f32_e32 v67, v61
	v_mul_f32_e32 v42, v42, v64
	v_mov_b32_e32 v60, v45
	v_mov_b32_e32 v61, v56
	v_mov_b32_e32 v45, v56
	v_mov_b32_e32 v64, v41
	v_mov_b32_e32 v65, v57
	v_mov_b32_e32 v41, v57
	v_rcp_f32_e32 v71, v33
	v_add_f32_e32 v33, 1.0, v54
	v_mul_f32_e32 v46, v46, v63
	v_pk_mul_f32 v[62:63], v[60:61], v[44:45]
	v_pk_mul_f32 v[40:41], v[64:65], v[40:41]
	v_rcp_f32_e32 v72, v33
	v_add_f32_e32 v33, 1.0, v55
	v_pk_fma_f32 v[44:45], v[60:61], v[44:45], v[40:41]
	v_pk_mul_f32 v[60:61], v[62:63], v[62:63]
	v_pk_mul_f32 v[64:65], v[40:41], v[40:41]
	v_rcp_f32_e32 v73, v33
	v_mov_b32_e32 v33, v60
	v_mov_b32_e32 v137, v64
	v_mul_f32_e32 v54, v47, v58
	v_mul_f32_e32 v58, v43, v59
	v_pk_add_f32 v[32:33], v[32:33], v[136:137]
	v_mul_f32_e32 v47, v46, v46
	v_mul_f32_e32 v43, v42, v42
	v_pk_add_f32 v[32:33], v[44:45], v[32:33]
	v_pk_add_f32 v[44:45], v[46:47], v[42:43]
	v_mul_f32_e32 v55, v54, v54
	v_mul_f32_e32 v59, v58, v58
	v_pk_add_f32 v[32:33], v[44:45], v[32:33]
	v_pk_add_f32 v[44:45], v[54:55], v[58:59]
	v_mul_f32_e32 v36, v36, v66
	v_pk_add_f32 v[44:45], v[44:45], v[32:33]
	v_cvt_pk_bf16_f32 v32, v56, v62
	v_cvt_pk_bf16_f32 v33, v46, v54
	v_mul_f32_e32 v46, v52, v67
	v_mul_f32_e32 v52, v37, v68
	v_mul_f32_e32 v54, v53, v69
	v_mul_f32_e32 v37, v36, v36
	v_mul_f32_e32 v47, v46, v46
	v_mul_f32_e32 v38, v38, v70
	v_mul_f32_e32 v60, v34, v71
	v_mul_f32_e32 v64, v35, v73
	v_pk_add_f32 v[34:35], v[36:37], v[46:47]
	v_mul_f32_e32 v53, v52, v52
	v_mul_f32_e32 v55, v54, v54
	v_mul_f32_e32 v62, v39, v72
	v_pk_add_f32 v[34:35], v[34:35], v[44:45]
	v_pk_add_f32 v[44:45], v[52:53], v[54:55]
	v_mul_f32_e32 v39, v38, v38
	v_mul_f32_e32 v61, v60, v60
	v_pk_add_f32 v[34:35], v[44:45], v[34:35]
	v_pk_add_f32 v[44:45], v[38:39], v[60:61]
	v_mul_f32_e32 v63, v62, v62
	v_mul_f32_e32 v65, v64, v64
	v_pk_add_f32 v[34:35], v[44:45], v[34:35]
	v_pk_add_f32 v[44:45], v[62:63], v[64:65]
	s_nop 0
	v_pk_add_f32 v[44:45], v[44:45], v[34:35]
	v_mov_b32_e32 v66, v44
	s_nop 1
	v_permlane16_swap_b32_e32 v66, v44
	v_mov_b32_e32 v67, v45
	s_nop 1
	v_permlane16_swap_b32_e32 v67, v45
	v_cvt_pk_bf16_f32 v34, v57, v40
	v_cvt_pk_bf16_f32 v35, v42, v58
	global_store_dwordx4 v[50:51], v[32:35], off
	v_cvt_pk_bf16_f32 v36, v36, v52
	v_cvt_pk_bf16_f32 v37, v38, v62
	v_cvt_pk_bf16_f32 v38, v46, v54
	v_cvt_pk_bf16_f32 v39, v60, v64
	global_store_dwordx4 v[50:51], v[36:39], off offset:256
	s_waitcnt lgkmcnt(0)
	v_pk_add_f32 v[32:33], v[44:45], v[66:67]
	v_mov_b32_e32 v34, v32
	s_nop 1
	v_permlane32_swap_b32_e32 v34, v32
	v_mov_b32_e32 v35, v33
	s_nop 1
	v_permlane32_swap_b32_e32 v35, v33
	s_and_saveexec_b64 s[48:49], s[46:47]
	s_cbranch_execz .LBB0_193
	s_lshl_b32 s14, s12, 2
	v_lshlrev_b64 v[36:37], 5, v[48:49]
	s_sub_i32 s14, s14, 32
	v_lshl_add_u64 v[36:37], v[36:37], 0, s[14:15]
	v_or_b32_e32 v36, s56, v36
	v_lshl_add_u64 v[36:37], v[36:37], 3, s[20:21]
	s_waitcnt lgkmcnt(0)
	v_pk_add_f32 v[32:33], v[32:33], v[34:35]
	global_store_dwordx2 v[36:37], v[32:33], off
.LBB0_193:
	s_or_b64 exec, exec, s[48:49]
	v_add_u32_e32 v32, 0xa0, v150
	v_ashrrev_i32_e32 v33, 31, v32
	s_waitcnt lgkmcnt(0)
	v_lshlrev_b64 v[34:35], 7, v[32:33]
	v_lshl_add_u64 v[38:39], v[138:139], 0, v[34:35]
	global_load_dwordx4 v[34:37], v[38:39], off
	s_nop 0
	global_load_dwordx4 v[38:41], v[38:39], off offset:16
	s_waitcnt vmcnt(1)
	v_mov_b32_e32 v42, v34
	s_waitcnt vmcnt(0)
	v_mov_b32_e32 v43, v38
	v_mov_b32_e32 v38, v35
	v_mov_b32_e32 v34, v36
	v_mov_b32_e32 v35, v40
	v_mov_b32_e32 v40, v37
	v_pk_add_f32 v[36:37], v[42:43], v[38:39]
	v_pk_add_f32 v[34:35], v[34:35], v[40:41]
	s_nop 0
	v_pk_add_f32 v[34:35], v[36:37], v[34:35]
	s_nop 0
	v_add_f32_e32 v34, 0, v34
	v_add_f32_e32 v34, v34, v35
	v_mov_b32_e32 v35, v34
	s_nop 1
	v_permlane16_swap_b32_e32 v35, v34
	s_waitcnt lgkmcnt(0)
	v_add_f32_e32 v34, v34, v35
	v_mov_b32_e32 v35, v34
	s_nop 1
	v_permlane32_swap_b32_e32 v35, v34
	s_waitcnt lgkmcnt(0)
	v_add_f32_e32 v34, v34, v35
	v_fmamk_f32 v34, v34, 0x3a000000, v161
	v_mul_f32_e32 v35, 0x4b800000, v34
	v_cmp_gt_f32_e32 vcc, s64, v34
	s_nop 1
	v_cndmask_b32_e32 v34, v34, v35, vcc
	v_rsq_f32_e32 v36, v34
	v_lshlrev_b64 v[34:35], 13, v[32:33]
	v_lshl_add_u64 v[34:35], s[18:19], 0, v[34:35]
	v_lshl_add_u64 v[34:35], v[148:149], 1, v[34:35]
	v_mul_f32_e32 v37, 0x45800000, v36
	v_cndmask_b32_e32 v36, v36, v37, vcc
	v_pk_mul_f32 v[28:29], v[28:29], v[36:37] op_sel_hi:[1,0]
	v_pk_mul_f32 v[24:25], v[24:25], v[36:37] op_sel_hi:[1,0]
	v_mul_f32_e32 v38, 0x3d122279, v28
	v_mul_f32_e32 v39, 0x3d122279, v24
	v_mul_f32_e32 v40, 0x3d122279, v29
	v_mul_f32_e32 v41, 0x3d122279, v25
	v_fmaak_f32 v38, v28, v38, 0x3f4c422a
	v_fmaak_f32 v39, v24, v39, 0x3f4c422a
	v_pk_mul_f32 v[30:31], v[30:31], v[36:37] op_sel_hi:[1,0]
	v_pk_mul_f32 v[26:27], v[26:27], v[36:37] op_sel_hi:[1,0]
	v_pk_mul_f32 v[22:23], v[22:23], v[36:37] op_sel_hi:[1,0]
	v_pk_mul_f32 v[20:21], v[20:21], v[36:37] op_sel_hi:[1,0]
	v_pk_mul_f32 v[18:19], v[18:19], v[36:37] op_sel_hi:[1,0]
	v_pk_mul_f32 v[36:37], v[16:17], v[36:37] op_sel_hi:[1,0]
	v_mov_b32_e32 v16, v28
	v_mov_b32_e32 v17, v24
	v_fmaak_f32 v40, v29, v40, 0x3f4c422a
	v_fmaak_f32 v41, v25, v41, 0x3f4c422a
	v_mul_f32_e32 v28, v28, v38
	v_mul_f32_e32 v24, v24, v39
	v_mul_f32_e32 v38, v29, v40
	v_mul_f32_e32 v39, v25, v41
	v_add_f32_e32 v28, v28, v28
	v_add_f32_e32 v24, v24, v24
	v_mul_f32_e32 v42, 0x3d122279, v30
	v_mul_f32_e32 v43, 0x3d122279, v26
	v_add_f32_e32 v38, v38, v38
	v_add_f32_e32 v39, v39, v39
	v_mul_f32_e32 v28, 0xbfb8aa3b, v28
	v_mul_f32_e32 v24, 0xbfb8aa3b, v24
	v_fmaak_f32 v42, v30, v42, 0x3f4c422a
	v_fmaak_f32 v43, v26, v43, 0x3f4c422a
	v_mul_f32_e32 v38, 0xbfb8aa3b, v38
	v_mul_f32_e32 v39, 0xbfb8aa3b, v39
	v_exp_f32_e32 v28, v28
	v_exp_f32_e32 v24, v24
	v_mul_f32_e32 v40, v30, v42
	v_mul_f32_e32 v41, v26, v43
	v_exp_f32_e32 v38, v38
	v_exp_f32_e32 v39, v39
	v_add_f32_e32 v40, v40, v40
	v_add_f32_e32 v41, v41, v41
	v_mul_f32_e32 v44, 0x3d122279, v31
	v_mul_f32_e32 v45, 0x3d122279, v27
	v_mul_f32_e32 v46, 0x3d122279, v20
	v_mul_f32_e32 v47, 0x3d122279, v36
	v_mul_f32_e32 v48, 0x3d122279, v21
	v_mul_f32_e32 v40, 0xbfb8aa3b, v40
	v_mul_f32_e32 v41, 0xbfb8aa3b, v41
	v_fmaak_f32 v44, v31, v44, 0x3f4c422a
	v_fmaak_f32 v45, v27, v45, 0x3f4c422a
	v_fmaak_f32 v46, v20, v46, 0x3f4c422a
	v_fmaak_f32 v47, v36, v47, 0x3f4c422a
	v_fmaak_f32 v48, v21, v48, 0x3f4c422a
	v_exp_f32_e32 v40, v40
	v_exp_f32_e32 v41, v41
	v_add_f32_e32 v28, 1.0, v28
	v_add_f32_e32 v24, 1.0, v24
	v_mul_f32_e32 v42, v31, v44
	v_mul_f32_e32 v43, v27, v45
	v_mul_f32_e32 v44, v20, v46
	v_mul_f32_e32 v45, v36, v47
	v_mul_f32_e32 v46, v21, v48
	v_add_f32_e32 v47, 1.0, v38
	v_add_f32_e32 v48, 1.0, v39
	v_rcp_f32_e32 v38, v28
	v_rcp_f32_e32 v39, v24
	v_add_f32_e32 v40, 1.0, v40
	v_add_f32_e32 v41, 1.0, v41
	v_rcp_f32_e32 v28, v47
	v_rcp_f32_e32 v24, v48
	v_rcp_f32_e32 v47, v40
	v_rcp_f32_e32 v48, v41
	v_pk_mul_f32 v[40:41], v[16:17], v[38:39]
	v_add_f32_e32 v46, v46, v46
	v_pk_fma_f32 v[16:17], v[16:17], v[38:39], v[40:41] op_sel:[0,0,1] op_sel_hi:[1,1,0]
	v_mul_f32_e32 v38, 0x3d122279, v37
	v_fmaak_f32 v38, v37, v38, 0x3f4c422a
	v_mul_f32_e32 v38, v37, v38
	v_mul_f32_e32 v17, 0xbfb8aa3b, v46
	v_add_f32_e32 v38, v38, v38
	v_exp_f32_e32 v17, v17
	v_mul_f32_e32 v38, 0xbfb8aa3b, v38
	v_exp_f32_e32 v38, v38
	v_mul_f32_e32 v39, 0x3d122279, v18
	v_add_f32_e32 v17, 1.0, v17
	v_rcp_f32_e32 v52, v17
	v_add_f32_e32 v17, 1.0, v38
	v_mul_f32_e32 v38, 0x3d122279, v22
	v_fmaak_f32 v38, v22, v38, 0x3f4c422a
	v_mul_f32_e32 v38, v22, v38
	v_fmaak_f32 v39, v18, v39, 0x3f4c422a
	v_add_f32_e32 v38, v38, v38
	v_mul_f32_e32 v39, v18, v39
	v_mul_f32_e32 v38, 0xbfb8aa3b, v38
	v_add_f32_e32 v39, v39, v39
	v_exp_f32_e32 v38, v38
	v_mul_f32_e32 v39, 0xbfb8aa3b, v39
	v_exp_f32_e32 v39, v39
	v_rcp_f32_e32 v53, v17
	v_add_f32_e32 v17, 1.0, v38
	v_mul_f32_e32 v38, 0x3d122279, v23
	v_add_f32_e32 v42, v42, v42
	v_add_f32_e32 v43, v43, v43
	v_add_f32_e32 v44, v44, v44
	v_add_f32_e32 v45, v45, v45
	v_rcp_f32_e32 v54, v17
	v_add_f32_e32 v17, 1.0, v39
	v_fmaak_f32 v38, v23, v38, 0x3f4c422a
	v_mul_f32_e32 v39, 0x3d122279, v19
	v_mul_f32_e32 v42, 0xbfb8aa3b, v42
	v_mul_f32_e32 v43, 0xbfb8aa3b, v43
	v_mul_f32_e32 v44, 0xbfb8aa3b, v44
	v_mul_f32_e32 v45, 0xbfb8aa3b, v45
	v_mul_f32_e32 v38, v23, v38
	v_fmaak_f32 v39, v19, v39, 0x3f4c422a
	v_exp_f32_e32 v42, v42
	v_exp_f32_e32 v43, v43
	v_exp_f32_e32 v44, v44
	v_exp_f32_e32 v45, v45
	v_add_f32_e32 v38, v38, v38
	v_mul_f32_e32 v39, v19, v39
	v_mul_f32_e32 v38, 0xbfb8aa3b, v38
	v_add_f32_e32 v39, v39, v39
	v_exp_f32_e32 v38, v38
	v_mul_f32_e32 v39, 0xbfb8aa3b, v39
	v_exp_f32_e32 v39, v39
	v_add_f32_e32 v42, 1.0, v42
	v_add_f32_e32 v43, 1.0, v43
	v_add_f32_e32 v44, 1.0, v44
	v_add_f32_e32 v45, 1.0, v45
	v_rcp_f32_e32 v42, v42
	v_rcp_f32_e32 v43, v43
	v_rcp_f32_e32 v50, v44
	v_rcp_f32_e32 v51, v45
	v_mul_f32_e32 v26, v26, v48
	v_mov_b32_e32 v44, v29
	v_mov_b32_e32 v45, v40
	v_mov_b32_e32 v29, v40
	v_mov_b32_e32 v48, v25
	v_mov_b32_e32 v49, v41
	v_mov_b32_e32 v25, v41
	v_rcp_f32_e32 v55, v17
	v_add_f32_e32 v17, 1.0, v38
	v_mul_f32_e32 v30, v30, v47
	v_pk_mul_f32 v[46:47], v[44:45], v[28:29]
	v_pk_mul_f32 v[24:25], v[48:49], v[24:25]
	v_rcp_f32_e32 v56, v17
	v_add_f32_e32 v17, 1.0, v39
	v_pk_fma_f32 v[28:29], v[44:45], v[28:29], v[24:25]
	v_pk_mul_f32 v[44:45], v[46:47], v[46:47]
	v_pk_mul_f32 v[48:49], v[24:25], v[24:25]
	v_rcp_f32_e32 v57, v17
	v_mov_b32_e32 v17, v44
	v_mov_b32_e32 v137, v48
	v_mul_f32_e32 v38, v31, v42
	v_mul_f32_e32 v42, v27, v43
	v_pk_add_f32 v[16:17], v[16:17], v[136:137]
	v_mul_f32_e32 v31, v30, v30
	v_mul_f32_e32 v27, v26, v26
	v_pk_add_f32 v[16:17], v[28:29], v[16:17]
	v_pk_add_f32 v[28:29], v[30:31], v[26:27]
	v_mul_f32_e32 v39, v38, v38
	v_mul_f32_e32 v43, v42, v42
	v_pk_add_f32 v[16:17], v[28:29], v[16:17]
	v_pk_add_f32 v[28:29], v[38:39], v[42:43]
	v_mul_f32_e32 v20, v20, v50
	v_pk_add_f32 v[28:29], v[28:29], v[16:17]
	v_cvt_pk_bf16_f32 v16, v40, v46
	v_cvt_pk_bf16_f32 v17, v30, v38
	v_mul_f32_e32 v30, v36, v51
	v_mul_f32_e32 v36, v21, v52
	v_mul_f32_e32 v38, v37, v53
	v_mul_f32_e32 v21, v20, v20
	v_mul_f32_e32 v31, v30, v30
	v_mul_f32_e32 v22, v22, v54
	v_mul_f32_e32 v44, v18, v55
	v_mul_f32_e32 v48, v19, v57
	v_pk_add_f32 v[18:19], v[20:21], v[30:31]
	v_mul_f32_e32 v37, v36, v36
	v_mul_f32_e32 v39, v38, v38
	v_mul_f32_e32 v46, v23, v56
	v_pk_add_f32 v[18:19], v[18:19], v[28:29]
	v_pk_add_f32 v[28:29], v[36:37], v[38:39]
	v_mul_f32_e32 v23, v22, v22
	v_mul_f32_e32 v45, v44, v44
	v_pk_add_f32 v[18:19], v[28:29], v[18:19]
	v_pk_add_f32 v[28:29], v[22:23], v[44:45]
	v_mul_f32_e32 v47, v46, v46
	v_mul_f32_e32 v49, v48, v48
	v_pk_add_f32 v[18:19], v[28:29], v[18:19]
	v_pk_add_f32 v[28:29], v[46:47], v[48:49]
	s_nop 0
	v_pk_add_f32 v[28:29], v[28:29], v[18:19]
	v_mov_b32_e32 v50, v28
	s_nop 1
	v_permlane16_swap_b32_e32 v50, v28
	v_mov_b32_e32 v51, v29
	s_nop 1
	v_permlane16_swap_b32_e32 v51, v29
	v_cvt_pk_bf16_f32 v18, v41, v24
	v_cvt_pk_bf16_f32 v19, v26, v42
	global_store_dwordx4 v[34:35], v[16:19], off
	v_cvt_pk_bf16_f32 v20, v20, v36
	v_cvt_pk_bf16_f32 v21, v22, v46
	v_cvt_pk_bf16_f32 v22, v30, v38
	v_cvt_pk_bf16_f32 v23, v44, v48
	global_store_dwordx4 v[34:35], v[20:23], off offset:256
	s_waitcnt lgkmcnt(0)
	v_pk_add_f32 v[16:17], v[28:29], v[50:51]
	v_mov_b32_e32 v18, v16
	s_nop 1
	v_permlane32_swap_b32_e32 v18, v16
	v_mov_b32_e32 v19, v17
	s_nop 1
	v_permlane32_swap_b32_e32 v19, v17
	s_and_saveexec_b64 s[48:49], s[46:47]
	s_cbranch_execz .LBB0_195
	s_lshl_b32 s14, s12, 2
	v_lshlrev_b64 v[20:21], 5, v[32:33]
	s_sub_i32 s14, s14, 32
	v_lshl_add_u64 v[20:21], v[20:21], 0, s[14:15]
	v_or_b32_e32 v20, s56, v20
	v_lshl_add_u64 v[20:21], v[20:21], 3, s[20:21]
	s_waitcnt lgkmcnt(0)
	v_pk_add_f32 v[16:17], v[16:17], v[18:19]
	global_store_dwordx2 v[20:21], v[16:17], off
.LBB0_195:
	s_or_b64 exec, exec, s[48:49]
	v_add_u32_e32 v16, 0xb0, v150
	v_ashrrev_i32_e32 v17, 31, v16
	s_waitcnt lgkmcnt(0)
	v_lshlrev_b64 v[18:19], 7, v[16:17]
	v_lshl_add_u64 v[22:23], v[138:139], 0, v[18:19]
	global_load_dwordx4 v[18:21], v[22:23], off
	s_nop 0
	global_load_dwordx4 v[22:25], v[22:23], off offset:16
	s_waitcnt vmcnt(1)
	v_mov_b32_e32 v26, v18
	s_waitcnt vmcnt(0)
	v_mov_b32_e32 v27, v22
	v_mov_b32_e32 v22, v19
	v_mov_b32_e32 v18, v20
	v_mov_b32_e32 v19, v24
	v_mov_b32_e32 v24, v21
	v_pk_add_f32 v[20:21], v[26:27], v[22:23]
	v_pk_add_f32 v[18:19], v[18:19], v[24:25]
	s_nop 0
	v_pk_add_f32 v[18:19], v[20:21], v[18:19]
	s_nop 0
	v_add_f32_e32 v18, 0, v18
	v_add_f32_e32 v18, v18, v19
	v_mov_b32_e32 v19, v18
	s_nop 1
	v_permlane16_swap_b32_e32 v19, v18
	s_waitcnt lgkmcnt(0)
	v_add_f32_e32 v18, v18, v19
	v_mov_b32_e32 v19, v18
	s_nop 1
	v_permlane32_swap_b32_e32 v19, v18
	s_waitcnt lgkmcnt(0)
	v_add_f32_e32 v18, v18, v19
	v_fmamk_f32 v18, v18, 0x3a000000, v161
	v_mul_f32_e32 v19, 0x4b800000, v18
	v_cmp_gt_f32_e32 vcc, s64, v18
	s_nop 1
	v_cndmask_b32_e32 v18, v18, v19, vcc
	v_rsq_f32_e32 v20, v18
	v_lshlrev_b64 v[18:19], 13, v[16:17]
	v_lshl_add_u64 v[18:19], s[18:19], 0, v[18:19]
	v_lshl_add_u64 v[18:19], v[148:149], 1, v[18:19]
	v_mul_f32_e32 v21, 0x45800000, v20
	v_cndmask_b32_e32 v20, v20, v21, vcc
	v_pk_mul_f32 v[12:13], v[12:13], v[20:21] op_sel_hi:[1,0]
	v_pk_mul_f32 v[8:9], v[8:9], v[20:21] op_sel_hi:[1,0]
	v_mul_f32_e32 v22, 0x3d122279, v12
	v_mul_f32_e32 v23, 0x3d122279, v8
	v_mul_f32_e32 v24, 0x3d122279, v13
	v_mul_f32_e32 v25, 0x3d122279, v9
	v_fmaak_f32 v22, v12, v22, 0x3f4c422a
	v_fmaak_f32 v23, v8, v23, 0x3f4c422a
	v_pk_mul_f32 v[14:15], v[14:15], v[20:21] op_sel_hi:[1,0]
	v_pk_mul_f32 v[10:11], v[10:11], v[20:21] op_sel_hi:[1,0]
	v_pk_mul_f32 v[6:7], v[6:7], v[20:21] op_sel_hi:[1,0]
	v_pk_mul_f32 v[4:5], v[4:5], v[20:21] op_sel_hi:[1,0]
	v_pk_mul_f32 v[2:3], v[2:3], v[20:21] op_sel_hi:[1,0]
	v_pk_mul_f32 v[20:21], v[0:1], v[20:21] op_sel_hi:[1,0]
	v_mov_b32_e32 v0, v12
	v_mov_b32_e32 v1, v8
	v_fmaak_f32 v24, v13, v24, 0x3f4c422a
	v_fmaak_f32 v25, v9, v25, 0x3f4c422a
	v_mul_f32_e32 v12, v12, v22
	v_mul_f32_e32 v8, v8, v23
	v_mul_f32_e32 v22, v13, v24
	v_mul_f32_e32 v23, v9, v25
	v_add_f32_e32 v12, v12, v12
	v_add_f32_e32 v8, v8, v8
	v_mul_f32_e32 v26, 0x3d122279, v14
	v_mul_f32_e32 v27, 0x3d122279, v10
	v_add_f32_e32 v22, v22, v22
	v_add_f32_e32 v23, v23, v23
	v_mul_f32_e32 v12, 0xbfb8aa3b, v12
	v_mul_f32_e32 v8, 0xbfb8aa3b, v8
	v_fmaak_f32 v26, v14, v26, 0x3f4c422a
	v_fmaak_f32 v27, v10, v27, 0x3f4c422a
	v_mul_f32_e32 v22, 0xbfb8aa3b, v22
	v_mul_f32_e32 v23, 0xbfb8aa3b, v23
	v_exp_f32_e32 v12, v12
	v_exp_f32_e32 v8, v8
	v_mul_f32_e32 v24, v14, v26
	v_mul_f32_e32 v25, v10, v27
	v_exp_f32_e32 v22, v22
	v_exp_f32_e32 v23, v23
	v_add_f32_e32 v24, v24, v24
	v_add_f32_e32 v25, v25, v25
	v_mul_f32_e32 v28, 0x3d122279, v15
	v_mul_f32_e32 v29, 0x3d122279, v11
	v_mul_f32_e32 v30, 0x3d122279, v4
	v_mul_f32_e32 v31, 0x3d122279, v20
	v_mul_f32_e32 v32, 0x3d122279, v5
	v_mul_f32_e32 v24, 0xbfb8aa3b, v24
	v_mul_f32_e32 v25, 0xbfb8aa3b, v25
	v_fmaak_f32 v28, v15, v28, 0x3f4c422a
	v_fmaak_f32 v29, v11, v29, 0x3f4c422a
	v_fmaak_f32 v30, v4, v30, 0x3f4c422a
	v_fmaak_f32 v31, v20, v31, 0x3f4c422a
	v_fmaak_f32 v32, v5, v32, 0x3f4c422a
	v_exp_f32_e32 v24, v24
	v_exp_f32_e32 v25, v25
	v_add_f32_e32 v12, 1.0, v12
	v_add_f32_e32 v8, 1.0, v8
	v_mul_f32_e32 v26, v15, v28
	v_mul_f32_e32 v27, v11, v29
	v_mul_f32_e32 v28, v4, v30
	v_mul_f32_e32 v29, v20, v31
	v_mul_f32_e32 v30, v5, v32
	v_add_f32_e32 v31, 1.0, v22
	v_add_f32_e32 v32, 1.0, v23
	v_rcp_f32_e32 v22, v12
	v_rcp_f32_e32 v23, v8
	v_add_f32_e32 v24, 1.0, v24
	v_add_f32_e32 v25, 1.0, v25
	v_rcp_f32_e32 v12, v31
	v_rcp_f32_e32 v8, v32
	v_rcp_f32_e32 v31, v24
	v_rcp_f32_e32 v32, v25
	v_pk_mul_f32 v[24:25], v[0:1], v[22:23]
	v_add_f32_e32 v30, v30, v30
	v_pk_fma_f32 v[0:1], v[0:1], v[22:23], v[24:25] op_sel:[0,0,1] op_sel_hi:[1,1,0]
	v_mul_f32_e32 v22, 0x3d122279, v21
	v_fmaak_f32 v22, v21, v22, 0x3f4c422a
	v_mul_f32_e32 v22, v21, v22
	v_mul_f32_e32 v1, 0xbfb8aa3b, v30
	v_add_f32_e32 v22, v22, v22
	v_exp_f32_e32 v1, v1
	v_mul_f32_e32 v22, 0xbfb8aa3b, v22
	v_exp_f32_e32 v22, v22
	v_mul_f32_e32 v23, 0x3d122279, v2
	v_add_f32_e32 v1, 1.0, v1
	v_rcp_f32_e32 v36, v1
	v_add_f32_e32 v1, 1.0, v22
	v_mul_f32_e32 v22, 0x3d122279, v6
	v_fmaak_f32 v22, v6, v22, 0x3f4c422a
	v_mul_f32_e32 v22, v6, v22
	v_fmaak_f32 v23, v2, v23, 0x3f4c422a
	v_add_f32_e32 v22, v22, v22
	v_mul_f32_e32 v23, v2, v23
	v_mul_f32_e32 v22, 0xbfb8aa3b, v22
	v_add_f32_e32 v23, v23, v23
	v_exp_f32_e32 v22, v22
	v_mul_f32_e32 v23, 0xbfb8aa3b, v23
	v_exp_f32_e32 v23, v23
	v_rcp_f32_e32 v37, v1
	v_add_f32_e32 v1, 1.0, v22
	v_mul_f32_e32 v22, 0x3d122279, v7
	v_add_f32_e32 v26, v26, v26
	v_add_f32_e32 v27, v27, v27
	v_add_f32_e32 v28, v28, v28
	v_add_f32_e32 v29, v29, v29
	v_rcp_f32_e32 v38, v1
	v_add_f32_e32 v1, 1.0, v23
	v_fmaak_f32 v22, v7, v22, 0x3f4c422a
	v_mul_f32_e32 v23, 0x3d122279, v3
	v_mul_f32_e32 v26, 0xbfb8aa3b, v26
	v_mul_f32_e32 v27, 0xbfb8aa3b, v27
	v_mul_f32_e32 v28, 0xbfb8aa3b, v28
	v_mul_f32_e32 v29, 0xbfb8aa3b, v29
	v_mul_f32_e32 v22, v7, v22
	v_fmaak_f32 v23, v3, v23, 0x3f4c422a
	v_exp_f32_e32 v26, v26
	v_exp_f32_e32 v27, v27
	v_exp_f32_e32 v28, v28
	v_exp_f32_e32 v29, v29
	v_add_f32_e32 v22, v22, v22
	v_mul_f32_e32 v23, v3, v23
	v_mul_f32_e32 v22, 0xbfb8aa3b, v22
	v_add_f32_e32 v23, v23, v23
	v_exp_f32_e32 v22, v22
	v_mul_f32_e32 v23, 0xbfb8aa3b, v23
	v_exp_f32_e32 v23, v23
	v_add_f32_e32 v26, 1.0, v26
	v_add_f32_e32 v27, 1.0, v27
	v_add_f32_e32 v28, 1.0, v28
	v_add_f32_e32 v29, 1.0, v29
	v_rcp_f32_e32 v26, v26
	v_rcp_f32_e32 v27, v27
	v_rcp_f32_e32 v34, v28
	v_rcp_f32_e32 v35, v29
	v_mul_f32_e32 v10, v10, v32
	v_mov_b32_e32 v28, v13
	v_mov_b32_e32 v29, v24
	v_mov_b32_e32 v13, v24
	v_mov_b32_e32 v32, v9
	v_mov_b32_e32 v33, v25
	v_mov_b32_e32 v9, v25
	v_rcp_f32_e32 v39, v1
	v_add_f32_e32 v1, 1.0, v22
	v_mul_f32_e32 v14, v14, v31
	v_pk_mul_f32 v[30:31], v[28:29], v[12:13]
	v_pk_mul_f32 v[8:9], v[32:33], v[8:9]
	v_rcp_f32_e32 v40, v1
	v_add_f32_e32 v1, 1.0, v23
	v_pk_fma_f32 v[12:13], v[28:29], v[12:13], v[8:9]
	v_pk_mul_f32 v[28:29], v[30:31], v[30:31]
	v_pk_mul_f32 v[32:33], v[8:9], v[8:9]
	v_rcp_f32_e32 v41, v1
	v_mov_b32_e32 v1, v28
	v_mov_b32_e32 v137, v32
	v_mul_f32_e32 v22, v15, v26
	v_mul_f32_e32 v26, v11, v27
	v_pk_add_f32 v[0:1], v[0:1], v[136:137]
	v_mul_f32_e32 v15, v14, v14
	v_mul_f32_e32 v11, v10, v10
	v_pk_add_f32 v[0:1], v[12:13], v[0:1]
	v_pk_add_f32 v[12:13], v[14:15], v[10:11]
	v_mul_f32_e32 v23, v22, v22
	v_mul_f32_e32 v27, v26, v26
	v_pk_add_f32 v[0:1], v[12:13], v[0:1]
	v_pk_add_f32 v[12:13], v[22:23], v[26:27]
	v_mul_f32_e32 v4, v4, v34
	v_pk_add_f32 v[12:13], v[12:13], v[0:1]
	v_cvt_pk_bf16_f32 v0, v24, v30
	v_cvt_pk_bf16_f32 v1, v14, v22
	v_mul_f32_e32 v14, v20, v35
	v_mul_f32_e32 v20, v5, v36
	v_mul_f32_e32 v22, v21, v37
	v_mul_f32_e32 v5, v4, v4
	v_mul_f32_e32 v15, v14, v14
	v_mul_f32_e32 v6, v6, v38
	v_mul_f32_e32 v28, v2, v39
	v_mul_f32_e32 v32, v3, v41
	v_pk_add_f32 v[2:3], v[4:5], v[14:15]
	v_mul_f32_e32 v21, v20, v20
	v_mul_f32_e32 v23, v22, v22
	v_mul_f32_e32 v30, v7, v40
	v_pk_add_f32 v[2:3], v[2:3], v[12:13]
	v_pk_add_f32 v[12:13], v[20:21], v[22:23]
	v_mul_f32_e32 v7, v6, v6
	v_mul_f32_e32 v29, v28, v28
	v_pk_add_f32 v[2:3], v[12:13], v[2:3]
	v_pk_add_f32 v[12:13], v[6:7], v[28:29]
	v_mul_f32_e32 v31, v30, v30
	v_mul_f32_e32 v33, v32, v32
	v_pk_add_f32 v[2:3], v[12:13], v[2:3]
	v_pk_add_f32 v[12:13], v[30:31], v[32:33]
	s_nop 0
	v_pk_add_f32 v[12:13], v[12:13], v[2:3]
	v_mov_b32_e32 v34, v12
	s_nop 1
	v_permlane16_swap_b32_e32 v34, v12
	v_mov_b32_e32 v35, v13
	s_nop 1
	v_permlane16_swap_b32_e32 v35, v13
	v_cvt_pk_bf16_f32 v2, v25, v8
	v_cvt_pk_bf16_f32 v3, v10, v26
	global_store_dwordx4 v[18:19], v[0:3], off
	v_cvt_pk_bf16_f32 v4, v4, v20
	v_cvt_pk_bf16_f32 v5, v6, v30
	v_cvt_pk_bf16_f32 v6, v14, v22
	v_cvt_pk_bf16_f32 v7, v28, v32
	global_store_dwordx4 v[18:19], v[4:7], off offset:256
	s_waitcnt lgkmcnt(0)
	v_pk_add_f32 v[0:1], v[12:13], v[34:35]
	v_mov_b32_e32 v2, v0
	s_nop 1
	v_permlane32_swap_b32_e32 v2, v0
	v_mov_b32_e32 v3, v1
	s_nop 1
	v_permlane32_swap_b32_e32 v3, v1
	s_and_saveexec_b64 s[48:49], s[46:47]
	s_cbranch_execz .LBB0_197
	s_lshl_b32 s12, s12, 2
	v_lshlrev_b64 v[4:5], 5, v[16:17]
	s_sub_i32 s14, s12, 32
	v_lshl_add_u64 v[4:5], v[4:5], 0, s[14:15]
	v_or_b32_e32 v4, s56, v4
	v_lshl_add_u64 v[4:5], v[4:5], 3, s[20:21]
	s_waitcnt lgkmcnt(0)
	v_pk_add_f32 v[0:1], v[0:1], v[2:3]
	global_store_dwordx2 v[4:5], v[0:1], off

.LBB0_340:
	v_lshl_add_u32 v146, s46, 8, v148
	v_lshl_or_b32 v144, s12, 8, v150
	v_ashrrev_i32_e32 v147, 31, v146
	v_ashrrev_i32_e32 v145, 31, v144
	v_lshlrev_b64 v[156:157], 11, v[146:147]
	v_lshl_add_u64 v[156:157], v[156:157], 0, v[144:145]
	v_lshlrev_b64 v[160:161], 1, v[156:157]
	v_lshl_add_u64 v[156:157], s[16:17], 0, v[160:161]
	global_load_dwordx4 v[156:159], v[156:157], off
	v_lshl_add_u64 v[162:163], s[18:19], 0, v[160:161]
	v_or_b32_e32 v160, 0x100, v160
	v_lshl_add_u64 v[164:165], s[16:17], 0, v[160:161]
	v_xor_b32_e32 v155, 32, v154
	s_lshl_b32 s46, s12, 2
	s_ashr_i32 s47, s46, 31
	s_waitcnt vmcnt(0)
	v_lshlrev_b32_e32 v166, 16, v156
	v_and_b32_e32 v167, 0xffff0000, v156
	v_lshlrev_b32_e32 v156, 16, v157
	v_and_b32_e32 v157, 0xffff0000, v157
	v_lshlrev_b32_e32 v168, 16, v158
	v_and_b32_e32 v169, 0xffff0000, v158
	v_lshlrev_b32_e32 v158, 16, v159
	v_and_b32_e32 v159, 0xffff0000, v159
	v_pk_add_f32 v[126:127], v[126:127], v[156:157]
	v_pk_add_f32 v[166:167], v[124:125], v[166:167]
	v_pk_add_f32 v[170:171], v[122:123], v[158:159]
	v_pk_add_f32 v[168:169], v[120:121], v[168:169]
	v_cvt_pk_bf16_f32 v122, v166, v167
	v_cvt_pk_bf16_f32 v123, v126, v127
	v_mul_f32_e32 v127, v127, v127
	v_cvt_pk_bf16_f32 v124, v168, v169
	v_cvt_pk_bf16_f32 v125, v170, v171
	global_load_dwordx4 v[156:159], v[164:165], off
	v_mul_f32_e32 v164, v167, v167
	v_mul_f32_e32 v165, v169, v169
	v_mul_f32_e32 v167, v171, v171
	v_fmac_f32_e32 v164, v166, v166
	v_fmac_f32_e32 v127, v126, v126
	v_fmac_f32_e32 v165, v168, v168
	v_fmac_f32_e32 v167, v170, v170
	v_add_f32_e32 v126, v164, v127
	v_add_f32_e32 v127, v165, v167
	v_add_f32_e32 v166, v126, v127
	v_and_b32_e32 v121, 64, v154
	v_xor_b32_e32 v120, 16, v154
	v_add_u32_e32 v121, 64, v121
	v_cmp_lt_i32_e32 vcc, v120, v121
	global_store_dwordx4 v[162:163], v[122:125], off
	s_waitcnt vmcnt(1)
	v_lshlrev_b32_e32 v126, 16, v156
	v_and_b32_e32 v127, 0xffff0000, v156
	v_lshlrev_b32_e32 v156, 16, v157
	v_and_b32_e32 v157, 0xffff0000, v157
	v_lshlrev_b32_e32 v164, 16, v158
	v_and_b32_e32 v165, 0xffff0000, v158
	v_lshlrev_b32_e32 v158, 16, v159
	v_and_b32_e32 v159, 0xffff0000, v159
	v_pk_add_f32 v[118:119], v[118:119], v[156:157]
	v_pk_add_f32 v[116:117], v[116:117], v[126:127]
	v_pk_add_f32 v[126:127], v[114:115], v[158:159]
	v_pk_add_f32 v[156:157], v[112:113], v[164:165]
	v_mul_f32_e32 v112, v117, v117
	v_mul_f32_e32 v113, v119, v119
	v_mul_f32_e32 v114, v157, v157
	v_mul_f32_e32 v115, v127, v127
	v_fmac_f32_e32 v112, v116, v116
	v_fmac_f32_e32 v113, v118, v118
	v_fmac_f32_e32 v114, v156, v156
	v_fmac_f32_e32 v115, v126, v126
	v_add_f32_e32 v112, v112, v113
	v_add_f32_e32 v113, v114, v115
	v_cndmask_b32_e32 v120, v154, v120, vcc
	v_add_f32_e32 v112, v112, v113
	v_lshlrev_b32_e32 v120, 2, v120
	v_add_f32_e32 v112, v166, v112
	v_mov_b32_e32 v113, v112
	s_nop 1
	v_permlane16_swap_b32_e32 v113, v112
	v_cmp_lt_i32_e32 vcc, v155, v121
	v_lshl_add_u64 v[122:123], s[18:19], 0, v[160:161]
	v_cvt_pk_bf16_f32 v116, v116, v117
	v_cvt_pk_bf16_f32 v117, v118, v119
	s_waitcnt lgkmcnt(0)
	v_add_f32_e32 v112, v112, v113
	v_cndmask_b32_e32 v114, v154, v155, vcc
	v_lshlrev_b32_e32 v114, 2, v114
	v_mov_b32_e32 v113, v112
	s_nop 1
	v_permlane32_swap_b32_e32 v113, v112
	v_cvt_pk_bf16_f32 v118, v156, v157
	v_cvt_pk_bf16_f32 v119, v126, v127
	global_store_dwordx4 v[122:123], v[116:119], off
	s_and_saveexec_b64 s[48:49], s[8:9]
	s_cbranch_execz .LBB0_342
	s_waitcnt lgkmcnt(0)
	v_add_f32_e32 v115, v112, v113
	v_lshlrev_b64 v[112:113], 7, v[146:147]
	v_lshl_add_u64 v[112:113], s[20:21], 0, v[112:113]
	v_lshl_add_u64 v[112:113], s[46:47], 2, v[112:113]
	s_lshl_b32 s12, s61, 2
	v_lshl_add_u64 v[112:113], v[112:113], 0, s[12:13]
	global_store_dword v[112:113], v115, off
.LBB0_342:
	s_or_b64 exec, exec, s[48:49]
	v_or_b32_e32 v112, 16, v146
	s_waitcnt lgkmcnt(0)
	v_ashrrev_i32_e32 v113, 31, v112
	v_lshlrev_b64 v[116:117], 11, v[112:113]
	v_lshl_add_u64 v[116:117], v[116:117], 0, v[144:145]
	v_lshlrev_b64 v[122:123], 1, v[116:117]
	v_lshl_add_u64 v[116:117], s[16:17], 0, v[122:123]
	global_load_dwordx4 v[116:119], v[116:117], off
	v_lshl_add_u64 v[124:125], s[18:19], 0, v[122:123]
	v_or_b32_e32 v122, 0x100, v122
	v_lshl_add_u64 v[126:127], s[16:17], 0, v[122:123]
	s_waitcnt vmcnt(0)
	v_lshlrev_b32_e32 v156, 16, v116
	v_and_b32_e32 v157, 0xffff0000, v116
	v_lshlrev_b32_e32 v116, 16, v117
	v_and_b32_e32 v117, 0xffff0000, v117
	v_lshlrev_b32_e32 v158, 16, v118
	v_and_b32_e32 v159, 0xffff0000, v118
	v_lshlrev_b32_e32 v118, 16, v119
	v_and_b32_e32 v119, 0xffff0000, v119
	v_pk_add_f32 v[116:117], v[110:111], v[116:117]
	v_pk_add_f32 v[156:157], v[108:109], v[156:157]
	v_pk_add_f32 v[118:119], v[106:107], v[118:119]
	v_pk_add_f32 v[158:159], v[104:105], v[158:159]
	v_cvt_pk_bf16_f32 v104, v156, v157
	v_cvt_pk_bf16_f32 v105, v116, v117
	v_mul_f32_e32 v115, v157, v157
	v_cvt_pk_bf16_f32 v106, v158, v159
	v_cvt_pk_bf16_f32 v107, v118, v119
	global_load_dwordx4 v[108:111], v[126:127], off
	v_mul_f32_e32 v117, v117, v117
	v_mul_f32_e32 v121, v159, v159
	v_mul_f32_e32 v119, v119, v119
	v_fmac_f32_e32 v115, v156, v156
	v_fmac_f32_e32 v117, v116, v116
	v_fmac_f32_e32 v121, v158, v158
	v_fmac_f32_e32 v119, v118, v118
	v_add_f32_e32 v115, v115, v117
	v_add_f32_e32 v116, v121, v119
	v_add_f32_e32 v115, v115, v116
	global_store_dwordx4 v[124:125], v[104:107], off
	s_waitcnt vmcnt(1)
	v_lshlrev_b32_e32 v116, 16, v108
	v_and_b32_e32 v117, 0xffff0000, v108
	v_lshlrev_b32_e32 v108, 16, v109
	v_and_b32_e32 v109, 0xffff0000, v109
	v_lshlrev_b32_e32 v118, 16, v110
	v_and_b32_e32 v119, 0xffff0000, v110
	v_lshlrev_b32_e32 v110, 16, v111
	v_and_b32_e32 v111, 0xffff0000, v111
	v_pk_add_f32 v[102:103], v[102:103], v[108:109]
	v_pk_add_f32 v[100:101], v[100:101], v[116:117]
	v_pk_add_f32 v[108:109], v[98:99], v[110:111]
	v_pk_add_f32 v[110:111], v[96:97], v[118:119]
	v_mul_f32_e32 v96, v101, v101
	v_mul_f32_e32 v97, v103, v103
	v_mul_f32_e32 v98, v111, v111
	v_mul_f32_e32 v99, v109, v109
	v_fmac_f32_e32 v96, v100, v100
	v_fmac_f32_e32 v97, v102, v102
	v_fmac_f32_e32 v98, v110, v110
	v_fmac_f32_e32 v99, v108, v108
	v_add_f32_e32 v96, v96, v97
	v_add_f32_e32 v97, v98, v99
	v_add_f32_e32 v96, v96, v97
	v_add_f32_e32 v96, v115, v96
	v_mov_b32_e32 v97, v96
	s_nop 1
	v_permlane16_swap_b32_e32 v97, v96
	v_cvt_pk_bf16_f32 v98, v100, v101
	v_cvt_pk_bf16_f32 v99, v102, v103
	v_lshl_add_u64 v[102:103], s[18:19], 0, v[122:123]
	v_cvt_pk_bf16_f32 v100, v110, v111
	s_waitcnt lgkmcnt(0)
	v_add_f32_e32 v96, v96, v97
	v_mov_b32_e32 v97, v96
	s_nop 1
	v_permlane32_swap_b32_e32 v97, v96
	v_cvt_pk_bf16_f32 v101, v108, v109
	global_store_dwordx4 v[102:103], v[98:101], off
	s_and_saveexec_b64 s[48:49], s[8:9]
	s_cbranch_execz .LBB0_344
	s_waitcnt lgkmcnt(0)
	v_add_f32_e32 v98, v96, v97
	v_lshlrev_b64 v[96:97], 7, v[112:113]
	v_lshl_add_u64 v[96:97], s[20:21], 0, v[96:97]
	v_lshl_add_u64 v[96:97], s[46:47], 2, v[96:97]
	s_lshl_b32 s12, s61, 2
	v_lshl_add_u64 v[96:97], v[96:97], 0, s[12:13]
	global_store_dword v[96:97], v98, off
.LBB0_344:
	s_or_b64 exec, exec, s[48:49]
	v_or_b32_e32 v96, 32, v146
	s_waitcnt lgkmcnt(0)
	v_ashrrev_i32_e32 v97, 31, v96
	v_lshlrev_b64 v[98:99], 11, v[96:97]
	v_lshl_add_u64 v[98:99], v[98:99], 0, v[144:145]
	v_lshlrev_b64 v[102:103], 1, v[98:99]
	v_lshl_add_u64 v[98:99], s[16:17], 0, v[102:103]
	global_load_dwordx4 v[98:101], v[98:99], off
	v_lshl_add_u64 v[104:105], s[18:19], 0, v[102:103]
	v_or_b32_e32 v102, 0x100, v102
	v_lshl_add_u64 v[106:107], s[16:17], 0, v[102:103]
	s_waitcnt vmcnt(0)
	v_lshlrev_b32_e32 v108, 16, v98
	v_and_b32_e32 v109, 0xffff0000, v98
	v_lshlrev_b32_e32 v98, 16, v99
	v_and_b32_e32 v99, 0xffff0000, v99
	v_lshlrev_b32_e32 v110, 16, v100
	v_and_b32_e32 v111, 0xffff0000, v100
	v_lshlrev_b32_e32 v100, 16, v101
	v_and_b32_e32 v101, 0xffff0000, v101
	v_pk_add_f32 v[98:99], v[94:95], v[98:99]
	v_pk_add_f32 v[108:109], v[92:93], v[108:109]
	v_pk_add_f32 v[100:101], v[90:91], v[100:101]
	v_pk_add_f32 v[110:111], v[88:89], v[110:111]
	v_cvt_pk_bf16_f32 v88, v108, v109
	v_cvt_pk_bf16_f32 v89, v98, v99
	v_mul_f32_e32 v99, v99, v99
	v_cvt_pk_bf16_f32 v90, v110, v111
	v_cvt_pk_bf16_f32 v91, v100, v101
	global_load_dwordx4 v[92:95], v[106:107], off
	v_mul_f32_e32 v106, v109, v109
	v_mul_f32_e32 v107, v111, v111
	v_mul_f32_e32 v101, v101, v101
	v_fmac_f32_e32 v106, v108, v108
	v_fmac_f32_e32 v99, v98, v98
	v_fmac_f32_e32 v107, v110, v110
	v_fmac_f32_e32 v101, v100, v100
	v_add_f32_e32 v98, v106, v99
	v_add_f32_e32 v99, v107, v101
	v_add_f32_e32 v106, v98, v99
	global_store_dwordx4 v[104:105], v[88:91], off
	s_waitcnt vmcnt(1)
	v_lshlrev_b32_e32 v98, 16, v92
	v_and_b32_e32 v99, 0xffff0000, v92
	v_lshlrev_b32_e32 v92, 16, v93
	v_and_b32_e32 v93, 0xffff0000, v93
	v_lshlrev_b32_e32 v100, 16, v94
	v_and_b32_e32 v101, 0xffff0000, v94
	v_lshlrev_b32_e32 v94, 16, v95
	v_and_b32_e32 v95, 0xffff0000, v95
	v_pk_add_f32 v[86:87], v[86:87], v[92:93]
	v_pk_add_f32 v[84:85], v[84:85], v[98:99]
	v_pk_add_f32 v[92:93], v[82:83], v[94:95]
	v_pk_add_f32 v[94:95], v[80:81], v[100:101]
	v_mul_f32_e32 v80, v85, v85
	v_mul_f32_e32 v81, v87, v87
	v_mul_f32_e32 v82, v95, v95
	v_mul_f32_e32 v83, v93, v93
	v_fmac_f32_e32 v80, v84, v84
	v_fmac_f32_e32 v81, v86, v86
	v_fmac_f32_e32 v82, v94, v94
	v_fmac_f32_e32 v83, v92, v92
	v_add_f32_e32 v80, v80, v81
	v_add_f32_e32 v81, v82, v83
	v_add_f32_e32 v80, v80, v81
	v_add_f32_e32 v80, v106, v80
	v_mov_b32_e32 v81, v80
	s_nop 1
	v_permlane16_swap_b32_e32 v81, v80
	v_cvt_pk_bf16_f32 v82, v84, v85
	v_cvt_pk_bf16_f32 v83, v86, v87
	v_lshl_add_u64 v[86:87], s[18:19], 0, v[102:103]
	v_cvt_pk_bf16_f32 v84, v94, v95
	s_waitcnt lgkmcnt(0)
	v_add_f32_e32 v80, v80, v81
	v_mov_b32_e32 v81, v80
	s_nop 1
	v_permlane32_swap_b32_e32 v81, v80
	v_cvt_pk_bf16_f32 v85, v92, v93
	global_store_dwordx4 v[86:87], v[82:85], off
	s_and_saveexec_b64 s[48:49], s[8:9]
	s_cbranch_execz .LBB0_346
	s_waitcnt lgkmcnt(0)
	v_add_f32_e32 v82, v80, v81
	v_lshlrev_b64 v[80:81], 7, v[96:97]
	v_lshl_add_u64 v[80:81], s[20:21], 0, v[80:81]
	v_lshl_add_u64 v[80:81], s[46:47], 2, v[80:81]
	s_lshl_b32 s12, s61, 2
	v_lshl_add_u64 v[80:81], v[80:81], 0, s[12:13]
	global_store_dword v[80:81], v82, off
.LBB0_346:
	s_or_b64 exec, exec, s[48:49]
	v_or_b32_e32 v80, 48, v146
	s_waitcnt lgkmcnt(0)
	v_ashrrev_i32_e32 v81, 31, v80
	v_lshlrev_b64 v[82:83], 11, v[80:81]
	v_lshl_add_u64 v[82:83], v[82:83], 0, v[144:145]
	v_lshlrev_b64 v[86:87], 1, v[82:83]
	v_lshl_add_u64 v[82:83], s[16:17], 0, v[86:87]
	global_load_dwordx4 v[82:85], v[82:83], off
	v_lshl_add_u64 v[88:89], s[18:19], 0, v[86:87]
	v_or_b32_e32 v86, 0x100, v86
	v_lshl_add_u64 v[90:91], s[16:17], 0, v[86:87]
	s_waitcnt vmcnt(0)
	v_lshlrev_b32_e32 v92, 16, v82
	v_and_b32_e32 v93, 0xffff0000, v82
	v_lshlrev_b32_e32 v82, 16, v83
	v_and_b32_e32 v83, 0xffff0000, v83
	v_lshlrev_b32_e32 v94, 16, v84
	v_and_b32_e32 v95, 0xffff0000, v84
	v_lshlrev_b32_e32 v84, 16, v85
	v_and_b32_e32 v85, 0xffff0000, v85
	v_pk_add_f32 v[82:83], v[78:79], v[82:83]
	v_pk_add_f32 v[92:93], v[76:77], v[92:93]
	v_pk_add_f32 v[84:85], v[74:75], v[84:85]
	v_pk_add_f32 v[94:95], v[72:73], v[94:95]
	v_cvt_pk_bf16_f32 v72, v92, v93
	v_cvt_pk_bf16_f32 v73, v82, v83
	v_mul_f32_e32 v83, v83, v83
	v_cvt_pk_bf16_f32 v74, v94, v95
	v_cvt_pk_bf16_f32 v75, v84, v85
	global_load_dwordx4 v[76:79], v[90:91], off
	v_mul_f32_e32 v90, v93, v93
	v_mul_f32_e32 v91, v95, v95
	v_mul_f32_e32 v85, v85, v85
	v_fmac_f32_e32 v90, v92, v92
	v_fmac_f32_e32 v83, v82, v82
	v_fmac_f32_e32 v91, v94, v94
	v_fmac_f32_e32 v85, v84, v84
	v_add_f32_e32 v82, v90, v83
	v_add_f32_e32 v83, v91, v85
	v_add_f32_e32 v90, v82, v83
	global_store_dwordx4 v[88:89], v[72:75], off
	s_waitcnt vmcnt(1)
	v_lshlrev_b32_e32 v82, 16, v76
	v_and_b32_e32 v83, 0xffff0000, v76
	v_lshlrev_b32_e32 v76, 16, v77
	v_and_b32_e32 v77, 0xffff0000, v77
	v_lshlrev_b32_e32 v84, 16, v78
	v_and_b32_e32 v85, 0xffff0000, v78
	v_lshlrev_b32_e32 v78, 16, v79
	v_and_b32_e32 v79, 0xffff0000, v79
	v_pk_add_f32 v[70:71], v[70:71], v[76:77]
	v_pk_add_f32 v[68:69], v[68:69], v[82:83]
	v_pk_add_f32 v[76:77], v[66:67], v[78:79]
	v_pk_add_f32 v[78:79], v[64:65], v[84:85]
	v_mul_f32_e32 v64, v69, v69
	v_mul_f32_e32 v65, v71, v71
	v_mul_f32_e32 v66, v79, v79
	v_mul_f32_e32 v67, v77, v77
	v_fmac_f32_e32 v64, v68, v68
	v_fmac_f32_e32 v65, v70, v70
	v_fmac_f32_e32 v66, v78, v78
	v_fmac_f32_e32 v67, v76, v76
	v_add_f32_e32 v64, v64, v65
	v_add_f32_e32 v65, v66, v67
	v_add_f32_e32 v64, v64, v65
	v_add_f32_e32 v64, v90, v64
	v_mov_b32_e32 v65, v64
	s_nop 1
	v_permlane16_swap_b32_e32 v65, v64
	v_cvt_pk_bf16_f32 v66, v68, v69
	v_cvt_pk_bf16_f32 v67, v70, v71
	v_lshl_add_u64 v[70:71], s[18:19], 0, v[86:87]
	v_cvt_pk_bf16_f32 v68, v78, v79
	s_waitcnt lgkmcnt(0)
	v_add_f32_e32 v64, v64, v65
	v_mov_b32_e32 v65, v64
	s_nop 1
	v_permlane32_swap_b32_e32 v65, v64
	v_cvt_pk_bf16_f32 v69, v76, v77
	global_store_dwordx4 v[70:71], v[66:69], off
	s_and_saveexec_b64 s[48:49], s[8:9]
	s_cbranch_execz .LBB0_348
	s_waitcnt lgkmcnt(0)
	v_add_f32_e32 v66, v64, v65
	v_lshlrev_b64 v[64:65], 7, v[80:81]
	v_lshl_add_u64 v[64:65], s[20:21], 0, v[64:65]
	v_lshl_add_u64 v[64:65], s[46:47], 2, v[64:65]
	s_lshl_b32 s12, s61, 2
	v_lshl_add_u64 v[64:65], v[64:65], 0, s[12:13]
	global_store_dword v[64:65], v66, off
.LBB0_348:
	s_or_b64 exec, exec, s[48:49]
	v_add_u32_e32 v64, 0x80, v146
	s_waitcnt lgkmcnt(0)
	v_ashrrev_i32_e32 v65, 31, v64
	v_lshlrev_b64 v[66:67], 11, v[64:65]
	v_lshl_add_u64 v[66:67], v[66:67], 0, v[144:145]
	v_lshlrev_b64 v[70:71], 1, v[66:67]
	v_lshl_add_u64 v[66:67], s[16:17], 0, v[70:71]
	global_load_dwordx4 v[66:69], v[66:67], off
	v_lshl_add_u64 v[72:73], s[18:19], 0, v[70:71]
	v_or_b32_e32 v70, 0x100, v70
	v_lshl_add_u64 v[74:75], s[16:17], 0, v[70:71]
	s_waitcnt vmcnt(0)
	v_lshlrev_b32_e32 v76, 16, v66
	v_and_b32_e32 v77, 0xffff0000, v66
	v_lshlrev_b32_e32 v66, 16, v67
	v_and_b32_e32 v67, 0xffff0000, v67
	v_lshlrev_b32_e32 v78, 16, v68
	v_and_b32_e32 v79, 0xffff0000, v68
	v_lshlrev_b32_e32 v68, 16, v69
	v_and_b32_e32 v69, 0xffff0000, v69
	v_pk_add_f32 v[66:67], v[62:63], v[66:67]
	v_pk_add_f32 v[76:77], v[60:61], v[76:77]
	v_pk_add_f32 v[68:69], v[58:59], v[68:69]
	v_pk_add_f32 v[78:79], v[56:57], v[78:79]
	v_cvt_pk_bf16_f32 v56, v76, v77
	v_cvt_pk_bf16_f32 v57, v66, v67
	v_mul_f32_e32 v67, v67, v67
	v_cvt_pk_bf16_f32 v58, v78, v79
	v_cvt_pk_bf16_f32 v59, v68, v69
	global_load_dwordx4 v[60:63], v[74:75], off
	v_mul_f32_e32 v74, v77, v77
	v_mul_f32_e32 v75, v79, v79
	v_mul_f32_e32 v69, v69, v69
	v_fmac_f32_e32 v74, v76, v76
	v_fmac_f32_e32 v67, v66, v66
	v_fmac_f32_e32 v75, v78, v78
	v_fmac_f32_e32 v69, v68, v68
	v_add_f32_e32 v66, v74, v67
	v_add_f32_e32 v67, v75, v69
	v_add_f32_e32 v74, v66, v67
	global_store_dwordx4 v[72:73], v[56:59], off
	s_waitcnt vmcnt(1)
	v_lshlrev_b32_e32 v66, 16, v60
	v_and_b32_e32 v67, 0xffff0000, v60
	v_lshlrev_b32_e32 v60, 16, v61
	v_and_b32_e32 v61, 0xffff0000, v61
	v_lshlrev_b32_e32 v68, 16, v62
	v_and_b32_e32 v69, 0xffff0000, v62
	v_lshlrev_b32_e32 v62, 16, v63
	v_and_b32_e32 v63, 0xffff0000, v63
	v_pk_add_f32 v[54:55], v[54:55], v[60:61]
	v_pk_add_f32 v[52:53], v[52:53], v[66:67]
	v_pk_add_f32 v[60:61], v[50:51], v[62:63]
	v_pk_add_f32 v[62:63], v[48:49], v[68:69]
	v_mul_f32_e32 v48, v53, v53
	v_mul_f32_e32 v49, v55, v55
	v_mul_f32_e32 v50, v63, v63
	v_mul_f32_e32 v51, v61, v61
	v_fmac_f32_e32 v48, v52, v52
	v_fmac_f32_e32 v49, v54, v54
	v_fmac_f32_e32 v50, v62, v62
	v_fmac_f32_e32 v51, v60, v60
	v_add_f32_e32 v48, v48, v49
	v_add_f32_e32 v49, v50, v51
	v_add_f32_e32 v48, v48, v49
	v_add_f32_e32 v48, v74, v48
	v_mov_b32_e32 v49, v48
	s_nop 1
	v_permlane16_swap_b32_e32 v49, v48
	v_cvt_pk_bf16_f32 v50, v52, v53
	v_cvt_pk_bf16_f32 v51, v54, v55
	v_lshl_add_u64 v[54:55], s[18:19], 0, v[70:71]
	v_cvt_pk_bf16_f32 v52, v62, v63
	s_waitcnt lgkmcnt(0)
	v_add_f32_e32 v48, v48, v49
	v_mov_b32_e32 v49, v48
	s_nop 1
	v_permlane32_swap_b32_e32 v49, v48
	v_cvt_pk_bf16_f32 v53, v60, v61
	global_store_dwordx4 v[54:55], v[50:53], off
	s_and_saveexec_b64 s[48:49], s[8:9]
	s_cbranch_execz .LBB0_350
	s_waitcnt lgkmcnt(0)
	v_add_f32_e32 v50, v48, v49
	v_lshlrev_b64 v[48:49], 7, v[64:65]
	v_lshl_add_u64 v[48:49], s[20:21], 0, v[48:49]
	v_lshl_add_u64 v[48:49], s[46:47], 2, v[48:49]
	s_lshl_b32 s12, s61, 2
	v_lshl_add_u64 v[48:49], v[48:49], 0, s[12:13]
	global_store_dword v[48:49], v50, off
.LBB0_350:
	s_or_b64 exec, exec, s[48:49]
	v_add_u32_e32 v48, 0x90, v146
	s_waitcnt lgkmcnt(0)
	v_ashrrev_i32_e32 v49, 31, v48
	v_lshlrev_b64 v[50:51], 11, v[48:49]
	v_lshl_add_u64 v[50:51], v[50:51], 0, v[144:145]
	v_lshlrev_b64 v[54:55], 1, v[50:51]
	v_lshl_add_u64 v[50:51], s[16:17], 0, v[54:55]
	global_load_dwordx4 v[50:53], v[50:51], off
	v_lshl_add_u64 v[56:57], s[18:19], 0, v[54:55]
	v_or_b32_e32 v54, 0x100, v54
	v_lshl_add_u64 v[58:59], s[16:17], 0, v[54:55]
	s_waitcnt vmcnt(0)
	v_lshlrev_b32_e32 v60, 16, v50
	v_and_b32_e32 v61, 0xffff0000, v50
	v_lshlrev_b32_e32 v50, 16, v51
	v_and_b32_e32 v51, 0xffff0000, v51
	v_lshlrev_b32_e32 v62, 16, v52
	v_and_b32_e32 v63, 0xffff0000, v52
	v_lshlrev_b32_e32 v52, 16, v53
	v_and_b32_e32 v53, 0xffff0000, v53
	v_pk_add_f32 v[50:51], v[46:47], v[50:51]
	v_pk_add_f32 v[60:61], v[44:45], v[60:61]
	v_pk_add_f32 v[52:53], v[42:43], v[52:53]
	v_pk_add_f32 v[62:63], v[40:41], v[62:63]
	v_cvt_pk_bf16_f32 v40, v60, v61
	v_cvt_pk_bf16_f32 v41, v50, v51
	v_mul_f32_e32 v51, v51, v51
	v_cvt_pk_bf16_f32 v42, v62, v63
	v_cvt_pk_bf16_f32 v43, v52, v53
	global_load_dwordx4 v[44:47], v[58:59], off
	v_mul_f32_e32 v58, v61, v61
	v_mul_f32_e32 v59, v63, v63
	v_mul_f32_e32 v53, v53, v53
	v_fmac_f32_e32 v58, v60, v60
	v_fmac_f32_e32 v51, v50, v50
	v_fmac_f32_e32 v59, v62, v62
	v_fmac_f32_e32 v53, v52, v52
	v_add_f32_e32 v50, v58, v51
	v_add_f32_e32 v51, v59, v53
	v_add_f32_e32 v58, v50, v51
	global_store_dwordx4 v[56:57], v[40:43], off
	s_waitcnt vmcnt(1)
	v_lshlrev_b32_e32 v50, 16, v44
	v_and_b32_e32 v51, 0xffff0000, v44
	v_lshlrev_b32_e32 v44, 16, v45
	v_and_b32_e32 v45, 0xffff0000, v45
	v_lshlrev_b32_e32 v52, 16, v46
	v_and_b32_e32 v53, 0xffff0000, v46
	v_lshlrev_b32_e32 v46, 16, v47
	v_and_b32_e32 v47, 0xffff0000, v47
	v_pk_add_f32 v[38:39], v[38:39], v[44:45]
	v_pk_add_f32 v[36:37], v[36:37], v[50:51]
	v_pk_add_f32 v[44:45], v[34:35], v[46:47]
	v_pk_add_f32 v[46:47], v[32:33], v[52:53]
	v_mul_f32_e32 v32, v37, v37
	v_mul_f32_e32 v33, v39, v39
	v_mul_f32_e32 v34, v47, v47
	v_mul_f32_e32 v35, v45, v45
	v_fmac_f32_e32 v32, v36, v36
	v_fmac_f32_e32 v33, v38, v38
	v_fmac_f32_e32 v34, v46, v46
	v_fmac_f32_e32 v35, v44, v44
	v_add_f32_e32 v32, v32, v33
	v_add_f32_e32 v33, v34, v35
	v_add_f32_e32 v32, v32, v33
	v_add_f32_e32 v32, v58, v32
	v_mov_b32_e32 v33, v32
	s_nop 1
	v_permlane16_swap_b32_e32 v33, v32
	v_cvt_pk_bf16_f32 v34, v36, v37
	v_cvt_pk_bf16_f32 v35, v38, v39
	v_lshl_add_u64 v[38:39], s[18:19], 0, v[54:55]
	v_cvt_pk_bf16_f32 v36, v46, v47
	s_waitcnt lgkmcnt(0)
	v_add_f32_e32 v32, v32, v33
	v_mov_b32_e32 v33, v32
	s_nop 1
	v_permlane32_swap_b32_e32 v33, v32
	v_cvt_pk_bf16_f32 v37, v44, v45
	global_store_dwordx4 v[38:39], v[34:37], off
	s_and_saveexec_b64 s[48:49], s[8:9]
	s_cbranch_execz .LBB0_352
	s_waitcnt lgkmcnt(0)
	v_add_f32_e32 v34, v32, v33
	v_lshlrev_b64 v[32:33], 7, v[48:49]
	v_lshl_add_u64 v[32:33], s[20:21], 0, v[32:33]
	v_lshl_add_u64 v[32:33], s[46:47], 2, v[32:33]
	s_lshl_b32 s12, s61, 2
	v_lshl_add_u64 v[32:33], v[32:33], 0, s[12:13]
	global_store_dword v[32:33], v34, off
.LBB0_352:
	s_or_b64 exec, exec, s[48:49]
	v_add_u32_e32 v32, 0xa0, v146
	s_waitcnt lgkmcnt(0)
	v_ashrrev_i32_e32 v33, 31, v32
	v_lshlrev_b64 v[34:35], 11, v[32:33]
	v_lshl_add_u64 v[34:35], v[34:35], 0, v[144:145]
	v_lshlrev_b64 v[38:39], 1, v[34:35]
	v_lshl_add_u64 v[34:35], s[16:17], 0, v[38:39]
	global_load_dwordx4 v[34:37], v[34:35], off
	v_lshl_add_u64 v[40:41], s[18:19], 0, v[38:39]
	v_or_b32_e32 v38, 0x100, v38
	v_lshl_add_u64 v[42:43], s[16:17], 0, v[38:39]
	s_waitcnt vmcnt(0)
	v_lshlrev_b32_e32 v44, 16, v34
	v_and_b32_e32 v45, 0xffff0000, v34
	v_lshlrev_b32_e32 v34, 16, v35
	v_and_b32_e32 v35, 0xffff0000, v35
	v_lshlrev_b32_e32 v46, 16, v36
	v_and_b32_e32 v47, 0xffff0000, v36
	v_lshlrev_b32_e32 v36, 16, v37
	v_and_b32_e32 v37, 0xffff0000, v37
	v_pk_add_f32 v[34:35], v[30:31], v[34:35]
	v_pk_add_f32 v[44:45], v[28:29], v[44:45]
	v_pk_add_f32 v[36:37], v[26:27], v[36:37]
	v_pk_add_f32 v[46:47], v[24:25], v[46:47]
	v_cvt_pk_bf16_f32 v24, v44, v45
	v_cvt_pk_bf16_f32 v25, v34, v35
	v_mul_f32_e32 v35, v35, v35
	v_cvt_pk_bf16_f32 v26, v46, v47
	v_cvt_pk_bf16_f32 v27, v36, v37
	global_load_dwordx4 v[28:31], v[42:43], off
	v_mul_f32_e32 v42, v45, v45
	v_mul_f32_e32 v43, v47, v47
	v_mul_f32_e32 v37, v37, v37
	v_fmac_f32_e32 v42, v44, v44
	v_fmac_f32_e32 v35, v34, v34
	v_fmac_f32_e32 v43, v46, v46
	v_fmac_f32_e32 v37, v36, v36
	v_add_f32_e32 v34, v42, v35
	v_add_f32_e32 v35, v43, v37
	v_add_f32_e32 v42, v34, v35
	global_store_dwordx4 v[40:41], v[24:27], off
	s_waitcnt vmcnt(1)
	v_lshlrev_b32_e32 v34, 16, v28
	v_and_b32_e32 v35, 0xffff0000, v28
	v_lshlrev_b32_e32 v28, 16, v29
	v_and_b32_e32 v29, 0xffff0000, v29
	v_lshlrev_b32_e32 v36, 16, v30
	v_and_b32_e32 v37, 0xffff0000, v30
	v_lshlrev_b32_e32 v30, 16, v31
	v_and_b32_e32 v31, 0xffff0000, v31
	v_pk_add_f32 v[22:23], v[22:23], v[28:29]
	v_pk_add_f32 v[20:21], v[20:21], v[34:35]
	v_pk_add_f32 v[28:29], v[18:19], v[30:31]
	v_pk_add_f32 v[30:31], v[16:17], v[36:37]
	v_mul_f32_e32 v16, v21, v21
	v_mul_f32_e32 v17, v23, v23
	v_mul_f32_e32 v18, v31, v31
	v_mul_f32_e32 v19, v29, v29
	v_fmac_f32_e32 v16, v20, v20
	v_fmac_f32_e32 v17, v22, v22
	v_fmac_f32_e32 v18, v30, v30
	v_fmac_f32_e32 v19, v28, v28
	v_add_f32_e32 v16, v16, v17
	v_add_f32_e32 v17, v18, v19
	v_add_f32_e32 v16, v16, v17
	v_add_f32_e32 v16, v42, v16
	v_mov_b32_e32 v17, v16
	s_nop 1
	v_permlane16_swap_b32_e32 v17, v16
	v_cvt_pk_bf16_f32 v18, v20, v21
	v_cvt_pk_bf16_f32 v19, v22, v23
	v_lshl_add_u64 v[22:23], s[18:19], 0, v[38:39]
	v_cvt_pk_bf16_f32 v20, v30, v31
	s_waitcnt lgkmcnt(0)
	v_add_f32_e32 v16, v16, v17
	v_mov_b32_e32 v17, v16
	s_nop 1
	v_permlane32_swap_b32_e32 v17, v16
	v_cvt_pk_bf16_f32 v21, v28, v29
	global_store_dwordx4 v[22:23], v[18:21], off
	s_and_saveexec_b64 s[48:49], s[8:9]
	s_cbranch_execz .LBB0_354
	s_waitcnt lgkmcnt(0)
	v_add_f32_e32 v18, v16, v17
	v_lshlrev_b64 v[16:17], 7, v[32:33]
	v_lshl_add_u64 v[16:17], s[20:21], 0, v[16:17]
	v_lshl_add_u64 v[16:17], s[46:47], 2, v[16:17]
	s_lshl_b32 s12, s61, 2
	v_lshl_add_u64 v[16:17], v[16:17], 0, s[12:13]
	global_store_dword v[16:17], v18, off
.LBB0_354:
	s_or_b64 exec, exec, s[48:49]
	v_add_u32_e32 v16, 0xb0, v146
	s_waitcnt lgkmcnt(0)
	v_ashrrev_i32_e32 v17, 31, v16
	v_lshlrev_b64 v[18:19], 11, v[16:17]
	v_lshl_add_u64 v[18:19], v[18:19], 0, v[144:145]
	v_lshlrev_b64 v[22:23], 1, v[18:19]
	v_lshl_add_u64 v[18:19], s[16:17], 0, v[22:23]
	global_load_dwordx4 v[18:21], v[18:19], off
	v_lshl_add_u64 v[24:25], s[18:19], 0, v[22:23]
	v_or_b32_e32 v22, 0x100, v22
	v_lshl_add_u64 v[26:27], s[16:17], 0, v[22:23]
	s_waitcnt vmcnt(0)
	v_lshlrev_b32_e32 v28, 16, v18
	v_and_b32_e32 v29, 0xffff0000, v18
	v_lshlrev_b32_e32 v18, 16, v19
	v_and_b32_e32 v19, 0xffff0000, v19
	v_lshlrev_b32_e32 v30, 16, v20
	v_and_b32_e32 v31, 0xffff0000, v20
	v_lshlrev_b32_e32 v20, 16, v21
	v_and_b32_e32 v21, 0xffff0000, v21
	v_pk_add_f32 v[18:19], v[14:15], v[18:19]
	v_pk_add_f32 v[28:29], v[12:13], v[28:29]
	v_pk_add_f32 v[20:21], v[10:11], v[20:21]
	v_pk_add_f32 v[30:31], v[8:9], v[30:31]
	v_cvt_pk_bf16_f32 v8, v28, v29
	v_cvt_pk_bf16_f32 v9, v18, v19
	v_mul_f32_e32 v19, v19, v19
	v_cvt_pk_bf16_f32 v10, v30, v31
	v_cvt_pk_bf16_f32 v11, v20, v21
	global_load_dwordx4 v[12:15], v[26:27], off
	v_mul_f32_e32 v26, v29, v29
	v_mul_f32_e32 v27, v31, v31
	v_mul_f32_e32 v21, v21, v21
	v_fmac_f32_e32 v26, v28, v28
	v_fmac_f32_e32 v19, v18, v18
	v_fmac_f32_e32 v27, v30, v30
	v_fmac_f32_e32 v21, v20, v20
	v_add_f32_e32 v18, v26, v19
	v_add_f32_e32 v19, v27, v21
	v_add_f32_e32 v26, v18, v19
	global_store_dwordx4 v[24:25], v[8:11], off
	s_waitcnt vmcnt(1)
	v_lshlrev_b32_e32 v18, 16, v12
	v_and_b32_e32 v19, 0xffff0000, v12
	v_lshlrev_b32_e32 v12, 16, v13
	v_and_b32_e32 v13, 0xffff0000, v13
	v_lshlrev_b32_e32 v20, 16, v14
	v_and_b32_e32 v21, 0xffff0000, v14
	v_lshlrev_b32_e32 v14, 16, v15
	v_and_b32_e32 v15, 0xffff0000, v15
	v_pk_add_f32 v[6:7], v[6:7], v[12:13]
	v_pk_add_f32 v[4:5], v[4:5], v[18:19]
	v_pk_add_f32 v[12:13], v[2:3], v[14:15]
	v_pk_add_f32 v[14:15], v[0:1], v[20:21]
	v_mul_f32_e32 v0, v5, v5
	v_mul_f32_e32 v1, v7, v7
	v_mul_f32_e32 v2, v15, v15
	v_mul_f32_e32 v3, v13, v13
	v_fmac_f32_e32 v0, v4, v4
	v_fmac_f32_e32 v1, v6, v6
	v_fmac_f32_e32 v2, v14, v14
	v_fmac_f32_e32 v3, v12, v12
	v_add_f32_e32 v0, v0, v1
	v_add_f32_e32 v1, v2, v3
	v_add_f32_e32 v0, v0, v1
	v_add_f32_e32 v0, v26, v0
	v_mov_b32_e32 v1, v0
	s_nop 1
	v_permlane16_swap_b32_e32 v1, v0
	v_cvt_pk_bf16_f32 v2, v4, v5
	v_cvt_pk_bf16_f32 v3, v6, v7
	v_lshl_add_u64 v[6:7], s[18:19], 0, v[22:23]
	v_cvt_pk_bf16_f32 v4, v14, v15
	s_waitcnt lgkmcnt(0)
	v_add_f32_e32 v0, v0, v1
	v_mov_b32_e32 v1, v0
	s_nop 1
	v_permlane32_swap_b32_e32 v1, v0
	v_cvt_pk_bf16_f32 v5, v12, v13
	global_store_dwordx4 v[6:7], v[2:5], off
	s_and_saveexec_b64 s[48:49], s[8:9]
	s_cbranch_execz .LBB0_356
	s_waitcnt lgkmcnt(0)
	v_add_f32_e32 v2, v0, v1
	v_lshlrev_b64 v[0:1], 7, v[16:17]
	v_lshl_add_u64 v[0:1], s[20:21], 0, v[0:1]
	v_lshl_add_u64 v[0:1], s[46:47], 2, v[0:1]
	s_lshl_b32 s12, s61, 2
	v_lshl_add_u64 v[0:1], v[0:1], 0, s[12:13]
	global_store_dword v[0:1], v2, off

.LBB0_441:
	s_lshl_b32 s23, s36, 8
	s_cmp_eq_u32 s50, 2
	s_cselect_b32 s25, 0x80, 0
	s_or_b32 s23, s23, s25
	v_add_u32_e32 v132, s23, v219
	v_ashrrev_i32_e32 v133, 31, v132
	v_lshlrev_b64 v[2:3], 7, v[132:133]
	v_lshl_add_u64 v[2:3], v[204:205], 0, v[2:3]
	global_load_dwordx4 v[134:137], v[2:3], off
	global_load_dwordx4 v[138:141], v[2:3], off offset:16
	v_and_b32_e32 v133, 64, v225
	v_xor_b32_e32 v1, 16, v225
	v_mov_b32_e32 v145, v118
	v_mov_b32_e32 v118, v127
	v_add_u32_e32 v127, 64, v133
	v_cmp_lt_i32_e32 vcc, v1, v127
	v_mov_b32_e32 v144, v126
	v_xor_b32_e32 v148, 32, v225
	v_cndmask_b32_e32 v1, v225, v1, vcc
	v_lshlrev_b32_e32 v126, 2, v1
	v_cmp_lt_i32_e32 vcc, v148, v127
	v_mov_b32_e32 v142, v128
	v_mov_b32_e32 v143, v120
	v_mov_b32_e32 v120, v129
	v_mov_b32_e32 v128, v130
	v_mov_b32_e32 v129, v122
	v_mov_b32_e32 v122, v131
	v_mov_b32_e32 v130, v124
	v_mov_b32_e32 v131, v116
	v_mov_b32_e32 v116, v125
	v_lshl_or_b32 v2, s51, 7, v221
	v_mov_b64_e32 v[124:125], s[14:15]
	v_ashrrev_i32_e32 v3, 31, v2
	v_lshlrev_b64 v[2:3], 1, v[2:3]
	s_waitcnt vmcnt(0)
	v_mov_b32_e32 v146, v134
	v_mov_b32_e32 v147, v138
	v_mov_b32_e32 v138, v135
	v_mov_b32_e32 v134, v136
	v_mov_b32_e32 v135, v140
	v_mov_b32_e32 v140, v137
	v_pk_add_f32 v[136:137], v[146:147], v[138:139]
	v_pk_add_f32 v[134:135], v[134:135], v[140:141]
	s_nop 0
	v_pk_add_f32 v[134:135], v[136:137], v[134:135]
	v_or_b32_e32 v136, 16, v132
	v_add_f32_e32 v1, 0, v134
	v_add_f32_e32 v133, v1, v135
	v_mov_b32_e32 v134, v133
	s_nop 1
	v_permlane16_swap_b32_e32 v134, v133
	v_cndmask_b32_e32 v1, v225, v148, vcc
	v_lshlrev_b32_e32 v1, 2, v1
	v_ashrrev_i32_e32 v137, 31, v136
	v_lshlrev_b64 v[138:139], 7, v[136:137]
	s_waitcnt lgkmcnt(0)
	v_add_f32_e32 v127, v133, v134
	v_mov_b32_e32 v133, v127
	s_nop 1
	v_permlane32_swap_b32_e32 v133, v127
	v_mad_i64_i32 v[134:135], s[46:47], v132, s72, v[124:125]
	v_lshl_add_u64 v[134:135], v[134:135], 0, v[2:3]
	v_lshl_add_u64 v[138:139], v[204:205], 0, v[138:139]
	s_waitcnt lgkmcnt(0)
	v_add_f32_e32 v127, v127, v133
	v_fmamk_f32 v127, v127, 0x3a000000, v226
	v_mul_f32_e32 v133, 0x4b800000, v127
	v_cmp_gt_f32_e32 vcc, s71, v127
	s_nop 1
	v_cndmask_b32_e32 v127, v127, v133, vcc
	v_rsq_f32_e32 v127, v127
	s_nop 0
	v_mul_f32_e32 v133, 0x45800000, v127
	v_cndmask_b32_e32 v140, v127, v133, vcc
	v_pk_mul_f32 v[118:119], v[118:119], v[140:141] op_sel_hi:[1,0]
	v_pk_mul_f32 v[142:143], v[142:143], v[140:141] op_sel_hi:[1,0]
	v_pk_mul_f32 v[120:121], v[120:121], v[140:141] op_sel_hi:[1,0]
	v_pk_mul_f32 v[128:129], v[128:129], v[140:141] op_sel_hi:[1,0]
	v_pk_mul_f32 v[122:123], v[122:123], v[140:141] op_sel_hi:[1,0]
	v_pk_mul_f32 v[130:131], v[130:131], v[140:141] op_sel_hi:[1,0]
	v_pk_mul_f32 v[116:117], v[116:117], v[140:141] op_sel_hi:[1,0]
	v_pk_mul_f32 v[144:145], v[144:145], v[140:141] op_sel_hi:[1,0]
	v_mul_f32_e32 v148, 0xbfb8aa3b, v119
	v_mul_f32_e32 v127, 0xbfb8aa3b, v143
	v_mul_f32_e32 v133, 0xbfb8aa3b, v121
	v_mul_f32_e32 v137, 0xbfb8aa3b, v129
	v_mul_f32_e32 v140, 0xbfb8aa3b, v123
	v_mul_f32_e32 v141, 0xbfb8aa3b, v131
	v_mul_f32_e32 v146, 0xbfb8aa3b, v117
	v_mul_f32_e32 v147, 0xbfb8aa3b, v145
	v_exp_f32_e32 v148, v148
	v_exp_f32_e32 v127, v127
	v_exp_f32_e32 v133, v133
	v_exp_f32_e32 v137, v137
	v_exp_f32_e32 v140, v140
	v_exp_f32_e32 v141, v141
	v_exp_f32_e32 v146, v146
	v_exp_f32_e32 v147, v147
	v_add_f32_e32 v148, 1.0, v148
	v_add_f32_e32 v127, 1.0, v127
	v_add_f32_e32 v133, 1.0, v133
	v_add_f32_e32 v137, 1.0, v137
	v_add_f32_e32 v140, 1.0, v140
	v_add_f32_e32 v141, 1.0, v141
	v_add_f32_e32 v146, 1.0, v146
	v_add_f32_e32 v147, 1.0, v147
	v_rcp_f32_e32 v148, v148
	v_rcp_f32_e32 v127, v127
	v_rcp_f32_e32 v133, v133
	v_rcp_f32_e32 v137, v137
	v_rcp_f32_e32 v140, v140
	v_rcp_f32_e32 v141, v141
	v_rcp_f32_e32 v146, v146
	v_rcp_f32_e32 v147, v147
	v_mul_f32_e32 v119, v119, v148
	v_mul_f32_e32 v127, v143, v127
	v_mul_f32_e32 v121, v121, v133
	v_mul_f32_e32 v129, v129, v137
	v_mul_f32_e32 v123, v123, v140
	v_mul_f32_e32 v131, v131, v141
	v_mul_f32_e32 v117, v117, v146
	v_mul_f32_e32 v133, v145, v147
	v_mul_f32_e32 v119, v118, v119
	v_mul_f32_e32 v127, v142, v127
	v_mul_f32_e32 v120, v120, v121
	v_mul_f32_e32 v121, v128, v129
	v_mul_f32_e32 v122, v122, v123
	v_mul_f32_e32 v123, v130, v131
	v_mul_f32_e32 v128, v116, v117
	v_mul_f32_e32 v129, v144, v133
	v_cvt_pk_bf16_f32 v116, v127, v120
	v_cvt_pk_bf16_f32 v117, v121, v122
	v_cvt_pk_bf16_f32 v118, v123, v128
	v_cvt_pk_bf16_f32 v119, v129, v119
	global_store_dwordx4 v[134:135], v[116:119], off
	global_load_dwordx4 v[116:119], v[138:139], off
	global_load_dwordx4 v[120:123], v[138:139], off offset:16
	v_mov_b32_e32 v129, v104
	v_mov_b32_e32 v104, v113
	v_mov_b32_e32 v113, v106
	v_mov_b32_e32 v106, v115
	v_mov_b32_e32 v115, v100
	v_mov_b32_e32 v128, v112
	v_mov_b32_e32 v112, v114
	v_mov_b32_e32 v114, v108
	v_mov_b32_e32 v108, v110
	v_or_b32_e32 v110, 32, v132
	s_waitcnt vmcnt(1)
	v_mov_b32_e32 v130, v116
	s_waitcnt vmcnt(0)
	v_mov_b32_e32 v131, v120
	v_mov_b32_e32 v120, v117
	v_mov_b32_e32 v116, v118
	v_mov_b32_e32 v117, v122
	v_mov_b32_e32 v122, v119
	v_pk_add_f32 v[118:119], v[130:131], v[120:121]
	v_pk_add_f32 v[116:117], v[116:117], v[122:123]
	s_nop 0
	v_pk_add_f32 v[116:117], v[118:119], v[116:117]
	s_nop 0
	v_add_f32_e32 v100, 0, v116
	v_add_f32_e32 v116, v100, v117
	v_mov_b32_e32 v117, v116
	s_nop 1
	v_permlane16_swap_b32_e32 v117, v116
	v_mov_b32_e32 v100, v109
	v_mov_b32_e32 v109, v102
	v_mov_b32_e32 v102, v111
	v_ashrrev_i32_e32 v111, 31, v110
	s_waitcnt lgkmcnt(0)
	v_add_f32_e32 v118, v116, v117
	v_mov_b32_e32 v119, v118
	s_nop 1
	v_permlane32_swap_b32_e32 v119, v118
	v_mad_i64_i32 v[116:117], s[46:47], v136, s72, v[124:125]
	v_lshl_add_u64 v[116:117], v[116:117], 0, v[2:3]
	s_waitcnt lgkmcnt(0)
	v_add_f32_e32 v118, v118, v119
	v_fmamk_f32 v118, v118, 0x3a000000, v226
	v_mul_f32_e32 v119, 0x4b800000, v118
	v_cmp_gt_f32_e32 vcc, s71, v118
	s_nop 1
	v_cndmask_b32_e32 v118, v118, v119, vcc
	v_rsq_f32_e32 v120, v118
	v_lshlrev_b64 v[118:119], 7, v[110:111]
	v_lshl_add_u64 v[118:119], v[204:205], 0, v[118:119]
	v_mul_f32_e32 v111, 0x45800000, v120
	v_cndmask_b32_e32 v120, v120, v111, vcc
	v_pk_mul_f32 v[102:103], v[102:103], v[120:121] op_sel_hi:[1,0]
	v_pk_mul_f32 v[122:123], v[128:129], v[120:121] op_sel_hi:[1,0]
	v_pk_mul_f32 v[104:105], v[104:105], v[120:121] op_sel_hi:[1,0]
	v_pk_mul_f32 v[112:113], v[112:113], v[120:121] op_sel_hi:[1,0]
	v_pk_mul_f32 v[106:107], v[106:107], v[120:121] op_sel_hi:[1,0]
	v_pk_mul_f32 v[114:115], v[114:115], v[120:121] op_sel_hi:[1,0]
	v_pk_mul_f32 v[100:101], v[100:101], v[120:121] op_sel_hi:[1,0]
	v_pk_mul_f32 v[108:109], v[108:109], v[120:121] op_sel_hi:[1,0]
	v_mul_f32_e32 v131, 0xbfb8aa3b, v103
	v_mul_f32_e32 v111, 0xbfb8aa3b, v123
	v_mul_f32_e32 v120, 0xbfb8aa3b, v105
	v_mul_f32_e32 v121, 0xbfb8aa3b, v113
	v_mul_f32_e32 v127, 0xbfb8aa3b, v107
	v_mul_f32_e32 v128, 0xbfb8aa3b, v115
	v_mul_f32_e32 v129, 0xbfb8aa3b, v101
	v_mul_f32_e32 v130, 0xbfb8aa3b, v109
	v_exp_f32_e32 v131, v131
	v_exp_f32_e32 v111, v111
	v_exp_f32_e32 v120, v120
	v_exp_f32_e32 v121, v121
	v_exp_f32_e32 v127, v127
	v_exp_f32_e32 v128, v128
	v_exp_f32_e32 v129, v129
	v_exp_f32_e32 v130, v130
	v_add_f32_e32 v131, 1.0, v131
	v_add_f32_e32 v111, 1.0, v111
	v_add_f32_e32 v120, 1.0, v120
	v_add_f32_e32 v121, 1.0, v121
	v_add_f32_e32 v127, 1.0, v127
	v_add_f32_e32 v128, 1.0, v128
	v_add_f32_e32 v129, 1.0, v129
	v_add_f32_e32 v130, 1.0, v130
	v_rcp_f32_e32 v131, v131
	v_rcp_f32_e32 v111, v111
	v_rcp_f32_e32 v120, v120
	v_rcp_f32_e32 v121, v121
	v_rcp_f32_e32 v127, v127
	v_rcp_f32_e32 v128, v128
	v_rcp_f32_e32 v129, v129
	v_rcp_f32_e32 v130, v130
	v_mul_f32_e32 v103, v103, v131
	v_mul_f32_e32 v111, v123, v111
	v_mul_f32_e32 v105, v105, v120
	v_mul_f32_e32 v113, v113, v121
	v_mul_f32_e32 v107, v107, v127
	v_mul_f32_e32 v115, v115, v128
	v_mul_f32_e32 v101, v101, v129
	v_mul_f32_e32 v109, v109, v130
	v_mul_f32_e32 v103, v102, v103
	v_mul_f32_e32 v111, v122, v111
	v_mul_f32_e32 v104, v104, v105
	v_mul_f32_e32 v105, v112, v113
	v_mul_f32_e32 v106, v106, v107
	v_mul_f32_e32 v107, v114, v115
	v_mul_f32_e32 v112, v100, v101
	v_mul_f32_e32 v108, v108, v109
	v_cvt_pk_bf16_f32 v100, v111, v104
	v_cvt_pk_bf16_f32 v101, v105, v106
	v_cvt_pk_bf16_f32 v102, v107, v112
	v_cvt_pk_bf16_f32 v103, v108, v103
	global_store_dwordx4 v[116:117], v[100:103], off
	global_load_dwordx4 v[100:103], v[118:119], off
	global_load_dwordx4 v[104:107], v[118:119], off offset:16
	v_mov_b32_e32 v109, v88
	v_mov_b32_e32 v88, v97
	v_mov_b32_e32 v97, v90
	v_mov_b32_e32 v90, v99
	v_mov_b32_e32 v99, v84
	v_mov_b32_e32 v108, v96
	v_mov_b32_e32 v96, v98
	v_mov_b32_e32 v98, v92
	v_mov_b32_e32 v92, v94
	v_or_b32_e32 v94, 48, v132
	s_waitcnt vmcnt(1)
	v_mov_b32_e32 v112, v100
	s_waitcnt vmcnt(0)
	v_mov_b32_e32 v113, v104
	v_mov_b32_e32 v104, v101
	v_mov_b32_e32 v100, v102
	v_mov_b32_e32 v101, v106
	v_mov_b32_e32 v106, v103
	v_pk_add_f32 v[102:103], v[112:113], v[104:105]
	v_pk_add_f32 v[100:101], v[100:101], v[106:107]
	s_nop 0
	v_pk_add_f32 v[100:101], v[102:103], v[100:101]
	s_nop 0
	v_add_f32_e32 v84, 0, v100
	v_add_f32_e32 v100, v84, v101
	v_mov_b32_e32 v101, v100
	s_nop 1
	v_permlane16_swap_b32_e32 v101, v100
	v_mov_b32_e32 v84, v93
	v_mov_b32_e32 v93, v86
	v_mov_b32_e32 v86, v95
	v_ashrrev_i32_e32 v95, 31, v94
	s_waitcnt lgkmcnt(0)
	v_add_f32_e32 v102, v100, v101
	v_mov_b32_e32 v103, v102
	s_nop 1
	v_permlane32_swap_b32_e32 v103, v102
	v_mad_i64_i32 v[100:101], s[46:47], v110, s72, v[124:125]
	v_lshl_add_u64 v[100:101], v[100:101], 0, v[2:3]
	s_waitcnt lgkmcnt(0)
	v_add_f32_e32 v102, v102, v103
	v_fmamk_f32 v102, v102, 0x3a000000, v226
	v_mul_f32_e32 v103, 0x4b800000, v102
	v_cmp_gt_f32_e32 vcc, s71, v102
	s_nop 1
	v_cndmask_b32_e32 v102, v102, v103, vcc
	v_rsq_f32_e32 v104, v102
	v_lshlrev_b64 v[102:103], 7, v[94:95]
	v_lshl_add_u64 v[102:103], v[204:205], 0, v[102:103]
	v_mul_f32_e32 v95, 0x45800000, v104
	v_cndmask_b32_e32 v104, v104, v95, vcc
	v_pk_mul_f32 v[86:87], v[86:87], v[104:105] op_sel_hi:[1,0]
	v_pk_mul_f32 v[106:107], v[108:109], v[104:105] op_sel_hi:[1,0]
	v_pk_mul_f32 v[88:89], v[88:89], v[104:105] op_sel_hi:[1,0]
	v_pk_mul_f32 v[96:97], v[96:97], v[104:105] op_sel_hi:[1,0]
	v_pk_mul_f32 v[90:91], v[90:91], v[104:105] op_sel_hi:[1,0]
	v_pk_mul_f32 v[98:99], v[98:99], v[104:105] op_sel_hi:[1,0]
	v_pk_mul_f32 v[84:85], v[84:85], v[104:105] op_sel_hi:[1,0]
	v_pk_mul_f32 v[92:93], v[92:93], v[104:105] op_sel_hi:[1,0]
	v_mul_f32_e32 v112, 0xbfb8aa3b, v87
	v_mul_f32_e32 v95, 0xbfb8aa3b, v107
	v_mul_f32_e32 v104, 0xbfb8aa3b, v89
	v_mul_f32_e32 v105, 0xbfb8aa3b, v97
	v_mul_f32_e32 v108, 0xbfb8aa3b, v91
	v_mul_f32_e32 v109, 0xbfb8aa3b, v99
	v_mul_f32_e32 v110, 0xbfb8aa3b, v85
	v_mul_f32_e32 v111, 0xbfb8aa3b, v93
	v_exp_f32_e32 v112, v112
	v_exp_f32_e32 v95, v95
	v_exp_f32_e32 v104, v104
	v_exp_f32_e32 v105, v105
	v_exp_f32_e32 v108, v108
	v_exp_f32_e32 v109, v109
	v_exp_f32_e32 v110, v110
	v_exp_f32_e32 v111, v111
	v_add_f32_e32 v112, 1.0, v112
	v_add_f32_e32 v95, 1.0, v95
	v_add_f32_e32 v104, 1.0, v104
	v_add_f32_e32 v105, 1.0, v105
	v_add_f32_e32 v108, 1.0, v108
	v_add_f32_e32 v109, 1.0, v109
	v_add_f32_e32 v110, 1.0, v110
	v_add_f32_e32 v111, 1.0, v111
	v_rcp_f32_e32 v112, v112
	v_rcp_f32_e32 v95, v95
	v_rcp_f32_e32 v104, v104
	v_rcp_f32_e32 v105, v105
	v_rcp_f32_e32 v108, v108
	v_rcp_f32_e32 v109, v109
	v_rcp_f32_e32 v110, v110
	v_rcp_f32_e32 v111, v111
	v_mul_f32_e32 v87, v87, v112
	v_mul_f32_e32 v95, v107, v95
	v_mul_f32_e32 v89, v89, v104
	v_mul_f32_e32 v97, v97, v105
	v_mul_f32_e32 v91, v91, v108
	v_mul_f32_e32 v99, v99, v109
	v_mul_f32_e32 v85, v85, v110
	v_mul_f32_e32 v93, v93, v111
	v_mul_f32_e32 v87, v86, v87
	v_mul_f32_e32 v95, v106, v95
	v_mul_f32_e32 v88, v88, v89
	v_mul_f32_e32 v89, v96, v97
	v_mul_f32_e32 v90, v90, v91
	v_mul_f32_e32 v91, v98, v99
	v_mul_f32_e32 v96, v84, v85
	v_mul_f32_e32 v92, v92, v93
	v_cvt_pk_bf16_f32 v84, v95, v88
	v_cvt_pk_bf16_f32 v85, v89, v90
	v_cvt_pk_bf16_f32 v86, v91, v96
	v_cvt_pk_bf16_f32 v87, v92, v87
	global_store_dwordx4 v[100:101], v[84:87], off
	global_load_dwordx4 v[84:87], v[102:103], off
	global_load_dwordx4 v[88:91], v[102:103], off offset:16
	v_mov_b32_e32 v93, v76
	v_mov_b32_e32 v76, v81
	v_mov_b32_e32 v92, v80
	v_mov_b32_e32 v80, v82
	v_mov_b32_e32 v82, v68
	v_mov_b32_e32 v68, v70
	s_waitcnt vmcnt(1)
	v_mov_b32_e32 v96, v84
	s_waitcnt vmcnt(0)
	v_mov_b32_e32 v97, v88
	v_mov_b32_e32 v88, v85
	v_mov_b32_e32 v84, v86
	v_mov_b32_e32 v85, v90
	v_mov_b32_e32 v90, v87
	v_pk_add_f32 v[86:87], v[96:97], v[88:89]
	v_pk_add_f32 v[84:85], v[84:85], v[90:91]
	s_nop 0
	v_pk_add_f32 v[84:85], v[86:87], v[84:85]
	s_nop 0
	v_add_f32_e32 v81, 0, v84
	v_add_f32_e32 v84, v81, v85
	v_mov_b32_e32 v85, v84
	s_nop 1
	v_permlane16_swap_b32_e32 v85, v84
	v_mov_b32_e32 v81, v78
	v_mov_b32_e32 v78, v83
	v_mov_b32_e32 v83, v72
	v_mov_b32_e32 v72, v69
	s_waitcnt lgkmcnt(0)
	v_add_f32_e32 v84, v84, v85
	v_mov_b32_e32 v85, v84
	s_nop 1
	v_permlane32_swap_b32_e32 v85, v84
	v_mov_b32_e32 v69, v74
	v_mov_b32_e32 v74, v71
	s_waitcnt lgkmcnt(0)
	v_add_f32_e32 v70, v84, v85
	v_fmamk_f32 v70, v70, 0x3a000000, v226
	v_mul_f32_e32 v71, 0x4b800000, v70
	v_cmp_gt_f32_e32 vcc, s71, v70
	s_nop 1
	v_cndmask_b32_e32 v70, v70, v71, vcc
	v_rsq_f32_e32 v86, v70
	v_mad_i64_i32 v[70:71], s[46:47], v94, s72, v[124:125]
	v_lshl_add_u64 v[84:85], v[70:71], 0, v[2:3]
	v_mul_f32_e32 v70, 0x45800000, v86
	v_cndmask_b32_e32 v70, v86, v70, vcc
	v_pk_mul_f32 v[86:87], v[92:93], v[70:71] op_sel_hi:[1,0]
	v_pk_mul_f32 v[76:77], v[76:77], v[70:71] op_sel_hi:[1,0]
	v_pk_mul_f32 v[80:81], v[80:81], v[70:71] op_sel_hi:[1,0]
	v_pk_mul_f32 v[78:79], v[78:79], v[70:71] op_sel_hi:[1,0]
	v_pk_mul_f32 v[82:83], v[82:83], v[70:71] op_sel_hi:[1,0]
	v_pk_mul_f32 v[72:73], v[72:73], v[70:71] op_sel_hi:[1,0]
	v_pk_mul_f32 v[68:69], v[68:69], v[70:71] op_sel_hi:[1,0]
	v_pk_mul_f32 v[70:71], v[74:75], v[70:71] op_sel_hi:[1,0]
	v_mul_f32_e32 v74, 0xbfb8aa3b, v87
	v_mul_f32_e32 v93, 0xbfb8aa3b, v71
	v_mul_f32_e32 v75, 0xbfb8aa3b, v77
	v_mul_f32_e32 v88, 0xbfb8aa3b, v81
	v_mul_f32_e32 v89, 0xbfb8aa3b, v79
	v_mul_f32_e32 v90, 0xbfb8aa3b, v83
	v_mul_f32_e32 v91, 0xbfb8aa3b, v73
	v_mul_f32_e32 v92, 0xbfb8aa3b, v69
	v_exp_f32_e32 v93, v93
	v_exp_f32_e32 v74, v74
	v_exp_f32_e32 v75, v75
	v_exp_f32_e32 v88, v88
	v_exp_f32_e32 v89, v89
	v_exp_f32_e32 v90, v90
	v_exp_f32_e32 v91, v91
	v_exp_f32_e32 v92, v92
	v_add_f32_e32 v93, 1.0, v93
	v_add_f32_e32 v74, 1.0, v74
	v_add_f32_e32 v75, 1.0, v75
	v_add_f32_e32 v88, 1.0, v88
	v_add_f32_e32 v89, 1.0, v89
	v_add_f32_e32 v90, 1.0, v90
	v_add_f32_e32 v91, 1.0, v91
	v_add_f32_e32 v92, 1.0, v92
	v_rcp_f32_e32 v93, v93
	v_rcp_f32_e32 v74, v74
	v_rcp_f32_e32 v75, v75
	v_rcp_f32_e32 v88, v88
	v_rcp_f32_e32 v89, v89
	v_rcp_f32_e32 v90, v90
	v_rcp_f32_e32 v91, v91
	v_rcp_f32_e32 v92, v92
	v_mul_f32_e32 v71, v71, v93
	v_mul_f32_e32 v74, v87, v74
	v_mul_f32_e32 v75, v77, v75
	v_mul_f32_e32 v77, v81, v88
	v_mul_f32_e32 v79, v79, v89
	v_mul_f32_e32 v81, v83, v90
	v_mul_f32_e32 v73, v73, v91
	v_mul_f32_e32 v69, v69, v92
	v_mul_f32_e32 v71, v70, v71
	v_mul_f32_e32 v74, v86, v74
	v_mul_f32_e32 v75, v76, v75
	v_mul_f32_e32 v76, v80, v77
	v_mul_f32_e32 v77, v78, v79
	v_mul_f32_e32 v78, v82, v81
	v_mul_f32_e32 v72, v72, v73
	v_mul_f32_e32 v73, v68, v69
	v_cvt_pk_bf16_f32 v68, v74, v75
	v_cvt_pk_bf16_f32 v69, v76, v77
	v_cvt_pk_bf16_f32 v70, v78, v72
	v_cvt_pk_bf16_f32 v71, v73, v71
	global_store_dwordx4 v[84:85], v[68:71], off
	s_and_b64 vcc, exec, s[10:11]
	s_cbranch_vccz .LBB0_443
	s_andn2_b64 vcc, exec, s[26:27]
	s_mov_b64 s[10:11], -1
	s_cbranch_vccnz .LBB0_422
	s_branch .LBB0_444
.LBB0_443:
	v_add_u32_e32 v76, 0x80, v132
	v_ashrrev_i32_e32 v77, 31, v76
	v_lshlrev_b64 v[68:69], 7, v[76:77]
	v_lshl_add_u64 v[72:73], v[204:205], 0, v[68:69]
	global_load_dwordx4 v[68:71], v[72:73], off
	s_nop 0
	global_load_dwordx4 v[72:75], v[72:73], off offset:16
	v_mov_b32_e32 v78, v64
	v_mov_b32_e32 v79, v56
	v_mov_b32_e32 v56, v65
	v_mov_b32_e32 v64, v66
	v_mov_b32_e32 v65, v58
	v_mov_b32_e32 v58, v67
	v_mov_b32_e32 v66, v60
	v_mov_b32_e32 v67, v52
	v_mov_b32_e32 v52, v61
	s_waitcnt vmcnt(1)
	v_mov_b32_e32 v60, v68
	s_waitcnt vmcnt(0)
	v_mov_b32_e32 v61, v72
	v_mov_b32_e32 v72, v69
	v_mov_b32_e32 v68, v70
	v_mov_b32_e32 v69, v74
	v_mov_b32_e32 v74, v71
	v_pk_add_f32 v[60:61], v[60:61], v[72:73]
	v_pk_add_f32 v[68:69], v[68:69], v[74:75]
	s_nop 0
	v_pk_add_f32 v[60:61], v[60:61], v[68:69]
	v_mov_b32_e32 v68, v62
	v_add_f32_e32 v60, 0, v60
	v_add_f32_e32 v70, v60, v61
	v_mov_b32_e32 v71, v70
	s_nop 1
	v_permlane16_swap_b32_e32 v71, v70
	v_add_u32_e32 v62, 0x90, v132
	v_mov_b32_e32 v69, v54
	v_mov_b32_e32 v54, v63
	v_ashrrev_i32_e32 v63, 31, v62
	s_waitcnt lgkmcnt(0)
	v_add_f32_e32 v72, v70, v71
	v_mov_b32_e32 v73, v72
	s_nop 1
	v_permlane32_swap_b32_e32 v73, v72
	v_mov_b64_e32 v[60:61], s[14:15]
	v_mad_i64_i32 v[70:71], s[10:11], v76, s72, v[60:61]
	v_lshl_add_u64 v[70:71], v[70:71], 0, v[2:3]
	s_waitcnt lgkmcnt(0)
	v_add_f32_e32 v72, v72, v73
	v_fmamk_f32 v72, v72, 0x3a000000, v226
	v_mul_f32_e32 v73, 0x4b800000, v72
	v_cmp_gt_f32_e32 vcc, s71, v72
	s_nop 1
	v_cndmask_b32_e32 v72, v72, v73, vcc
	v_rsq_f32_e32 v74, v72
	v_lshlrev_b64 v[72:73], 7, v[62:63]
	v_lshl_add_u64 v[72:73], v[204:205], 0, v[72:73]
	v_mul_f32_e32 v63, 0x45800000, v74
	v_cndmask_b32_e32 v74, v74, v63, vcc
	v_pk_mul_f32 v[54:55], v[54:55], v[74:75] op_sel_hi:[1,0]
	v_pk_mul_f32 v[76:77], v[78:79], v[74:75] op_sel_hi:[1,0]
	v_pk_mul_f32 v[56:57], v[56:57], v[74:75] op_sel_hi:[1,0]
	v_pk_mul_f32 v[64:65], v[64:65], v[74:75] op_sel_hi:[1,0]
	v_pk_mul_f32 v[58:59], v[58:59], v[74:75] op_sel_hi:[1,0]
	v_pk_mul_f32 v[66:67], v[66:67], v[74:75] op_sel_hi:[1,0]
	v_pk_mul_f32 v[52:53], v[52:53], v[74:75] op_sel_hi:[1,0]
	v_pk_mul_f32 v[68:69], v[68:69], v[74:75] op_sel_hi:[1,0]
	v_mul_f32_e32 v82, 0xbfb8aa3b, v55
	v_mul_f32_e32 v63, 0xbfb8aa3b, v77
	v_mul_f32_e32 v74, 0xbfb8aa3b, v57
	v_mul_f32_e32 v75, 0xbfb8aa3b, v65
	v_mul_f32_e32 v78, 0xbfb8aa3b, v59
	v_mul_f32_e32 v79, 0xbfb8aa3b, v67
	v_mul_f32_e32 v80, 0xbfb8aa3b, v53
	v_mul_f32_e32 v81, 0xbfb8aa3b, v69
	v_exp_f32_e32 v82, v82
	v_exp_f32_e32 v63, v63
	v_exp_f32_e32 v74, v74
	v_exp_f32_e32 v75, v75
	v_exp_f32_e32 v78, v78
	v_exp_f32_e32 v79, v79
	v_exp_f32_e32 v80, v80
	v_exp_f32_e32 v81, v81
	v_add_f32_e32 v82, 1.0, v82
	v_add_f32_e32 v63, 1.0, v63
	v_add_f32_e32 v74, 1.0, v74
	v_add_f32_e32 v75, 1.0, v75
	v_add_f32_e32 v78, 1.0, v78
	v_add_f32_e32 v79, 1.0, v79
	v_add_f32_e32 v80, 1.0, v80
	v_add_f32_e32 v81, 1.0, v81
	v_rcp_f32_e32 v82, v82
	v_rcp_f32_e32 v63, v63
	v_rcp_f32_e32 v74, v74
	v_rcp_f32_e32 v75, v75
	v_rcp_f32_e32 v78, v78
	v_rcp_f32_e32 v79, v79
	v_rcp_f32_e32 v80, v80
	v_rcp_f32_e32 v81, v81
	v_mul_f32_e32 v55, v55, v82
	v_mul_f32_e32 v63, v77, v63
	v_mul_f32_e32 v57, v57, v74
	v_mul_f32_e32 v65, v65, v75
	v_mul_f32_e32 v59, v59, v78
	v_mul_f32_e32 v67, v67, v79
	v_mul_f32_e32 v53, v53, v80
	v_mul_f32_e32 v69, v69, v81
	v_mul_f32_e32 v55, v54, v55
	v_mul_f32_e32 v63, v76, v63
	v_mul_f32_e32 v56, v56, v57
	v_mul_f32_e32 v57, v64, v65
	v_mul_f32_e32 v58, v58, v59
	v_mul_f32_e32 v59, v66, v67
	v_mul_f32_e32 v64, v52, v53
	v_mul_f32_e32 v65, v68, v69
	v_cvt_pk_bf16_f32 v52, v63, v56
	v_cvt_pk_bf16_f32 v53, v57, v58
	v_cvt_pk_bf16_f32 v54, v59, v64
	v_cvt_pk_bf16_f32 v55, v65, v55
	global_store_dwordx4 v[70:71], v[52:55], off
	global_load_dwordx4 v[52:55], v[72:73], off
	global_load_dwordx4 v[56:59], v[72:73], off offset:16
	v_mov_b32_e32 v65, v40
	v_mov_b32_e32 v40, v49
	v_mov_b32_e32 v49, v42
	v_mov_b32_e32 v42, v51
	v_mov_b32_e32 v51, v36
	v_mov_b32_e32 v64, v48
	v_mov_b32_e32 v48, v50
	v_mov_b32_e32 v50, v44
	v_mov_b32_e32 v44, v46
	v_add_u32_e32 v46, 0xa0, v132
	s_waitcnt vmcnt(1)
	v_mov_b32_e32 v66, v52
	s_waitcnt vmcnt(0)
	v_mov_b32_e32 v67, v56
	v_mov_b32_e32 v56, v53
	v_mov_b32_e32 v52, v54
	v_mov_b32_e32 v53, v58
	v_mov_b32_e32 v58, v55
	v_pk_add_f32 v[54:55], v[66:67], v[56:57]
	v_pk_add_f32 v[52:53], v[52:53], v[58:59]
	s_nop 0
	v_pk_add_f32 v[52:53], v[54:55], v[52:53]
	s_nop 0
	v_add_f32_e32 v36, 0, v52
	v_add_f32_e32 v52, v36, v53
	v_mov_b32_e32 v53, v52
	s_nop 1
	v_permlane16_swap_b32_e32 v53, v52
	v_mov_b32_e32 v36, v45
	v_mov_b32_e32 v45, v38
	v_mov_b32_e32 v38, v47
	v_ashrrev_i32_e32 v47, 31, v46
	s_waitcnt lgkmcnt(0)
	v_add_f32_e32 v54, v52, v53
	v_mov_b32_e32 v55, v54
	s_nop 1
	v_permlane32_swap_b32_e32 v55, v54
	v_mad_i64_i32 v[52:53], s[10:11], v62, s72, v[60:61]
	v_lshl_add_u64 v[52:53], v[52:53], 0, v[2:3]
	s_waitcnt lgkmcnt(0)
	v_add_f32_e32 v54, v54, v55
	v_fmamk_f32 v54, v54, 0x3a000000, v226
	v_mul_f32_e32 v55, 0x4b800000, v54
	v_cmp_gt_f32_e32 vcc, s71, v54
	s_nop 1
	v_cndmask_b32_e32 v54, v54, v55, vcc
	v_rsq_f32_e32 v56, v54
	v_lshlrev_b64 v[54:55], 7, v[46:47]
	v_lshl_add_u64 v[54:55], v[204:205], 0, v[54:55]
	v_mul_f32_e32 v47, 0x45800000, v56
	v_cndmask_b32_e32 v56, v56, v47, vcc
	v_pk_mul_f32 v[38:39], v[38:39], v[56:57] op_sel_hi:[1,0]
	v_pk_mul_f32 v[58:59], v[64:65], v[56:57] op_sel_hi:[1,0]
	v_pk_mul_f32 v[40:41], v[40:41], v[56:57] op_sel_hi:[1,0]
	v_pk_mul_f32 v[48:49], v[48:49], v[56:57] op_sel_hi:[1,0]
	v_pk_mul_f32 v[42:43], v[42:43], v[56:57] op_sel_hi:[1,0]
	v_pk_mul_f32 v[50:51], v[50:51], v[56:57] op_sel_hi:[1,0]
	v_pk_mul_f32 v[36:37], v[36:37], v[56:57] op_sel_hi:[1,0]
	v_pk_mul_f32 v[44:45], v[44:45], v[56:57] op_sel_hi:[1,0]
	v_mul_f32_e32 v66, 0xbfb8aa3b, v39
	v_mul_f32_e32 v47, 0xbfb8aa3b, v59
	v_mul_f32_e32 v56, 0xbfb8aa3b, v41
	v_mul_f32_e32 v57, 0xbfb8aa3b, v49
	v_mul_f32_e32 v62, 0xbfb8aa3b, v43
	v_mul_f32_e32 v63, 0xbfb8aa3b, v51
	v_mul_f32_e32 v64, 0xbfb8aa3b, v37
	v_mul_f32_e32 v65, 0xbfb8aa3b, v45
	v_exp_f32_e32 v66, v66
	v_exp_f32_e32 v47, v47
	v_exp_f32_e32 v56, v56
	v_exp_f32_e32 v57, v57
	v_exp_f32_e32 v62, v62
	v_exp_f32_e32 v63, v63
	v_exp_f32_e32 v64, v64
	v_exp_f32_e32 v65, v65
	v_add_f32_e32 v66, 1.0, v66
	v_add_f32_e32 v47, 1.0, v47
	v_add_f32_e32 v56, 1.0, v56
	v_add_f32_e32 v57, 1.0, v57
	v_add_f32_e32 v62, 1.0, v62
	v_add_f32_e32 v63, 1.0, v63
	v_add_f32_e32 v64, 1.0, v64
	v_add_f32_e32 v65, 1.0, v65
	v_rcp_f32_e32 v66, v66
	v_rcp_f32_e32 v47, v47
	v_rcp_f32_e32 v56, v56
	v_rcp_f32_e32 v57, v57
	v_rcp_f32_e32 v62, v62
	v_rcp_f32_e32 v63, v63
	v_rcp_f32_e32 v64, v64
	v_rcp_f32_e32 v65, v65
	v_mul_f32_e32 v39, v39, v66
	v_mul_f32_e32 v47, v59, v47
	v_mul_f32_e32 v41, v41, v56
	v_mul_f32_e32 v49, v49, v57
	v_mul_f32_e32 v43, v43, v62
	v_mul_f32_e32 v51, v51, v63
	v_mul_f32_e32 v37, v37, v64
	v_mul_f32_e32 v45, v45, v65
	v_mul_f32_e32 v39, v38, v39
	v_mul_f32_e32 v47, v58, v47
	v_mul_f32_e32 v40, v40, v41
	v_mul_f32_e32 v41, v48, v49
	v_mul_f32_e32 v42, v42, v43
	v_mul_f32_e32 v43, v50, v51
	v_mul_f32_e32 v48, v36, v37
	v_mul_f32_e32 v44, v44, v45
	v_cvt_pk_bf16_f32 v36, v47, v40
	v_cvt_pk_bf16_f32 v37, v41, v42
	v_cvt_pk_bf16_f32 v38, v43, v48
	v_cvt_pk_bf16_f32 v39, v44, v39
	global_store_dwordx4 v[52:53], v[36:39], off
	global_load_dwordx4 v[36:39], v[54:55], off
	global_load_dwordx4 v[40:43], v[54:55], off offset:16
	v_mov_b32_e32 v45, v24
	v_mov_b32_e32 v24, v33
	v_mov_b32_e32 v33, v26
	v_mov_b32_e32 v26, v35
	v_mov_b32_e32 v35, v20
	v_mov_b32_e32 v44, v32
	v_mov_b32_e32 v32, v34
	v_mov_b32_e32 v34, v28
	v_mov_b32_e32 v28, v30
	v_add_u32_e32 v30, 0xb0, v132
	s_waitcnt vmcnt(1)
	v_mov_b32_e32 v48, v36
	s_waitcnt vmcnt(0)
	v_mov_b32_e32 v49, v40
	v_mov_b32_e32 v40, v37
	v_mov_b32_e32 v36, v38
	v_mov_b32_e32 v37, v42
	v_mov_b32_e32 v42, v39
	v_pk_add_f32 v[38:39], v[48:49], v[40:41]
	v_pk_add_f32 v[36:37], v[36:37], v[42:43]
	s_nop 0
	v_pk_add_f32 v[36:37], v[38:39], v[36:37]
	s_nop 0
	v_add_f32_e32 v20, 0, v36
	v_add_f32_e32 v36, v20, v37
	v_mov_b32_e32 v37, v36
	s_nop 1
	v_permlane16_swap_b32_e32 v37, v36
	v_mov_b32_e32 v20, v29
	v_mov_b32_e32 v29, v22
	v_mov_b32_e32 v22, v31
	v_ashrrev_i32_e32 v31, 31, v30
	s_waitcnt lgkmcnt(0)
	v_add_f32_e32 v38, v36, v37
	v_mov_b32_e32 v39, v38
	s_nop 1
	v_permlane32_swap_b32_e32 v39, v38
	v_mad_i64_i32 v[36:37], s[10:11], v46, s72, v[60:61]
	v_lshl_add_u64 v[36:37], v[36:37], 0, v[2:3]
	s_waitcnt lgkmcnt(0)
	v_add_f32_e32 v38, v38, v39
	v_fmamk_f32 v38, v38, 0x3a000000, v226
	v_mul_f32_e32 v39, 0x4b800000, v38
	v_cmp_gt_f32_e32 vcc, s71, v38
	s_nop 1
	v_cndmask_b32_e32 v38, v38, v39, vcc
	v_rsq_f32_e32 v40, v38
	v_lshlrev_b64 v[38:39], 7, v[30:31]
	v_lshl_add_u64 v[38:39], v[204:205], 0, v[38:39]
	v_mul_f32_e32 v31, 0x45800000, v40
	v_cndmask_b32_e32 v40, v40, v31, vcc
	v_pk_mul_f32 v[22:23], v[22:23], v[40:41] op_sel_hi:[1,0]
	v_pk_mul_f32 v[42:43], v[44:45], v[40:41] op_sel_hi:[1,0]
	v_pk_mul_f32 v[24:25], v[24:25], v[40:41] op_sel_hi:[1,0]
	v_pk_mul_f32 v[32:33], v[32:33], v[40:41] op_sel_hi:[1,0]
	v_pk_mul_f32 v[26:27], v[26:27], v[40:41] op_sel_hi:[1,0]
	v_pk_mul_f32 v[34:35], v[34:35], v[40:41] op_sel_hi:[1,0]
	v_pk_mul_f32 v[20:21], v[20:21], v[40:41] op_sel_hi:[1,0]
	v_pk_mul_f32 v[28:29], v[28:29], v[40:41] op_sel_hi:[1,0]
	v_mul_f32_e32 v48, 0xbfb8aa3b, v23
	v_mul_f32_e32 v31, 0xbfb8aa3b, v43
	v_mul_f32_e32 v40, 0xbfb8aa3b, v25
	v_mul_f32_e32 v41, 0xbfb8aa3b, v33
	v_mul_f32_e32 v44, 0xbfb8aa3b, v27
	v_mul_f32_e32 v45, 0xbfb8aa3b, v35
	v_mul_f32_e32 v46, 0xbfb8aa3b, v21
	v_mul_f32_e32 v47, 0xbfb8aa3b, v29
	v_exp_f32_e32 v48, v48
	v_exp_f32_e32 v31, v31
	v_exp_f32_e32 v40, v40
	v_exp_f32_e32 v41, v41
	v_exp_f32_e32 v44, v44
	v_exp_f32_e32 v45, v45
	v_exp_f32_e32 v46, v46
	v_exp_f32_e32 v47, v47
	v_add_f32_e32 v48, 1.0, v48
	v_add_f32_e32 v31, 1.0, v31
	v_add_f32_e32 v40, 1.0, v40
	v_add_f32_e32 v41, 1.0, v41
	v_add_f32_e32 v44, 1.0, v44
	v_add_f32_e32 v45, 1.0, v45
	v_add_f32_e32 v46, 1.0, v46
	v_add_f32_e32 v47, 1.0, v47
	v_rcp_f32_e32 v48, v48
	v_rcp_f32_e32 v31, v31
	v_rcp_f32_e32 v40, v40
	v_rcp_f32_e32 v41, v41
	v_rcp_f32_e32 v44, v44
	v_rcp_f32_e32 v45, v45
	v_rcp_f32_e32 v46, v46
	v_rcp_f32_e32 v47, v47
	v_mul_f32_e32 v23, v23, v48
	v_mul_f32_e32 v31, v43, v31
	v_mul_f32_e32 v25, v25, v40
	v_mul_f32_e32 v33, v33, v41
	v_mul_f32_e32 v27, v27, v44
	v_mul_f32_e32 v35, v35, v45
	v_mul_f32_e32 v21, v21, v46
	v_mul_f32_e32 v29, v29, v47
	v_mul_f32_e32 v23, v22, v23
	v_mul_f32_e32 v31, v42, v31
	v_mul_f32_e32 v24, v24, v25
	v_mul_f32_e32 v25, v32, v33
	v_mul_f32_e32 v26, v26, v27
	v_mul_f32_e32 v27, v34, v35
	v_mul_f32_e32 v32, v20, v21
	v_mul_f32_e32 v28, v28, v29
	v_cvt_pk_bf16_f32 v20, v31, v24
	v_cvt_pk_bf16_f32 v21, v25, v26
	v_cvt_pk_bf16_f32 v22, v27, v32
	v_cvt_pk_bf16_f32 v23, v28, v23
	global_store_dwordx4 v[36:37], v[20:23], off
	global_load_dwordx4 v[20:23], v[38:39], off
	global_load_dwordx4 v[24:27], v[38:39], off offset:16
	v_mov_b32_e32 v28, v16
	v_mov_b32_e32 v29, v8
	v_mov_b32_e32 v8, v17
	s_waitcnt vmcnt(1)
	v_mov_b32_e32 v16, v20
	s_waitcnt vmcnt(0)
	v_mov_b32_e32 v17, v24
	v_mov_b32_e32 v24, v21
	v_mov_b32_e32 v20, v22
	v_mov_b32_e32 v21, v26
	v_mov_b32_e32 v26, v23
	v_pk_add_f32 v[16:17], v[16:17], v[24:25]
	v_pk_add_f32 v[20:21], v[20:21], v[26:27]
	s_nop 0
	v_pk_add_f32 v[16:17], v[16:17], v[20:21]
	s_nop 0
	v_add_f32_e32 v16, 0, v16
	v_add_f32_e32 v20, v16, v17
	v_mov_b32_e32 v21, v20
	s_nop 1
	v_permlane16_swap_b32_e32 v21, v20
	v_mov_b32_e32 v17, v10
	v_mov_b32_e32 v10, v19
	v_mov_b32_e32 v19, v4
	v_mov_b32_e32 v4, v13
	s_waitcnt lgkmcnt(0)
	v_add_f32_e32 v20, v20, v21
	v_mov_b32_e32 v1, v20
	s_nop 1
	v_permlane32_swap_b32_e32 v1, v20
	v_mov_b32_e32 v13, v6
	v_mov_b32_e32 v16, v18
	v_mov_b32_e32 v18, v12
	v_mov_b32_e32 v12, v14
	s_waitcnt lgkmcnt(0)
	v_add_f32_e32 v1, v20, v1
	v_fmamk_f32 v1, v1, 0x3a000000, v226
	v_mul_f32_e32 v6, 0x4b800000, v1
	v_cmp_gt_f32_e32 vcc, s71, v1
	s_nop 1
	v_cndmask_b32_e32 v1, v1, v6, vcc
	v_rsq_f32_e32 v1, v1
	v_mov_b32_e32 v6, v15
	v_mad_i64_i32 v[14:15], s[10:11], v30, s72, v[60:61]
	v_mul_f32_e32 v20, 0x45800000, v1
	v_cndmask_b32_e32 v20, v1, v20, vcc
	v_pk_mul_f32 v[6:7], v[6:7], v[20:21] op_sel_hi:[1,0]
	v_pk_mul_f32 v[22:23], v[28:29], v[20:21] op_sel_hi:[1,0]
	v_pk_mul_f32 v[8:9], v[8:9], v[20:21] op_sel_hi:[1,0]
	v_pk_mul_f32 v[16:17], v[16:17], v[20:21] op_sel_hi:[1,0]
	v_pk_mul_f32 v[10:11], v[10:11], v[20:21] op_sel_hi:[1,0]
	v_pk_mul_f32 v[18:19], v[18:19], v[20:21] op_sel_hi:[1,0]
	v_pk_mul_f32 v[4:5], v[4:5], v[20:21] op_sel_hi:[1,0]
	v_pk_mul_f32 v[12:13], v[12:13], v[20:21] op_sel_hi:[1,0]
	v_mul_f32_e32 v28, 0xbfb8aa3b, v7
	v_mul_f32_e32 v1, 0xbfb8aa3b, v23
	v_mul_f32_e32 v20, 0xbfb8aa3b, v9
	v_mul_f32_e32 v21, 0xbfb8aa3b, v17
	v_mul_f32_e32 v24, 0xbfb8aa3b, v11
	v_mul_f32_e32 v25, 0xbfb8aa3b, v19
	v_mul_f32_e32 v26, 0xbfb8aa3b, v5
	v_mul_f32_e32 v27, 0xbfb8aa3b, v13
	v_exp_f32_e32 v28, v28
	v_exp_f32_e32 v1, v1
	v_exp_f32_e32 v20, v20
	v_exp_f32_e32 v21, v21
	v_exp_f32_e32 v24, v24
	v_exp_f32_e32 v25, v25
	v_exp_f32_e32 v26, v26
	v_exp_f32_e32 v27, v27
	v_add_f32_e32 v28, 1.0, v28
	v_add_f32_e32 v1, 1.0, v1
	v_add_f32_e32 v20, 1.0, v20
	v_add_f32_e32 v21, 1.0, v21
	v_add_f32_e32 v24, 1.0, v24
	v_add_f32_e32 v25, 1.0, v25
	v_add_f32_e32 v26, 1.0, v26
	v_add_f32_e32 v27, 1.0, v27
	v_rcp_f32_e32 v28, v28
	v_rcp_f32_e32 v1, v1
	v_rcp_f32_e32 v20, v20
	v_rcp_f32_e32 v21, v21
	v_rcp_f32_e32 v24, v24
	v_rcp_f32_e32 v25, v25
	v_rcp_f32_e32 v26, v26
	v_rcp_f32_e32 v27, v27
	v_mul_f32_e32 v7, v7, v28
	v_mul_f32_e32 v1, v23, v1
	v_mul_f32_e32 v9, v9, v20
	v_mul_f32_e32 v17, v17, v21
	v_mul_f32_e32 v11, v11, v24
	v_mul_f32_e32 v19, v19, v25
	v_mul_f32_e32 v5, v5, v26
	v_mul_f32_e32 v13, v13, v27
	v_mul_f32_e32 v7, v6, v7
	v_lshl_add_u64 v[2:3], v[14:15], 0, v[2:3]
	v_mul_f32_e32 v1, v22, v1
	v_mul_f32_e32 v8, v8, v9
	v_mul_f32_e32 v9, v16, v17
	v_mul_f32_e32 v10, v10, v11
	v_mul_f32_e32 v11, v18, v19
	v_mul_f32_e32 v16, v4, v5
	v_mul_f32_e32 v12, v12, v13
	v_cvt_pk_bf16_f32 v4, v1, v8
	v_cvt_pk_bf16_f32 v5, v9, v10
	v_cvt_pk_bf16_f32 v6, v11, v16
	v_cvt_pk_bf16_f32 v7, v12, v7
	global_store_dwordx4 v[2:3], v[4:7], off
	s_andn2_b64 vcc, exec, s[26:27]
	s_mov_b64 s[10:11], -1
	s_cbranch_vccnz .LBB0_422

.LBB0_526:
	v_lshl_add_u32 v146, s51, 8, v148
	v_lshl_or_b32 v144, s16, 8, v150
	v_ashrrev_i32_e32 v147, 31, v146
	v_ashrrev_i32_e32 v145, 31, v144
	v_lshlrev_b64 v[156:157], 11, v[146:147]
	v_lshl_add_u64 v[156:157], v[156:157], 0, v[144:145]
	v_lshlrev_b64 v[160:161], 1, v[156:157]
	v_lshl_add_u64 v[156:157], s[22:23], 0, v[160:161]
	global_load_dwordx4 v[156:159], v[156:157], off
	v_lshl_add_u64 v[162:163], s[20:21], 0, v[160:161]
	v_or_b32_e32 v160, 0x100, v160
	v_lshl_add_u64 v[164:165], s[22:23], 0, v[160:161]
	v_xor_b32_e32 v155, 32, v154
	s_lshl_b32 s34, s16, 2
	s_ashr_i32 s35, s34, 31
	s_waitcnt vmcnt(0)
	v_lshlrev_b32_e32 v166, 16, v156
	v_and_b32_e32 v167, 0xffff0000, v156
	v_lshlrev_b32_e32 v156, 16, v157
	v_and_b32_e32 v157, 0xffff0000, v157
	v_lshlrev_b32_e32 v168, 16, v158
	v_and_b32_e32 v169, 0xffff0000, v158
	v_lshlrev_b32_e32 v158, 16, v159
	v_and_b32_e32 v159, 0xffff0000, v159
	v_pk_add_f32 v[126:127], v[126:127], v[156:157]
	v_pk_add_f32 v[166:167], v[124:125], v[166:167]
	v_pk_add_f32 v[170:171], v[122:123], v[158:159]
	v_pk_add_f32 v[168:169], v[120:121], v[168:169]
	v_cvt_pk_bf16_f32 v122, v166, v167
	v_cvt_pk_bf16_f32 v123, v126, v127
	v_mul_f32_e32 v127, v127, v127
	v_cvt_pk_bf16_f32 v124, v168, v169
	v_cvt_pk_bf16_f32 v125, v170, v171
	global_load_dwordx4 v[156:159], v[164:165], off
	v_mul_f32_e32 v164, v167, v167
	v_mul_f32_e32 v165, v169, v169
	v_mul_f32_e32 v167, v171, v171
	v_fmac_f32_e32 v164, v166, v166
	v_fmac_f32_e32 v127, v126, v126
	v_fmac_f32_e32 v165, v168, v168
	v_fmac_f32_e32 v167, v170, v170
	v_add_f32_e32 v126, v164, v127
	v_add_f32_e32 v127, v165, v167
	v_add_f32_e32 v166, v126, v127
	v_and_b32_e32 v121, 64, v154
	v_xor_b32_e32 v120, 16, v154
	v_add_u32_e32 v121, 64, v121
	v_cmp_lt_i32_e32 vcc, v120, v121
	global_store_dwordx4 v[162:163], v[122:125], off
	s_waitcnt vmcnt(1)
	v_lshlrev_b32_e32 v126, 16, v156
	v_and_b32_e32 v127, 0xffff0000, v156
	v_lshlrev_b32_e32 v156, 16, v157
	v_and_b32_e32 v157, 0xffff0000, v157
	v_lshlrev_b32_e32 v164, 16, v158
	v_and_b32_e32 v165, 0xffff0000, v158
	v_lshlrev_b32_e32 v158, 16, v159
	v_and_b32_e32 v159, 0xffff0000, v159
	v_pk_add_f32 v[118:119], v[118:119], v[156:157]
	v_pk_add_f32 v[116:117], v[116:117], v[126:127]
	v_pk_add_f32 v[126:127], v[114:115], v[158:159]
	v_pk_add_f32 v[156:157], v[112:113], v[164:165]
	v_mul_f32_e32 v112, v117, v117
	v_mul_f32_e32 v113, v119, v119
	v_mul_f32_e32 v114, v157, v157
	v_mul_f32_e32 v115, v127, v127
	v_fmac_f32_e32 v112, v116, v116
	v_fmac_f32_e32 v113, v118, v118
	v_fmac_f32_e32 v114, v156, v156
	v_fmac_f32_e32 v115, v126, v126
	v_add_f32_e32 v112, v112, v113
	v_add_f32_e32 v113, v114, v115
	v_cndmask_b32_e32 v120, v154, v120, vcc
	v_add_f32_e32 v112, v112, v113
	v_lshlrev_b32_e32 v120, 2, v120
	v_add_f32_e32 v112, v166, v112
	v_mov_b32_e32 v113, v112
	s_nop 1
	v_permlane16_swap_b32_e32 v113, v112
	v_cmp_lt_i32_e32 vcc, v155, v121
	v_lshl_add_u64 v[122:123], s[20:21], 0, v[160:161]
	v_cvt_pk_bf16_f32 v116, v116, v117
	v_cvt_pk_bf16_f32 v117, v118, v119
	s_waitcnt lgkmcnt(0)
	v_add_f32_e32 v112, v112, v113
	v_cndmask_b32_e32 v114, v154, v155, vcc
	v_lshlrev_b32_e32 v114, 2, v114
	v_mov_b32_e32 v113, v112
	s_nop 1
	v_permlane32_swap_b32_e32 v113, v112
	v_cvt_pk_bf16_f32 v118, v156, v157
	v_cvt_pk_bf16_f32 v119, v126, v127
	global_store_dwordx4 v[122:123], v[116:119], off
	s_and_saveexec_b64 s[36:37], s[8:9]
	s_cbranch_execz .LBB0_528
	s_waitcnt lgkmcnt(0)
	v_add_f32_e32 v115, v112, v113
	v_lshlrev_b64 v[112:113], 7, v[146:147]
	v_lshl_add_u64 v[112:113], s[14:15], 0, v[112:113]
	v_lshl_add_u64 v[112:113], s[34:35], 2, v[112:113]
	s_lshl_b32 s16, s59, 2
	v_lshl_add_u64 v[112:113], v[112:113], 0, s[16:17]
	global_store_dword v[112:113], v115, off
.LBB0_528:
	s_or_b64 exec, exec, s[36:37]
	v_or_b32_e32 v112, 16, v146
	s_waitcnt lgkmcnt(0)
	v_ashrrev_i32_e32 v113, 31, v112
	v_lshlrev_b64 v[116:117], 11, v[112:113]
	v_lshl_add_u64 v[116:117], v[116:117], 0, v[144:145]
	v_lshlrev_b64 v[122:123], 1, v[116:117]
	v_lshl_add_u64 v[116:117], s[22:23], 0, v[122:123]
	global_load_dwordx4 v[116:119], v[116:117], off
	v_lshl_add_u64 v[124:125], s[20:21], 0, v[122:123]
	v_or_b32_e32 v122, 0x100, v122
	v_lshl_add_u64 v[126:127], s[22:23], 0, v[122:123]
	s_waitcnt vmcnt(0)
	v_lshlrev_b32_e32 v156, 16, v116
	v_and_b32_e32 v157, 0xffff0000, v116
	v_lshlrev_b32_e32 v116, 16, v117
	v_and_b32_e32 v117, 0xffff0000, v117
	v_lshlrev_b32_e32 v158, 16, v118
	v_and_b32_e32 v159, 0xffff0000, v118
	v_lshlrev_b32_e32 v118, 16, v119
	v_and_b32_e32 v119, 0xffff0000, v119
	v_pk_add_f32 v[116:117], v[110:111], v[116:117]
	v_pk_add_f32 v[156:157], v[108:109], v[156:157]
	v_pk_add_f32 v[118:119], v[106:107], v[118:119]
	v_pk_add_f32 v[158:159], v[104:105], v[158:159]
	v_cvt_pk_bf16_f32 v104, v156, v157
	v_cvt_pk_bf16_f32 v105, v116, v117
	v_mul_f32_e32 v115, v157, v157
	v_cvt_pk_bf16_f32 v106, v158, v159
	v_cvt_pk_bf16_f32 v107, v118, v119
	global_load_dwordx4 v[108:111], v[126:127], off
	v_mul_f32_e32 v117, v117, v117
	v_mul_f32_e32 v121, v159, v159
	v_mul_f32_e32 v119, v119, v119
	v_fmac_f32_e32 v115, v156, v156
	v_fmac_f32_e32 v117, v116, v116
	v_fmac_f32_e32 v121, v158, v158
	v_fmac_f32_e32 v119, v118, v118
	v_add_f32_e32 v115, v115, v117
	v_add_f32_e32 v116, v121, v119
	v_add_f32_e32 v115, v115, v116
	global_store_dwordx4 v[124:125], v[104:107], off
	s_waitcnt vmcnt(1)
	v_lshlrev_b32_e32 v116, 16, v108
	v_and_b32_e32 v117, 0xffff0000, v108
	v_lshlrev_b32_e32 v108, 16, v109
	v_and_b32_e32 v109, 0xffff0000, v109
	v_lshlrev_b32_e32 v118, 16, v110
	v_and_b32_e32 v119, 0xffff0000, v110
	v_lshlrev_b32_e32 v110, 16, v111
	v_and_b32_e32 v111, 0xffff0000, v111
	v_pk_add_f32 v[102:103], v[102:103], v[108:109]
	v_pk_add_f32 v[100:101], v[100:101], v[116:117]
	v_pk_add_f32 v[108:109], v[98:99], v[110:111]
	v_pk_add_f32 v[110:111], v[96:97], v[118:119]
	v_mul_f32_e32 v96, v101, v101
	v_mul_f32_e32 v97, v103, v103
	v_mul_f32_e32 v98, v111, v111
	v_mul_f32_e32 v99, v109, v109
	v_fmac_f32_e32 v96, v100, v100
	v_fmac_f32_e32 v97, v102, v102
	v_fmac_f32_e32 v98, v110, v110
	v_fmac_f32_e32 v99, v108, v108
	v_add_f32_e32 v96, v96, v97
	v_add_f32_e32 v97, v98, v99
	v_add_f32_e32 v96, v96, v97
	v_add_f32_e32 v96, v115, v96
	v_mov_b32_e32 v97, v96
	s_nop 1
	v_permlane16_swap_b32_e32 v97, v96
	v_cvt_pk_bf16_f32 v98, v100, v101
	v_cvt_pk_bf16_f32 v99, v102, v103
	v_lshl_add_u64 v[102:103], s[20:21], 0, v[122:123]
	v_cvt_pk_bf16_f32 v100, v110, v111
	s_waitcnt lgkmcnt(0)
	v_add_f32_e32 v96, v96, v97
	v_mov_b32_e32 v97, v96
	s_nop 1
	v_permlane32_swap_b32_e32 v97, v96
	v_cvt_pk_bf16_f32 v101, v108, v109
	global_store_dwordx4 v[102:103], v[98:101], off
	s_and_saveexec_b64 s[36:37], s[8:9]
	s_cbranch_execz .LBB0_530
	s_waitcnt lgkmcnt(0)
	v_add_f32_e32 v98, v96, v97
	v_lshlrev_b64 v[96:97], 7, v[112:113]
	v_lshl_add_u64 v[96:97], s[14:15], 0, v[96:97]
	v_lshl_add_u64 v[96:97], s[34:35], 2, v[96:97]
	s_lshl_b32 s16, s59, 2
	v_lshl_add_u64 v[96:97], v[96:97], 0, s[16:17]
	global_store_dword v[96:97], v98, off
.LBB0_530:
	s_or_b64 exec, exec, s[36:37]
	v_or_b32_e32 v96, 32, v146
	s_waitcnt lgkmcnt(0)
	v_ashrrev_i32_e32 v97, 31, v96
	v_lshlrev_b64 v[98:99], 11, v[96:97]
	v_lshl_add_u64 v[98:99], v[98:99], 0, v[144:145]
	v_lshlrev_b64 v[102:103], 1, v[98:99]
	v_lshl_add_u64 v[98:99], s[22:23], 0, v[102:103]
	global_load_dwordx4 v[98:101], v[98:99], off
	v_lshl_add_u64 v[104:105], s[20:21], 0, v[102:103]
	v_or_b32_e32 v102, 0x100, v102
	v_lshl_add_u64 v[106:107], s[22:23], 0, v[102:103]
	s_waitcnt vmcnt(0)
	v_lshlrev_b32_e32 v108, 16, v98
	v_and_b32_e32 v109, 0xffff0000, v98
	v_lshlrev_b32_e32 v98, 16, v99
	v_and_b32_e32 v99, 0xffff0000, v99
	v_lshlrev_b32_e32 v110, 16, v100
	v_and_b32_e32 v111, 0xffff0000, v100
	v_lshlrev_b32_e32 v100, 16, v101
	v_and_b32_e32 v101, 0xffff0000, v101
	v_pk_add_f32 v[98:99], v[94:95], v[98:99]
	v_pk_add_f32 v[108:109], v[92:93], v[108:109]
	v_pk_add_f32 v[100:101], v[90:91], v[100:101]
	v_pk_add_f32 v[110:111], v[88:89], v[110:111]
	v_cvt_pk_bf16_f32 v88, v108, v109
	v_cvt_pk_bf16_f32 v89, v98, v99
	v_mul_f32_e32 v99, v99, v99
	v_cvt_pk_bf16_f32 v90, v110, v111
	v_cvt_pk_bf16_f32 v91, v100, v101
	global_load_dwordx4 v[92:95], v[106:107], off
	v_mul_f32_e32 v106, v109, v109
	v_mul_f32_e32 v107, v111, v111
	v_mul_f32_e32 v101, v101, v101
	v_fmac_f32_e32 v106, v108, v108
	v_fmac_f32_e32 v99, v98, v98
	v_fmac_f32_e32 v107, v110, v110
	v_fmac_f32_e32 v101, v100, v100
	v_add_f32_e32 v98, v106, v99
	v_add_f32_e32 v99, v107, v101
	v_add_f32_e32 v106, v98, v99
	global_store_dwordx4 v[104:105], v[88:91], off
	s_waitcnt vmcnt(1)
	v_lshlrev_b32_e32 v98, 16, v92
	v_and_b32_e32 v99, 0xffff0000, v92
	v_lshlrev_b32_e32 v92, 16, v93
	v_and_b32_e32 v93, 0xffff0000, v93
	v_lshlrev_b32_e32 v100, 16, v94
	v_and_b32_e32 v101, 0xffff0000, v94
	v_lshlrev_b32_e32 v94, 16, v95
	v_and_b32_e32 v95, 0xffff0000, v95
	v_pk_add_f32 v[86:87], v[86:87], v[92:93]
	v_pk_add_f32 v[84:85], v[84:85], v[98:99]
	v_pk_add_f32 v[92:93], v[82:83], v[94:95]
	v_pk_add_f32 v[94:95], v[80:81], v[100:101]
	v_mul_f32_e32 v80, v85, v85
	v_mul_f32_e32 v81, v87, v87
	v_mul_f32_e32 v82, v95, v95
	v_mul_f32_e32 v83, v93, v93
	v_fmac_f32_e32 v80, v84, v84
	v_fmac_f32_e32 v81, v86, v86
	v_fmac_f32_e32 v82, v94, v94
	v_fmac_f32_e32 v83, v92, v92
	v_add_f32_e32 v80, v80, v81
	v_add_f32_e32 v81, v82, v83
	v_add_f32_e32 v80, v80, v81
	v_add_f32_e32 v80, v106, v80
	v_mov_b32_e32 v81, v80
	s_nop 1
	v_permlane16_swap_b32_e32 v81, v80
	v_cvt_pk_bf16_f32 v82, v84, v85
	v_cvt_pk_bf16_f32 v83, v86, v87
	v_lshl_add_u64 v[86:87], s[20:21], 0, v[102:103]
	v_cvt_pk_bf16_f32 v84, v94, v95
	s_waitcnt lgkmcnt(0)
	v_add_f32_e32 v80, v80, v81
	v_mov_b32_e32 v81, v80
	s_nop 1
	v_permlane32_swap_b32_e32 v81, v80
	v_cvt_pk_bf16_f32 v85, v92, v93
	global_store_dwordx4 v[86:87], v[82:85], off
	s_and_saveexec_b64 s[36:37], s[8:9]
	s_cbranch_execz .LBB0_532
	s_waitcnt lgkmcnt(0)
	v_add_f32_e32 v82, v80, v81
	v_lshlrev_b64 v[80:81], 7, v[96:97]
	v_lshl_add_u64 v[80:81], s[14:15], 0, v[80:81]
	v_lshl_add_u64 v[80:81], s[34:35], 2, v[80:81]
	s_lshl_b32 s16, s59, 2
	v_lshl_add_u64 v[80:81], v[80:81], 0, s[16:17]
	global_store_dword v[80:81], v82, off
.LBB0_532:
	s_or_b64 exec, exec, s[36:37]
	v_or_b32_e32 v80, 48, v146
	s_waitcnt lgkmcnt(0)
	v_ashrrev_i32_e32 v81, 31, v80
	v_lshlrev_b64 v[82:83], 11, v[80:81]
	v_lshl_add_u64 v[82:83], v[82:83], 0, v[144:145]
	v_lshlrev_b64 v[86:87], 1, v[82:83]
	v_lshl_add_u64 v[82:83], s[22:23], 0, v[86:87]
	global_load_dwordx4 v[82:85], v[82:83], off
	v_lshl_add_u64 v[88:89], s[20:21], 0, v[86:87]
	v_or_b32_e32 v86, 0x100, v86
	v_lshl_add_u64 v[90:91], s[22:23], 0, v[86:87]
	s_waitcnt vmcnt(0)
	v_lshlrev_b32_e32 v92, 16, v82
	v_and_b32_e32 v93, 0xffff0000, v82
	v_lshlrev_b32_e32 v82, 16, v83
	v_and_b32_e32 v83, 0xffff0000, v83
	v_lshlrev_b32_e32 v94, 16, v84
	v_and_b32_e32 v95, 0xffff0000, v84
	v_lshlrev_b32_e32 v84, 16, v85
	v_and_b32_e32 v85, 0xffff0000, v85
	v_pk_add_f32 v[82:83], v[78:79], v[82:83]
	v_pk_add_f32 v[92:93], v[76:77], v[92:93]
	v_pk_add_f32 v[84:85], v[74:75], v[84:85]
	v_pk_add_f32 v[94:95], v[72:73], v[94:95]
	v_cvt_pk_bf16_f32 v72, v92, v93
	v_cvt_pk_bf16_f32 v73, v82, v83
	v_mul_f32_e32 v83, v83, v83
	v_cvt_pk_bf16_f32 v74, v94, v95
	v_cvt_pk_bf16_f32 v75, v84, v85
	global_load_dwordx4 v[76:79], v[90:91], off
	v_mul_f32_e32 v90, v93, v93
	v_mul_f32_e32 v91, v95, v95
	v_mul_f32_e32 v85, v85, v85
	v_fmac_f32_e32 v90, v92, v92
	v_fmac_f32_e32 v83, v82, v82
	v_fmac_f32_e32 v91, v94, v94
	v_fmac_f32_e32 v85, v84, v84
	v_add_f32_e32 v82, v90, v83
	v_add_f32_e32 v83, v91, v85
	v_add_f32_e32 v90, v82, v83
	global_store_dwordx4 v[88:89], v[72:75], off
	s_waitcnt vmcnt(1)
	v_lshlrev_b32_e32 v82, 16, v76
	v_and_b32_e32 v83, 0xffff0000, v76
	v_lshlrev_b32_e32 v76, 16, v77
	v_and_b32_e32 v77, 0xffff0000, v77
	v_lshlrev_b32_e32 v84, 16, v78
	v_and_b32_e32 v85, 0xffff0000, v78
	v_lshlrev_b32_e32 v78, 16, v79
	v_and_b32_e32 v79, 0xffff0000, v79
	v_pk_add_f32 v[70:71], v[70:71], v[76:77]
	v_pk_add_f32 v[68:69], v[68:69], v[82:83]
	v_pk_add_f32 v[76:77], v[66:67], v[78:79]
	v_pk_add_f32 v[78:79], v[64:65], v[84:85]
	v_mul_f32_e32 v64, v69, v69
	v_mul_f32_e32 v65, v71, v71
	v_mul_f32_e32 v66, v79, v79
	v_mul_f32_e32 v67, v77, v77
	v_fmac_f32_e32 v64, v68, v68
	v_fmac_f32_e32 v65, v70, v70
	v_fmac_f32_e32 v66, v78, v78
	v_fmac_f32_e32 v67, v76, v76
	v_add_f32_e32 v64, v64, v65
	v_add_f32_e32 v65, v66, v67
	v_add_f32_e32 v64, v64, v65
	v_add_f32_e32 v64, v90, v64
	v_mov_b32_e32 v65, v64
	s_nop 1
	v_permlane16_swap_b32_e32 v65, v64
	v_cvt_pk_bf16_f32 v66, v68, v69
	v_cvt_pk_bf16_f32 v67, v70, v71
	v_lshl_add_u64 v[70:71], s[20:21], 0, v[86:87]
	v_cvt_pk_bf16_f32 v68, v78, v79
	s_waitcnt lgkmcnt(0)
	v_add_f32_e32 v64, v64, v65
	v_mov_b32_e32 v65, v64
	s_nop 1
	v_permlane32_swap_b32_e32 v65, v64
	v_cvt_pk_bf16_f32 v69, v76, v77
	global_store_dwordx4 v[70:71], v[66:69], off
	s_and_saveexec_b64 s[36:37], s[8:9]
	s_cbranch_execz .LBB0_534
	s_waitcnt lgkmcnt(0)
	v_add_f32_e32 v66, v64, v65
	v_lshlrev_b64 v[64:65], 7, v[80:81]
	v_lshl_add_u64 v[64:65], s[14:15], 0, v[64:65]
	v_lshl_add_u64 v[64:65], s[34:35], 2, v[64:65]
	s_lshl_b32 s16, s59, 2
	v_lshl_add_u64 v[64:65], v[64:65], 0, s[16:17]
	global_store_dword v[64:65], v66, off
.LBB0_534:
	s_or_b64 exec, exec, s[36:37]
	v_add_u32_e32 v64, 0x80, v146
	s_waitcnt lgkmcnt(0)
	v_ashrrev_i32_e32 v65, 31, v64
	v_lshlrev_b64 v[66:67], 11, v[64:65]
	v_lshl_add_u64 v[66:67], v[66:67], 0, v[144:145]
	v_lshlrev_b64 v[70:71], 1, v[66:67]
	v_lshl_add_u64 v[66:67], s[22:23], 0, v[70:71]
	global_load_dwordx4 v[66:69], v[66:67], off
	v_lshl_add_u64 v[72:73], s[20:21], 0, v[70:71]
	v_or_b32_e32 v70, 0x100, v70
	v_lshl_add_u64 v[74:75], s[22:23], 0, v[70:71]
	s_waitcnt vmcnt(0)
	v_lshlrev_b32_e32 v76, 16, v66
	v_and_b32_e32 v77, 0xffff0000, v66
	v_lshlrev_b32_e32 v66, 16, v67
	v_and_b32_e32 v67, 0xffff0000, v67
	v_lshlrev_b32_e32 v78, 16, v68
	v_and_b32_e32 v79, 0xffff0000, v68
	v_lshlrev_b32_e32 v68, 16, v69
	v_and_b32_e32 v69, 0xffff0000, v69
	v_pk_add_f32 v[66:67], v[62:63], v[66:67]
	v_pk_add_f32 v[76:77], v[60:61], v[76:77]
	v_pk_add_f32 v[68:69], v[58:59], v[68:69]
	v_pk_add_f32 v[78:79], v[56:57], v[78:79]
	v_cvt_pk_bf16_f32 v56, v76, v77
	v_cvt_pk_bf16_f32 v57, v66, v67
	v_mul_f32_e32 v67, v67, v67
	v_cvt_pk_bf16_f32 v58, v78, v79
	v_cvt_pk_bf16_f32 v59, v68, v69
	global_load_dwordx4 v[60:63], v[74:75], off
	v_mul_f32_e32 v74, v77, v77
	v_mul_f32_e32 v75, v79, v79
	v_mul_f32_e32 v69, v69, v69
	v_fmac_f32_e32 v74, v76, v76
	v_fmac_f32_e32 v67, v66, v66
	v_fmac_f32_e32 v75, v78, v78
	v_fmac_f32_e32 v69, v68, v68
	v_add_f32_e32 v66, v74, v67
	v_add_f32_e32 v67, v75, v69
	v_add_f32_e32 v74, v66, v67
	global_store_dwordx4 v[72:73], v[56:59], off
	s_waitcnt vmcnt(1)
	v_lshlrev_b32_e32 v66, 16, v60
	v_and_b32_e32 v67, 0xffff0000, v60
	v_lshlrev_b32_e32 v60, 16, v61
	v_and_b32_e32 v61, 0xffff0000, v61
	v_lshlrev_b32_e32 v68, 16, v62
	v_and_b32_e32 v69, 0xffff0000, v62
	v_lshlrev_b32_e32 v62, 16, v63
	v_and_b32_e32 v63, 0xffff0000, v63
	v_pk_add_f32 v[54:55], v[54:55], v[60:61]
	v_pk_add_f32 v[52:53], v[52:53], v[66:67]
	v_pk_add_f32 v[60:61], v[50:51], v[62:63]
	v_pk_add_f32 v[62:63], v[48:49], v[68:69]
	v_mul_f32_e32 v48, v53, v53
	v_mul_f32_e32 v49, v55, v55
	v_mul_f32_e32 v50, v63, v63
	v_mul_f32_e32 v51, v61, v61
	v_fmac_f32_e32 v48, v52, v52
	v_fmac_f32_e32 v49, v54, v54
	v_fmac_f32_e32 v50, v62, v62
	v_fmac_f32_e32 v51, v60, v60
	v_add_f32_e32 v48, v48, v49
	v_add_f32_e32 v49, v50, v51
	v_add_f32_e32 v48, v48, v49
	v_add_f32_e32 v48, v74, v48
	v_mov_b32_e32 v49, v48
	s_nop 1
	v_permlane16_swap_b32_e32 v49, v48
	v_cvt_pk_bf16_f32 v50, v52, v53
	v_cvt_pk_bf16_f32 v51, v54, v55
	v_lshl_add_u64 v[54:55], s[20:21], 0, v[70:71]
	v_cvt_pk_bf16_f32 v52, v62, v63
	s_waitcnt lgkmcnt(0)
	v_add_f32_e32 v48, v48, v49
	v_mov_b32_e32 v49, v48
	s_nop 1
	v_permlane32_swap_b32_e32 v49, v48
	v_cvt_pk_bf16_f32 v53, v60, v61
	global_store_dwordx4 v[54:55], v[50:53], off
	s_and_saveexec_b64 s[36:37], s[8:9]
	s_cbranch_execz .LBB0_536
	s_waitcnt lgkmcnt(0)
	v_add_f32_e32 v50, v48, v49
	v_lshlrev_b64 v[48:49], 7, v[64:65]
	v_lshl_add_u64 v[48:49], s[14:15], 0, v[48:49]
	v_lshl_add_u64 v[48:49], s[34:35], 2, v[48:49]
	s_lshl_b32 s16, s59, 2
	v_lshl_add_u64 v[48:49], v[48:49], 0, s[16:17]
	global_store_dword v[48:49], v50, off
.LBB0_536:
	s_or_b64 exec, exec, s[36:37]
	v_add_u32_e32 v48, 0x90, v146
	s_waitcnt lgkmcnt(0)
	v_ashrrev_i32_e32 v49, 31, v48
	v_lshlrev_b64 v[50:51], 11, v[48:49]
	v_lshl_add_u64 v[50:51], v[50:51], 0, v[144:145]
	v_lshlrev_b64 v[54:55], 1, v[50:51]
	v_lshl_add_u64 v[50:51], s[22:23], 0, v[54:55]
	global_load_dwordx4 v[50:53], v[50:51], off
	v_lshl_add_u64 v[56:57], s[20:21], 0, v[54:55]
	v_or_b32_e32 v54, 0x100, v54
	v_lshl_add_u64 v[58:59], s[22:23], 0, v[54:55]
	s_waitcnt vmcnt(0)
	v_lshlrev_b32_e32 v60, 16, v50
	v_and_b32_e32 v61, 0xffff0000, v50
	v_lshlrev_b32_e32 v50, 16, v51
	v_and_b32_e32 v51, 0xffff0000, v51
	v_lshlrev_b32_e32 v62, 16, v52
	v_and_b32_e32 v63, 0xffff0000, v52
	v_lshlrev_b32_e32 v52, 16, v53
	v_and_b32_e32 v53, 0xffff0000, v53
	v_pk_add_f32 v[50:51], v[46:47], v[50:51]
	v_pk_add_f32 v[60:61], v[44:45], v[60:61]
	v_pk_add_f32 v[52:53], v[42:43], v[52:53]
	v_pk_add_f32 v[62:63], v[40:41], v[62:63]
	v_cvt_pk_bf16_f32 v40, v60, v61
	v_cvt_pk_bf16_f32 v41, v50, v51
	v_mul_f32_e32 v51, v51, v51
	v_cvt_pk_bf16_f32 v42, v62, v63
	v_cvt_pk_bf16_f32 v43, v52, v53
	global_load_dwordx4 v[44:47], v[58:59], off
	v_mul_f32_e32 v58, v61, v61
	v_mul_f32_e32 v59, v63, v63
	v_mul_f32_e32 v53, v53, v53
	v_fmac_f32_e32 v58, v60, v60
	v_fmac_f32_e32 v51, v50, v50
	v_fmac_f32_e32 v59, v62, v62
	v_fmac_f32_e32 v53, v52, v52
	v_add_f32_e32 v50, v58, v51
	v_add_f32_e32 v51, v59, v53
	v_add_f32_e32 v58, v50, v51
	global_store_dwordx4 v[56:57], v[40:43], off
	s_waitcnt vmcnt(1)
	v_lshlrev_b32_e32 v50, 16, v44
	v_and_b32_e32 v51, 0xffff0000, v44
	v_lshlrev_b32_e32 v44, 16, v45
	v_and_b32_e32 v45, 0xffff0000, v45
	v_lshlrev_b32_e32 v52, 16, v46
	v_and_b32_e32 v53, 0xffff0000, v46
	v_lshlrev_b32_e32 v46, 16, v47
	v_and_b32_e32 v47, 0xffff0000, v47
	v_pk_add_f32 v[38:39], v[38:39], v[44:45]
	v_pk_add_f32 v[36:37], v[36:37], v[50:51]
	v_pk_add_f32 v[44:45], v[34:35], v[46:47]
	v_pk_add_f32 v[46:47], v[32:33], v[52:53]
	v_mul_f32_e32 v32, v37, v37
	v_mul_f32_e32 v33, v39, v39
	v_mul_f32_e32 v34, v47, v47
	v_mul_f32_e32 v35, v45, v45
	v_fmac_f32_e32 v32, v36, v36
	v_fmac_f32_e32 v33, v38, v38
	v_fmac_f32_e32 v34, v46, v46
	v_fmac_f32_e32 v35, v44, v44
	v_add_f32_e32 v32, v32, v33
	v_add_f32_e32 v33, v34, v35
	v_add_f32_e32 v32, v32, v33
	v_add_f32_e32 v32, v58, v32
	v_mov_b32_e32 v33, v32
	s_nop 1
	v_permlane16_swap_b32_e32 v33, v32
	v_cvt_pk_bf16_f32 v34, v36, v37
	v_cvt_pk_bf16_f32 v35, v38, v39
	v_lshl_add_u64 v[38:39], s[20:21], 0, v[54:55]
	v_cvt_pk_bf16_f32 v36, v46, v47
	s_waitcnt lgkmcnt(0)
	v_add_f32_e32 v32, v32, v33
	v_mov_b32_e32 v33, v32
	s_nop 1
	v_permlane32_swap_b32_e32 v33, v32
	v_cvt_pk_bf16_f32 v37, v44, v45
	global_store_dwordx4 v[38:39], v[34:37], off
	s_and_saveexec_b64 s[36:37], s[8:9]
	s_cbranch_execz .LBB0_538
	s_waitcnt lgkmcnt(0)
	v_add_f32_e32 v34, v32, v33
	v_lshlrev_b64 v[32:33], 7, v[48:49]
	v_lshl_add_u64 v[32:33], s[14:15], 0, v[32:33]
	v_lshl_add_u64 v[32:33], s[34:35], 2, v[32:33]
	s_lshl_b32 s16, s59, 2
	v_lshl_add_u64 v[32:33], v[32:33], 0, s[16:17]
	global_store_dword v[32:33], v34, off
.LBB0_538:
	s_or_b64 exec, exec, s[36:37]
	v_add_u32_e32 v32, 0xa0, v146
	s_waitcnt lgkmcnt(0)
	v_ashrrev_i32_e32 v33, 31, v32
	v_lshlrev_b64 v[34:35], 11, v[32:33]
	v_lshl_add_u64 v[34:35], v[34:35], 0, v[144:145]
	v_lshlrev_b64 v[38:39], 1, v[34:35]
	v_lshl_add_u64 v[34:35], s[22:23], 0, v[38:39]
	global_load_dwordx4 v[34:37], v[34:35], off
	v_lshl_add_u64 v[40:41], s[20:21], 0, v[38:39]
	v_or_b32_e32 v38, 0x100, v38
	v_lshl_add_u64 v[42:43], s[22:23], 0, v[38:39]
	s_waitcnt vmcnt(0)
	v_lshlrev_b32_e32 v44, 16, v34
	v_and_b32_e32 v45, 0xffff0000, v34
	v_lshlrev_b32_e32 v34, 16, v35
	v_and_b32_e32 v35, 0xffff0000, v35
	v_lshlrev_b32_e32 v46, 16, v36
	v_and_b32_e32 v47, 0xffff0000, v36
	v_lshlrev_b32_e32 v36, 16, v37
	v_and_b32_e32 v37, 0xffff0000, v37
	v_pk_add_f32 v[34:35], v[30:31], v[34:35]
	v_pk_add_f32 v[44:45], v[28:29], v[44:45]
	v_pk_add_f32 v[36:37], v[26:27], v[36:37]
	v_pk_add_f32 v[46:47], v[24:25], v[46:47]
	v_cvt_pk_bf16_f32 v24, v44, v45
	v_cvt_pk_bf16_f32 v25, v34, v35
	v_mul_f32_e32 v35, v35, v35
	v_cvt_pk_bf16_f32 v26, v46, v47
	v_cvt_pk_bf16_f32 v27, v36, v37
	global_load_dwordx4 v[28:31], v[42:43], off
	v_mul_f32_e32 v42, v45, v45
	v_mul_f32_e32 v43, v47, v47
	v_mul_f32_e32 v37, v37, v37
	v_fmac_f32_e32 v42, v44, v44
	v_fmac_f32_e32 v35, v34, v34
	v_fmac_f32_e32 v43, v46, v46
	v_fmac_f32_e32 v37, v36, v36
	v_add_f32_e32 v34, v42, v35
	v_add_f32_e32 v35, v43, v37
	v_add_f32_e32 v42, v34, v35
	global_store_dwordx4 v[40:41], v[24:27], off
	s_waitcnt vmcnt(1)
	v_lshlrev_b32_e32 v34, 16, v28
	v_and_b32_e32 v35, 0xffff0000, v28
	v_lshlrev_b32_e32 v28, 16, v29
	v_and_b32_e32 v29, 0xffff0000, v29
	v_lshlrev_b32_e32 v36, 16, v30
	v_and_b32_e32 v37, 0xffff0000, v30
	v_lshlrev_b32_e32 v30, 16, v31
	v_and_b32_e32 v31, 0xffff0000, v31
	v_pk_add_f32 v[22:23], v[22:23], v[28:29]
	v_pk_add_f32 v[20:21], v[20:21], v[34:35]
	v_pk_add_f32 v[28:29], v[18:19], v[30:31]
	v_pk_add_f32 v[30:31], v[16:17], v[36:37]
	v_mul_f32_e32 v16, v21, v21
	v_mul_f32_e32 v17, v23, v23
	v_mul_f32_e32 v18, v31, v31
	v_mul_f32_e32 v19, v29, v29
	v_fmac_f32_e32 v16, v20, v20
	v_fmac_f32_e32 v17, v22, v22
	v_fmac_f32_e32 v18, v30, v30
	v_fmac_f32_e32 v19, v28, v28
	v_add_f32_e32 v16, v16, v17
	v_add_f32_e32 v17, v18, v19
	v_add_f32_e32 v16, v16, v17
	v_add_f32_e32 v16, v42, v16
	v_mov_b32_e32 v17, v16
	s_nop 1
	v_permlane16_swap_b32_e32 v17, v16
	v_cvt_pk_bf16_f32 v18, v20, v21
	v_cvt_pk_bf16_f32 v19, v22, v23
	v_lshl_add_u64 v[22:23], s[20:21], 0, v[38:39]
	v_cvt_pk_bf16_f32 v20, v30, v31
	s_waitcnt lgkmcnt(0)
	v_add_f32_e32 v16, v16, v17
	v_mov_b32_e32 v17, v16
	s_nop 1
	v_permlane32_swap_b32_e32 v17, v16
	v_cvt_pk_bf16_f32 v21, v28, v29
	global_store_dwordx4 v[22:23], v[18:21], off
	s_and_saveexec_b64 s[36:37], s[8:9]
	s_cbranch_execz .LBB0_540
	s_waitcnt lgkmcnt(0)
	v_add_f32_e32 v18, v16, v17
	v_lshlrev_b64 v[16:17], 7, v[32:33]
	v_lshl_add_u64 v[16:17], s[14:15], 0, v[16:17]
	v_lshl_add_u64 v[16:17], s[34:35], 2, v[16:17]
	s_lshl_b32 s16, s59, 2
	v_lshl_add_u64 v[16:17], v[16:17], 0, s[16:17]
	global_store_dword v[16:17], v18, off
.LBB0_540:
	s_or_b64 exec, exec, s[36:37]
	v_add_u32_e32 v16, 0xb0, v146
	s_waitcnt lgkmcnt(0)
	v_ashrrev_i32_e32 v17, 31, v16
	v_lshlrev_b64 v[18:19], 11, v[16:17]
	v_lshl_add_u64 v[18:19], v[18:19], 0, v[144:145]
	v_lshlrev_b64 v[22:23], 1, v[18:19]
	v_lshl_add_u64 v[18:19], s[22:23], 0, v[22:23]
	global_load_dwordx4 v[18:21], v[18:19], off
	v_lshl_add_u64 v[24:25], s[20:21], 0, v[22:23]
	v_or_b32_e32 v22, 0x100, v22
	v_lshl_add_u64 v[26:27], s[22:23], 0, v[22:23]
	s_waitcnt vmcnt(0)
	v_lshlrev_b32_e32 v28, 16, v18
	v_and_b32_e32 v29, 0xffff0000, v18
	v_lshlrev_b32_e32 v18, 16, v19
	v_and_b32_e32 v19, 0xffff0000, v19
	v_lshlrev_b32_e32 v30, 16, v20
	v_and_b32_e32 v31, 0xffff0000, v20
	v_lshlrev_b32_e32 v20, 16, v21
	v_and_b32_e32 v21, 0xffff0000, v21
	v_pk_add_f32 v[18:19], v[14:15], v[18:19]
	v_pk_add_f32 v[28:29], v[12:13], v[28:29]
	v_pk_add_f32 v[20:21], v[10:11], v[20:21]
	v_pk_add_f32 v[30:31], v[8:9], v[30:31]
	v_cvt_pk_bf16_f32 v8, v28, v29
	v_cvt_pk_bf16_f32 v9, v18, v19
	v_mul_f32_e32 v19, v19, v19
	v_cvt_pk_bf16_f32 v10, v30, v31
	v_cvt_pk_bf16_f32 v11, v20, v21
	global_load_dwordx4 v[12:15], v[26:27], off
	v_mul_f32_e32 v26, v29, v29
	v_mul_f32_e32 v27, v31, v31
	v_mul_f32_e32 v21, v21, v21
	v_fmac_f32_e32 v26, v28, v28
	v_fmac_f32_e32 v19, v18, v18
	v_fmac_f32_e32 v27, v30, v30
	v_fmac_f32_e32 v21, v20, v20
	v_add_f32_e32 v18, v26, v19
	v_add_f32_e32 v19, v27, v21
	v_add_f32_e32 v26, v18, v19
	global_store_dwordx4 v[24:25], v[8:11], off
	s_waitcnt vmcnt(1)
	v_lshlrev_b32_e32 v18, 16, v12
	v_and_b32_e32 v19, 0xffff0000, v12
	v_lshlrev_b32_e32 v12, 16, v13
	v_and_b32_e32 v13, 0xffff0000, v13
	v_lshlrev_b32_e32 v20, 16, v14
	v_and_b32_e32 v21, 0xffff0000, v14
	v_lshlrev_b32_e32 v14, 16, v15
	v_and_b32_e32 v15, 0xffff0000, v15
	v_pk_add_f32 v[6:7], v[6:7], v[12:13]
	v_pk_add_f32 v[4:5], v[4:5], v[18:19]
	v_pk_add_f32 v[12:13], v[2:3], v[14:15]
	v_pk_add_f32 v[14:15], v[0:1], v[20:21]
	v_mul_f32_e32 v0, v5, v5
	v_mul_f32_e32 v1, v7, v7
	v_mul_f32_e32 v2, v15, v15
	v_mul_f32_e32 v3, v13, v13
	v_fmac_f32_e32 v0, v4, v4
	v_fmac_f32_e32 v1, v6, v6
	v_fmac_f32_e32 v2, v14, v14
	v_fmac_f32_e32 v3, v12, v12
	v_add_f32_e32 v0, v0, v1
	v_add_f32_e32 v1, v2, v3
	v_add_f32_e32 v0, v0, v1
	v_add_f32_e32 v0, v26, v0
	v_mov_b32_e32 v1, v0
	s_nop 1
	v_permlane16_swap_b32_e32 v1, v0
	v_cvt_pk_bf16_f32 v2, v4, v5
	v_cvt_pk_bf16_f32 v3, v6, v7
	v_lshl_add_u64 v[6:7], s[20:21], 0, v[22:23]
	v_cvt_pk_bf16_f32 v4, v14, v15
	s_waitcnt lgkmcnt(0)
	v_add_f32_e32 v0, v0, v1
	v_mov_b32_e32 v1, v0
	s_nop 1
	v_permlane32_swap_b32_e32 v1, v0
	v_cvt_pk_bf16_f32 v5, v12, v13
	global_store_dwordx4 v[6:7], v[2:5], off
	s_and_saveexec_b64 s[36:37], s[8:9]
	s_cbranch_execz .LBB0_542
	s_waitcnt lgkmcnt(0)
	v_add_f32_e32 v2, v0, v1
	v_lshlrev_b64 v[0:1], 7, v[16:17]
	v_lshl_add_u64 v[0:1], s[14:15], 0, v[0:1]
	v_lshl_add_u64 v[0:1], s[34:35], 2, v[0:1]
	s_lshl_b32 s16, s59, 2
	v_lshl_add_u64 v[0:1], v[0:1], 0, s[16:17]
	global_store_dword v[0:1], v2, off

.LBB0_620:
	v_lshl_add_u32 v148, s54, 8, v156
	v_ashrrev_i32_e32 v149, 31, v148
	v_lshlrev_b64 v[150:151], 7, v[148:149]
	v_lshl_add_u64 v[146:147], v[136:137], 0, v[150:151]
	global_load_dwordx4 v[166:169], v[146:147], off
	global_load_dwordx4 v[170:173], v[146:147], off offset:16
	v_lshl_or_b32 v146, s14, 8, v158
	v_ashrrev_i32_e32 v147, 31, v146
	v_lshlrev_b64 v[152:153], 11, v[148:149]
	v_lshl_add_u64 v[152:153], v[152:153], 0, v[146:147]
	v_lshlrev_b64 v[152:153], 1, v[152:153]
	v_lshl_add_u64 v[154:155], s[12:13], 0, v[152:153]
	global_load_dwordx4 v[174:177], v[154:155], off
	v_lshl_add_u64 v[154:155], s[22:23], 0, v[152:153]
	global_load_dwordx4 v[178:181], v[154:155], off
	v_and_b32_e32 v154, 64, v162
	v_xor_b32_e32 v149, 16, v162
	v_add_u32_e32 v154, 64, v154
	v_cmp_lt_i32_e32 vcc, v149, v154
	v_xor_b32_e32 v155, 32, v162
	s_lshl_b32 s54, s14, 2
	v_cndmask_b32_e32 v149, v162, v149, vcc
	v_lshlrev_b32_e32 v164, 2, v149
	v_cmp_lt_i32_e32 vcc, v155, v154
	s_ashr_i32 s55, s54, 31
	s_waitcnt vmcnt(0)
	v_mov_b32_e32 v184, v166
	v_mov_b32_e32 v185, v170
	v_mov_b32_e32 v170, v167
	v_mov_b32_e32 v166, v168
	v_mov_b32_e32 v167, v172
	v_mov_b32_e32 v172, v169
	v_pk_add_f32 v[168:169], v[184:185], v[170:171]
	v_pk_add_f32 v[166:167], v[166:167], v[172:173]
	v_lshlrev_b32_e32 v170, 16, v175
	v_pk_add_f32 v[166:167], v[168:169], v[166:167]
	v_and_b32_e32 v171, 0xffff0000, v175
	v_add_f32_e32 v165, 0, v166
	v_add_f32_e32 v165, v165, v167
	v_mov_b32_e32 v175, v165
	s_nop 1
	v_permlane16_swap_b32_e32 v175, v165
	v_cndmask_b32_e32 v154, v162, v155, vcc
	v_lshlrev_b32_e32 v149, 2, v154
	v_lshlrev_b32_e32 v172, 16, v176
	v_and_b32_e32 v173, 0xffff0000, v176
	s_waitcnt lgkmcnt(0)
	v_add_f32_e32 v165, v165, v175
	v_mov_b32_e32 v184, v165
	s_nop 1
	v_permlane32_swap_b32_e32 v184, v165
	v_lshlrev_b32_e32 v166, 16, v177
	v_and_b32_e32 v167, 0xffff0000, v177
	v_lshlrev_b32_e32 v176, 16, v179
	v_and_b32_e32 v177, 0xffff0000, v179
	s_waitcnt lgkmcnt(0)
	v_add_f32_e32 v165, v165, v184
	v_fmamk_f32 v165, v165, 0x3a000000, v163
	v_mul_f32_e32 v179, 0x4b800000, v165
	v_cmp_gt_f32_e32 vcc, s70, v165
	v_lshl_add_u64 v[154:155], s[18:19], 0, v[152:153]
	v_or_b32_e32 v152, 0x100, v152
	v_cndmask_b32_e32 v165, v165, v179, vcc
	v_rsq_f32_e32 v165, v165
	v_lshlrev_b32_e32 v168, 16, v174
	v_and_b32_e32 v169, 0xffff0000, v174
	v_lshlrev_b32_e32 v174, 16, v178
	v_mul_f32_e32 v184, 0x45800000, v165
	v_cndmask_b32_e32 v165, v165, v184, vcc
	v_mul_f32_e32 v126, v126, v165
	v_mul_f32_e32 v127, v127, v165
	v_mul_f32_e32 v122, v122, v165
	v_mul_f32_e32 v123, v123, v165
	v_mul_f32_e32 v124, v124, v165
	v_mul_f32_e32 v125, v125, v165
	v_mul_f32_e32 v120, v120, v165
	v_mul_f32_e32 v121, v121, v165
	v_mul_f32_e32 v126, 0xbfb8aa3b, v126
	v_mul_f32_e32 v127, 0xbfb8aa3b, v127
	v_mul_f32_e32 v122, 0xbfb8aa3b, v122
	v_mul_f32_e32 v123, 0xbfb8aa3b, v123
	v_mul_f32_e32 v124, 0xbfb8aa3b, v124
	v_mul_f32_e32 v125, 0xbfb8aa3b, v125
	v_mul_f32_e32 v120, 0xbfb8aa3b, v120
	v_mul_f32_e32 v121, 0xbfb8aa3b, v121
	v_exp_f32_e32 v126, v126
	v_exp_f32_e32 v127, v127
	v_exp_f32_e32 v122, v122
	v_exp_f32_e32 v123, v123
	v_exp_f32_e32 v124, v124
	v_exp_f32_e32 v125, v125
	v_exp_f32_e32 v120, v120
	v_exp_f32_e32 v121, v121
	v_add_f32_e32 v126, 1.0, v126
	v_add_f32_e32 v127, 1.0, v127
	v_add_f32_e32 v186, 1.0, v122
	v_add_f32_e32 v187, 1.0, v123
	v_add_f32_e32 v124, 1.0, v124
	v_add_f32_e32 v125, 1.0, v125
	v_add_f32_e32 v184, 1.0, v120
	v_add_f32_e32 v185, 1.0, v121
	v_rcp_f32_e32 v122, v126
	v_rcp_f32_e32 v123, v127
	v_rcp_f32_e32 v126, v186
	v_rcp_f32_e32 v127, v187
	v_rcp_f32_e32 v120, v124
	v_rcp_f32_e32 v121, v125
	v_rcp_f32_e32 v124, v184
	v_rcp_f32_e32 v125, v185
	v_and_b32_e32 v175, 0xffff0000, v178
	v_lshlrev_b32_e32 v178, 16, v180
	v_and_b32_e32 v179, 0xffff0000, v180
	v_lshlrev_b32_e32 v180, 16, v181
	v_and_b32_e32 v181, 0xffff0000, v181
	v_lshl_add_u64 v[182:183], s[12:13], 0, v[152:153]
	v_pk_fma_f32 v[170:171], v[122:123], v[176:177], v[170:171]
	v_pk_fma_f32 v[176:177], v[126:127], v[180:181], v[166:167]
	v_lshl_add_u64 v[166:167], s[22:23], 0, v[152:153]
	v_pk_fma_f32 v[174:175], v[120:121], v[174:175], v[168:169]
	v_pk_fma_f32 v[172:173], v[124:125], v[178:179], v[172:173]
	v_cvt_pk_bf16_f32 v120, v174, v175
	v_cvt_pk_bf16_f32 v121, v170, v171
	v_mul_f32_e32 v116, v116, v165
	v_cvt_pk_bf16_f32 v122, v172, v173
	v_cvt_pk_bf16_f32 v123, v176, v177
	global_load_dwordx4 v[124:127], v[182:183], off
	v_mul_f32_e32 v117, v117, v165
	global_load_dwordx4 v[166:169], v[166:167], off
	v_mul_f32_e32 v118, v118, v165
	v_mul_f32_e32 v119, v119, v165
	v_mul_f32_e32 v112, v112, v165
	v_mul_f32_e32 v113, v113, v165
	v_mul_f32_e32 v114, v114, v165
	v_mul_f32_e32 v115, v115, v165
	v_mul_f32_e32 v116, 0xbfb8aa3b, v116
	v_mul_f32_e32 v117, 0xbfb8aa3b, v117
	v_mul_f32_e32 v118, 0xbfb8aa3b, v118
	v_mul_f32_e32 v119, 0xbfb8aa3b, v119
	v_mul_f32_e32 v112, 0xbfb8aa3b, v112
	v_mul_f32_e32 v113, 0xbfb8aa3b, v113
	v_mul_f32_e32 v114, 0xbfb8aa3b, v114
	v_mul_f32_e32 v115, 0xbfb8aa3b, v115
	v_exp_f32_e32 v116, v116
	v_exp_f32_e32 v117, v117
	v_exp_f32_e32 v118, v118
	v_exp_f32_e32 v119, v119
	v_exp_f32_e32 v112, v112
	v_exp_f32_e32 v113, v113
	v_exp_f32_e32 v114, v114
	v_exp_f32_e32 v115, v115
	v_add_f32_e32 v116, 1.0, v116
	v_add_f32_e32 v117, 1.0, v117
	v_add_f32_e32 v118, 1.0, v118
	v_add_f32_e32 v119, 1.0, v119
	v_add_f32_e32 v165, 1.0, v112
	v_add_f32_e32 v178, 1.0, v113
	v_add_f32_e32 v179, 1.0, v114
	v_add_f32_e32 v180, 1.0, v115
	v_rcp_f32_e32 v112, v116
	v_rcp_f32_e32 v113, v117
	v_rcp_f32_e32 v114, v118
	v_rcp_f32_e32 v115, v119
	v_rcp_f32_e32 v116, v165
	v_rcp_f32_e32 v117, v178
	v_rcp_f32_e32 v118, v179
	v_rcp_f32_e32 v119, v180
	v_mul_f32_e32 v165, v175, v175
	v_mul_f32_e32 v171, v171, v171
	v_mul_f32_e32 v173, v173, v173
	v_mul_f32_e32 v175, v177, v177
	v_fmac_f32_e32 v165, v174, v174
	v_fmac_f32_e32 v171, v170, v170
	v_fmac_f32_e32 v173, v172, v172
	v_fmac_f32_e32 v175, v176, v176
	v_add_f32_e32 v165, v165, v171
	v_add_f32_e32 v170, v173, v175
	v_add_f32_e32 v165, v165, v170
	global_store_dwordx4 v[154:155], v[120:123], off
	s_waitcnt vmcnt(2)
	v_lshlrev_b32_e32 v170, 16, v124
	v_and_b32_e32 v171, 0xffff0000, v124
	v_lshlrev_b32_e32 v124, 16, v125
	v_and_b32_e32 v125, 0xffff0000, v125
	v_lshlrev_b32_e32 v172, 16, v126
	v_and_b32_e32 v173, 0xffff0000, v126
	v_lshlrev_b32_e32 v126, 16, v127
	v_and_b32_e32 v127, 0xffff0000, v127
	s_waitcnt vmcnt(1)
	v_lshlrev_b32_e32 v174, 16, v166
	v_and_b32_e32 v175, 0xffff0000, v166
	v_lshlrev_b32_e32 v166, 16, v167
	v_and_b32_e32 v167, 0xffff0000, v167
	v_lshlrev_b32_e32 v176, 16, v168
	v_and_b32_e32 v177, 0xffff0000, v168
	v_lshlrev_b32_e32 v168, 16, v169
	v_and_b32_e32 v169, 0xffff0000, v169
	v_pk_fma_f32 v[124:125], v[114:115], v[166:167], v[124:125]
	v_pk_fma_f32 v[112:113], v[112:113], v[174:175], v[170:171]
	v_pk_fma_f32 v[118:119], v[118:119], v[168:169], v[126:127]
	v_pk_fma_f32 v[116:117], v[116:117], v[176:177], v[172:173]
	v_mul_f32_e32 v114, v113, v113
	v_mul_f32_e32 v115, v125, v125
	v_mul_f32_e32 v126, v117, v117
	v_mul_f32_e32 v127, v119, v119
	v_fmac_f32_e32 v114, v112, v112
	v_fmac_f32_e32 v115, v124, v124
	v_fmac_f32_e32 v126, v116, v116
	v_fmac_f32_e32 v127, v118, v118
	v_add_f32_e32 v114, v114, v115
	v_add_f32_e32 v115, v126, v127
	v_add_f32_e32 v114, v114, v115
	v_add_f32_e32 v126, v165, v114
	v_mov_b32_e32 v127, v126
	s_nop 1
	v_permlane16_swap_b32_e32 v127, v126
	v_cvt_pk_bf16_f32 v114, v112, v113
	v_cvt_pk_bf16_f32 v115, v124, v125
	v_cvt_pk_bf16_f32 v116, v116, v117
	v_cvt_pk_bf16_f32 v117, v118, v119
	s_waitcnt lgkmcnt(0)
	v_add_f32_e32 v112, v126, v127
	v_mov_b32_e32 v113, v112
	s_nop 1
	v_permlane32_swap_b32_e32 v113, v112
	v_lshl_add_u64 v[118:119], s[18:19], 0, v[152:153]
	global_store_dwordx4 v[118:119], v[114:117], off
	s_and_saveexec_b64 s[56:57], s[8:9]
	s_cbranch_execz .LBB0_622
	s_waitcnt lgkmcnt(0)
	v_add_f32_e32 v114, v112, v113
	v_lshl_add_u64 v[112:113], s[20:21], 0, v[150:151]
	v_lshl_add_u64 v[112:113], s[54:55], 2, v[112:113]
	s_lshl_b32 s14, s63, 2
	v_lshl_add_u64 v[112:113], v[112:113], 0, s[14:15]
	global_store_dword v[112:113], v114, off
.LBB0_622:
	s_or_b64 exec, exec, s[56:57]
	v_or_b32_e32 v114, 16, v148
	v_ashrrev_i32_e32 v115, 31, v114
	s_waitcnt lgkmcnt(0)
	v_lshlrev_b64 v[112:113], 7, v[114:115]
	v_lshl_add_u64 v[116:117], v[136:137], 0, v[112:113]
	global_load_dwordx4 v[118:121], v[116:117], off
	global_load_dwordx4 v[122:125], v[116:117], off offset:16
	v_lshlrev_b64 v[114:115], 11, v[114:115]
	v_lshl_add_u64 v[114:115], v[114:115], 0, v[146:147]
	v_lshlrev_b64 v[114:115], 1, v[114:115]
	v_lshl_add_u64 v[116:117], s[12:13], 0, v[114:115]
	global_load_dwordx4 v[150:153], v[116:117], off
	v_lshl_add_u64 v[116:117], s[22:23], 0, v[114:115]
	global_load_dwordx4 v[166:169], v[116:117], off
	v_lshl_add_u64 v[116:117], s[18:19], 0, v[114:115]
	v_or_b32_e32 v114, 0x100, v114
	v_lshl_add_u64 v[126:127], s[12:13], 0, v[114:115]
	s_waitcnt vmcnt(3)
	v_mov_b32_e32 v154, v118
	s_waitcnt vmcnt(2)
	v_mov_b32_e32 v155, v122
	v_mov_b32_e32 v122, v119
	v_mov_b32_e32 v118, v120
	v_mov_b32_e32 v119, v124
	v_mov_b32_e32 v124, v121
	v_pk_add_f32 v[120:121], v[154:155], v[122:123]
	v_pk_add_f32 v[118:119], v[118:119], v[124:125]
	s_waitcnt vmcnt(1)
	v_lshlrev_b32_e32 v122, 16, v151
	v_pk_add_f32 v[118:119], v[120:121], v[118:119]
	v_and_b32_e32 v123, 0xffff0000, v151
	v_add_f32_e32 v118, 0, v118
	v_add_f32_e32 v151, v118, v119
	v_mov_b32_e32 v154, v151
	s_nop 1
	v_permlane16_swap_b32_e32 v154, v151
	v_lshlrev_b32_e32 v120, 16, v150
	v_and_b32_e32 v121, 0xffff0000, v150
	v_lshlrev_b32_e32 v124, 16, v152
	v_and_b32_e32 v125, 0xffff0000, v152
	s_waitcnt lgkmcnt(0)
	v_add_f32_e32 v155, v151, v154
	v_mov_b32_e32 v165, v155
	s_nop 1
	v_permlane32_swap_b32_e32 v165, v155
	s_waitcnt vmcnt(0)
	v_lshlrev_b32_e32 v154, 16, v168
	v_lshlrev_b32_e32 v118, 16, v153
	v_and_b32_e32 v119, 0xffff0000, v153
	v_lshlrev_b32_e32 v150, 16, v166
	s_waitcnt lgkmcnt(0)
	v_add_f32_e32 v155, v155, v165
	v_fmamk_f32 v155, v155, 0x3a000000, v163
	v_mul_f32_e32 v165, 0x4b800000, v155
	v_cmp_gt_f32_e32 vcc, s70, v155
	v_and_b32_e32 v151, 0xffff0000, v166
	v_lshlrev_b32_e32 v152, 16, v167
	v_cndmask_b32_e32 v155, v155, v165, vcc
	v_rsq_f32_e32 v165, v155
	v_and_b32_e32 v155, 0xffff0000, v168
	v_and_b32_e32 v153, 0xffff0000, v167
	v_lshlrev_b32_e32 v166, 16, v169
	v_mul_f32_e32 v168, 0x45800000, v165
	v_cndmask_b32_e32 v165, v165, v168, vcc
	v_mul_f32_e32 v110, v110, v165
	v_mul_f32_e32 v111, v111, v165
	v_mul_f32_e32 v106, v106, v165
	v_mul_f32_e32 v107, v107, v165
	v_mul_f32_e32 v108, v108, v165
	v_mul_f32_e32 v109, v109, v165
	v_mul_f32_e32 v104, v104, v165
	v_mul_f32_e32 v105, v105, v165
	v_mul_f32_e32 v110, 0xbfb8aa3b, v110
	v_mul_f32_e32 v111, 0xbfb8aa3b, v111
	v_mul_f32_e32 v106, 0xbfb8aa3b, v106
	v_mul_f32_e32 v107, 0xbfb8aa3b, v107
	v_mul_f32_e32 v108, 0xbfb8aa3b, v108
	v_mul_f32_e32 v109, 0xbfb8aa3b, v109
	v_mul_f32_e32 v104, 0xbfb8aa3b, v104
	v_mul_f32_e32 v105, 0xbfb8aa3b, v105
	v_exp_f32_e32 v110, v110
	v_exp_f32_e32 v111, v111
	v_exp_f32_e32 v106, v106
	v_exp_f32_e32 v107, v107
	v_exp_f32_e32 v108, v108
	v_exp_f32_e32 v109, v109
	v_exp_f32_e32 v104, v104
	v_exp_f32_e32 v105, v105
	v_add_f32_e32 v110, 1.0, v110
	v_add_f32_e32 v111, 1.0, v111
	v_add_f32_e32 v170, 1.0, v106
	v_add_f32_e32 v171, 1.0, v107
	v_and_b32_e32 v167, 0xffff0000, v169
	v_add_f32_e32 v108, 1.0, v108
	v_add_f32_e32 v109, 1.0, v109
	v_add_f32_e32 v168, 1.0, v104
	v_add_f32_e32 v169, 1.0, v105
	v_rcp_f32_e32 v106, v110
	v_rcp_f32_e32 v107, v111
	v_rcp_f32_e32 v110, v170
	v_rcp_f32_e32 v111, v171
	v_rcp_f32_e32 v104, v108
	v_rcp_f32_e32 v105, v109
	v_rcp_f32_e32 v108, v168
	v_rcp_f32_e32 v109, v169
	v_pk_fma_f32 v[122:123], v[106:107], v[152:153], v[122:123]
	v_pk_fma_f32 v[152:153], v[110:111], v[166:167], v[118:119]
	v_lshl_add_u64 v[118:119], s[22:23], 0, v[114:115]
	v_pk_fma_f32 v[150:151], v[104:105], v[150:151], v[120:121]
	v_pk_fma_f32 v[124:125], v[108:109], v[154:155], v[124:125]
	v_cvt_pk_bf16_f32 v104, v150, v151
	v_cvt_pk_bf16_f32 v105, v122, v123
	v_mul_f32_e32 v100, v100, v165
	v_cvt_pk_bf16_f32 v106, v124, v125
	v_cvt_pk_bf16_f32 v107, v152, v153
	global_load_dwordx4 v[108:111], v[126:127], off
	v_mul_f32_e32 v101, v101, v165
	global_load_dwordx4 v[118:121], v[118:119], off
	v_mul_f32_e32 v102, v102, v165
	v_mul_f32_e32 v103, v103, v165
	v_mul_f32_e32 v96, v96, v165
	v_mul_f32_e32 v97, v97, v165
	v_mul_f32_e32 v98, v98, v165
	v_mul_f32_e32 v99, v99, v165
	v_mul_f32_e32 v100, 0xbfb8aa3b, v100
	v_mul_f32_e32 v101, 0xbfb8aa3b, v101
	v_mul_f32_e32 v102, 0xbfb8aa3b, v102
	v_mul_f32_e32 v103, 0xbfb8aa3b, v103
	v_mul_f32_e32 v96, 0xbfb8aa3b, v96
	v_mul_f32_e32 v97, 0xbfb8aa3b, v97
	v_mul_f32_e32 v98, 0xbfb8aa3b, v98
	v_mul_f32_e32 v99, 0xbfb8aa3b, v99
	v_exp_f32_e32 v100, v100
	v_exp_f32_e32 v101, v101
	v_exp_f32_e32 v102, v102
	v_exp_f32_e32 v103, v103
	v_exp_f32_e32 v96, v96
	v_exp_f32_e32 v97, v97
	v_exp_f32_e32 v98, v98
	v_exp_f32_e32 v99, v99
	v_add_f32_e32 v100, 1.0, v100
	v_add_f32_e32 v101, 1.0, v101
	v_add_f32_e32 v102, 1.0, v102
	v_add_f32_e32 v103, 1.0, v103
	v_add_f32_e32 v126, 1.0, v96
	v_add_f32_e32 v127, 1.0, v97
	v_add_f32_e32 v154, 1.0, v98
	v_add_f32_e32 v155, 1.0, v99
	v_rcp_f32_e32 v96, v100
	v_rcp_f32_e32 v97, v101
	v_rcp_f32_e32 v98, v102
	v_rcp_f32_e32 v99, v103
	v_rcp_f32_e32 v100, v126
	v_rcp_f32_e32 v101, v127
	v_rcp_f32_e32 v102, v154
	v_rcp_f32_e32 v103, v155
	v_mul_f32_e32 v126, v151, v151
	v_mul_f32_e32 v123, v123, v123
	v_mul_f32_e32 v125, v125, v125
	v_mul_f32_e32 v127, v153, v153
	v_fmac_f32_e32 v126, v150, v150
	v_fmac_f32_e32 v123, v122, v122
	v_fmac_f32_e32 v125, v124, v124
	v_fmac_f32_e32 v127, v152, v152
	v_add_f32_e32 v122, v126, v123
	v_add_f32_e32 v123, v125, v127
	v_add_f32_e32 v152, v122, v123
	global_store_dwordx4 v[116:117], v[104:107], off
	s_waitcnt vmcnt(2)
	v_lshlrev_b32_e32 v122, 16, v108
	v_and_b32_e32 v123, 0xffff0000, v108
	v_lshlrev_b32_e32 v108, 16, v109
	v_and_b32_e32 v109, 0xffff0000, v109
	v_lshlrev_b32_e32 v124, 16, v110
	v_and_b32_e32 v125, 0xffff0000, v110
	v_lshlrev_b32_e32 v110, 16, v111
	v_and_b32_e32 v111, 0xffff0000, v111
	s_waitcnt vmcnt(1)
	v_lshlrev_b32_e32 v126, 16, v118
	v_and_b32_e32 v127, 0xffff0000, v118
	v_lshlrev_b32_e32 v118, 16, v119
	v_and_b32_e32 v119, 0xffff0000, v119
	v_lshlrev_b32_e32 v150, 16, v120
	v_and_b32_e32 v151, 0xffff0000, v120
	v_lshlrev_b32_e32 v120, 16, v121
	v_and_b32_e32 v121, 0xffff0000, v121
	v_pk_fma_f32 v[108:109], v[98:99], v[118:119], v[108:109]
	v_pk_fma_f32 v[96:97], v[96:97], v[126:127], v[122:123]
	v_pk_fma_f32 v[102:103], v[102:103], v[120:121], v[110:111]
	v_pk_fma_f32 v[100:101], v[100:101], v[150:151], v[124:125]
	v_mul_f32_e32 v98, v97, v97
	v_mul_f32_e32 v99, v109, v109
	v_mul_f32_e32 v110, v101, v101
	v_mul_f32_e32 v111, v103, v103
	v_fmac_f32_e32 v98, v96, v96
	v_fmac_f32_e32 v99, v108, v108
	v_fmac_f32_e32 v110, v100, v100
	v_fmac_f32_e32 v111, v102, v102
	v_add_f32_e32 v98, v98, v99
	v_add_f32_e32 v99, v110, v111
	v_add_f32_e32 v98, v98, v99
	v_add_f32_e32 v110, v152, v98
	v_mov_b32_e32 v111, v110
	s_nop 1
	v_permlane16_swap_b32_e32 v111, v110
	v_cvt_pk_bf16_f32 v98, v96, v97
	v_cvt_pk_bf16_f32 v99, v108, v109
	v_cvt_pk_bf16_f32 v100, v100, v101
	v_cvt_pk_bf16_f32 v101, v102, v103
	s_waitcnt lgkmcnt(0)
	v_add_f32_e32 v96, v110, v111
	v_mov_b32_e32 v97, v96
	s_nop 1
	v_permlane32_swap_b32_e32 v97, v96
	v_lshl_add_u64 v[102:103], s[18:19], 0, v[114:115]
	global_store_dwordx4 v[102:103], v[98:101], off
	s_and_saveexec_b64 s[56:57], s[8:9]
	s_cbranch_execz .LBB0_624
	s_waitcnt lgkmcnt(0)
	v_add_f32_e32 v98, v96, v97
	v_lshl_add_u64 v[96:97], s[20:21], 0, v[112:113]
	v_lshl_add_u64 v[96:97], s[54:55], 2, v[96:97]
	s_lshl_b32 s14, s63, 2
	v_lshl_add_u64 v[96:97], v[96:97], 0, s[14:15]
	global_store_dword v[96:97], v98, off
.LBB0_624:
	s_or_b64 exec, exec, s[56:57]
	v_or_b32_e32 v98, 32, v148
	v_ashrrev_i32_e32 v99, 31, v98
	s_waitcnt lgkmcnt(0)
	v_lshlrev_b64 v[96:97], 7, v[98:99]
	v_lshl_add_u64 v[100:101], v[136:137], 0, v[96:97]
	global_load_dwordx4 v[102:105], v[100:101], off
	global_load_dwordx4 v[106:109], v[100:101], off offset:16
	v_lshlrev_b64 v[98:99], 11, v[98:99]
	v_lshl_add_u64 v[98:99], v[98:99], 0, v[146:147]
	v_lshlrev_b64 v[98:99], 1, v[98:99]
	v_lshl_add_u64 v[100:101], s[12:13], 0, v[98:99]
	global_load_dwordx4 v[110:113], v[100:101], off
	v_lshl_add_u64 v[100:101], s[22:23], 0, v[98:99]
	global_load_dwordx4 v[114:117], v[100:101], off
	v_lshl_add_u64 v[100:101], s[18:19], 0, v[98:99]
	v_or_b32_e32 v98, 0x100, v98
	v_lshl_add_u64 v[118:119], s[12:13], 0, v[98:99]
	s_waitcnt vmcnt(3)
	v_mov_b32_e32 v120, v102
	s_waitcnt vmcnt(2)
	v_mov_b32_e32 v121, v106
	v_mov_b32_e32 v106, v103
	v_mov_b32_e32 v102, v104
	v_mov_b32_e32 v103, v108
	v_mov_b32_e32 v108, v105
	v_pk_add_f32 v[104:105], v[120:121], v[106:107]
	v_pk_add_f32 v[102:103], v[102:103], v[108:109]
	s_waitcnt vmcnt(1)
	v_lshlrev_b32_e32 v106, 16, v111
	v_pk_add_f32 v[102:103], v[104:105], v[102:103]
	v_and_b32_e32 v107, 0xffff0000, v111
	v_add_f32_e32 v102, 0, v102
	v_add_f32_e32 v111, v102, v103
	v_mov_b32_e32 v120, v111
	s_nop 1
	v_permlane16_swap_b32_e32 v120, v111
	v_lshlrev_b32_e32 v108, 16, v112
	v_and_b32_e32 v109, 0xffff0000, v112
	v_lshlrev_b32_e32 v102, 16, v113
	v_and_b32_e32 v103, 0xffff0000, v113
	s_waitcnt lgkmcnt(0)
	v_add_f32_e32 v120, v111, v120
	v_mov_b32_e32 v121, v120
	s_nop 1
	v_permlane32_swap_b32_e32 v121, v120
	s_waitcnt vmcnt(0)
	v_lshlrev_b32_e32 v112, 16, v115
	v_and_b32_e32 v113, 0xffff0000, v115
	v_lshlrev_b32_e32 v104, 16, v110
	v_and_b32_e32 v105, 0xffff0000, v110
	s_waitcnt lgkmcnt(0)
	v_add_f32_e32 v115, v120, v121
	v_fmamk_f32 v115, v115, 0x3a000000, v163
	v_mul_f32_e32 v120, 0x4b800000, v115
	v_cmp_gt_f32_e32 vcc, s70, v115
	v_lshlrev_b32_e32 v110, 16, v114
	v_and_b32_e32 v111, 0xffff0000, v114
	v_cndmask_b32_e32 v115, v115, v120, vcc
	v_rsq_f32_e32 v120, v115
	v_lshlrev_b32_e32 v114, 16, v116
	v_and_b32_e32 v115, 0xffff0000, v116
	v_lshlrev_b32_e32 v116, 16, v117
	v_mul_f32_e32 v121, 0x45800000, v120
	v_cndmask_b32_e32 v120, v120, v121, vcc
	v_mul_f32_e32 v94, v94, v120
	v_mul_f32_e32 v95, v95, v120
	v_mul_f32_e32 v90, v90, v120
	v_mul_f32_e32 v91, v91, v120
	v_mul_f32_e32 v92, v92, v120
	v_mul_f32_e32 v93, v93, v120
	v_mul_f32_e32 v88, v88, v120
	v_mul_f32_e32 v89, v89, v120
	v_mul_f32_e32 v94, 0xbfb8aa3b, v94
	v_mul_f32_e32 v95, 0xbfb8aa3b, v95
	v_mul_f32_e32 v90, 0xbfb8aa3b, v90
	v_mul_f32_e32 v91, 0xbfb8aa3b, v91
	v_mul_f32_e32 v92, 0xbfb8aa3b, v92
	v_mul_f32_e32 v93, 0xbfb8aa3b, v93
	v_mul_f32_e32 v88, 0xbfb8aa3b, v88
	v_mul_f32_e32 v89, 0xbfb8aa3b, v89
	v_exp_f32_e32 v94, v94
	v_exp_f32_e32 v95, v95
	v_exp_f32_e32 v90, v90
	v_exp_f32_e32 v91, v91
	v_exp_f32_e32 v92, v92
	v_exp_f32_e32 v93, v93
	v_exp_f32_e32 v88, v88
	v_exp_f32_e32 v89, v89
	v_add_f32_e32 v94, 1.0, v94
	v_add_f32_e32 v95, 1.0, v95
	v_add_f32_e32 v123, 1.0, v90
	v_add_f32_e32 v124, 1.0, v91
	v_add_f32_e32 v92, 1.0, v92
	v_add_f32_e32 v93, 1.0, v93
	v_add_f32_e32 v121, 1.0, v88
	v_add_f32_e32 v122, 1.0, v89
	v_rcp_f32_e32 v90, v94
	v_rcp_f32_e32 v91, v95
	v_rcp_f32_e32 v94, v123
	v_rcp_f32_e32 v95, v124
	v_rcp_f32_e32 v88, v92
	v_rcp_f32_e32 v89, v93
	v_rcp_f32_e32 v92, v121
	v_rcp_f32_e32 v93, v122
	v_and_b32_e32 v117, 0xffff0000, v117
	v_pk_fma_f32 v[106:107], v[90:91], v[112:113], v[106:107]
	v_pk_fma_f32 v[112:113], v[94:95], v[116:117], v[102:103]
	v_lshl_add_u64 v[102:103], s[22:23], 0, v[98:99]
	v_pk_fma_f32 v[110:111], v[88:89], v[110:111], v[104:105]
	v_pk_fma_f32 v[108:109], v[92:93], v[114:115], v[108:109]
	v_cvt_pk_bf16_f32 v88, v110, v111
	v_cvt_pk_bf16_f32 v89, v106, v107
	v_mul_f32_e32 v84, v84, v120
	v_cvt_pk_bf16_f32 v90, v108, v109
	v_cvt_pk_bf16_f32 v91, v112, v113
	global_load_dwordx4 v[92:95], v[118:119], off
	v_mul_f32_e32 v85, v85, v120
	global_load_dwordx4 v[102:105], v[102:103], off
	v_mul_f32_e32 v86, v86, v120
	v_mul_f32_e32 v87, v87, v120
	v_mul_f32_e32 v80, v80, v120
	v_mul_f32_e32 v81, v81, v120
	v_mul_f32_e32 v82, v82, v120
	v_mul_f32_e32 v83, v83, v120
	v_mul_f32_e32 v84, 0xbfb8aa3b, v84
	v_mul_f32_e32 v85, 0xbfb8aa3b, v85
	v_mul_f32_e32 v86, 0xbfb8aa3b, v86
	v_mul_f32_e32 v87, 0xbfb8aa3b, v87
	v_mul_f32_e32 v80, 0xbfb8aa3b, v80
	v_mul_f32_e32 v81, 0xbfb8aa3b, v81
	v_mul_f32_e32 v82, 0xbfb8aa3b, v82
	v_mul_f32_e32 v83, 0xbfb8aa3b, v83
	v_exp_f32_e32 v84, v84
	v_exp_f32_e32 v85, v85
	v_exp_f32_e32 v86, v86
	v_exp_f32_e32 v87, v87
	v_exp_f32_e32 v80, v80
	v_exp_f32_e32 v81, v81
	v_exp_f32_e32 v82, v82
	v_exp_f32_e32 v83, v83
	v_add_f32_e32 v84, 1.0, v84
	v_add_f32_e32 v85, 1.0, v85
	v_add_f32_e32 v86, 1.0, v86
	v_add_f32_e32 v87, 1.0, v87
	v_add_f32_e32 v114, 1.0, v80
	v_add_f32_e32 v115, 1.0, v81
	v_add_f32_e32 v116, 1.0, v82
	v_add_f32_e32 v117, 1.0, v83
	v_rcp_f32_e32 v80, v84
	v_rcp_f32_e32 v81, v85
	v_rcp_f32_e32 v82, v86
	v_rcp_f32_e32 v83, v87
	v_rcp_f32_e32 v84, v114
	v_rcp_f32_e32 v85, v115
	v_rcp_f32_e32 v86, v116
	v_rcp_f32_e32 v87, v117
	v_mul_f32_e32 v111, v111, v111
	v_mul_f32_e32 v107, v107, v107
	v_mul_f32_e32 v109, v109, v109
	v_mul_f32_e32 v113, v113, v113
	v_fmac_f32_e32 v111, v110, v110
	v_fmac_f32_e32 v107, v106, v106
	v_fmac_f32_e32 v109, v108, v108
	v_fmac_f32_e32 v113, v112, v112
	v_add_f32_e32 v106, v111, v107
	v_add_f32_e32 v107, v109, v113
	v_add_f32_e32 v114, v106, v107
	global_store_dwordx4 v[100:101], v[88:91], off
	s_waitcnt vmcnt(2)
	v_lshlrev_b32_e32 v106, 16, v92
	v_and_b32_e32 v107, 0xffff0000, v92
	v_lshlrev_b32_e32 v92, 16, v93
	v_and_b32_e32 v93, 0xffff0000, v93
	v_lshlrev_b32_e32 v108, 16, v94
	v_and_b32_e32 v109, 0xffff0000, v94
	v_lshlrev_b32_e32 v94, 16, v95
	v_and_b32_e32 v95, 0xffff0000, v95
	s_waitcnt vmcnt(1)
	v_lshlrev_b32_e32 v110, 16, v102
	v_and_b32_e32 v111, 0xffff0000, v102
	v_lshlrev_b32_e32 v102, 16, v103
	v_and_b32_e32 v103, 0xffff0000, v103
	v_lshlrev_b32_e32 v112, 16, v104
	v_and_b32_e32 v113, 0xffff0000, v104
	v_lshlrev_b32_e32 v104, 16, v105
	v_and_b32_e32 v105, 0xffff0000, v105
	v_pk_fma_f32 v[92:93], v[82:83], v[102:103], v[92:93]
	v_pk_fma_f32 v[80:81], v[80:81], v[110:111], v[106:107]
	v_pk_fma_f32 v[86:87], v[86:87], v[104:105], v[94:95]
	v_pk_fma_f32 v[84:85], v[84:85], v[112:113], v[108:109]
	v_mul_f32_e32 v82, v81, v81
	v_mul_f32_e32 v83, v93, v93
	v_mul_f32_e32 v94, v85, v85
	v_mul_f32_e32 v95, v87, v87
	v_fmac_f32_e32 v82, v80, v80
	v_fmac_f32_e32 v83, v92, v92
	v_fmac_f32_e32 v94, v84, v84
	v_fmac_f32_e32 v95, v86, v86
	v_add_f32_e32 v82, v82, v83
	v_add_f32_e32 v83, v94, v95
	v_add_f32_e32 v82, v82, v83
	v_add_f32_e32 v94, v114, v82
	v_mov_b32_e32 v95, v94
	s_nop 1
	v_permlane16_swap_b32_e32 v95, v94
	v_cvt_pk_bf16_f32 v82, v80, v81
	v_cvt_pk_bf16_f32 v83, v92, v93
	v_cvt_pk_bf16_f32 v84, v84, v85
	v_cvt_pk_bf16_f32 v85, v86, v87
	s_waitcnt lgkmcnt(0)
	v_add_f32_e32 v80, v94, v95
	v_mov_b32_e32 v81, v80
	s_nop 1
	v_permlane32_swap_b32_e32 v81, v80
	v_lshl_add_u64 v[86:87], s[18:19], 0, v[98:99]
	global_store_dwordx4 v[86:87], v[82:85], off
	s_and_saveexec_b64 s[56:57], s[8:9]
	s_cbranch_execz .LBB0_626
	s_waitcnt lgkmcnt(0)
	v_add_f32_e32 v82, v80, v81
	v_lshl_add_u64 v[80:81], s[20:21], 0, v[96:97]
	v_lshl_add_u64 v[80:81], s[54:55], 2, v[80:81]
	s_lshl_b32 s14, s63, 2
	v_lshl_add_u64 v[80:81], v[80:81], 0, s[14:15]
	global_store_dword v[80:81], v82, off
.LBB0_626:
	s_or_b64 exec, exec, s[56:57]
	v_or_b32_e32 v82, 48, v148
	v_ashrrev_i32_e32 v83, 31, v82
	s_waitcnt lgkmcnt(0)
	v_lshlrev_b64 v[80:81], 7, v[82:83]
	v_lshl_add_u64 v[84:85], v[136:137], 0, v[80:81]
	global_load_dwordx4 v[86:89], v[84:85], off
	global_load_dwordx4 v[90:93], v[84:85], off offset:16
	v_lshlrev_b64 v[82:83], 11, v[82:83]
	v_lshl_add_u64 v[82:83], v[82:83], 0, v[146:147]
	v_lshlrev_b64 v[82:83], 1, v[82:83]
	v_lshl_add_u64 v[84:85], s[12:13], 0, v[82:83]
	global_load_dwordx4 v[94:97], v[84:85], off
	v_lshl_add_u64 v[84:85], s[22:23], 0, v[82:83]
	global_load_dwordx4 v[98:101], v[84:85], off
	v_lshl_add_u64 v[84:85], s[18:19], 0, v[82:83]
	v_or_b32_e32 v82, 0x100, v82
	v_lshl_add_u64 v[102:103], s[12:13], 0, v[82:83]
	s_waitcnt vmcnt(3)
	v_mov_b32_e32 v104, v86
	s_waitcnt vmcnt(2)
	v_mov_b32_e32 v105, v90
	v_mov_b32_e32 v90, v87
	v_mov_b32_e32 v86, v88
	v_mov_b32_e32 v87, v92
	v_mov_b32_e32 v92, v89
	v_pk_add_f32 v[88:89], v[104:105], v[90:91]
	v_pk_add_f32 v[86:87], v[86:87], v[92:93]
	s_waitcnt vmcnt(1)
	v_lshlrev_b32_e32 v90, 16, v95
	v_pk_add_f32 v[86:87], v[88:89], v[86:87]
	v_and_b32_e32 v91, 0xffff0000, v95
	v_add_f32_e32 v86, 0, v86
	v_add_f32_e32 v95, v86, v87
	v_mov_b32_e32 v104, v95
	s_nop 1
	v_permlane16_swap_b32_e32 v104, v95
	v_lshlrev_b32_e32 v92, 16, v96
	v_and_b32_e32 v93, 0xffff0000, v96
	v_lshlrev_b32_e32 v86, 16, v97
	v_and_b32_e32 v87, 0xffff0000, v97
	s_waitcnt lgkmcnt(0)
	v_add_f32_e32 v104, v95, v104
	v_mov_b32_e32 v105, v104
	s_nop 1
	v_permlane32_swap_b32_e32 v105, v104
	s_waitcnt vmcnt(0)
	v_lshlrev_b32_e32 v96, 16, v99
	v_and_b32_e32 v97, 0xffff0000, v99
	v_lshlrev_b32_e32 v88, 16, v94
	v_and_b32_e32 v89, 0xffff0000, v94
	s_waitcnt lgkmcnt(0)
	v_add_f32_e32 v99, v104, v105
	v_fmamk_f32 v99, v99, 0x3a000000, v163
	v_mul_f32_e32 v104, 0x4b800000, v99
	v_cmp_gt_f32_e32 vcc, s70, v99
	v_lshlrev_b32_e32 v94, 16, v98
	v_and_b32_e32 v95, 0xffff0000, v98
	v_cndmask_b32_e32 v99, v99, v104, vcc
	v_rsq_f32_e32 v104, v99
	v_lshlrev_b32_e32 v98, 16, v100
	v_and_b32_e32 v99, 0xffff0000, v100
	v_lshlrev_b32_e32 v100, 16, v101
	v_mul_f32_e32 v105, 0x45800000, v104
	v_cndmask_b32_e32 v104, v104, v105, vcc
	v_mul_f32_e32 v78, v78, v104
	v_mul_f32_e32 v79, v79, v104
	v_mul_f32_e32 v74, v74, v104
	v_mul_f32_e32 v75, v75, v104
	v_mul_f32_e32 v76, v76, v104
	v_mul_f32_e32 v77, v77, v104
	v_mul_f32_e32 v72, v72, v104
	v_mul_f32_e32 v73, v73, v104
	v_mul_f32_e32 v78, 0xbfb8aa3b, v78
	v_mul_f32_e32 v79, 0xbfb8aa3b, v79
	v_mul_f32_e32 v74, 0xbfb8aa3b, v74
	v_mul_f32_e32 v75, 0xbfb8aa3b, v75
	v_mul_f32_e32 v76, 0xbfb8aa3b, v76
	v_mul_f32_e32 v77, 0xbfb8aa3b, v77
	v_mul_f32_e32 v72, 0xbfb8aa3b, v72
	v_mul_f32_e32 v73, 0xbfb8aa3b, v73
	v_exp_f32_e32 v78, v78
	v_exp_f32_e32 v79, v79
	v_exp_f32_e32 v74, v74
	v_exp_f32_e32 v75, v75
	v_exp_f32_e32 v76, v76
	v_exp_f32_e32 v77, v77
	v_exp_f32_e32 v72, v72
	v_exp_f32_e32 v73, v73
	v_add_f32_e32 v78, 1.0, v78
	v_add_f32_e32 v79, 1.0, v79
	v_add_f32_e32 v107, 1.0, v74
	v_add_f32_e32 v108, 1.0, v75
	v_add_f32_e32 v76, 1.0, v76
	v_add_f32_e32 v77, 1.0, v77
	v_add_f32_e32 v105, 1.0, v72
	v_add_f32_e32 v106, 1.0, v73
	v_rcp_f32_e32 v74, v78
	v_rcp_f32_e32 v75, v79
	v_rcp_f32_e32 v78, v107
	v_rcp_f32_e32 v79, v108
	v_rcp_f32_e32 v72, v76
	v_rcp_f32_e32 v73, v77
	v_rcp_f32_e32 v76, v105
	v_rcp_f32_e32 v77, v106
	v_and_b32_e32 v101, 0xffff0000, v101
	v_pk_fma_f32 v[90:91], v[74:75], v[96:97], v[90:91]
	v_pk_fma_f32 v[96:97], v[78:79], v[100:101], v[86:87]
	v_lshl_add_u64 v[86:87], s[22:23], 0, v[82:83]
	v_pk_fma_f32 v[94:95], v[72:73], v[94:95], v[88:89]
	v_pk_fma_f32 v[92:93], v[76:77], v[98:99], v[92:93]
	v_cvt_pk_bf16_f32 v72, v94, v95
	v_cvt_pk_bf16_f32 v73, v90, v91
	v_mul_f32_e32 v68, v68, v104
	v_cvt_pk_bf16_f32 v74, v92, v93
	v_cvt_pk_bf16_f32 v75, v96, v97
	global_load_dwordx4 v[76:79], v[102:103], off
	v_mul_f32_e32 v69, v69, v104
	global_load_dwordx4 v[86:89], v[86:87], off
	v_mul_f32_e32 v70, v70, v104
	v_mul_f32_e32 v71, v71, v104
	v_mul_f32_e32 v64, v64, v104
	v_mul_f32_e32 v65, v65, v104
	v_mul_f32_e32 v66, v66, v104
	v_mul_f32_e32 v67, v67, v104
	v_mul_f32_e32 v68, 0xbfb8aa3b, v68
	v_mul_f32_e32 v69, 0xbfb8aa3b, v69
	v_mul_f32_e32 v70, 0xbfb8aa3b, v70
	v_mul_f32_e32 v71, 0xbfb8aa3b, v71
	v_mul_f32_e32 v64, 0xbfb8aa3b, v64
	v_mul_f32_e32 v65, 0xbfb8aa3b, v65
	v_mul_f32_e32 v66, 0xbfb8aa3b, v66
	v_mul_f32_e32 v67, 0xbfb8aa3b, v67
	v_exp_f32_e32 v68, v68
	v_exp_f32_e32 v69, v69
	v_exp_f32_e32 v70, v70
	v_exp_f32_e32 v71, v71
	v_exp_f32_e32 v64, v64
	v_exp_f32_e32 v65, v65
	v_exp_f32_e32 v66, v66
	v_exp_f32_e32 v67, v67
	v_add_f32_e32 v68, 1.0, v68
	v_add_f32_e32 v69, 1.0, v69
	v_add_f32_e32 v70, 1.0, v70
	v_add_f32_e32 v71, 1.0, v71
	v_add_f32_e32 v98, 1.0, v64
	v_add_f32_e32 v99, 1.0, v65
	v_add_f32_e32 v100, 1.0, v66
	v_add_f32_e32 v101, 1.0, v67
	v_rcp_f32_e32 v64, v68
	v_rcp_f32_e32 v65, v69
	v_rcp_f32_e32 v66, v70
	v_rcp_f32_e32 v67, v71
	v_rcp_f32_e32 v68, v98
	v_rcp_f32_e32 v69, v99
	v_rcp_f32_e32 v70, v100
	v_rcp_f32_e32 v71, v101
	v_mul_f32_e32 v95, v95, v95
	v_mul_f32_e32 v91, v91, v91
	v_mul_f32_e32 v93, v93, v93
	v_mul_f32_e32 v97, v97, v97
	v_fmac_f32_e32 v95, v94, v94
	v_fmac_f32_e32 v91, v90, v90
	v_fmac_f32_e32 v93, v92, v92
	v_fmac_f32_e32 v97, v96, v96
	v_add_f32_e32 v90, v95, v91
	v_add_f32_e32 v91, v93, v97
	v_add_f32_e32 v98, v90, v91
	global_store_dwordx4 v[84:85], v[72:75], off
	s_waitcnt vmcnt(2)
	v_lshlrev_b32_e32 v90, 16, v76
	v_and_b32_e32 v91, 0xffff0000, v76
	v_lshlrev_b32_e32 v76, 16, v77
	v_and_b32_e32 v77, 0xffff0000, v77
	v_lshlrev_b32_e32 v92, 16, v78
	v_and_b32_e32 v93, 0xffff0000, v78
	v_lshlrev_b32_e32 v78, 16, v79
	v_and_b32_e32 v79, 0xffff0000, v79
	s_waitcnt vmcnt(1)
	v_lshlrev_b32_e32 v94, 16, v86
	v_and_b32_e32 v95, 0xffff0000, v86
	v_lshlrev_b32_e32 v86, 16, v87
	v_and_b32_e32 v87, 0xffff0000, v87
	v_lshlrev_b32_e32 v96, 16, v88
	v_and_b32_e32 v97, 0xffff0000, v88
	v_lshlrev_b32_e32 v88, 16, v89
	v_and_b32_e32 v89, 0xffff0000, v89
	v_pk_fma_f32 v[76:77], v[66:67], v[86:87], v[76:77]
	v_pk_fma_f32 v[64:65], v[64:65], v[94:95], v[90:91]
	v_pk_fma_f32 v[70:71], v[70:71], v[88:89], v[78:79]
	v_pk_fma_f32 v[68:69], v[68:69], v[96:97], v[92:93]
	v_mul_f32_e32 v66, v65, v65
	v_mul_f32_e32 v67, v77, v77
	v_mul_f32_e32 v78, v69, v69
	v_mul_f32_e32 v79, v71, v71
	v_fmac_f32_e32 v66, v64, v64
	v_fmac_f32_e32 v67, v76, v76
	v_fmac_f32_e32 v78, v68, v68
	v_fmac_f32_e32 v79, v70, v70
	v_add_f32_e32 v66, v66, v67
	v_add_f32_e32 v67, v78, v79
	v_add_f32_e32 v66, v66, v67
	v_add_f32_e32 v78, v98, v66
	v_mov_b32_e32 v79, v78
	s_nop 1
	v_permlane16_swap_b32_e32 v79, v78
	v_cvt_pk_bf16_f32 v66, v64, v65
	v_cvt_pk_bf16_f32 v67, v76, v77
	v_cvt_pk_bf16_f32 v68, v68, v69
	v_cvt_pk_bf16_f32 v69, v70, v71
	s_waitcnt lgkmcnt(0)
	v_add_f32_e32 v64, v78, v79
	v_mov_b32_e32 v65, v64
	s_nop 1
	v_permlane32_swap_b32_e32 v65, v64
	v_lshl_add_u64 v[70:71], s[18:19], 0, v[82:83]
	global_store_dwordx4 v[70:71], v[66:69], off
	s_and_saveexec_b64 s[56:57], s[8:9]
	s_cbranch_execz .LBB0_628
	s_waitcnt lgkmcnt(0)
	v_add_f32_e32 v66, v64, v65
	v_lshl_add_u64 v[64:65], s[20:21], 0, v[80:81]
	v_lshl_add_u64 v[64:65], s[54:55], 2, v[64:65]
	s_lshl_b32 s14, s63, 2
	v_lshl_add_u64 v[64:65], v[64:65], 0, s[14:15]
	global_store_dword v[64:65], v66, off
.LBB0_628:
	s_or_b64 exec, exec, s[56:57]
	v_add_u32_e32 v66, 0x80, v148
	v_ashrrev_i32_e32 v67, 31, v66
	s_waitcnt lgkmcnt(0)
	v_lshlrev_b64 v[64:65], 7, v[66:67]
	v_lshl_add_u64 v[68:69], v[136:137], 0, v[64:65]
	global_load_dwordx4 v[70:73], v[68:69], off
	global_load_dwordx4 v[74:77], v[68:69], off offset:16
	v_lshlrev_b64 v[66:67], 11, v[66:67]
	v_lshl_add_u64 v[66:67], v[66:67], 0, v[146:147]
	v_lshlrev_b64 v[66:67], 1, v[66:67]
	v_lshl_add_u64 v[68:69], s[12:13], 0, v[66:67]
	global_load_dwordx4 v[78:81], v[68:69], off
	v_lshl_add_u64 v[68:69], s[22:23], 0, v[66:67]
	global_load_dwordx4 v[82:85], v[68:69], off
	v_lshl_add_u64 v[68:69], s[18:19], 0, v[66:67]
	v_or_b32_e32 v66, 0x100, v66
	v_lshl_add_u64 v[86:87], s[12:13], 0, v[66:67]
	s_waitcnt vmcnt(3)
	v_mov_b32_e32 v88, v70
	s_waitcnt vmcnt(2)
	v_mov_b32_e32 v89, v74
	v_mov_b32_e32 v74, v71
	v_mov_b32_e32 v70, v72
	v_mov_b32_e32 v71, v76
	v_mov_b32_e32 v76, v73
	v_pk_add_f32 v[72:73], v[88:89], v[74:75]
	v_pk_add_f32 v[70:71], v[70:71], v[76:77]
	s_waitcnt vmcnt(1)
	v_lshlrev_b32_e32 v74, 16, v79
	v_pk_add_f32 v[70:71], v[72:73], v[70:71]
	v_and_b32_e32 v75, 0xffff0000, v79
	v_add_f32_e32 v70, 0, v70
	v_add_f32_e32 v79, v70, v71
	v_mov_b32_e32 v88, v79
	s_nop 1
	v_permlane16_swap_b32_e32 v88, v79
	v_lshlrev_b32_e32 v76, 16, v80
	v_and_b32_e32 v77, 0xffff0000, v80
	v_lshlrev_b32_e32 v70, 16, v81
	v_and_b32_e32 v71, 0xffff0000, v81
	s_waitcnt lgkmcnt(0)
	v_add_f32_e32 v88, v79, v88
	v_mov_b32_e32 v89, v88
	s_nop 1
	v_permlane32_swap_b32_e32 v89, v88
	s_waitcnt vmcnt(0)
	v_lshlrev_b32_e32 v80, 16, v83
	v_and_b32_e32 v81, 0xffff0000, v83
	v_lshlrev_b32_e32 v72, 16, v78
	v_and_b32_e32 v73, 0xffff0000, v78
	s_waitcnt lgkmcnt(0)
	v_add_f32_e32 v83, v88, v89
	v_fmamk_f32 v83, v83, 0x3a000000, v163
	v_mul_f32_e32 v88, 0x4b800000, v83
	v_cmp_gt_f32_e32 vcc, s70, v83
	v_lshlrev_b32_e32 v78, 16, v82
	v_and_b32_e32 v79, 0xffff0000, v82
	v_cndmask_b32_e32 v83, v83, v88, vcc
	v_rsq_f32_e32 v88, v83
	v_lshlrev_b32_e32 v82, 16, v84
	v_and_b32_e32 v83, 0xffff0000, v84
	v_lshlrev_b32_e32 v84, 16, v85
	v_mul_f32_e32 v89, 0x45800000, v88
	v_cndmask_b32_e32 v88, v88, v89, vcc
	v_mul_f32_e32 v62, v62, v88
	v_mul_f32_e32 v63, v63, v88
	v_mul_f32_e32 v58, v58, v88
	v_mul_f32_e32 v59, v59, v88
	v_mul_f32_e32 v60, v60, v88
	v_mul_f32_e32 v61, v61, v88
	v_mul_f32_e32 v56, v56, v88
	v_mul_f32_e32 v57, v57, v88
	v_mul_f32_e32 v62, 0xbfb8aa3b, v62
	v_mul_f32_e32 v63, 0xbfb8aa3b, v63
	v_mul_f32_e32 v58, 0xbfb8aa3b, v58
	v_mul_f32_e32 v59, 0xbfb8aa3b, v59
	v_mul_f32_e32 v60, 0xbfb8aa3b, v60
	v_mul_f32_e32 v61, 0xbfb8aa3b, v61
	v_mul_f32_e32 v56, 0xbfb8aa3b, v56
	v_mul_f32_e32 v57, 0xbfb8aa3b, v57
	v_exp_f32_e32 v62, v62
	v_exp_f32_e32 v63, v63
	v_exp_f32_e32 v58, v58
	v_exp_f32_e32 v59, v59
	v_exp_f32_e32 v60, v60
	v_exp_f32_e32 v61, v61
	v_exp_f32_e32 v56, v56
	v_exp_f32_e32 v57, v57
	v_add_f32_e32 v62, 1.0, v62
	v_add_f32_e32 v63, 1.0, v63
	v_add_f32_e32 v91, 1.0, v58
	v_add_f32_e32 v92, 1.0, v59
	v_add_f32_e32 v60, 1.0, v60
	v_add_f32_e32 v61, 1.0, v61
	v_add_f32_e32 v89, 1.0, v56
	v_add_f32_e32 v90, 1.0, v57
	v_rcp_f32_e32 v58, v62
	v_rcp_f32_e32 v59, v63
	v_rcp_f32_e32 v62, v91
	v_rcp_f32_e32 v63, v92
	v_rcp_f32_e32 v56, v60
	v_rcp_f32_e32 v57, v61
	v_rcp_f32_e32 v60, v89
	v_rcp_f32_e32 v61, v90
	v_and_b32_e32 v85, 0xffff0000, v85
	v_pk_fma_f32 v[74:75], v[58:59], v[80:81], v[74:75]
	v_pk_fma_f32 v[80:81], v[62:63], v[84:85], v[70:71]
	v_lshl_add_u64 v[70:71], s[22:23], 0, v[66:67]
	v_pk_fma_f32 v[78:79], v[56:57], v[78:79], v[72:73]
	v_pk_fma_f32 v[76:77], v[60:61], v[82:83], v[76:77]
	v_cvt_pk_bf16_f32 v56, v78, v79
	v_cvt_pk_bf16_f32 v57, v74, v75
	v_mul_f32_e32 v52, v52, v88
	v_cvt_pk_bf16_f32 v58, v76, v77
	v_cvt_pk_bf16_f32 v59, v80, v81
	global_load_dwordx4 v[60:63], v[86:87], off
	v_mul_f32_e32 v53, v53, v88
	global_load_dwordx4 v[70:73], v[70:71], off
	v_mul_f32_e32 v54, v54, v88
	v_mul_f32_e32 v55, v55, v88
	v_mul_f32_e32 v48, v48, v88
	v_mul_f32_e32 v49, v49, v88
	v_mul_f32_e32 v50, v50, v88
	v_mul_f32_e32 v51, v51, v88
	v_mul_f32_e32 v52, 0xbfb8aa3b, v52
	v_mul_f32_e32 v53, 0xbfb8aa3b, v53
	v_mul_f32_e32 v54, 0xbfb8aa3b, v54
	v_mul_f32_e32 v55, 0xbfb8aa3b, v55
	v_mul_f32_e32 v48, 0xbfb8aa3b, v48
	v_mul_f32_e32 v49, 0xbfb8aa3b, v49
	v_mul_f32_e32 v50, 0xbfb8aa3b, v50
	v_mul_f32_e32 v51, 0xbfb8aa3b, v51
	v_exp_f32_e32 v52, v52
	v_exp_f32_e32 v53, v53
	v_exp_f32_e32 v54, v54
	v_exp_f32_e32 v55, v55
	v_exp_f32_e32 v48, v48
	v_exp_f32_e32 v49, v49
	v_exp_f32_e32 v50, v50
	v_exp_f32_e32 v51, v51
	v_add_f32_e32 v52, 1.0, v52
	v_add_f32_e32 v53, 1.0, v53
	v_add_f32_e32 v54, 1.0, v54
	v_add_f32_e32 v55, 1.0, v55
	v_add_f32_e32 v82, 1.0, v48
	v_add_f32_e32 v83, 1.0, v49
	v_add_f32_e32 v84, 1.0, v50
	v_add_f32_e32 v85, 1.0, v51
	v_rcp_f32_e32 v48, v52
	v_rcp_f32_e32 v49, v53
	v_rcp_f32_e32 v50, v54
	v_rcp_f32_e32 v51, v55
	v_rcp_f32_e32 v52, v82
	v_rcp_f32_e32 v53, v83
	v_rcp_f32_e32 v54, v84
	v_rcp_f32_e32 v55, v85
	v_mul_f32_e32 v79, v79, v79
	v_mul_f32_e32 v75, v75, v75
	v_mul_f32_e32 v77, v77, v77
	v_mul_f32_e32 v81, v81, v81
	v_fmac_f32_e32 v79, v78, v78
	v_fmac_f32_e32 v75, v74, v74
	v_fmac_f32_e32 v77, v76, v76
	v_fmac_f32_e32 v81, v80, v80
	v_add_f32_e32 v74, v79, v75
	v_add_f32_e32 v75, v77, v81
	v_add_f32_e32 v82, v74, v75
	global_store_dwordx4 v[68:69], v[56:59], off
	s_waitcnt vmcnt(2)
	v_lshlrev_b32_e32 v74, 16, v60
	v_and_b32_e32 v75, 0xffff0000, v60
	v_lshlrev_b32_e32 v60, 16, v61
	v_and_b32_e32 v61, 0xffff0000, v61
	v_lshlrev_b32_e32 v76, 16, v62
	v_and_b32_e32 v77, 0xffff0000, v62
	v_lshlrev_b32_e32 v62, 16, v63
	v_and_b32_e32 v63, 0xffff0000, v63
	s_waitcnt vmcnt(1)
	v_lshlrev_b32_e32 v78, 16, v70
	v_and_b32_e32 v79, 0xffff0000, v70
	v_lshlrev_b32_e32 v70, 16, v71
	v_and_b32_e32 v71, 0xffff0000, v71
	v_lshlrev_b32_e32 v80, 16, v72
	v_and_b32_e32 v81, 0xffff0000, v72
	v_lshlrev_b32_e32 v72, 16, v73
	v_and_b32_e32 v73, 0xffff0000, v73
	v_pk_fma_f32 v[60:61], v[50:51], v[70:71], v[60:61]
	v_pk_fma_f32 v[48:49], v[48:49], v[78:79], v[74:75]
	v_pk_fma_f32 v[54:55], v[54:55], v[72:73], v[62:63]
	v_pk_fma_f32 v[52:53], v[52:53], v[80:81], v[76:77]
	v_mul_f32_e32 v50, v49, v49
	v_mul_f32_e32 v51, v61, v61
	v_mul_f32_e32 v62, v53, v53
	v_mul_f32_e32 v63, v55, v55
	v_fmac_f32_e32 v50, v48, v48
	v_fmac_f32_e32 v51, v60, v60
	v_fmac_f32_e32 v62, v52, v52
	v_fmac_f32_e32 v63, v54, v54
	v_add_f32_e32 v50, v50, v51
	v_add_f32_e32 v51, v62, v63
	v_add_f32_e32 v50, v50, v51
	v_add_f32_e32 v62, v82, v50
	v_mov_b32_e32 v63, v62
	s_nop 1
	v_permlane16_swap_b32_e32 v63, v62
	v_cvt_pk_bf16_f32 v50, v48, v49
	v_cvt_pk_bf16_f32 v51, v60, v61
	v_cvt_pk_bf16_f32 v52, v52, v53
	v_cvt_pk_bf16_f32 v53, v54, v55
	s_waitcnt lgkmcnt(0)
	v_add_f32_e32 v48, v62, v63
	v_mov_b32_e32 v49, v48
	s_nop 1
	v_permlane32_swap_b32_e32 v49, v48
	v_lshl_add_u64 v[54:55], s[18:19], 0, v[66:67]
	global_store_dwordx4 v[54:55], v[50:53], off
	s_and_saveexec_b64 s[56:57], s[8:9]
	s_cbranch_execz .LBB0_630
	s_waitcnt lgkmcnt(0)
	v_add_f32_e32 v50, v48, v49
	v_lshl_add_u64 v[48:49], s[20:21], 0, v[64:65]
	v_lshl_add_u64 v[48:49], s[54:55], 2, v[48:49]
	s_lshl_b32 s14, s63, 2
	v_lshl_add_u64 v[48:49], v[48:49], 0, s[14:15]
	global_store_dword v[48:49], v50, off
.LBB0_630:
	s_or_b64 exec, exec, s[56:57]
	v_add_u32_e32 v50, 0x90, v148
	v_ashrrev_i32_e32 v51, 31, v50
	s_waitcnt lgkmcnt(0)
	v_lshlrev_b64 v[48:49], 7, v[50:51]
	v_lshl_add_u64 v[52:53], v[136:137], 0, v[48:49]
	global_load_dwordx4 v[54:57], v[52:53], off
	global_load_dwordx4 v[58:61], v[52:53], off offset:16
	v_lshlrev_b64 v[50:51], 11, v[50:51]
	v_lshl_add_u64 v[50:51], v[50:51], 0, v[146:147]
	v_lshlrev_b64 v[50:51], 1, v[50:51]
	v_lshl_add_u64 v[52:53], s[12:13], 0, v[50:51]
	global_load_dwordx4 v[62:65], v[52:53], off
	v_lshl_add_u64 v[52:53], s[22:23], 0, v[50:51]
	global_load_dwordx4 v[66:69], v[52:53], off
	v_lshl_add_u64 v[52:53], s[18:19], 0, v[50:51]
	v_or_b32_e32 v50, 0x100, v50
	v_lshl_add_u64 v[70:71], s[12:13], 0, v[50:51]
	s_waitcnt vmcnt(3)
	v_mov_b32_e32 v72, v54
	s_waitcnt vmcnt(2)
	v_mov_b32_e32 v73, v58
	v_mov_b32_e32 v58, v55
	v_mov_b32_e32 v54, v56
	v_mov_b32_e32 v55, v60
	v_mov_b32_e32 v60, v57
	v_pk_add_f32 v[56:57], v[72:73], v[58:59]
	v_pk_add_f32 v[54:55], v[54:55], v[60:61]
	s_waitcnt vmcnt(1)
	v_lshlrev_b32_e32 v58, 16, v63
	v_pk_add_f32 v[54:55], v[56:57], v[54:55]
	v_and_b32_e32 v59, 0xffff0000, v63
	v_add_f32_e32 v54, 0, v54
	v_add_f32_e32 v63, v54, v55
	v_mov_b32_e32 v72, v63
	s_nop 1
	v_permlane16_swap_b32_e32 v72, v63
	v_lshlrev_b32_e32 v60, 16, v64
	v_and_b32_e32 v61, 0xffff0000, v64
	v_lshlrev_b32_e32 v54, 16, v65
	v_and_b32_e32 v55, 0xffff0000, v65
	s_waitcnt lgkmcnt(0)
	v_add_f32_e32 v72, v63, v72
	v_mov_b32_e32 v73, v72
	s_nop 1
	v_permlane32_swap_b32_e32 v73, v72
	s_waitcnt vmcnt(0)
	v_lshlrev_b32_e32 v64, 16, v67
	v_and_b32_e32 v65, 0xffff0000, v67
	v_lshlrev_b32_e32 v56, 16, v62
	v_and_b32_e32 v57, 0xffff0000, v62
	s_waitcnt lgkmcnt(0)
	v_add_f32_e32 v67, v72, v73
	v_fmamk_f32 v67, v67, 0x3a000000, v163
	v_mul_f32_e32 v72, 0x4b800000, v67
	v_cmp_gt_f32_e32 vcc, s70, v67
	v_lshlrev_b32_e32 v62, 16, v66
	v_and_b32_e32 v63, 0xffff0000, v66
	v_cndmask_b32_e32 v67, v67, v72, vcc
	v_rsq_f32_e32 v72, v67
	v_lshlrev_b32_e32 v66, 16, v68
	v_and_b32_e32 v67, 0xffff0000, v68
	v_lshlrev_b32_e32 v68, 16, v69
	v_mul_f32_e32 v73, 0x45800000, v72
	v_cndmask_b32_e32 v72, v72, v73, vcc
	v_mul_f32_e32 v46, v46, v72
	v_mul_f32_e32 v47, v47, v72
	v_mul_f32_e32 v42, v42, v72
	v_mul_f32_e32 v43, v43, v72
	v_mul_f32_e32 v44, v44, v72
	v_mul_f32_e32 v45, v45, v72
	v_mul_f32_e32 v40, v40, v72
	v_mul_f32_e32 v41, v41, v72
	v_mul_f32_e32 v46, 0xbfb8aa3b, v46
	v_mul_f32_e32 v47, 0xbfb8aa3b, v47
	v_mul_f32_e32 v42, 0xbfb8aa3b, v42
	v_mul_f32_e32 v43, 0xbfb8aa3b, v43
	v_mul_f32_e32 v44, 0xbfb8aa3b, v44
	v_mul_f32_e32 v45, 0xbfb8aa3b, v45
	v_mul_f32_e32 v40, 0xbfb8aa3b, v40
	v_mul_f32_e32 v41, 0xbfb8aa3b, v41
	v_exp_f32_e32 v46, v46
	v_exp_f32_e32 v47, v47
	v_exp_f32_e32 v42, v42
	v_exp_f32_e32 v43, v43
	v_exp_f32_e32 v44, v44
	v_exp_f32_e32 v45, v45
	v_exp_f32_e32 v40, v40
	v_exp_f32_e32 v41, v41
	v_add_f32_e32 v46, 1.0, v46
	v_add_f32_e32 v47, 1.0, v47
	v_add_f32_e32 v75, 1.0, v42
	v_add_f32_e32 v76, 1.0, v43
	v_add_f32_e32 v44, 1.0, v44
	v_add_f32_e32 v45, 1.0, v45
	v_add_f32_e32 v73, 1.0, v40
	v_add_f32_e32 v74, 1.0, v41
	v_rcp_f32_e32 v42, v46
	v_rcp_f32_e32 v43, v47
	v_rcp_f32_e32 v46, v75
	v_rcp_f32_e32 v47, v76
	v_rcp_f32_e32 v40, v44
	v_rcp_f32_e32 v41, v45
	v_rcp_f32_e32 v44, v73
	v_rcp_f32_e32 v45, v74
	v_and_b32_e32 v69, 0xffff0000, v69
	v_pk_fma_f32 v[58:59], v[42:43], v[64:65], v[58:59]
	v_pk_fma_f32 v[64:65], v[46:47], v[68:69], v[54:55]
	v_lshl_add_u64 v[54:55], s[22:23], 0, v[50:51]
	v_pk_fma_f32 v[62:63], v[40:41], v[62:63], v[56:57]
	v_pk_fma_f32 v[60:61], v[44:45], v[66:67], v[60:61]
	v_cvt_pk_bf16_f32 v40, v62, v63
	v_cvt_pk_bf16_f32 v41, v58, v59
	v_mul_f32_e32 v36, v36, v72
	v_cvt_pk_bf16_f32 v42, v60, v61
	v_cvt_pk_bf16_f32 v43, v64, v65
	global_load_dwordx4 v[44:47], v[70:71], off
	v_mul_f32_e32 v37, v37, v72
	global_load_dwordx4 v[54:57], v[54:55], off
	v_mul_f32_e32 v38, v38, v72
	v_mul_f32_e32 v39, v39, v72
	v_mul_f32_e32 v32, v32, v72
	v_mul_f32_e32 v33, v33, v72
	v_mul_f32_e32 v34, v34, v72
	v_mul_f32_e32 v35, v35, v72
	v_mul_f32_e32 v36, 0xbfb8aa3b, v36
	v_mul_f32_e32 v37, 0xbfb8aa3b, v37
	v_mul_f32_e32 v38, 0xbfb8aa3b, v38
	v_mul_f32_e32 v39, 0xbfb8aa3b, v39
	v_mul_f32_e32 v32, 0xbfb8aa3b, v32
	v_mul_f32_e32 v33, 0xbfb8aa3b, v33
	v_mul_f32_e32 v34, 0xbfb8aa3b, v34
	v_mul_f32_e32 v35, 0xbfb8aa3b, v35
	v_exp_f32_e32 v36, v36
	v_exp_f32_e32 v37, v37
	v_exp_f32_e32 v38, v38
	v_exp_f32_e32 v39, v39
	v_exp_f32_e32 v32, v32
	v_exp_f32_e32 v33, v33
	v_exp_f32_e32 v34, v34
	v_exp_f32_e32 v35, v35
	v_add_f32_e32 v36, 1.0, v36
	v_add_f32_e32 v37, 1.0, v37
	v_add_f32_e32 v38, 1.0, v38
	v_add_f32_e32 v39, 1.0, v39
	v_add_f32_e32 v66, 1.0, v32
	v_add_f32_e32 v67, 1.0, v33
	v_add_f32_e32 v68, 1.0, v34
	v_add_f32_e32 v69, 1.0, v35
	v_rcp_f32_e32 v32, v36
	v_rcp_f32_e32 v33, v37
	v_rcp_f32_e32 v34, v38
	v_rcp_f32_e32 v35, v39
	v_rcp_f32_e32 v36, v66
	v_rcp_f32_e32 v37, v67
	v_rcp_f32_e32 v38, v68
	v_rcp_f32_e32 v39, v69
	v_mul_f32_e32 v63, v63, v63
	v_mul_f32_e32 v59, v59, v59
	v_mul_f32_e32 v61, v61, v61
	v_mul_f32_e32 v65, v65, v65
	v_fmac_f32_e32 v63, v62, v62
	v_fmac_f32_e32 v59, v58, v58
	v_fmac_f32_e32 v61, v60, v60
	v_fmac_f32_e32 v65, v64, v64
	v_add_f32_e32 v58, v63, v59
	v_add_f32_e32 v59, v61, v65
	v_add_f32_e32 v66, v58, v59
	global_store_dwordx4 v[52:53], v[40:43], off
	s_waitcnt vmcnt(2)
	v_lshlrev_b32_e32 v58, 16, v44
	v_and_b32_e32 v59, 0xffff0000, v44
	v_lshlrev_b32_e32 v44, 16, v45
	v_and_b32_e32 v45, 0xffff0000, v45
	v_lshlrev_b32_e32 v60, 16, v46
	v_and_b32_e32 v61, 0xffff0000, v46
	v_lshlrev_b32_e32 v46, 16, v47
	v_and_b32_e32 v47, 0xffff0000, v47
	s_waitcnt vmcnt(1)
	v_lshlrev_b32_e32 v62, 16, v54
	v_and_b32_e32 v63, 0xffff0000, v54
	v_lshlrev_b32_e32 v54, 16, v55
	v_and_b32_e32 v55, 0xffff0000, v55
	v_lshlrev_b32_e32 v64, 16, v56
	v_and_b32_e32 v65, 0xffff0000, v56
	v_lshlrev_b32_e32 v56, 16, v57
	v_and_b32_e32 v57, 0xffff0000, v57
	v_pk_fma_f32 v[44:45], v[34:35], v[54:55], v[44:45]
	v_pk_fma_f32 v[32:33], v[32:33], v[62:63], v[58:59]
	v_pk_fma_f32 v[38:39], v[38:39], v[56:57], v[46:47]
	v_pk_fma_f32 v[36:37], v[36:37], v[64:65], v[60:61]
	v_mul_f32_e32 v34, v33, v33
	v_mul_f32_e32 v35, v45, v45
	v_mul_f32_e32 v46, v37, v37
	v_mul_f32_e32 v47, v39, v39
	v_fmac_f32_e32 v34, v32, v32
	v_fmac_f32_e32 v35, v44, v44
	v_fmac_f32_e32 v46, v36, v36
	v_fmac_f32_e32 v47, v38, v38
	v_add_f32_e32 v34, v34, v35
	v_add_f32_e32 v35, v46, v47
	v_add_f32_e32 v34, v34, v35
	v_add_f32_e32 v46, v66, v34
	v_mov_b32_e32 v47, v46
	s_nop 1
	v_permlane16_swap_b32_e32 v47, v46
	v_cvt_pk_bf16_f32 v34, v32, v33
	v_cvt_pk_bf16_f32 v35, v44, v45
	v_cvt_pk_bf16_f32 v36, v36, v37
	v_cvt_pk_bf16_f32 v37, v38, v39
	s_waitcnt lgkmcnt(0)
	v_add_f32_e32 v32, v46, v47
	v_mov_b32_e32 v33, v32
	s_nop 1
	v_permlane32_swap_b32_e32 v33, v32
	v_lshl_add_u64 v[38:39], s[18:19], 0, v[50:51]
	global_store_dwordx4 v[38:39], v[34:37], off
	s_and_saveexec_b64 s[56:57], s[8:9]
	s_cbranch_execz .LBB0_632
	s_waitcnt lgkmcnt(0)
	v_add_f32_e32 v34, v32, v33
	v_lshl_add_u64 v[32:33], s[20:21], 0, v[48:49]
	v_lshl_add_u64 v[32:33], s[54:55], 2, v[32:33]
	s_lshl_b32 s14, s63, 2
	v_lshl_add_u64 v[32:33], v[32:33], 0, s[14:15]
	global_store_dword v[32:33], v34, off
.LBB0_632:
	s_or_b64 exec, exec, s[56:57]
	v_add_u32_e32 v34, 0xa0, v148
	v_ashrrev_i32_e32 v35, 31, v34
	s_waitcnt lgkmcnt(0)
	v_lshlrev_b64 v[32:33], 7, v[34:35]
	v_lshl_add_u64 v[36:37], v[136:137], 0, v[32:33]
	global_load_dwordx4 v[38:41], v[36:37], off
	global_load_dwordx4 v[42:45], v[36:37], off offset:16
	v_lshlrev_b64 v[34:35], 11, v[34:35]
	v_lshl_add_u64 v[34:35], v[34:35], 0, v[146:147]
	v_lshlrev_b64 v[34:35], 1, v[34:35]
	v_lshl_add_u64 v[36:37], s[12:13], 0, v[34:35]
	global_load_dwordx4 v[46:49], v[36:37], off
	v_lshl_add_u64 v[36:37], s[22:23], 0, v[34:35]
	global_load_dwordx4 v[50:53], v[36:37], off
	v_lshl_add_u64 v[36:37], s[18:19], 0, v[34:35]
	v_or_b32_e32 v34, 0x100, v34
	v_lshl_add_u64 v[54:55], s[12:13], 0, v[34:35]
	s_waitcnt vmcnt(3)
	v_mov_b32_e32 v56, v38
	s_waitcnt vmcnt(2)
	v_mov_b32_e32 v57, v42
	v_mov_b32_e32 v42, v39
	v_mov_b32_e32 v38, v40
	v_mov_b32_e32 v39, v44
	v_mov_b32_e32 v44, v41
	v_pk_add_f32 v[40:41], v[56:57], v[42:43]
	v_pk_add_f32 v[38:39], v[38:39], v[44:45]
	s_waitcnt vmcnt(1)
	v_lshlrev_b32_e32 v42, 16, v47
	v_pk_add_f32 v[38:39], v[40:41], v[38:39]
	v_and_b32_e32 v43, 0xffff0000, v47
	v_add_f32_e32 v38, 0, v38
	v_add_f32_e32 v47, v38, v39
	v_mov_b32_e32 v56, v47
	s_nop 1
	v_permlane16_swap_b32_e32 v56, v47
	v_lshlrev_b32_e32 v44, 16, v48
	v_and_b32_e32 v45, 0xffff0000, v48
	v_lshlrev_b32_e32 v38, 16, v49
	v_and_b32_e32 v39, 0xffff0000, v49
	s_waitcnt lgkmcnt(0)
	v_add_f32_e32 v56, v47, v56
	v_mov_b32_e32 v57, v56
	s_nop 1
	v_permlane32_swap_b32_e32 v57, v56
	s_waitcnt vmcnt(0)
	v_lshlrev_b32_e32 v48, 16, v51
	v_and_b32_e32 v49, 0xffff0000, v51
	v_lshlrev_b32_e32 v40, 16, v46
	v_and_b32_e32 v41, 0xffff0000, v46
	s_waitcnt lgkmcnt(0)
	v_add_f32_e32 v51, v56, v57
	v_fmamk_f32 v51, v51, 0x3a000000, v163
	v_mul_f32_e32 v56, 0x4b800000, v51
	v_cmp_gt_f32_e32 vcc, s70, v51
	v_lshlrev_b32_e32 v46, 16, v50
	v_and_b32_e32 v47, 0xffff0000, v50
	v_cndmask_b32_e32 v51, v51, v56, vcc
	v_rsq_f32_e32 v56, v51
	v_lshlrev_b32_e32 v50, 16, v52
	v_and_b32_e32 v51, 0xffff0000, v52
	v_lshlrev_b32_e32 v52, 16, v53
	v_mul_f32_e32 v57, 0x45800000, v56
	v_cndmask_b32_e32 v56, v56, v57, vcc
	v_mul_f32_e32 v30, v30, v56
	v_mul_f32_e32 v31, v31, v56
	v_mul_f32_e32 v26, v26, v56
	v_mul_f32_e32 v27, v27, v56
	v_mul_f32_e32 v28, v28, v56
	v_mul_f32_e32 v29, v29, v56
	v_mul_f32_e32 v24, v24, v56
	v_mul_f32_e32 v25, v25, v56
	v_mul_f32_e32 v30, 0xbfb8aa3b, v30
	v_mul_f32_e32 v31, 0xbfb8aa3b, v31
	v_mul_f32_e32 v26, 0xbfb8aa3b, v26
	v_mul_f32_e32 v27, 0xbfb8aa3b, v27
	v_mul_f32_e32 v28, 0xbfb8aa3b, v28
	v_mul_f32_e32 v29, 0xbfb8aa3b, v29
	v_mul_f32_e32 v24, 0xbfb8aa3b, v24
	v_mul_f32_e32 v25, 0xbfb8aa3b, v25
	v_exp_f32_e32 v30, v30
	v_exp_f32_e32 v31, v31
	v_exp_f32_e32 v26, v26
	v_exp_f32_e32 v27, v27
	v_exp_f32_e32 v28, v28
	v_exp_f32_e32 v29, v29
	v_exp_f32_e32 v24, v24
	v_exp_f32_e32 v25, v25
	v_add_f32_e32 v30, 1.0, v30
	v_add_f32_e32 v31, 1.0, v31
	v_add_f32_e32 v59, 1.0, v26
	v_add_f32_e32 v60, 1.0, v27
	v_add_f32_e32 v28, 1.0, v28
	v_add_f32_e32 v29, 1.0, v29
	v_add_f32_e32 v57, 1.0, v24
	v_add_f32_e32 v58, 1.0, v25
	v_rcp_f32_e32 v26, v30
	v_rcp_f32_e32 v27, v31
	v_rcp_f32_e32 v30, v59
	v_rcp_f32_e32 v31, v60
	v_rcp_f32_e32 v24, v28
	v_rcp_f32_e32 v25, v29
	v_rcp_f32_e32 v28, v57
	v_rcp_f32_e32 v29, v58
	v_and_b32_e32 v53, 0xffff0000, v53
	v_pk_fma_f32 v[42:43], v[26:27], v[48:49], v[42:43]
	v_pk_fma_f32 v[48:49], v[30:31], v[52:53], v[38:39]
	v_lshl_add_u64 v[38:39], s[22:23], 0, v[34:35]
	v_pk_fma_f32 v[46:47], v[24:25], v[46:47], v[40:41]
	v_pk_fma_f32 v[44:45], v[28:29], v[50:51], v[44:45]
	v_cvt_pk_bf16_f32 v24, v46, v47
	v_cvt_pk_bf16_f32 v25, v42, v43
	v_mul_f32_e32 v20, v20, v56
	v_cvt_pk_bf16_f32 v26, v44, v45
	v_cvt_pk_bf16_f32 v27, v48, v49
	global_load_dwordx4 v[28:31], v[54:55], off
	v_mul_f32_e32 v21, v21, v56
	global_load_dwordx4 v[38:41], v[38:39], off
	v_mul_f32_e32 v22, v22, v56
	v_mul_f32_e32 v23, v23, v56
	v_mul_f32_e32 v16, v16, v56
	v_mul_f32_e32 v17, v17, v56
	v_mul_f32_e32 v18, v18, v56
	v_mul_f32_e32 v19, v19, v56
	v_mul_f32_e32 v20, 0xbfb8aa3b, v20
	v_mul_f32_e32 v21, 0xbfb8aa3b, v21
	v_mul_f32_e32 v22, 0xbfb8aa3b, v22
	v_mul_f32_e32 v23, 0xbfb8aa3b, v23
	v_mul_f32_e32 v16, 0xbfb8aa3b, v16
	v_mul_f32_e32 v17, 0xbfb8aa3b, v17
	v_mul_f32_e32 v18, 0xbfb8aa3b, v18
	v_mul_f32_e32 v19, 0xbfb8aa3b, v19
	v_exp_f32_e32 v20, v20
	v_exp_f32_e32 v21, v21
	v_exp_f32_e32 v22, v22
	v_exp_f32_e32 v23, v23
	v_exp_f32_e32 v16, v16
	v_exp_f32_e32 v17, v17
	v_exp_f32_e32 v18, v18
	v_exp_f32_e32 v19, v19
	v_add_f32_e32 v20, 1.0, v20
	v_add_f32_e32 v21, 1.0, v21
	v_add_f32_e32 v22, 1.0, v22
	v_add_f32_e32 v23, 1.0, v23
	v_add_f32_e32 v50, 1.0, v16
	v_add_f32_e32 v51, 1.0, v17
	v_add_f32_e32 v52, 1.0, v18
	v_add_f32_e32 v53, 1.0, v19
	v_rcp_f32_e32 v16, v20
	v_rcp_f32_e32 v17, v21
	v_rcp_f32_e32 v18, v22
	v_rcp_f32_e32 v19, v23
	v_rcp_f32_e32 v20, v50
	v_rcp_f32_e32 v21, v51
	v_rcp_f32_e32 v22, v52
	v_rcp_f32_e32 v23, v53
	v_mul_f32_e32 v47, v47, v47
	v_mul_f32_e32 v43, v43, v43
	v_mul_f32_e32 v45, v45, v45
	v_mul_f32_e32 v49, v49, v49
	v_fmac_f32_e32 v47, v46, v46
	v_fmac_f32_e32 v43, v42, v42
	v_fmac_f32_e32 v45, v44, v44
	v_fmac_f32_e32 v49, v48, v48
	v_add_f32_e32 v42, v47, v43
	v_add_f32_e32 v43, v45, v49
	v_add_f32_e32 v50, v42, v43
	global_store_dwordx4 v[36:37], v[24:27], off
	s_waitcnt vmcnt(2)
	v_lshlrev_b32_e32 v42, 16, v28
	v_and_b32_e32 v43, 0xffff0000, v28
	v_lshlrev_b32_e32 v28, 16, v29
	v_and_b32_e32 v29, 0xffff0000, v29
	v_lshlrev_b32_e32 v44, 16, v30
	v_and_b32_e32 v45, 0xffff0000, v30
	v_lshlrev_b32_e32 v30, 16, v31
	v_and_b32_e32 v31, 0xffff0000, v31
	s_waitcnt vmcnt(1)
	v_lshlrev_b32_e32 v46, 16, v38
	v_and_b32_e32 v47, 0xffff0000, v38
	v_lshlrev_b32_e32 v38, 16, v39
	v_and_b32_e32 v39, 0xffff0000, v39
	v_lshlrev_b32_e32 v48, 16, v40
	v_and_b32_e32 v49, 0xffff0000, v40
	v_lshlrev_b32_e32 v40, 16, v41
	v_and_b32_e32 v41, 0xffff0000, v41
	v_pk_fma_f32 v[28:29], v[18:19], v[38:39], v[28:29]
	v_pk_fma_f32 v[16:17], v[16:17], v[46:47], v[42:43]
	v_pk_fma_f32 v[22:23], v[22:23], v[40:41], v[30:31]
	v_pk_fma_f32 v[20:21], v[20:21], v[48:49], v[44:45]
	v_mul_f32_e32 v18, v17, v17
	v_mul_f32_e32 v19, v29, v29
	v_mul_f32_e32 v30, v21, v21
	v_mul_f32_e32 v31, v23, v23
	v_fmac_f32_e32 v18, v16, v16
	v_fmac_f32_e32 v19, v28, v28
	v_fmac_f32_e32 v30, v20, v20
	v_fmac_f32_e32 v31, v22, v22
	v_add_f32_e32 v18, v18, v19
	v_add_f32_e32 v19, v30, v31
	v_add_f32_e32 v18, v18, v19
	v_add_f32_e32 v30, v50, v18
	v_mov_b32_e32 v31, v30
	s_nop 1
	v_permlane16_swap_b32_e32 v31, v30
	v_cvt_pk_bf16_f32 v18, v16, v17
	v_cvt_pk_bf16_f32 v19, v28, v29
	v_cvt_pk_bf16_f32 v20, v20, v21
	v_cvt_pk_bf16_f32 v21, v22, v23
	s_waitcnt lgkmcnt(0)
	v_add_f32_e32 v16, v30, v31
	v_mov_b32_e32 v17, v16
	s_nop 1
	v_permlane32_swap_b32_e32 v17, v16
	v_lshl_add_u64 v[22:23], s[18:19], 0, v[34:35]
	global_store_dwordx4 v[22:23], v[18:21], off
	s_and_saveexec_b64 s[56:57], s[8:9]
	s_cbranch_execz .LBB0_634
	s_waitcnt lgkmcnt(0)
	v_add_f32_e32 v18, v16, v17
	v_lshl_add_u64 v[16:17], s[20:21], 0, v[32:33]
	v_lshl_add_u64 v[16:17], s[54:55], 2, v[16:17]
	s_lshl_b32 s14, s63, 2
	v_lshl_add_u64 v[16:17], v[16:17], 0, s[14:15]
	global_store_dword v[16:17], v18, off
.LBB0_634:
	s_or_b64 exec, exec, s[56:57]
	v_add_u32_e32 v18, 0xb0, v148
	v_ashrrev_i32_e32 v19, 31, v18
	s_waitcnt lgkmcnt(0)
	v_lshlrev_b64 v[16:17], 7, v[18:19]
	v_lshl_add_u64 v[20:21], v[136:137], 0, v[16:17]
	global_load_dwordx4 v[22:25], v[20:21], off
	global_load_dwordx4 v[26:29], v[20:21], off offset:16
	v_lshlrev_b64 v[18:19], 11, v[18:19]
	v_lshl_add_u64 v[18:19], v[18:19], 0, v[146:147]
	v_lshlrev_b64 v[18:19], 1, v[18:19]
	v_lshl_add_u64 v[20:21], s[12:13], 0, v[18:19]
	global_load_dwordx4 v[30:33], v[20:21], off
	v_lshl_add_u64 v[20:21], s[22:23], 0, v[18:19]
	global_load_dwordx4 v[34:37], v[20:21], off
	v_lshl_add_u64 v[20:21], s[18:19], 0, v[18:19]
	v_or_b32_e32 v18, 0x100, v18
	v_lshl_add_u64 v[38:39], s[12:13], 0, v[18:19]
	s_waitcnt vmcnt(3)
	v_mov_b32_e32 v40, v22
	s_waitcnt vmcnt(2)
	v_mov_b32_e32 v41, v26
	v_mov_b32_e32 v26, v23
	v_mov_b32_e32 v22, v24
	v_mov_b32_e32 v23, v28
	v_mov_b32_e32 v28, v25
	v_pk_add_f32 v[24:25], v[40:41], v[26:27]
	v_pk_add_f32 v[22:23], v[22:23], v[28:29]
	s_waitcnt vmcnt(1)
	v_lshlrev_b32_e32 v26, 16, v31
	v_pk_add_f32 v[22:23], v[24:25], v[22:23]
	v_and_b32_e32 v27, 0xffff0000, v31
	v_add_f32_e32 v22, 0, v22
	v_add_f32_e32 v31, v22, v23
	v_mov_b32_e32 v40, v31
	s_nop 1
	v_permlane16_swap_b32_e32 v40, v31
	v_lshlrev_b32_e32 v28, 16, v32
	v_and_b32_e32 v29, 0xffff0000, v32
	v_lshlrev_b32_e32 v22, 16, v33
	v_and_b32_e32 v23, 0xffff0000, v33
	s_waitcnt lgkmcnt(0)
	v_add_f32_e32 v40, v31, v40
	v_mov_b32_e32 v41, v40
	s_nop 1
	v_permlane32_swap_b32_e32 v41, v40
	s_waitcnt vmcnt(0)
	v_lshlrev_b32_e32 v32, 16, v35
	v_and_b32_e32 v33, 0xffff0000, v35
	v_lshlrev_b32_e32 v24, 16, v30
	v_and_b32_e32 v25, 0xffff0000, v30
	s_waitcnt lgkmcnt(0)
	v_add_f32_e32 v35, v40, v41
	v_fmamk_f32 v35, v35, 0x3a000000, v163
	v_mul_f32_e32 v40, 0x4b800000, v35
	v_cmp_gt_f32_e32 vcc, s70, v35
	v_lshlrev_b32_e32 v30, 16, v34
	v_and_b32_e32 v31, 0xffff0000, v34
	v_cndmask_b32_e32 v35, v35, v40, vcc
	v_rsq_f32_e32 v40, v35
	v_lshlrev_b32_e32 v34, 16, v36
	v_and_b32_e32 v35, 0xffff0000, v36
	v_lshlrev_b32_e32 v36, 16, v37
	v_mul_f32_e32 v41, 0x45800000, v40
	v_cndmask_b32_e32 v40, v40, v41, vcc
	v_mul_f32_e32 v14, v14, v40
	v_mul_f32_e32 v15, v15, v40
	v_mul_f32_e32 v10, v10, v40
	v_mul_f32_e32 v11, v11, v40
	v_mul_f32_e32 v12, v12, v40
	v_mul_f32_e32 v13, v13, v40
	v_mul_f32_e32 v8, v8, v40
	v_mul_f32_e32 v9, v9, v40
	v_mul_f32_e32 v14, 0xbfb8aa3b, v14
	v_mul_f32_e32 v15, 0xbfb8aa3b, v15
	v_mul_f32_e32 v10, 0xbfb8aa3b, v10
	v_mul_f32_e32 v11, 0xbfb8aa3b, v11
	v_mul_f32_e32 v12, 0xbfb8aa3b, v12
	v_mul_f32_e32 v13, 0xbfb8aa3b, v13
	v_mul_f32_e32 v8, 0xbfb8aa3b, v8
	v_mul_f32_e32 v9, 0xbfb8aa3b, v9
	v_exp_f32_e32 v14, v14
	v_exp_f32_e32 v15, v15
	v_exp_f32_e32 v10, v10
	v_exp_f32_e32 v11, v11
	v_exp_f32_e32 v12, v12
	v_exp_f32_e32 v13, v13
	v_exp_f32_e32 v8, v8
	v_exp_f32_e32 v9, v9
	v_add_f32_e32 v14, 1.0, v14
	v_add_f32_e32 v15, 1.0, v15
	v_add_f32_e32 v43, 1.0, v10
	v_add_f32_e32 v44, 1.0, v11
	v_add_f32_e32 v12, 1.0, v12
	v_add_f32_e32 v13, 1.0, v13
	v_add_f32_e32 v41, 1.0, v8
	v_add_f32_e32 v42, 1.0, v9
	v_rcp_f32_e32 v10, v14
	v_rcp_f32_e32 v11, v15
	v_rcp_f32_e32 v14, v43
	v_rcp_f32_e32 v15, v44
	v_rcp_f32_e32 v8, v12
	v_rcp_f32_e32 v9, v13
	v_rcp_f32_e32 v12, v41
	v_rcp_f32_e32 v13, v42
	v_and_b32_e32 v37, 0xffff0000, v37
	v_pk_fma_f32 v[26:27], v[10:11], v[32:33], v[26:27]
	v_pk_fma_f32 v[32:33], v[14:15], v[36:37], v[22:23]
	v_lshl_add_u64 v[22:23], s[22:23], 0, v[18:19]
	v_pk_fma_f32 v[30:31], v[8:9], v[30:31], v[24:25]
	v_pk_fma_f32 v[28:29], v[12:13], v[34:35], v[28:29]
	v_cvt_pk_bf16_f32 v8, v30, v31
	v_cvt_pk_bf16_f32 v9, v26, v27
	v_mul_f32_e32 v4, v4, v40
	v_cvt_pk_bf16_f32 v10, v28, v29
	v_cvt_pk_bf16_f32 v11, v32, v33
	global_load_dwordx4 v[12:15], v[38:39], off
	v_mul_f32_e32 v5, v5, v40
	global_load_dwordx4 v[22:25], v[22:23], off
	v_mul_f32_e32 v6, v6, v40
	v_mul_f32_e32 v7, v7, v40
	v_mul_f32_e32 v0, v0, v40
	v_mul_f32_e32 v1, v1, v40
	v_mul_f32_e32 v2, v2, v40
	v_mul_f32_e32 v3, v3, v40
	v_mul_f32_e32 v4, 0xbfb8aa3b, v4
	v_mul_f32_e32 v5, 0xbfb8aa3b, v5
	v_mul_f32_e32 v6, 0xbfb8aa3b, v6
	v_mul_f32_e32 v7, 0xbfb8aa3b, v7
	v_mul_f32_e32 v0, 0xbfb8aa3b, v0
	v_mul_f32_e32 v1, 0xbfb8aa3b, v1
	v_mul_f32_e32 v2, 0xbfb8aa3b, v2
	v_mul_f32_e32 v3, 0xbfb8aa3b, v3
	v_exp_f32_e32 v4, v4
	v_exp_f32_e32 v5, v5
	v_exp_f32_e32 v6, v6
	v_exp_f32_e32 v7, v7
	v_exp_f32_e32 v0, v0
	v_exp_f32_e32 v1, v1
	v_exp_f32_e32 v2, v2
	v_exp_f32_e32 v3, v3
	v_add_f32_e32 v4, 1.0, v4
	v_add_f32_e32 v5, 1.0, v5
	v_add_f32_e32 v6, 1.0, v6
	v_add_f32_e32 v7, 1.0, v7
	v_add_f32_e32 v34, 1.0, v0
	v_add_f32_e32 v35, 1.0, v1
	v_add_f32_e32 v36, 1.0, v2
	v_add_f32_e32 v37, 1.0, v3
	v_rcp_f32_e32 v0, v4
	v_rcp_f32_e32 v1, v5
	v_rcp_f32_e32 v2, v6
	v_rcp_f32_e32 v3, v7
	v_rcp_f32_e32 v4, v34
	v_rcp_f32_e32 v5, v35
	v_rcp_f32_e32 v6, v36
	v_rcp_f32_e32 v7, v37
	v_mul_f32_e32 v31, v31, v31
	v_mul_f32_e32 v27, v27, v27
	v_mul_f32_e32 v29, v29, v29
	v_mul_f32_e32 v33, v33, v33
	v_fmac_f32_e32 v31, v30, v30
	v_fmac_f32_e32 v27, v26, v26
	v_fmac_f32_e32 v29, v28, v28
	v_fmac_f32_e32 v33, v32, v32
	v_add_f32_e32 v26, v31, v27
	v_add_f32_e32 v27, v29, v33
	v_add_f32_e32 v34, v26, v27
	global_store_dwordx4 v[20:21], v[8:11], off
	s_waitcnt vmcnt(2)
	v_lshlrev_b32_e32 v26, 16, v12
	v_and_b32_e32 v27, 0xffff0000, v12
	v_lshlrev_b32_e32 v12, 16, v13
	v_and_b32_e32 v13, 0xffff0000, v13
	v_lshlrev_b32_e32 v28, 16, v14
	v_and_b32_e32 v29, 0xffff0000, v14
	v_lshlrev_b32_e32 v14, 16, v15
	v_and_b32_e32 v15, 0xffff0000, v15
	s_waitcnt vmcnt(1)
	v_lshlrev_b32_e32 v30, 16, v22
	v_and_b32_e32 v31, 0xffff0000, v22
	v_lshlrev_b32_e32 v22, 16, v23
	v_and_b32_e32 v23, 0xffff0000, v23
	v_lshlrev_b32_e32 v32, 16, v24
	v_and_b32_e32 v33, 0xffff0000, v24
	v_lshlrev_b32_e32 v24, 16, v25
	v_and_b32_e32 v25, 0xffff0000, v25
	v_pk_fma_f32 v[12:13], v[2:3], v[22:23], v[12:13]
	v_pk_fma_f32 v[0:1], v[0:1], v[30:31], v[26:27]
	v_pk_fma_f32 v[6:7], v[6:7], v[24:25], v[14:15]
	v_pk_fma_f32 v[4:5], v[4:5], v[32:33], v[28:29]
	v_mul_f32_e32 v2, v1, v1
	v_mul_f32_e32 v3, v13, v13
	v_mul_f32_e32 v14, v5, v5
	v_mul_f32_e32 v15, v7, v7
	v_fmac_f32_e32 v2, v0, v0
	v_fmac_f32_e32 v3, v12, v12
	v_fmac_f32_e32 v14, v4, v4
	v_fmac_f32_e32 v15, v6, v6
	v_add_f32_e32 v2, v2, v3
	v_add_f32_e32 v3, v14, v15
	v_add_f32_e32 v2, v2, v3
	v_add_f32_e32 v14, v34, v2
	v_mov_b32_e32 v15, v14
	s_nop 1
	v_permlane16_swap_b32_e32 v15, v14
	v_cvt_pk_bf16_f32 v2, v0, v1
	v_cvt_pk_bf16_f32 v3, v12, v13
	v_cvt_pk_bf16_f32 v4, v4, v5
	v_cvt_pk_bf16_f32 v5, v6, v7
	s_waitcnt lgkmcnt(0)
	v_add_f32_e32 v0, v14, v15
	v_mov_b32_e32 v1, v0
	s_nop 1
	v_permlane32_swap_b32_e32 v1, v0
	v_lshl_add_u64 v[6:7], s[18:19], 0, v[18:19]
	global_store_dwordx4 v[6:7], v[2:5], off
	s_and_saveexec_b64 s[56:57], s[8:9]
	s_cbranch_execz .LBB0_636
	s_waitcnt lgkmcnt(0)
	v_add_f32_e32 v2, v0, v1
	v_lshl_add_u64 v[0:1], s[20:21], 0, v[16:17]
	v_lshl_add_u64 v[0:1], s[54:55], 2, v[0:1]
	s_lshl_b32 s14, s63, 2
	v_lshl_add_u64 v[0:1], v[0:1], 0, s[14:15]
	global_store_dword v[0:1], v2, off

.LBB0_734:
	v_lshl_add_u32 v146, s26, 8, v150
	v_ashrrev_i32_e32 v147, 31, v146
	v_lshlrev_b64 v[148:149], 7, v[146:147]
	v_lshl_add_u64 v[148:149], v[136:137], 0, v[148:149]
	global_load_dwordx4 v[160:163], v[148:149], off
	global_load_dwordx4 v[164:167], v[148:149], off offset:16
	v_and_b32_e32 v149, 64, v156
	v_xor_b32_e32 v158, 16, v156
	v_add_u32_e32 v170, 64, v149
	v_cmp_lt_i32_e32 vcc, v158, v170
	v_xor_b32_e32 v159, 32, v156
	v_lshl_or_b32 v148, s58, 8, v152
	v_cndmask_b32_e32 v158, v156, v158, vcc
	v_lshlrev_b32_e32 v158, 2, v158
	v_cmp_lt_i32_e32 vcc, v159, v170
	v_ashrrev_i32_e32 v149, 31, v148
	v_lshlrev_b64 v[148:149], 1, v[148:149]
	v_cndmask_b32_e32 v159, v156, v159, vcc
	v_lshlrev_b32_e32 v159, 2, v159
	s_waitcnt vmcnt(0)
	v_mov_b32_e32 v168, v160
	v_mov_b32_e32 v169, v164
	v_mov_b32_e32 v164, v161
	v_mov_b32_e32 v160, v162
	v_mov_b32_e32 v161, v166
	v_mov_b32_e32 v166, v163
	v_pk_add_f32 v[162:163], v[168:169], v[164:165]
	v_pk_add_f32 v[160:161], v[160:161], v[166:167]
	s_nop 0
	v_pk_add_f32 v[160:161], v[162:163], v[160:161]
	s_nop 0
	v_add_f32_e32 v160, 0, v160
	v_add_f32_e32 v161, v160, v161
	v_mov_b32_e32 v162, v161
	s_nop 1
	v_permlane16_swap_b32_e32 v162, v161
	v_or_b32_e32 v160, 16, v146
	s_waitcnt lgkmcnt(0)
	v_add_f32_e32 v164, v161, v162
	v_mov_b32_e32 v165, v164
	s_nop 1
	v_permlane32_swap_b32_e32 v165, v164
	v_lshlrev_b64 v[162:163], 12, v[146:147]
	v_lshl_add_u64 v[162:163], s[12:13], 0, v[162:163]
	v_ashrrev_i32_e32 v161, 31, v160
	v_lshl_add_u64 v[162:163], v[162:163], 0, v[148:149]
	s_waitcnt lgkmcnt(0)
	v_add_f32_e32 v147, v164, v165
	v_fmamk_f32 v147, v147, 0x3a000000, v157
	v_mul_f32_e32 v164, 0x4b800000, v147
	v_cmp_gt_f32_e32 vcc, s57, v147
	s_nop 1
	v_cndmask_b32_e32 v147, v147, v164, vcc
	v_rsq_f32_e32 v147, v147
	v_lshlrev_b64 v[164:165], 7, v[160:161]
	v_lshl_add_u64 v[164:165], v[136:137], 0, v[164:165]
	v_mul_f32_e32 v166, 0x45800000, v147
	v_cndmask_b32_e32 v166, v147, v166, vcc
	v_pk_mul_f32 v[126:127], v[126:127], v[166:167] op_sel_hi:[1,0]
	v_pk_mul_f32 v[124:125], v[124:125], v[166:167] op_sel_hi:[1,0]
	v_pk_mul_f32 v[122:123], v[122:123], v[166:167] op_sel_hi:[1,0]
	v_pk_mul_f32 v[120:121], v[120:121], v[166:167] op_sel_hi:[1,0]
	v_pk_mul_f32 v[118:119], v[118:119], v[166:167] op_sel_hi:[1,0]
	v_pk_mul_f32 v[116:117], v[116:117], v[166:167] op_sel_hi:[1,0]
	v_pk_mul_f32 v[168:169], v[114:115], v[166:167] op_sel_hi:[1,0]
	v_pk_mul_f32 v[166:167], v[112:113], v[166:167] op_sel_hi:[1,0]
	v_cvt_pk_bf16_f32 v112, v124, v125
	v_cvt_pk_bf16_f32 v113, v126, v127
	v_cvt_pk_bf16_f32 v114, v120, v121
	v_cvt_pk_bf16_f32 v115, v122, v123
	global_store_dwordx4 v[162:163], v[112:115], off
	s_nop 1
	v_cvt_pk_bf16_f32 v112, v116, v117
	v_cvt_pk_bf16_f32 v113, v118, v119
	v_cvt_pk_bf16_f32 v114, v166, v167
	v_cvt_pk_bf16_f32 v115, v168, v169
	global_store_dwordx4 v[162:163], v[112:115], off offset:256
	global_load_dwordx4 v[112:115], v[164:165], off
	global_load_dwordx4 v[116:119], v[164:165], off offset:16
	s_waitcnt vmcnt(1)
	v_mov_b32_e32 v120, v112
	s_waitcnt vmcnt(0)
	v_mov_b32_e32 v121, v116
	v_mov_b32_e32 v116, v113
	v_mov_b32_e32 v112, v114
	v_mov_b32_e32 v113, v118
	v_mov_b32_e32 v118, v115
	v_pk_add_f32 v[114:115], v[120:121], v[116:117]
	v_pk_add_f32 v[112:113], v[112:113], v[118:119]
	s_nop 0
	v_pk_add_f32 v[112:113], v[114:115], v[112:113]
	v_lshlrev_b64 v[114:115], 12, v[160:161]
	v_add_f32_e32 v112, 0, v112
	v_add_f32_e32 v112, v112, v113
	v_mov_b32_e32 v113, v112
	s_nop 1
	v_permlane16_swap_b32_e32 v113, v112
	v_lshl_add_u64 v[114:115], s[12:13], 0, v[114:115]
	v_lshl_add_u64 v[114:115], v[114:115], 0, v[148:149]
	s_waitcnt lgkmcnt(0)
	v_add_f32_e32 v118, v112, v113
	v_mov_b32_e32 v119, v118
	s_nop 1
	v_permlane32_swap_b32_e32 v119, v118
	v_or_b32_e32 v112, 32, v146
	v_ashrrev_i32_e32 v113, 31, v112
	v_lshlrev_b64 v[116:117], 7, v[112:113]
	v_lshl_add_u64 v[116:117], v[136:137], 0, v[116:117]
	s_waitcnt lgkmcnt(0)
	v_add_f32_e32 v118, v118, v119
	v_fmamk_f32 v118, v118, 0x3a000000, v157
	v_mul_f32_e32 v119, 0x4b800000, v118
	v_cmp_gt_f32_e32 vcc, s57, v118
	s_nop 1
	v_cndmask_b32_e32 v118, v118, v119, vcc
	v_rsq_f32_e32 v118, v118
	s_nop 0
	v_mul_f32_e32 v119, 0x45800000, v118
	v_cndmask_b32_e32 v118, v118, v119, vcc
	v_pk_mul_f32 v[110:111], v[110:111], v[118:119] op_sel_hi:[1,0]
	v_pk_mul_f32 v[108:109], v[108:109], v[118:119] op_sel_hi:[1,0]
	v_pk_mul_f32 v[106:107], v[106:107], v[118:119] op_sel_hi:[1,0]
	v_pk_mul_f32 v[104:105], v[104:105], v[118:119] op_sel_hi:[1,0]
	v_pk_mul_f32 v[102:103], v[102:103], v[118:119] op_sel_hi:[1,0]
	v_pk_mul_f32 v[100:101], v[100:101], v[118:119] op_sel_hi:[1,0]
	v_pk_mul_f32 v[120:121], v[98:99], v[118:119] op_sel_hi:[1,0]
	v_pk_mul_f32 v[118:119], v[96:97], v[118:119] op_sel_hi:[1,0]
	v_cvt_pk_bf16_f32 v96, v108, v109
	v_cvt_pk_bf16_f32 v97, v110, v111
	v_cvt_pk_bf16_f32 v98, v104, v105
	v_cvt_pk_bf16_f32 v99, v106, v107
	global_store_dwordx4 v[114:115], v[96:99], off
	s_nop 1
	v_cvt_pk_bf16_f32 v96, v100, v101
	v_cvt_pk_bf16_f32 v97, v102, v103
	v_cvt_pk_bf16_f32 v98, v118, v119
	v_cvt_pk_bf16_f32 v99, v120, v121
	global_store_dwordx4 v[114:115], v[96:99], off offset:256
	global_load_dwordx4 v[96:99], v[116:117], off
	global_load_dwordx4 v[100:103], v[116:117], off offset:16
	s_waitcnt vmcnt(1)
	v_mov_b32_e32 v104, v96
	s_waitcnt vmcnt(0)
	v_mov_b32_e32 v105, v100
	v_mov_b32_e32 v100, v97
	v_mov_b32_e32 v96, v98
	v_mov_b32_e32 v97, v102
	v_mov_b32_e32 v102, v99
	v_pk_add_f32 v[98:99], v[104:105], v[100:101]
	v_pk_add_f32 v[96:97], v[96:97], v[102:103]
	s_nop 0
	v_pk_add_f32 v[96:97], v[98:99], v[96:97]
	v_lshlrev_b64 v[98:99], 12, v[112:113]
	v_add_f32_e32 v96, 0, v96
	v_add_f32_e32 v96, v96, v97
	v_mov_b32_e32 v97, v96
	s_nop 1
	v_permlane16_swap_b32_e32 v97, v96
	v_lshl_add_u64 v[98:99], s[12:13], 0, v[98:99]
	v_lshl_add_u64 v[98:99], v[98:99], 0, v[148:149]
	s_waitcnt lgkmcnt(0)
	v_add_f32_e32 v102, v96, v97
	v_mov_b32_e32 v103, v102
	s_nop 1
	v_permlane32_swap_b32_e32 v103, v102
	v_or_b32_e32 v96, 48, v146
	v_ashrrev_i32_e32 v97, 31, v96
	v_lshlrev_b64 v[100:101], 7, v[96:97]
	v_lshl_add_u64 v[100:101], v[136:137], 0, v[100:101]
	s_waitcnt lgkmcnt(0)
	v_add_f32_e32 v102, v102, v103
	v_fmamk_f32 v102, v102, 0x3a000000, v157
	v_mul_f32_e32 v103, 0x4b800000, v102
	v_cmp_gt_f32_e32 vcc, s57, v102
	s_nop 1
	v_cndmask_b32_e32 v102, v102, v103, vcc
	v_rsq_f32_e32 v102, v102
	s_nop 0
	v_mul_f32_e32 v103, 0x45800000, v102
	v_cndmask_b32_e32 v102, v102, v103, vcc
	v_pk_mul_f32 v[94:95], v[94:95], v[102:103] op_sel_hi:[1,0]
	v_pk_mul_f32 v[92:93], v[92:93], v[102:103] op_sel_hi:[1,0]
	v_pk_mul_f32 v[90:91], v[90:91], v[102:103] op_sel_hi:[1,0]
	v_pk_mul_f32 v[88:89], v[88:89], v[102:103] op_sel_hi:[1,0]
	v_pk_mul_f32 v[86:87], v[86:87], v[102:103] op_sel_hi:[1,0]
	v_pk_mul_f32 v[84:85], v[84:85], v[102:103] op_sel_hi:[1,0]
	v_pk_mul_f32 v[104:105], v[82:83], v[102:103] op_sel_hi:[1,0]
	v_pk_mul_f32 v[102:103], v[80:81], v[102:103] op_sel_hi:[1,0]
	v_cvt_pk_bf16_f32 v80, v92, v93
	v_cvt_pk_bf16_f32 v81, v94, v95
	v_cvt_pk_bf16_f32 v82, v88, v89
	v_cvt_pk_bf16_f32 v83, v90, v91
	global_store_dwordx4 v[98:99], v[80:83], off
	s_nop 1
	v_cvt_pk_bf16_f32 v80, v84, v85
	v_cvt_pk_bf16_f32 v81, v86, v87
	v_cvt_pk_bf16_f32 v82, v102, v103
	v_cvt_pk_bf16_f32 v83, v104, v105
	global_store_dwordx4 v[98:99], v[80:83], off offset:256
	global_load_dwordx4 v[80:83], v[100:101], off
	global_load_dwordx4 v[84:87], v[100:101], off offset:16
	s_waitcnt vmcnt(1)
	v_mov_b32_e32 v88, v80
	s_waitcnt vmcnt(0)
	v_mov_b32_e32 v89, v84
	v_mov_b32_e32 v84, v81
	v_mov_b32_e32 v80, v82
	v_mov_b32_e32 v81, v86
	v_mov_b32_e32 v86, v83
	v_pk_add_f32 v[82:83], v[88:89], v[84:85]
	v_pk_add_f32 v[80:81], v[80:81], v[86:87]
	s_nop 0
	v_pk_add_f32 v[80:81], v[82:83], v[80:81]
	v_lshlrev_b64 v[82:83], 12, v[96:97]
	v_add_f32_e32 v80, 0, v80
	v_add_f32_e32 v80, v80, v81
	v_mov_b32_e32 v81, v80
	s_nop 1
	v_permlane16_swap_b32_e32 v81, v80
	v_lshl_add_u64 v[82:83], s[12:13], 0, v[82:83]
	v_lshl_add_u64 v[82:83], v[82:83], 0, v[148:149]
	s_waitcnt lgkmcnt(0)
	v_add_f32_e32 v86, v80, v81
	v_mov_b32_e32 v87, v86
	s_nop 1
	v_permlane32_swap_b32_e32 v87, v86
	v_add_u32_e32 v80, 0x80, v146
	v_ashrrev_i32_e32 v81, 31, v80
	v_lshlrev_b64 v[84:85], 7, v[80:81]
	v_lshl_add_u64 v[84:85], v[136:137], 0, v[84:85]
	s_waitcnt lgkmcnt(0)
	v_add_f32_e32 v86, v86, v87
	v_fmamk_f32 v86, v86, 0x3a000000, v157
	v_mul_f32_e32 v87, 0x4b800000, v86
	v_cmp_gt_f32_e32 vcc, s57, v86
	s_nop 1
	v_cndmask_b32_e32 v86, v86, v87, vcc
	v_rsq_f32_e32 v86, v86
	s_nop 0
	v_mul_f32_e32 v87, 0x45800000, v86
	v_cndmask_b32_e32 v86, v86, v87, vcc
	v_pk_mul_f32 v[78:79], v[78:79], v[86:87] op_sel_hi:[1,0]
	v_pk_mul_f32 v[76:77], v[76:77], v[86:87] op_sel_hi:[1,0]
	v_pk_mul_f32 v[74:75], v[74:75], v[86:87] op_sel_hi:[1,0]
	v_pk_mul_f32 v[72:73], v[72:73], v[86:87] op_sel_hi:[1,0]
	v_pk_mul_f32 v[70:71], v[70:71], v[86:87] op_sel_hi:[1,0]
	v_pk_mul_f32 v[68:69], v[68:69], v[86:87] op_sel_hi:[1,0]
	v_pk_mul_f32 v[88:89], v[66:67], v[86:87] op_sel_hi:[1,0]
	v_pk_mul_f32 v[86:87], v[64:65], v[86:87] op_sel_hi:[1,0]
	v_cvt_pk_bf16_f32 v64, v76, v77
	v_cvt_pk_bf16_f32 v65, v78, v79
	v_cvt_pk_bf16_f32 v66, v72, v73
	v_cvt_pk_bf16_f32 v67, v74, v75
	global_store_dwordx4 v[82:83], v[64:67], off
	s_nop 1
	v_cvt_pk_bf16_f32 v64, v68, v69
	v_cvt_pk_bf16_f32 v65, v70, v71
	v_cvt_pk_bf16_f32 v66, v86, v87
	v_cvt_pk_bf16_f32 v67, v88, v89
	global_store_dwordx4 v[82:83], v[64:67], off offset:256
	global_load_dwordx4 v[64:67], v[84:85], off
	global_load_dwordx4 v[68:71], v[84:85], off offset:16
	s_waitcnt vmcnt(1)
	v_mov_b32_e32 v72, v64
	s_waitcnt vmcnt(0)
	v_mov_b32_e32 v73, v68
	v_mov_b32_e32 v68, v65
	v_mov_b32_e32 v64, v66
	v_mov_b32_e32 v65, v70
	v_mov_b32_e32 v70, v67
	v_pk_add_f32 v[66:67], v[72:73], v[68:69]
	v_pk_add_f32 v[64:65], v[64:65], v[70:71]
	s_nop 0
	v_pk_add_f32 v[64:65], v[66:67], v[64:65]
	v_lshlrev_b64 v[66:67], 12, v[80:81]
	v_add_f32_e32 v64, 0, v64
	v_add_f32_e32 v64, v64, v65
	v_mov_b32_e32 v65, v64
	s_nop 1
	v_permlane16_swap_b32_e32 v65, v64
	v_lshl_add_u64 v[66:67], s[12:13], 0, v[66:67]
	v_lshl_add_u64 v[66:67], v[66:67], 0, v[148:149]
	s_waitcnt lgkmcnt(0)
	v_add_f32_e32 v70, v64, v65
	v_mov_b32_e32 v71, v70
	s_nop 1
	v_permlane32_swap_b32_e32 v71, v70
	v_add_u32_e32 v64, 0x90, v146
	v_ashrrev_i32_e32 v65, 31, v64
	v_lshlrev_b64 v[68:69], 7, v[64:65]
	v_lshl_add_u64 v[68:69], v[136:137], 0, v[68:69]
	s_waitcnt lgkmcnt(0)
	v_add_f32_e32 v70, v70, v71
	v_fmamk_f32 v70, v70, 0x3a000000, v157
	v_mul_f32_e32 v71, 0x4b800000, v70
	v_cmp_gt_f32_e32 vcc, s57, v70
	s_nop 1
	v_cndmask_b32_e32 v70, v70, v71, vcc
	v_rsq_f32_e32 v70, v70
	s_nop 0
	v_mul_f32_e32 v71, 0x45800000, v70
	v_cndmask_b32_e32 v70, v70, v71, vcc
	v_pk_mul_f32 v[62:63], v[62:63], v[70:71] op_sel_hi:[1,0]
	v_pk_mul_f32 v[60:61], v[60:61], v[70:71] op_sel_hi:[1,0]
	v_pk_mul_f32 v[58:59], v[58:59], v[70:71] op_sel_hi:[1,0]
	v_pk_mul_f32 v[56:57], v[56:57], v[70:71] op_sel_hi:[1,0]
	v_pk_mul_f32 v[54:55], v[54:55], v[70:71] op_sel_hi:[1,0]
	v_pk_mul_f32 v[52:53], v[52:53], v[70:71] op_sel_hi:[1,0]
	v_pk_mul_f32 v[72:73], v[50:51], v[70:71] op_sel_hi:[1,0]
	v_pk_mul_f32 v[70:71], v[48:49], v[70:71] op_sel_hi:[1,0]
	v_cvt_pk_bf16_f32 v48, v60, v61
	v_cvt_pk_bf16_f32 v49, v62, v63
	v_cvt_pk_bf16_f32 v50, v56, v57
	v_cvt_pk_bf16_f32 v51, v58, v59
	global_store_dwordx4 v[66:67], v[48:51], off
	s_nop 1
	v_cvt_pk_bf16_f32 v48, v52, v53
	v_cvt_pk_bf16_f32 v49, v54, v55
	v_cvt_pk_bf16_f32 v50, v70, v71
	v_cvt_pk_bf16_f32 v51, v72, v73
	global_store_dwordx4 v[66:67], v[48:51], off offset:256
	global_load_dwordx4 v[48:51], v[68:69], off
	global_load_dwordx4 v[52:55], v[68:69], off offset:16
	s_waitcnt vmcnt(1)
	v_mov_b32_e32 v56, v48
	s_waitcnt vmcnt(0)
	v_mov_b32_e32 v57, v52
	v_mov_b32_e32 v52, v49
	v_mov_b32_e32 v48, v50
	v_mov_b32_e32 v49, v54
	v_mov_b32_e32 v54, v51
	v_pk_add_f32 v[50:51], v[56:57], v[52:53]
	v_pk_add_f32 v[48:49], v[48:49], v[54:55]
	s_nop 0
	v_pk_add_f32 v[48:49], v[50:51], v[48:49]
	v_lshlrev_b64 v[50:51], 12, v[64:65]
	v_add_f32_e32 v48, 0, v48
	v_add_f32_e32 v48, v48, v49
	v_mov_b32_e32 v49, v48
	s_nop 1
	v_permlane16_swap_b32_e32 v49, v48
	v_lshl_add_u64 v[50:51], s[12:13], 0, v[50:51]
	v_lshl_add_u64 v[50:51], v[50:51], 0, v[148:149]
	s_waitcnt lgkmcnt(0)
	v_add_f32_e32 v54, v48, v49
	v_mov_b32_e32 v55, v54
	s_nop 1
	v_permlane32_swap_b32_e32 v55, v54
	v_add_u32_e32 v48, 0xa0, v146
	v_ashrrev_i32_e32 v49, 31, v48
	v_lshlrev_b64 v[52:53], 7, v[48:49]
	v_lshl_add_u64 v[52:53], v[136:137], 0, v[52:53]
	s_waitcnt lgkmcnt(0)
	v_add_f32_e32 v54, v54, v55
	v_fmamk_f32 v54, v54, 0x3a000000, v157
	v_mul_f32_e32 v55, 0x4b800000, v54
	v_cmp_gt_f32_e32 vcc, s57, v54
	s_nop 1
	v_cndmask_b32_e32 v54, v54, v55, vcc
	v_rsq_f32_e32 v54, v54
	s_nop 0
	v_mul_f32_e32 v55, 0x45800000, v54
	v_cndmask_b32_e32 v54, v54, v55, vcc
	v_pk_mul_f32 v[46:47], v[46:47], v[54:55] op_sel_hi:[1,0]
	v_pk_mul_f32 v[44:45], v[44:45], v[54:55] op_sel_hi:[1,0]
	v_pk_mul_f32 v[42:43], v[42:43], v[54:55] op_sel_hi:[1,0]
	v_pk_mul_f32 v[40:41], v[40:41], v[54:55] op_sel_hi:[1,0]
	v_pk_mul_f32 v[38:39], v[38:39], v[54:55] op_sel_hi:[1,0]
	v_pk_mul_f32 v[36:37], v[36:37], v[54:55] op_sel_hi:[1,0]
	v_pk_mul_f32 v[56:57], v[34:35], v[54:55] op_sel_hi:[1,0]
	v_pk_mul_f32 v[54:55], v[32:33], v[54:55] op_sel_hi:[1,0]
	v_cvt_pk_bf16_f32 v32, v44, v45
	v_cvt_pk_bf16_f32 v33, v46, v47
	v_cvt_pk_bf16_f32 v34, v40, v41
	v_cvt_pk_bf16_f32 v35, v42, v43
	global_store_dwordx4 v[50:51], v[32:35], off
	s_nop 1
	v_cvt_pk_bf16_f32 v32, v36, v37
	v_cvt_pk_bf16_f32 v33, v38, v39
	v_cvt_pk_bf16_f32 v34, v54, v55
	v_cvt_pk_bf16_f32 v35, v56, v57
	global_store_dwordx4 v[50:51], v[32:35], off offset:256
	global_load_dwordx4 v[32:35], v[52:53], off
	global_load_dwordx4 v[36:39], v[52:53], off offset:16
	s_waitcnt vmcnt(1)
	v_mov_b32_e32 v40, v32
	s_waitcnt vmcnt(0)
	v_mov_b32_e32 v41, v36
	v_mov_b32_e32 v36, v33
	v_mov_b32_e32 v32, v34
	v_mov_b32_e32 v33, v38
	v_mov_b32_e32 v38, v35
	v_pk_add_f32 v[34:35], v[40:41], v[36:37]
	v_pk_add_f32 v[32:33], v[32:33], v[38:39]
	s_nop 0
	v_pk_add_f32 v[32:33], v[34:35], v[32:33]
	v_lshlrev_b64 v[34:35], 12, v[48:49]
	v_add_f32_e32 v32, 0, v32
	v_add_f32_e32 v32, v32, v33
	v_mov_b32_e32 v33, v32
	s_nop 1
	v_permlane16_swap_b32_e32 v33, v32
	v_lshl_add_u64 v[34:35], s[12:13], 0, v[34:35]
	v_lshl_add_u64 v[34:35], v[34:35], 0, v[148:149]
	s_waitcnt lgkmcnt(0)
	v_add_f32_e32 v38, v32, v33
	v_mov_b32_e32 v39, v38
	s_nop 1
	v_permlane32_swap_b32_e32 v39, v38
	v_add_u32_e32 v32, 0xb0, v146
	v_ashrrev_i32_e32 v33, 31, v32
	v_lshlrev_b64 v[36:37], 7, v[32:33]
	v_lshl_add_u64 v[36:37], v[136:137], 0, v[36:37]
	s_waitcnt lgkmcnt(0)
	v_add_f32_e32 v38, v38, v39
	v_fmamk_f32 v38, v38, 0x3a000000, v157
	v_mul_f32_e32 v39, 0x4b800000, v38
	v_cmp_gt_f32_e32 vcc, s57, v38
	s_nop 1
	v_cndmask_b32_e32 v38, v38, v39, vcc
	v_rsq_f32_e32 v38, v38
	s_nop 0
	v_mul_f32_e32 v39, 0x45800000, v38
	v_cndmask_b32_e32 v38, v38, v39, vcc
	v_pk_mul_f32 v[30:31], v[30:31], v[38:39] op_sel_hi:[1,0]
	v_pk_mul_f32 v[28:29], v[28:29], v[38:39] op_sel_hi:[1,0]
	v_pk_mul_f32 v[26:27], v[26:27], v[38:39] op_sel_hi:[1,0]
	v_pk_mul_f32 v[24:25], v[24:25], v[38:39] op_sel_hi:[1,0]
	v_pk_mul_f32 v[22:23], v[22:23], v[38:39] op_sel_hi:[1,0]
	v_pk_mul_f32 v[20:21], v[20:21], v[38:39] op_sel_hi:[1,0]
	v_pk_mul_f32 v[40:41], v[18:19], v[38:39] op_sel_hi:[1,0]
	v_pk_mul_f32 v[38:39], v[16:17], v[38:39] op_sel_hi:[1,0]
	v_cvt_pk_bf16_f32 v16, v28, v29
	v_cvt_pk_bf16_f32 v17, v30, v31
	v_cvt_pk_bf16_f32 v18, v24, v25
	v_cvt_pk_bf16_f32 v19, v26, v27
	global_store_dwordx4 v[34:35], v[16:19], off
	s_nop 1
	v_cvt_pk_bf16_f32 v16, v20, v21
	v_cvt_pk_bf16_f32 v17, v22, v23
	v_cvt_pk_bf16_f32 v18, v38, v39
	v_cvt_pk_bf16_f32 v19, v40, v41
	global_store_dwordx4 v[34:35], v[16:19], off offset:256
	global_load_dwordx4 v[16:19], v[36:37], off
	global_load_dwordx4 v[20:23], v[36:37], off offset:16
	s_waitcnt vmcnt(1)
	v_mov_b32_e32 v24, v16
	s_waitcnt vmcnt(0)
	v_mov_b32_e32 v25, v20
	v_mov_b32_e32 v20, v17
	v_mov_b32_e32 v16, v18
	v_mov_b32_e32 v17, v22
	v_mov_b32_e32 v22, v19
	v_pk_add_f32 v[18:19], v[24:25], v[20:21]
	v_pk_add_f32 v[16:17], v[16:17], v[22:23]
	s_nop 0
	v_pk_add_f32 v[16:17], v[18:19], v[16:17]
	s_nop 0
	v_add_f32_e32 v16, 0, v16
	v_add_f32_e32 v16, v16, v17
	v_mov_b32_e32 v17, v16
	s_nop 1
	v_permlane16_swap_b32_e32 v17, v16
	s_waitcnt lgkmcnt(0)
	v_add_f32_e32 v16, v16, v17
	v_mov_b32_e32 v17, v16
	s_nop 1
	v_permlane32_swap_b32_e32 v17, v16
	s_waitcnt lgkmcnt(0)
	v_add_f32_e32 v16, v16, v17
	v_fmamk_f32 v16, v16, 0x3a000000, v157
	v_mul_f32_e32 v17, 0x4b800000, v16
	v_cmp_gt_f32_e32 vcc, s57, v16
	s_nop 1
	v_cndmask_b32_e32 v16, v16, v17, vcc
	v_rsq_f32_e32 v18, v16
	v_lshlrev_b64 v[16:17], 12, v[32:33]
	v_lshl_add_u64 v[16:17], s[12:13], 0, v[16:17]
	v_lshl_add_u64 v[16:17], v[16:17], 0, v[148:149]
	v_mul_f32_e32 v19, 0x45800000, v18
	v_cndmask_b32_e32 v18, v18, v19, vcc
	v_pk_mul_f32 v[14:15], v[14:15], v[18:19] op_sel_hi:[1,0]
	v_pk_mul_f32 v[12:13], v[12:13], v[18:19] op_sel_hi:[1,0]
	v_pk_mul_f32 v[10:11], v[10:11], v[18:19] op_sel_hi:[1,0]
	v_pk_mul_f32 v[8:9], v[8:9], v[18:19] op_sel_hi:[1,0]
	v_pk_mul_f32 v[6:7], v[6:7], v[18:19] op_sel_hi:[1,0]
	v_pk_mul_f32 v[4:5], v[4:5], v[18:19] op_sel_hi:[1,0]
	v_pk_mul_f32 v[20:21], v[2:3], v[18:19] op_sel_hi:[1,0]
	v_pk_mul_f32 v[18:19], v[0:1], v[18:19] op_sel_hi:[1,0]
	v_cvt_pk_bf16_f32 v0, v12, v13
	v_cvt_pk_bf16_f32 v1, v14, v15
	v_cvt_pk_bf16_f32 v2, v8, v9
	v_cvt_pk_bf16_f32 v3, v10, v11
	global_store_dwordx4 v[16:17], v[0:3], off
	s_andn2_b64 vcc, exec, s[8:9]
	s_mov_b64 s[8:9], -1
	v_cvt_pk_bf16_f32 v0, v4, v5
	v_cvt_pk_bf16_f32 v1, v6, v7
	v_cvt_pk_bf16_f32 v2, v18, v19
	v_cvt_pk_bf16_f32 v3, v20, v21
	global_store_dwordx4 v[16:17], v[0:3], off offset:256
	s_cbranch_vccnz .LBB0_723
	s_andn2_b64 vcc, exec, s[10:11]
	s_cbranch_vccnz .LBB0_722
	s_barrier
	s_branch .LBB0_722

.LBB0_955:
	v_lshl_add_u32 v146, s36, 8, v148
	v_lshl_or_b32 v144, s12, 7, v150
	v_ashrrev_i32_e32 v147, 31, v146
	v_ashrrev_i32_e32 v145, 31, v144
	v_lshlrev_b64 v[156:157], 11, v[146:147]
	v_lshl_add_u64 v[156:157], v[156:157], 0, v[144:145]
	v_lshlrev_b64 v[160:161], 1, v[156:157]
	v_lshl_add_u64 v[156:157], s[16:17], 0, v[160:161]
	global_load_dwordx4 v[156:159], v[156:157], off
	v_mul_f32_e32 v125, 0xbfb8aa3b, v125
	v_mul_f32_e32 v124, 0xbfb8aa3b, v124
	v_mul_f32_e32 v120, 0xbfb8aa3b, v120
	v_exp_f32_e32 v125, v125
	v_mul_f32_e32 v126, 0xbfb8aa3b, v126
	v_exp_f32_e32 v124, v124
	v_exp_f32_e32 v164, v120
	v_mul_f32_e32 v127, 0xbfb8aa3b, v127
	v_and_b32_e32 v162, 64, v154
	v_exp_f32_e32 v126, v126
	v_xor_b32_e32 v155, 16, v154
	v_exp_f32_e32 v127, v127
	v_add_u32_e32 v162, 64, v162
	v_mul_f32_e32 v121, 0xbfb8aa3b, v121
	v_cmp_lt_i32_e32 vcc, v155, v162
	v_add_f32_e32 v125, 1.0, v125
	v_mul_f32_e32 v122, 0xbfb8aa3b, v122
	v_exp_f32_e32 v121, v121
	v_cndmask_b32_e32 v120, v154, v155, vcc
	v_add_f32_e32 v124, 1.0, v124
	v_add_f32_e32 v155, 1.0, v164
	v_rcp_f32_e32 v125, v125
	v_mul_f32_e32 v123, 0xbfb8aa3b, v123
	v_exp_f32_e32 v122, v122
	v_add_f32_e32 v126, 1.0, v126
	v_rcp_f32_e32 v124, v124
	v_rcp_f32_e32 v155, v155
	v_exp_f32_e32 v123, v123
	v_add_f32_e32 v127, 1.0, v127
	v_rcp_f32_e32 v126, v126
	v_rcp_f32_e32 v127, v127
	v_add_f32_e32 v121, 1.0, v121
	v_add_f32_e32 v122, 1.0, v122
	v_rcp_f32_e32 v121, v121
	v_add_f32_e32 v123, 1.0, v123
	v_rcp_f32_e32 v122, v122
	v_rcp_f32_e32 v123, v123
	v_lshlrev_b32_e32 v120, 2, v120
	v_xor_b32_e32 v163, 32, v154
	v_cmp_lt_i32_e32 vcc, v163, v162
	s_lshl_b32 s36, s12, 2
	s_ashr_i32 s37, s36, 31
	s_waitcnt vmcnt(0)
	v_lshlrev_b32_e32 v164, 16, v156
	v_and_b32_e32 v156, 0xffff0000, v156
	v_lshlrev_b32_e32 v166, 16, v158
	v_fmac_f32_e32 v156, v117, v125
	v_lshlrev_b32_e32 v165, 16, v157
	v_fmac_f32_e32 v164, v116, v124
	v_fmac_f32_e32 v166, v112, v155
	v_mul_f32_e32 v112, v156, v156
	v_and_b32_e32 v157, 0xffff0000, v157
	v_fmac_f32_e32 v165, v118, v126
	v_fmac_f32_e32 v112, v164, v164
	v_fmac_f32_e32 v157, v119, v127
	v_fmac_f32_e32 v112, v165, v165
	v_and_b32_e32 v158, 0xffff0000, v158
	v_fmac_f32_e32 v112, v157, v157
	v_lshlrev_b32_e32 v167, 16, v159
	v_fmac_f32_e32 v158, v113, v121
	v_fmac_f32_e32 v112, v166, v166
	v_and_b32_e32 v159, 0xffff0000, v159
	v_fmac_f32_e32 v167, v114, v122
	v_fmac_f32_e32 v112, v158, v158
	v_fmac_f32_e32 v159, v115, v123
	v_fmac_f32_e32 v112, v167, v167
	v_fmac_f32_e32 v112, v159, v159
	v_mov_b32_e32 v113, v112
	s_nop 1
	v_permlane16_swap_b32_e32 v113, v112
	v_cndmask_b32_e32 v114, v154, v163, vcc
	v_lshlrev_b32_e32 v114, 2, v114
	v_lshl_add_u64 v[122:123], s[18:19], 0, v[160:161]
	v_cvt_pk_bf16_f32 v116, v164, v156
	s_waitcnt lgkmcnt(0)
	v_add_f32_e32 v112, v112, v113
	v_mov_b32_e32 v113, v112
	s_nop 1
	v_permlane32_swap_b32_e32 v113, v112
	v_cvt_pk_bf16_f32 v117, v165, v157
	v_cvt_pk_bf16_f32 v118, v166, v158
	v_cvt_pk_bf16_f32 v119, v167, v159
	global_store_dwordx4 v[122:123], v[116:119], off
	s_and_saveexec_b64 s[52:53], s[6:7]
	s_cbranch_execz .LBB0_957
	s_waitcnt lgkmcnt(0)
	v_add_f32_e32 v115, v112, v113
	v_lshlrev_b64 v[112:113], 8, v[146:147]
	v_lshl_add_u64 v[112:113], s[10:11], 0, v[112:113]
	v_lshl_add_u64 v[112:113], s[36:37], 2, v[112:113]
	s_lshl_b32 s12, s61, 2
	v_lshl_add_u64 v[112:113], v[112:113], 0, s[12:13]
	global_store_dword v[112:113], v115, off
.LBB0_957:
	s_or_b64 exec, exec, s[52:53]
	v_or_b32_e32 v112, 16, v146
	s_waitcnt lgkmcnt(0)
	v_ashrrev_i32_e32 v113, 31, v112
	v_lshlrev_b64 v[116:117], 11, v[112:113]
	v_lshl_add_u64 v[116:117], v[116:117], 0, v[144:145]
	v_lshlrev_b64 v[122:123], 1, v[116:117]
	v_lshl_add_u64 v[116:117], s[16:17], 0, v[122:123]
	global_load_dwordx4 v[116:119], v[116:117], off
	v_mul_f32_e32 v109, 0xbfb8aa3b, v109
	v_mul_f32_e32 v108, 0xbfb8aa3b, v108
	v_mul_f32_e32 v100, 0xbfb8aa3b, v100
	v_exp_f32_e32 v109, v109
	v_mul_f32_e32 v110, 0xbfb8aa3b, v110
	v_exp_f32_e32 v108, v108
	v_exp_f32_e32 v100, v100
	v_mul_f32_e32 v111, 0xbfb8aa3b, v111
	v_exp_f32_e32 v110, v110
	v_exp_f32_e32 v111, v111
	v_mul_f32_e32 v101, 0xbfb8aa3b, v101
	v_add_f32_e32 v109, 1.0, v109
	v_mul_f32_e32 v102, 0xbfb8aa3b, v102
	v_exp_f32_e32 v101, v101
	v_add_f32_e32 v108, 1.0, v108
	v_add_f32_e32 v100, 1.0, v100
	v_rcp_f32_e32 v109, v109
	v_mul_f32_e32 v103, 0xbfb8aa3b, v103
	v_exp_f32_e32 v102, v102
	v_add_f32_e32 v110, 1.0, v110
	v_rcp_f32_e32 v108, v108
	v_rcp_f32_e32 v100, v100
	v_exp_f32_e32 v103, v103
	v_add_f32_e32 v111, 1.0, v111
	v_rcp_f32_e32 v110, v110
	v_rcp_f32_e32 v111, v111
	v_add_f32_e32 v101, 1.0, v101
	v_add_f32_e32 v102, 1.0, v102
	v_rcp_f32_e32 v101, v101
	v_add_f32_e32 v103, 1.0, v103
	v_rcp_f32_e32 v102, v102
	v_rcp_f32_e32 v103, v103
	s_waitcnt vmcnt(0)
	v_lshlrev_b32_e32 v115, 16, v116
	v_and_b32_e32 v116, 0xffff0000, v116
	v_lshlrev_b32_e32 v124, 16, v118
	v_fmac_f32_e32 v116, v105, v109
	v_lshlrev_b32_e32 v121, 16, v117
	v_fmac_f32_e32 v115, v104, v108
	v_fmac_f32_e32 v124, v96, v100
	v_mul_f32_e32 v96, v116, v116
	v_and_b32_e32 v117, 0xffff0000, v117
	v_fmac_f32_e32 v121, v106, v110
	v_fmac_f32_e32 v96, v115, v115
	v_fmac_f32_e32 v117, v107, v111
	v_fmac_f32_e32 v96, v121, v121
	v_and_b32_e32 v118, 0xffff0000, v118
	v_fmac_f32_e32 v96, v117, v117
	v_lshlrev_b32_e32 v125, 16, v119
	v_fmac_f32_e32 v118, v97, v101
	v_fmac_f32_e32 v96, v124, v124
	v_and_b32_e32 v119, 0xffff0000, v119
	v_fmac_f32_e32 v125, v98, v102
	v_fmac_f32_e32 v96, v118, v118
	v_fmac_f32_e32 v96, v125, v125
	v_fmac_f32_e32 v119, v99, v103
	v_fmac_f32_e32 v96, v119, v119
	v_mov_b32_e32 v97, v96
	s_nop 1
	v_permlane16_swap_b32_e32 v97, v96
	v_lshl_add_u64 v[102:103], s[18:19], 0, v[122:123]
	v_cvt_pk_bf16_f32 v98, v115, v116
	v_cvt_pk_bf16_f32 v99, v121, v117
	v_cvt_pk_bf16_f32 v100, v124, v118
	s_waitcnt lgkmcnt(0)
	v_add_f32_e32 v96, v96, v97
	v_mov_b32_e32 v97, v96
	s_nop 1
	v_permlane32_swap_b32_e32 v97, v96
	v_cvt_pk_bf16_f32 v101, v125, v119
	global_store_dwordx4 v[102:103], v[98:101], off
	s_and_saveexec_b64 s[52:53], s[6:7]
	s_cbranch_execz .LBB0_959
	s_waitcnt lgkmcnt(0)
	v_add_f32_e32 v98, v96, v97
	v_lshlrev_b64 v[96:97], 8, v[112:113]
	v_lshl_add_u64 v[96:97], s[10:11], 0, v[96:97]
	v_lshl_add_u64 v[96:97], s[36:37], 2, v[96:97]
	s_lshl_b32 s12, s61, 2
	v_lshl_add_u64 v[96:97], v[96:97], 0, s[12:13]
	global_store_dword v[96:97], v98, off
.LBB0_959:
	s_or_b64 exec, exec, s[52:53]
	v_or_b32_e32 v96, 32, v146
	s_waitcnt lgkmcnt(0)
	v_ashrrev_i32_e32 v97, 31, v96
	v_lshlrev_b64 v[98:99], 11, v[96:97]
	v_lshl_add_u64 v[98:99], v[98:99], 0, v[144:145]
	v_lshlrev_b64 v[102:103], 1, v[98:99]
	v_lshl_add_u64 v[98:99], s[16:17], 0, v[102:103]
	global_load_dwordx4 v[98:101], v[98:99], off
	v_mul_f32_e32 v93, 0xbfb8aa3b, v93
	v_mul_f32_e32 v92, 0xbfb8aa3b, v92
	v_mul_f32_e32 v84, 0xbfb8aa3b, v84
	v_exp_f32_e32 v93, v93
	v_mul_f32_e32 v94, 0xbfb8aa3b, v94
	v_exp_f32_e32 v92, v92
	v_exp_f32_e32 v84, v84
	v_mul_f32_e32 v95, 0xbfb8aa3b, v95
	v_exp_f32_e32 v94, v94
	v_exp_f32_e32 v95, v95
	v_mul_f32_e32 v85, 0xbfb8aa3b, v85
	v_add_f32_e32 v93, 1.0, v93
	v_mul_f32_e32 v86, 0xbfb8aa3b, v86
	v_exp_f32_e32 v85, v85
	v_add_f32_e32 v92, 1.0, v92
	v_add_f32_e32 v84, 1.0, v84
	v_rcp_f32_e32 v93, v93
	v_mul_f32_e32 v87, 0xbfb8aa3b, v87
	v_exp_f32_e32 v86, v86
	v_add_f32_e32 v94, 1.0, v94
	v_rcp_f32_e32 v92, v92
	v_rcp_f32_e32 v84, v84
	v_exp_f32_e32 v87, v87
	v_add_f32_e32 v95, 1.0, v95
	v_rcp_f32_e32 v94, v94
	v_rcp_f32_e32 v95, v95
	v_add_f32_e32 v85, 1.0, v85
	v_add_f32_e32 v86, 1.0, v86
	v_rcp_f32_e32 v85, v85
	v_add_f32_e32 v87, 1.0, v87
	v_rcp_f32_e32 v86, v86
	v_rcp_f32_e32 v87, v87
	s_waitcnt vmcnt(0)
	v_lshlrev_b32_e32 v104, 16, v98
	v_and_b32_e32 v98, 0xffff0000, v98
	v_lshlrev_b32_e32 v106, 16, v100
	v_fmac_f32_e32 v98, v89, v93
	v_lshlrev_b32_e32 v105, 16, v99
	v_fmac_f32_e32 v104, v88, v92
	v_fmac_f32_e32 v106, v80, v84
	v_mul_f32_e32 v80, v98, v98
	v_and_b32_e32 v99, 0xffff0000, v99
	v_fmac_f32_e32 v105, v90, v94
	v_fmac_f32_e32 v80, v104, v104
	v_fmac_f32_e32 v99, v91, v95
	v_fmac_f32_e32 v80, v105, v105
	v_and_b32_e32 v100, 0xffff0000, v100
	v_fmac_f32_e32 v80, v99, v99
	v_lshlrev_b32_e32 v107, 16, v101
	v_fmac_f32_e32 v100, v81, v85
	v_fmac_f32_e32 v80, v106, v106
	v_and_b32_e32 v101, 0xffff0000, v101
	v_fmac_f32_e32 v107, v82, v86
	v_fmac_f32_e32 v80, v100, v100
	v_fmac_f32_e32 v80, v107, v107
	v_fmac_f32_e32 v101, v83, v87
	v_fmac_f32_e32 v80, v101, v101
	v_mov_b32_e32 v81, v80
	s_nop 1
	v_permlane16_swap_b32_e32 v81, v80
	v_lshl_add_u64 v[86:87], s[18:19], 0, v[102:103]
	v_cvt_pk_bf16_f32 v82, v104, v98
	v_cvt_pk_bf16_f32 v83, v105, v99
	v_cvt_pk_bf16_f32 v84, v106, v100
	s_waitcnt lgkmcnt(0)
	v_add_f32_e32 v80, v80, v81
	v_mov_b32_e32 v81, v80
	s_nop 1
	v_permlane32_swap_b32_e32 v81, v80
	v_cvt_pk_bf16_f32 v85, v107, v101
	global_store_dwordx4 v[86:87], v[82:85], off
	s_and_saveexec_b64 s[52:53], s[6:7]
	s_cbranch_execz .LBB0_961
	s_waitcnt lgkmcnt(0)
	v_add_f32_e32 v82, v80, v81
	v_lshlrev_b64 v[80:81], 8, v[96:97]
	v_lshl_add_u64 v[80:81], s[10:11], 0, v[80:81]
	v_lshl_add_u64 v[80:81], s[36:37], 2, v[80:81]
	s_lshl_b32 s12, s61, 2
	v_lshl_add_u64 v[80:81], v[80:81], 0, s[12:13]
	global_store_dword v[80:81], v82, off
.LBB0_961:
	s_or_b64 exec, exec, s[52:53]
	v_or_b32_e32 v80, 48, v146
	s_waitcnt lgkmcnt(0)
	v_ashrrev_i32_e32 v81, 31, v80
	v_lshlrev_b64 v[82:83], 11, v[80:81]
	v_lshl_add_u64 v[82:83], v[82:83], 0, v[144:145]
	v_lshlrev_b64 v[86:87], 1, v[82:83]
	v_lshl_add_u64 v[82:83], s[16:17], 0, v[86:87]
	global_load_dwordx4 v[82:85], v[82:83], off
	v_mul_f32_e32 v77, 0xbfb8aa3b, v77
	v_mul_f32_e32 v76, 0xbfb8aa3b, v76
	v_mul_f32_e32 v68, 0xbfb8aa3b, v68
	v_exp_f32_e32 v77, v77
	v_mul_f32_e32 v78, 0xbfb8aa3b, v78
	v_exp_f32_e32 v76, v76
	v_exp_f32_e32 v68, v68
	v_mul_f32_e32 v79, 0xbfb8aa3b, v79
	v_exp_f32_e32 v78, v78
	v_exp_f32_e32 v79, v79
	v_mul_f32_e32 v69, 0xbfb8aa3b, v69
	v_add_f32_e32 v77, 1.0, v77
	v_mul_f32_e32 v70, 0xbfb8aa3b, v70
	v_exp_f32_e32 v69, v69
	v_add_f32_e32 v76, 1.0, v76
	v_add_f32_e32 v68, 1.0, v68
	v_rcp_f32_e32 v77, v77
	v_mul_f32_e32 v71, 0xbfb8aa3b, v71
	v_exp_f32_e32 v70, v70
	v_add_f32_e32 v78, 1.0, v78
	v_rcp_f32_e32 v76, v76
	v_rcp_f32_e32 v68, v68
	v_exp_f32_e32 v71, v71
	v_add_f32_e32 v79, 1.0, v79
	v_rcp_f32_e32 v78, v78
	v_rcp_f32_e32 v79, v79
	v_add_f32_e32 v69, 1.0, v69
	v_add_f32_e32 v70, 1.0, v70
	v_rcp_f32_e32 v69, v69
	v_add_f32_e32 v71, 1.0, v71
	v_rcp_f32_e32 v70, v70
	v_rcp_f32_e32 v71, v71
	s_waitcnt vmcnt(0)
	v_lshlrev_b32_e32 v88, 16, v82
	v_and_b32_e32 v82, 0xffff0000, v82
	v_lshlrev_b32_e32 v90, 16, v84
	v_fmac_f32_e32 v82, v73, v77
	v_lshlrev_b32_e32 v89, 16, v83
	v_fmac_f32_e32 v88, v72, v76
	v_fmac_f32_e32 v90, v64, v68
	v_mul_f32_e32 v64, v82, v82
	v_and_b32_e32 v83, 0xffff0000, v83
	v_fmac_f32_e32 v89, v74, v78
	v_fmac_f32_e32 v64, v88, v88
	v_fmac_f32_e32 v83, v75, v79
	v_fmac_f32_e32 v64, v89, v89
	v_and_b32_e32 v84, 0xffff0000, v84
	v_fmac_f32_e32 v64, v83, v83
	v_lshlrev_b32_e32 v91, 16, v85
	v_fmac_f32_e32 v84, v65, v69
	v_fmac_f32_e32 v64, v90, v90
	v_and_b32_e32 v85, 0xffff0000, v85
	v_fmac_f32_e32 v91, v66, v70
	v_fmac_f32_e32 v64, v84, v84
	v_fmac_f32_e32 v64, v91, v91
	v_fmac_f32_e32 v85, v67, v71
	v_fmac_f32_e32 v64, v85, v85
	v_mov_b32_e32 v65, v64
	s_nop 1
	v_permlane16_swap_b32_e32 v65, v64
	v_lshl_add_u64 v[70:71], s[18:19], 0, v[86:87]
	v_cvt_pk_bf16_f32 v66, v88, v82
	v_cvt_pk_bf16_f32 v67, v89, v83
	v_cvt_pk_bf16_f32 v68, v90, v84
	s_waitcnt lgkmcnt(0)
	v_add_f32_e32 v64, v64, v65
	v_mov_b32_e32 v65, v64
	s_nop 1
	v_permlane32_swap_b32_e32 v65, v64
	v_cvt_pk_bf16_f32 v69, v91, v85
	global_store_dwordx4 v[70:71], v[66:69], off
	s_and_saveexec_b64 s[52:53], s[6:7]
	s_cbranch_execz .LBB0_963
	s_waitcnt lgkmcnt(0)
	v_add_f32_e32 v66, v64, v65
	v_lshlrev_b64 v[64:65], 8, v[80:81]
	v_lshl_add_u64 v[64:65], s[10:11], 0, v[64:65]
	v_lshl_add_u64 v[64:65], s[36:37], 2, v[64:65]
	s_lshl_b32 s12, s61, 2
	v_lshl_add_u64 v[64:65], v[64:65], 0, s[12:13]
	global_store_dword v[64:65], v66, off
.LBB0_963:
	s_or_b64 exec, exec, s[52:53]
	v_add_u32_e32 v64, 0x80, v146
	s_waitcnt lgkmcnt(0)
	v_ashrrev_i32_e32 v65, 31, v64
	v_lshlrev_b64 v[66:67], 11, v[64:65]
	v_lshl_add_u64 v[66:67], v[66:67], 0, v[144:145]
	v_lshlrev_b64 v[70:71], 1, v[66:67]
	v_lshl_add_u64 v[66:67], s[16:17], 0, v[70:71]
	global_load_dwordx4 v[66:69], v[66:67], off
	v_mul_f32_e32 v61, 0xbfb8aa3b, v61
	v_mul_f32_e32 v60, 0xbfb8aa3b, v60
	v_mul_f32_e32 v52, 0xbfb8aa3b, v52
	v_exp_f32_e32 v61, v61
	v_mul_f32_e32 v62, 0xbfb8aa3b, v62
	v_exp_f32_e32 v60, v60
	v_exp_f32_e32 v52, v52
	v_mul_f32_e32 v63, 0xbfb8aa3b, v63
	v_exp_f32_e32 v62, v62
	v_exp_f32_e32 v63, v63
	v_mul_f32_e32 v53, 0xbfb8aa3b, v53
	v_add_f32_e32 v61, 1.0, v61
	v_mul_f32_e32 v54, 0xbfb8aa3b, v54
	v_exp_f32_e32 v53, v53
	v_add_f32_e32 v60, 1.0, v60
	v_add_f32_e32 v52, 1.0, v52
	v_rcp_f32_e32 v61, v61
	v_mul_f32_e32 v55, 0xbfb8aa3b, v55
	v_exp_f32_e32 v54, v54
	v_add_f32_e32 v62, 1.0, v62
	v_rcp_f32_e32 v60, v60
	v_rcp_f32_e32 v52, v52
	v_exp_f32_e32 v55, v55
	v_add_f32_e32 v63, 1.0, v63
	v_rcp_f32_e32 v62, v62
	v_rcp_f32_e32 v63, v63
	v_add_f32_e32 v53, 1.0, v53
	v_add_f32_e32 v54, 1.0, v54
	v_rcp_f32_e32 v53, v53
	v_add_f32_e32 v55, 1.0, v55
	v_rcp_f32_e32 v54, v54
	v_rcp_f32_e32 v55, v55
	s_waitcnt vmcnt(0)
	v_lshlrev_b32_e32 v72, 16, v66
	v_and_b32_e32 v66, 0xffff0000, v66
	v_lshlrev_b32_e32 v74, 16, v68
	v_fmac_f32_e32 v66, v57, v61
	v_lshlrev_b32_e32 v73, 16, v67
	v_fmac_f32_e32 v72, v56, v60
	v_fmac_f32_e32 v74, v48, v52
	v_mul_f32_e32 v48, v66, v66
	v_and_b32_e32 v67, 0xffff0000, v67
	v_fmac_f32_e32 v73, v58, v62
	v_fmac_f32_e32 v48, v72, v72
	v_fmac_f32_e32 v67, v59, v63
	v_fmac_f32_e32 v48, v73, v73
	v_and_b32_e32 v68, 0xffff0000, v68
	v_fmac_f32_e32 v48, v67, v67
	v_lshlrev_b32_e32 v75, 16, v69
	v_fmac_f32_e32 v68, v49, v53
	v_fmac_f32_e32 v48, v74, v74
	v_and_b32_e32 v69, 0xffff0000, v69
	v_fmac_f32_e32 v75, v50, v54
	v_fmac_f32_e32 v48, v68, v68
	v_fmac_f32_e32 v48, v75, v75
	v_fmac_f32_e32 v69, v51, v55
	v_fmac_f32_e32 v48, v69, v69
	v_mov_b32_e32 v49, v48
	s_nop 1
	v_permlane16_swap_b32_e32 v49, v48
	v_lshl_add_u64 v[54:55], s[18:19], 0, v[70:71]
	v_cvt_pk_bf16_f32 v50, v72, v66
	v_cvt_pk_bf16_f32 v51, v73, v67
	v_cvt_pk_bf16_f32 v52, v74, v68
	s_waitcnt lgkmcnt(0)
	v_add_f32_e32 v48, v48, v49
	v_mov_b32_e32 v49, v48
	s_nop 1
	v_permlane32_swap_b32_e32 v49, v48
	v_cvt_pk_bf16_f32 v53, v75, v69
	global_store_dwordx4 v[54:55], v[50:53], off
	s_and_saveexec_b64 s[52:53], s[6:7]
	s_cbranch_execz .LBB0_965
	s_waitcnt lgkmcnt(0)
	v_add_f32_e32 v50, v48, v49
	v_lshlrev_b64 v[48:49], 8, v[64:65]
	v_lshl_add_u64 v[48:49], s[10:11], 0, v[48:49]
	v_lshl_add_u64 v[48:49], s[36:37], 2, v[48:49]
	s_lshl_b32 s12, s61, 2
	v_lshl_add_u64 v[48:49], v[48:49], 0, s[12:13]
	global_store_dword v[48:49], v50, off
.LBB0_965:
	s_or_b64 exec, exec, s[52:53]
	v_add_u32_e32 v48, 0x90, v146
	s_waitcnt lgkmcnt(0)
	v_ashrrev_i32_e32 v49, 31, v48
	v_lshlrev_b64 v[50:51], 11, v[48:49]
	v_lshl_add_u64 v[50:51], v[50:51], 0, v[144:145]
	v_lshlrev_b64 v[54:55], 1, v[50:51]
	v_lshl_add_u64 v[50:51], s[16:17], 0, v[54:55]
	global_load_dwordx4 v[50:53], v[50:51], off
	v_mul_f32_e32 v45, 0xbfb8aa3b, v45
	v_mul_f32_e32 v44, 0xbfb8aa3b, v44
	v_mul_f32_e32 v36, 0xbfb8aa3b, v36
	v_exp_f32_e32 v45, v45
	v_mul_f32_e32 v46, 0xbfb8aa3b, v46
	v_exp_f32_e32 v44, v44
	v_exp_f32_e32 v36, v36
	v_mul_f32_e32 v47, 0xbfb8aa3b, v47
	v_exp_f32_e32 v46, v46
	v_exp_f32_e32 v47, v47
	v_mul_f32_e32 v37, 0xbfb8aa3b, v37
	v_add_f32_e32 v45, 1.0, v45
	v_mul_f32_e32 v38, 0xbfb8aa3b, v38
	v_exp_f32_e32 v37, v37
	v_add_f32_e32 v44, 1.0, v44
	v_add_f32_e32 v36, 1.0, v36
	v_rcp_f32_e32 v45, v45
	v_mul_f32_e32 v39, 0xbfb8aa3b, v39
	v_exp_f32_e32 v38, v38
	v_add_f32_e32 v46, 1.0, v46
	v_rcp_f32_e32 v44, v44
	v_rcp_f32_e32 v36, v36
	v_exp_f32_e32 v39, v39
	v_add_f32_e32 v47, 1.0, v47
	v_rcp_f32_e32 v46, v46
	v_rcp_f32_e32 v47, v47
	v_add_f32_e32 v37, 1.0, v37
	v_add_f32_e32 v38, 1.0, v38
	v_rcp_f32_e32 v37, v37
	v_add_f32_e32 v39, 1.0, v39
	v_rcp_f32_e32 v38, v38
	v_rcp_f32_e32 v39, v39
	s_waitcnt vmcnt(0)
	v_lshlrev_b32_e32 v56, 16, v50
	v_and_b32_e32 v50, 0xffff0000, v50
	v_lshlrev_b32_e32 v58, 16, v52
	v_fmac_f32_e32 v50, v41, v45
	v_lshlrev_b32_e32 v57, 16, v51
	v_fmac_f32_e32 v56, v40, v44
	v_fmac_f32_e32 v58, v32, v36
	v_mul_f32_e32 v32, v50, v50
	v_and_b32_e32 v51, 0xffff0000, v51
	v_fmac_f32_e32 v57, v42, v46
	v_fmac_f32_e32 v32, v56, v56
	v_fmac_f32_e32 v51, v43, v47
	v_fmac_f32_e32 v32, v57, v57
	v_and_b32_e32 v52, 0xffff0000, v52
	v_fmac_f32_e32 v32, v51, v51
	v_lshlrev_b32_e32 v59, 16, v53
	v_fmac_f32_e32 v52, v33, v37
	v_fmac_f32_e32 v32, v58, v58
	v_and_b32_e32 v53, 0xffff0000, v53
	v_fmac_f32_e32 v59, v34, v38
	v_fmac_f32_e32 v32, v52, v52
	v_fmac_f32_e32 v32, v59, v59
	v_fmac_f32_e32 v53, v35, v39
	v_fmac_f32_e32 v32, v53, v53
	v_mov_b32_e32 v33, v32
	s_nop 1
	v_permlane16_swap_b32_e32 v33, v32
	v_lshl_add_u64 v[38:39], s[18:19], 0, v[54:55]
	v_cvt_pk_bf16_f32 v34, v56, v50
	v_cvt_pk_bf16_f32 v35, v57, v51
	v_cvt_pk_bf16_f32 v36, v58, v52
	s_waitcnt lgkmcnt(0)
	v_add_f32_e32 v32, v32, v33
	v_mov_b32_e32 v33, v32
	s_nop 1
	v_permlane32_swap_b32_e32 v33, v32
	v_cvt_pk_bf16_f32 v37, v59, v53
	global_store_dwordx4 v[38:39], v[34:37], off
	s_and_saveexec_b64 s[52:53], s[6:7]
	s_cbranch_execz .LBB0_967
	s_waitcnt lgkmcnt(0)
	v_add_f32_e32 v34, v32, v33
	v_lshlrev_b64 v[32:33], 8, v[48:49]
	v_lshl_add_u64 v[32:33], s[10:11], 0, v[32:33]
	v_lshl_add_u64 v[32:33], s[36:37], 2, v[32:33]
	s_lshl_b32 s12, s61, 2
	v_lshl_add_u64 v[32:33], v[32:33], 0, s[12:13]
	global_store_dword v[32:33], v34, off
.LBB0_967:
	s_or_b64 exec, exec, s[52:53]
	v_add_u32_e32 v32, 0xa0, v146
	s_waitcnt lgkmcnt(0)
	v_ashrrev_i32_e32 v33, 31, v32
	v_lshlrev_b64 v[34:35], 11, v[32:33]
	v_lshl_add_u64 v[34:35], v[34:35], 0, v[144:145]
	v_lshlrev_b64 v[38:39], 1, v[34:35]
	v_lshl_add_u64 v[34:35], s[16:17], 0, v[38:39]
	global_load_dwordx4 v[34:37], v[34:35], off
	v_mul_f32_e32 v29, 0xbfb8aa3b, v29
	v_mul_f32_e32 v28, 0xbfb8aa3b, v28
	v_mul_f32_e32 v20, 0xbfb8aa3b, v20
	v_exp_f32_e32 v29, v29
	v_mul_f32_e32 v30, 0xbfb8aa3b, v30
	v_exp_f32_e32 v28, v28
	v_exp_f32_e32 v20, v20
	v_mul_f32_e32 v31, 0xbfb8aa3b, v31
	v_exp_f32_e32 v30, v30
	v_exp_f32_e32 v31, v31
	v_mul_f32_e32 v21, 0xbfb8aa3b, v21
	v_add_f32_e32 v29, 1.0, v29
	v_mul_f32_e32 v22, 0xbfb8aa3b, v22
	v_exp_f32_e32 v21, v21
	v_add_f32_e32 v28, 1.0, v28
	v_add_f32_e32 v20, 1.0, v20
	v_rcp_f32_e32 v29, v29
	v_mul_f32_e32 v23, 0xbfb8aa3b, v23
	v_exp_f32_e32 v22, v22
	v_add_f32_e32 v30, 1.0, v30
	v_rcp_f32_e32 v28, v28
	v_rcp_f32_e32 v20, v20
	v_exp_f32_e32 v23, v23
	v_add_f32_e32 v31, 1.0, v31
	v_rcp_f32_e32 v30, v30
	v_rcp_f32_e32 v31, v31
	v_add_f32_e32 v21, 1.0, v21
	v_add_f32_e32 v22, 1.0, v22
	v_rcp_f32_e32 v21, v21
	v_add_f32_e32 v23, 1.0, v23
	v_rcp_f32_e32 v22, v22
	v_rcp_f32_e32 v23, v23
	s_waitcnt vmcnt(0)
	v_lshlrev_b32_e32 v40, 16, v34
	v_and_b32_e32 v34, 0xffff0000, v34
	v_lshlrev_b32_e32 v42, 16, v36
	v_fmac_f32_e32 v34, v25, v29
	v_lshlrev_b32_e32 v41, 16, v35
	v_fmac_f32_e32 v40, v24, v28
	v_fmac_f32_e32 v42, v16, v20
	v_mul_f32_e32 v16, v34, v34
	v_and_b32_e32 v35, 0xffff0000, v35
	v_fmac_f32_e32 v41, v26, v30
	v_fmac_f32_e32 v16, v40, v40
	v_fmac_f32_e32 v35, v27, v31
	v_fmac_f32_e32 v16, v41, v41
	v_and_b32_e32 v36, 0xffff0000, v36
	v_fmac_f32_e32 v16, v35, v35
	v_lshlrev_b32_e32 v43, 16, v37
	v_fmac_f32_e32 v36, v17, v21
	v_fmac_f32_e32 v16, v42, v42
	v_and_b32_e32 v37, 0xffff0000, v37
	v_fmac_f32_e32 v43, v18, v22
	v_fmac_f32_e32 v16, v36, v36
	v_fmac_f32_e32 v16, v43, v43
	v_fmac_f32_e32 v37, v19, v23
	v_fmac_f32_e32 v16, v37, v37
	v_mov_b32_e32 v17, v16
	s_nop 1
	v_permlane16_swap_b32_e32 v17, v16
	v_lshl_add_u64 v[22:23], s[18:19], 0, v[38:39]
	v_cvt_pk_bf16_f32 v18, v40, v34
	v_cvt_pk_bf16_f32 v19, v41, v35
	v_cvt_pk_bf16_f32 v20, v42, v36
	s_waitcnt lgkmcnt(0)
	v_add_f32_e32 v16, v16, v17
	v_mov_b32_e32 v17, v16
	s_nop 1
	v_permlane32_swap_b32_e32 v17, v16
	v_cvt_pk_bf16_f32 v21, v43, v37
	global_store_dwordx4 v[22:23], v[18:21], off
	s_and_saveexec_b64 s[52:53], s[6:7]
	s_cbranch_execz .LBB0_969
	s_waitcnt lgkmcnt(0)
	v_add_f32_e32 v18, v16, v17
	v_lshlrev_b64 v[16:17], 8, v[32:33]
	v_lshl_add_u64 v[16:17], s[10:11], 0, v[16:17]
	v_lshl_add_u64 v[16:17], s[36:37], 2, v[16:17]
	s_lshl_b32 s12, s61, 2
	v_lshl_add_u64 v[16:17], v[16:17], 0, s[12:13]
	global_store_dword v[16:17], v18, off
.LBB0_969:
	s_or_b64 exec, exec, s[52:53]
	v_add_u32_e32 v16, 0xb0, v146
	s_waitcnt lgkmcnt(0)
	v_ashrrev_i32_e32 v17, 31, v16
	v_lshlrev_b64 v[18:19], 11, v[16:17]
	v_lshl_add_u64 v[18:19], v[18:19], 0, v[144:145]
	v_lshlrev_b64 v[22:23], 1, v[18:19]
	v_lshl_add_u64 v[18:19], s[16:17], 0, v[22:23]
	global_load_dwordx4 v[18:21], v[18:19], off
	v_mul_f32_e32 v13, 0xbfb8aa3b, v13
	v_mul_f32_e32 v12, 0xbfb8aa3b, v12
	v_mul_f32_e32 v4, 0xbfb8aa3b, v4
	v_exp_f32_e32 v13, v13
	v_mul_f32_e32 v14, 0xbfb8aa3b, v14
	v_exp_f32_e32 v12, v12
	v_exp_f32_e32 v4, v4
	v_mul_f32_e32 v15, 0xbfb8aa3b, v15
	v_exp_f32_e32 v14, v14
	v_exp_f32_e32 v15, v15
	v_mul_f32_e32 v5, 0xbfb8aa3b, v5
	v_add_f32_e32 v13, 1.0, v13
	v_mul_f32_e32 v6, 0xbfb8aa3b, v6
	v_exp_f32_e32 v5, v5
	v_add_f32_e32 v12, 1.0, v12
	v_add_f32_e32 v4, 1.0, v4
	v_rcp_f32_e32 v13, v13
	v_mul_f32_e32 v7, 0xbfb8aa3b, v7
	v_exp_f32_e32 v6, v6
	v_add_f32_e32 v14, 1.0, v14
	v_rcp_f32_e32 v12, v12
	v_rcp_f32_e32 v4, v4
	v_exp_f32_e32 v7, v7
	v_add_f32_e32 v15, 1.0, v15
	v_rcp_f32_e32 v14, v14
	v_rcp_f32_e32 v15, v15
	v_add_f32_e32 v5, 1.0, v5
	v_add_f32_e32 v6, 1.0, v6
	v_rcp_f32_e32 v5, v5
	v_add_f32_e32 v7, 1.0, v7
	v_rcp_f32_e32 v6, v6
	v_rcp_f32_e32 v7, v7
	s_waitcnt vmcnt(0)
	v_lshlrev_b32_e32 v24, 16, v18
	v_and_b32_e32 v18, 0xffff0000, v18
	v_lshlrev_b32_e32 v26, 16, v20
	v_fmac_f32_e32 v18, v9, v13
	v_lshlrev_b32_e32 v25, 16, v19
	v_fmac_f32_e32 v24, v8, v12
	v_fmac_f32_e32 v26, v0, v4
	v_mul_f32_e32 v0, v18, v18
	v_and_b32_e32 v19, 0xffff0000, v19
	v_fmac_f32_e32 v25, v10, v14
	v_fmac_f32_e32 v0, v24, v24
	v_fmac_f32_e32 v19, v11, v15
	v_fmac_f32_e32 v0, v25, v25
	v_and_b32_e32 v20, 0xffff0000, v20
	v_fmac_f32_e32 v0, v19, v19
	v_lshlrev_b32_e32 v27, 16, v21
	v_fmac_f32_e32 v20, v1, v5
	v_fmac_f32_e32 v0, v26, v26
	v_and_b32_e32 v21, 0xffff0000, v21
	v_fmac_f32_e32 v27, v2, v6
	v_fmac_f32_e32 v0, v20, v20
	v_fmac_f32_e32 v0, v27, v27
	v_fmac_f32_e32 v21, v3, v7
	v_fmac_f32_e32 v0, v21, v21
	v_mov_b32_e32 v1, v0
	s_nop 1
	v_permlane16_swap_b32_e32 v1, v0
	v_lshl_add_u64 v[6:7], s[18:19], 0, v[22:23]
	v_cvt_pk_bf16_f32 v2, v24, v18
	v_cvt_pk_bf16_f32 v3, v25, v19
	v_cvt_pk_bf16_f32 v4, v26, v20
	s_waitcnt lgkmcnt(0)
	v_add_f32_e32 v0, v0, v1
	v_mov_b32_e32 v1, v0
	s_nop 1
	v_permlane32_swap_b32_e32 v1, v0
	v_cvt_pk_bf16_f32 v5, v27, v21
	global_store_dwordx4 v[6:7], v[2:5], off
	s_and_saveexec_b64 s[52:53], s[6:7]
	s_cbranch_execz .LBB0_971
	s_waitcnt lgkmcnt(0)
	v_add_f32_e32 v2, v0, v1
	v_lshlrev_b64 v[0:1], 8, v[16:17]
	v_lshl_add_u64 v[0:1], s[10:11], 0, v[0:1]
	v_lshl_add_u64 v[0:1], s[36:37], 2, v[0:1]
	s_lshl_b32 s12, s61, 2
	v_lshl_add_u64 v[0:1], v[0:1], 0, s[12:13]
	global_store_dword v[0:1], v2, off

.LBB0_1055:
	s_lshl_b32 s21, s34, 8
	s_cmp_eq_u32 s71, 2
	s_cselect_b32 s23, 0x80, 0
	s_or_b32 s21, s21, s23
	v_add_u32_e32 v132, s21, v219
	v_ashrrev_i32_e32 v133, 31, v132
	v_lshlrev_b64 v[2:3], 8, v[132:133]
	v_lshl_add_u64 v[2:3], v[204:205], 0, v[2:3]
	global_load_dwordx4 v[134:137], v[2:3], off
	global_load_dwordx4 v[138:141], v[2:3], off offset:16
	global_load_dwordx4 v[142:145], v[2:3], off offset:32
	global_load_dwordx4 v[146:149], v[2:3], off offset:48
	v_mov_b32_e32 v150, v128
	v_mov_b32_e32 v151, v124
	v_mov_b32_e32 v124, v129
	v_mov_b32_e32 v152, v130
	v_mov_b32_e32 v153, v126
	v_mov_b32_e32 v126, v131
	v_and_b32_e32 v3, 64, v225
	v_xor_b32_e32 v1, 16, v225
	v_add_u32_e32 v3, 64, v3
	v_cmp_lt_i32_e32 vcc, v1, v3
	v_xor_b32_e32 v133, 32, v225
	v_lshl_or_b32 v2, s72, 7, v221
	v_cndmask_b32_e32 v1, v225, v1, vcc
	v_lshlrev_b32_e32 v1, 2, v1
	v_cmp_lt_i32_e32 vcc, v133, v3
	s_waitcnt vmcnt(0)
	v_mov_b32_e32 v128, v135
	v_mov_b32_e32 v129, v136
	v_mov_b32_e32 v135, v137
	v_mov_b32_e32 v130, v139
	v_mov_b32_e32 v131, v140
	v_mov_b32_e32 v139, v141
	v_add_f32_e32 v136, v142, v143
	v_add_f32_e32 v140, v144, v145
	v_mov_b32_e32 v137, v148
	v_mov_b32_e32 v141, v149
	v_pk_add_f32 v[128:129], v[128:129], v[134:135]
	v_pk_add_f32 v[130:131], v[130:131], v[138:139]
	v_pk_add_f32 v[134:135], v[136:137], v[140:141]
	v_add_f32_e32 v136, v128, v129
	v_pk_add_f32 v[128:129], v[130:131], v[130:131] op_sel:[0,1] op_sel_hi:[1,0]
	v_mov_b32_e32 v143, v146
	v_add_f32_e32 v142, 0, v136
	v_mov_b32_e32 v129, v147
	v_pk_add_f32 v[128:129], v[142:143], v[128:129]
	v_cndmask_b32_e32 v3, v225, v133, vcc
	v_pk_add_f32 v[128:129], v[128:129], v[134:135]
	v_mov_b32_e32 v130, v116
	v_add_f32_e32 v129, v128, v129
	v_mov_b32_e32 v131, v129
	s_nop 1
	v_permlane16_swap_b32_e32 v131, v129
	v_lshlrev_b32_e32 v128, 2, v3
	v_mov_b32_e32 v134, v118
	v_mov_b32_e32 v135, v122
	v_mov_b32_e32 v122, v119
	s_waitcnt lgkmcnt(0)
	v_add_f32_e32 v3, v129, v131
	v_mov_b32_e32 v116, v3
	s_nop 1
	v_permlane32_swap_b32_e32 v116, v3
	v_mov_b32_e32 v131, v120
	v_mov_b32_e32 v120, v117
	s_waitcnt lgkmcnt(0)
	v_add_f32_e32 v3, v3, v116
	v_fmamk_f32 v3, v3, 0x3a000000, v226
	v_mul_f32_e32 v116, 0x4b800000, v3
	v_cmp_gt_f32_e32 vcc, s67, v3
	s_nop 1
	v_cndmask_b32_e32 v3, v3, v116, vcc
	v_rsq_f32_e32 v118, v3
	v_mov_b64_e32 v[116:117], s[12:13]
	v_ashrrev_i32_e32 v3, 31, v2
	v_lshlrev_b64 v[2:3], 1, v[2:3]
	v_mul_f32_e32 v119, 0x45800000, v118
	v_cndmask_b32_e32 v118, v118, v119, vcc
	v_pk_mul_f32 v[136:137], v[150:151], v[118:119] op_sel_hi:[1,0]
	v_pk_mul_f32 v[124:125], v[124:125], v[118:119] op_sel_hi:[1,0]
	v_pk_mul_f32 v[138:139], v[152:153], v[118:119] op_sel_hi:[1,0]
	v_pk_mul_f32 v[126:127], v[126:127], v[118:119] op_sel_hi:[1,0]
	v_pk_mul_f32 v[130:131], v[130:131], v[118:119] op_sel_hi:[1,0]
	v_pk_mul_f32 v[120:121], v[120:121], v[118:119] op_sel_hi:[1,0]
	v_pk_mul_f32 v[134:135], v[134:135], v[118:119] op_sel_hi:[1,0]
	v_pk_mul_f32 v[118:119], v[122:123], v[118:119] op_sel_hi:[1,0]
	v_mul_f32_e32 v122, 0xbfb8aa3b, v137
	v_mul_f32_e32 v123, 0xbfb8aa3b, v125
	v_mul_f32_e32 v129, 0xbfb8aa3b, v139
	v_mul_f32_e32 v133, 0xbfb8aa3b, v127
	v_mul_f32_e32 v140, 0xbfb8aa3b, v131
	v_mul_f32_e32 v141, 0xbfb8aa3b, v121
	v_mul_f32_e32 v142, 0xbfb8aa3b, v135
	v_mul_f32_e32 v143, 0xbfb8aa3b, v119
	v_exp_f32_e32 v122, v122
	v_exp_f32_e32 v123, v123
	v_exp_f32_e32 v129, v129
	v_exp_f32_e32 v133, v133
	v_exp_f32_e32 v140, v140
	v_exp_f32_e32 v141, v141
	v_exp_f32_e32 v142, v142
	v_exp_f32_e32 v143, v143
	v_add_f32_e32 v122, 1.0, v122
	v_add_f32_e32 v123, 1.0, v123
	v_add_f32_e32 v129, 1.0, v129
	v_add_f32_e32 v133, 1.0, v133
	v_add_f32_e32 v140, 1.0, v140
	v_add_f32_e32 v141, 1.0, v141
	v_add_f32_e32 v142, 1.0, v142
	v_add_f32_e32 v143, 1.0, v143
	v_rcp_f32_e32 v122, v122
	v_rcp_f32_e32 v123, v123
	v_rcp_f32_e32 v129, v129
	v_rcp_f32_e32 v133, v133
	v_rcp_f32_e32 v140, v140
	v_rcp_f32_e32 v141, v141
	v_rcp_f32_e32 v142, v142
	v_rcp_f32_e32 v143, v143
	v_mul_f32_e32 v122, v137, v122
	v_mul_f32_e32 v123, v125, v123
	v_mul_f32_e32 v125, v139, v129
	v_mul_f32_e32 v127, v127, v133
	v_mul_f32_e32 v129, v131, v140
	v_mul_f32_e32 v121, v121, v141
	v_mul_f32_e32 v131, v135, v142
	v_mul_f32_e32 v119, v119, v143
	v_mul_f32_e32 v122, v136, v122
	v_mul_f32_e32 v123, v124, v123
	v_mul_f32_e32 v124, v138, v125
	v_mul_f32_e32 v125, v126, v127
	v_mul_f32_e32 v126, v130, v129
	v_mul_f32_e32 v120, v120, v121
	v_mul_f32_e32 v121, v134, v131
	v_mul_f32_e32 v127, v118, v119
	v_cvt_pk_bf16_f32 v118, v122, v123
	v_cvt_pk_bf16_f32 v119, v124, v125
	v_cvt_pk_bf16_f32 v120, v126, v120
	v_mad_i64_i32 v[122:123], s[36:37], v132, s68, v[116:117]
	v_or_b32_e32 v126, 16, v132
	v_cvt_pk_bf16_f32 v121, v121, v127
	v_lshl_add_u64 v[122:123], v[122:123], 0, v[2:3]
	v_ashrrev_i32_e32 v127, 31, v126
	global_store_dwordx4 v[122:123], v[118:121], off
	s_nop 1
	v_lshlrev_b64 v[118:119], 8, v[126:127]
	v_lshl_add_u64 v[130:131], v[204:205], 0, v[118:119]
	global_load_dwordx4 v[118:121], v[130:131], off
	global_load_dwordx4 v[122:125], v[130:131], off offset:16
	global_load_dwordx4 v[134:137], v[130:131], off offset:32
	global_load_dwordx4 v[138:141], v[130:131], off offset:48
	v_mov_b32_e32 v131, v104
	v_mov_b32_e32 v104, v113
	v_mov_b32_e32 v113, v106
	v_mov_b32_e32 v106, v115
	v_mov_b32_e32 v115, v100
	v_mov_b32_e32 v130, v112
	v_mov_b32_e32 v112, v114
	v_mov_b32_e32 v114, v108
	v_mov_b32_e32 v108, v110
	s_waitcnt vmcnt(3)
	v_mov_b32_e32 v142, v119
	v_mov_b32_e32 v143, v120
	v_mov_b32_e32 v119, v121
	s_waitcnt vmcnt(2)
	v_mov_b32_e32 v120, v123
	v_mov_b32_e32 v121, v124
	v_mov_b32_e32 v123, v125
	v_pk_add_f32 v[118:119], v[142:143], v[118:119]
	v_pk_add_f32 v[120:121], v[120:121], v[122:123]
	v_add_f32_e32 v100, v118, v119
	v_pk_add_f32 v[118:119], v[120:121], v[120:121] op_sel:[0,1] op_sel_hi:[1,0]
	s_waitcnt vmcnt(1)
	v_add_f32_e32 v124, v134, v135
	v_add_f32_e32 v134, v136, v137
	s_waitcnt vmcnt(0)
	v_mov_b32_e32 v137, v138
	v_mov_b32_e32 v125, v140
	v_mov_b32_e32 v135, v141
	v_add_f32_e32 v136, 0, v100
	v_mov_b32_e32 v119, v139
	v_pk_add_f32 v[122:123], v[124:125], v[134:135]
	v_pk_add_f32 v[118:119], v[136:137], v[118:119]
	v_mov_b32_e32 v100, v109
	v_pk_add_f32 v[118:119], v[118:119], v[122:123]
	v_mov_b32_e32 v109, v102
	v_add_f32_e32 v118, v118, v119
	v_mov_b32_e32 v119, v118
	s_nop 1
	v_permlane16_swap_b32_e32 v119, v118
	v_mov_b32_e32 v102, v111
	v_mad_i64_i32 v[110:111], s[36:37], v126, s68, v[116:117]
	v_lshl_add_u64 v[110:111], v[110:111], 0, v[2:3]
	s_waitcnt lgkmcnt(0)
	v_add_f32_e32 v120, v118, v119
	v_mov_b32_e32 v121, v120
	s_nop 1
	v_permlane32_swap_b32_e32 v121, v120
	v_or_b32_e32 v118, 32, v132
	v_ashrrev_i32_e32 v119, 31, v118
	s_waitcnt lgkmcnt(0)
	v_add_f32_e32 v120, v120, v121
	v_fmamk_f32 v120, v120, 0x3a000000, v226
	v_mul_f32_e32 v121, 0x4b800000, v120
	v_cmp_gt_f32_e32 vcc, s67, v120
	s_nop 1
	v_cndmask_b32_e32 v120, v120, v121, vcc
	v_rsq_f32_e32 v122, v120
	v_lshlrev_b64 v[120:121], 8, v[118:119]
	v_lshl_add_u64 v[120:121], v[204:205], 0, v[120:121]
	v_mul_f32_e32 v119, 0x45800000, v122
	v_cndmask_b32_e32 v122, v122, v119, vcc
	v_pk_mul_f32 v[102:103], v[102:103], v[122:123] op_sel_hi:[1,0]
	v_pk_mul_f32 v[124:125], v[130:131], v[122:123] op_sel_hi:[1,0]
	v_pk_mul_f32 v[104:105], v[104:105], v[122:123] op_sel_hi:[1,0]
	v_pk_mul_f32 v[112:113], v[112:113], v[122:123] op_sel_hi:[1,0]
	v_pk_mul_f32 v[106:107], v[106:107], v[122:123] op_sel_hi:[1,0]
	v_pk_mul_f32 v[114:115], v[114:115], v[122:123] op_sel_hi:[1,0]
	v_pk_mul_f32 v[100:101], v[100:101], v[122:123] op_sel_hi:[1,0]
	v_pk_mul_f32 v[108:109], v[108:109], v[122:123] op_sel_hi:[1,0]
	v_mul_f32_e32 v131, 0xbfb8aa3b, v103
	v_mul_f32_e32 v119, 0xbfb8aa3b, v125
	v_mul_f32_e32 v122, 0xbfb8aa3b, v105
	v_mul_f32_e32 v123, 0xbfb8aa3b, v113
	v_mul_f32_e32 v126, 0xbfb8aa3b, v107
	v_mul_f32_e32 v127, 0xbfb8aa3b, v115
	v_mul_f32_e32 v129, 0xbfb8aa3b, v101
	v_mul_f32_e32 v130, 0xbfb8aa3b, v109
	v_exp_f32_e32 v131, v131
	v_exp_f32_e32 v119, v119
	v_exp_f32_e32 v122, v122
	v_exp_f32_e32 v123, v123
	v_exp_f32_e32 v126, v126
	v_exp_f32_e32 v127, v127
	v_exp_f32_e32 v129, v129
	v_exp_f32_e32 v130, v130
	v_add_f32_e32 v131, 1.0, v131
	v_add_f32_e32 v119, 1.0, v119
	v_add_f32_e32 v122, 1.0, v122
	v_add_f32_e32 v123, 1.0, v123
	v_add_f32_e32 v126, 1.0, v126
	v_add_f32_e32 v127, 1.0, v127
	v_add_f32_e32 v129, 1.0, v129
	v_add_f32_e32 v130, 1.0, v130
	v_rcp_f32_e32 v131, v131
	v_rcp_f32_e32 v119, v119
	v_rcp_f32_e32 v122, v122
	v_rcp_f32_e32 v123, v123
	v_rcp_f32_e32 v126, v126
	v_rcp_f32_e32 v127, v127
	v_rcp_f32_e32 v129, v129
	v_rcp_f32_e32 v130, v130
	v_mul_f32_e32 v103, v103, v131
	v_mul_f32_e32 v119, v125, v119
	v_mul_f32_e32 v105, v105, v122
	v_mul_f32_e32 v113, v113, v123
	v_mul_f32_e32 v107, v107, v126
	v_mul_f32_e32 v115, v115, v127
	v_mul_f32_e32 v101, v101, v129
	v_mul_f32_e32 v109, v109, v130
	v_mul_f32_e32 v103, v102, v103
	v_mul_f32_e32 v119, v124, v119
	v_mul_f32_e32 v104, v104, v105
	v_mul_f32_e32 v105, v112, v113
	v_mul_f32_e32 v106, v106, v107
	v_mul_f32_e32 v107, v114, v115
	v_mul_f32_e32 v112, v100, v101
	v_mul_f32_e32 v108, v108, v109
	v_cvt_pk_bf16_f32 v100, v119, v104
	v_cvt_pk_bf16_f32 v101, v105, v106
	v_cvt_pk_bf16_f32 v102, v107, v112
	v_cvt_pk_bf16_f32 v103, v108, v103
	global_store_dwordx4 v[110:111], v[100:103], off
	global_load_dwordx4 v[100:103], v[120:121], off
	global_load_dwordx4 v[104:107], v[120:121], off offset:16
	global_load_dwordx4 v[108:111], v[120:121], off offset:32
	global_load_dwordx4 v[112:115], v[120:121], off offset:48
	v_mov_b32_e32 v121, v88
	v_mov_b32_e32 v88, v97
	v_mov_b32_e32 v97, v90
	v_mov_b32_e32 v90, v99
	v_mov_b32_e32 v99, v84
	v_mov_b32_e32 v120, v96
	v_mov_b32_e32 v96, v98
	v_mov_b32_e32 v98, v92
	v_mov_b32_e32 v92, v94
	s_waitcnt vmcnt(3)
	v_mov_b32_e32 v122, v101
	v_mov_b32_e32 v123, v102
	v_mov_b32_e32 v101, v103
	s_waitcnt vmcnt(2)
	v_mov_b32_e32 v102, v105
	v_mov_b32_e32 v103, v106
	v_mov_b32_e32 v105, v107
	v_pk_add_f32 v[100:101], v[122:123], v[100:101]
	v_pk_add_f32 v[102:103], v[102:103], v[104:105]
	v_add_f32_e32 v84, v100, v101
	v_pk_add_f32 v[100:101], v[102:103], v[102:103] op_sel:[0,1] op_sel_hi:[1,0]
	s_waitcnt vmcnt(1)
	v_add_f32_e32 v106, v108, v109
	v_add_f32_e32 v108, v110, v111
	s_waitcnt vmcnt(0)
	v_mov_b32_e32 v111, v112
	v_mov_b32_e32 v107, v114
	v_mov_b32_e32 v109, v115
	v_add_f32_e32 v110, 0, v84
	v_mov_b32_e32 v101, v113
	v_pk_add_f32 v[104:105], v[106:107], v[108:109]
	v_pk_add_f32 v[100:101], v[110:111], v[100:101]
	v_mov_b32_e32 v84, v93
	v_pk_add_f32 v[100:101], v[100:101], v[104:105]
	v_mov_b32_e32 v93, v86
	v_add_f32_e32 v100, v100, v101
	v_mov_b32_e32 v101, v100
	s_nop 1
	v_permlane16_swap_b32_e32 v101, v100
	v_mov_b32_e32 v86, v95
	v_mad_i64_i32 v[94:95], s[36:37], v118, s68, v[116:117]
	v_lshl_add_u64 v[94:95], v[94:95], 0, v[2:3]
	s_waitcnt lgkmcnt(0)
	v_add_f32_e32 v102, v100, v101
	v_mov_b32_e32 v103, v102
	s_nop 1
	v_permlane32_swap_b32_e32 v103, v102
	v_or_b32_e32 v100, 48, v132
	v_ashrrev_i32_e32 v101, 31, v100
	s_waitcnt lgkmcnt(0)
	v_add_f32_e32 v102, v102, v103
	v_fmamk_f32 v102, v102, 0x3a000000, v226
	v_mul_f32_e32 v103, 0x4b800000, v102
	v_cmp_gt_f32_e32 vcc, s67, v102
	s_nop 1
	v_cndmask_b32_e32 v102, v102, v103, vcc
	v_rsq_f32_e32 v104, v102
	v_lshlrev_b64 v[102:103], 8, v[100:101]
	v_lshl_add_u64 v[102:103], v[204:205], 0, v[102:103]
	v_mul_f32_e32 v101, 0x45800000, v104
	v_cndmask_b32_e32 v104, v104, v101, vcc
	v_pk_mul_f32 v[86:87], v[86:87], v[104:105] op_sel_hi:[1,0]
	v_pk_mul_f32 v[106:107], v[120:121], v[104:105] op_sel_hi:[1,0]
	v_pk_mul_f32 v[88:89], v[88:89], v[104:105] op_sel_hi:[1,0]
	v_pk_mul_f32 v[96:97], v[96:97], v[104:105] op_sel_hi:[1,0]
	v_pk_mul_f32 v[90:91], v[90:91], v[104:105] op_sel_hi:[1,0]
	v_pk_mul_f32 v[98:99], v[98:99], v[104:105] op_sel_hi:[1,0]
	v_pk_mul_f32 v[84:85], v[84:85], v[104:105] op_sel_hi:[1,0]
	v_pk_mul_f32 v[92:93], v[92:93], v[104:105] op_sel_hi:[1,0]
	v_mul_f32_e32 v112, 0xbfb8aa3b, v87
	v_mul_f32_e32 v101, 0xbfb8aa3b, v107
	v_mul_f32_e32 v104, 0xbfb8aa3b, v89
	v_mul_f32_e32 v105, 0xbfb8aa3b, v97
	v_mul_f32_e32 v108, 0xbfb8aa3b, v91
	v_mul_f32_e32 v109, 0xbfb8aa3b, v99
	v_mul_f32_e32 v110, 0xbfb8aa3b, v85
	v_mul_f32_e32 v111, 0xbfb8aa3b, v93
	v_exp_f32_e32 v112, v112
	v_exp_f32_e32 v101, v101
	v_exp_f32_e32 v104, v104
	v_exp_f32_e32 v105, v105
	v_exp_f32_e32 v108, v108
	v_exp_f32_e32 v109, v109
	v_exp_f32_e32 v110, v110
	v_exp_f32_e32 v111, v111
	v_add_f32_e32 v112, 1.0, v112
	v_add_f32_e32 v101, 1.0, v101
	v_add_f32_e32 v104, 1.0, v104
	v_add_f32_e32 v105, 1.0, v105
	v_add_f32_e32 v108, 1.0, v108
	v_add_f32_e32 v109, 1.0, v109
	v_add_f32_e32 v110, 1.0, v110
	v_add_f32_e32 v111, 1.0, v111
	v_rcp_f32_e32 v112, v112
	v_rcp_f32_e32 v101, v101
	v_rcp_f32_e32 v104, v104
	v_rcp_f32_e32 v105, v105
	v_rcp_f32_e32 v108, v108
	v_rcp_f32_e32 v109, v109
	v_rcp_f32_e32 v110, v110
	v_rcp_f32_e32 v111, v111
	v_mul_f32_e32 v87, v87, v112
	v_mul_f32_e32 v101, v107, v101
	v_mul_f32_e32 v89, v89, v104
	v_mul_f32_e32 v97, v97, v105
	v_mul_f32_e32 v91, v91, v108
	v_mul_f32_e32 v99, v99, v109
	v_mul_f32_e32 v85, v85, v110
	v_mul_f32_e32 v93, v93, v111
	v_mul_f32_e32 v87, v86, v87
	v_mul_f32_e32 v101, v106, v101
	v_mul_f32_e32 v88, v88, v89
	v_mul_f32_e32 v89, v96, v97
	v_mul_f32_e32 v90, v90, v91
	v_mul_f32_e32 v91, v98, v99
	v_mul_f32_e32 v96, v84, v85
	v_mul_f32_e32 v92, v92, v93
	v_cvt_pk_bf16_f32 v84, v101, v88
	v_cvt_pk_bf16_f32 v85, v89, v90
	v_cvt_pk_bf16_f32 v86, v91, v96
	v_cvt_pk_bf16_f32 v87, v92, v87
	global_store_dwordx4 v[94:95], v[84:87], off
	global_load_dwordx4 v[84:87], v[102:103], off
	global_load_dwordx4 v[88:91], v[102:103], off offset:16
	global_load_dwordx4 v[92:95], v[102:103], off offset:32
	global_load_dwordx4 v[96:99], v[102:103], off offset:48
	v_mov_b32_e32 v103, v76
	v_mov_b32_e32 v76, v81
	v_mov_b32_e32 v102, v80
	v_mov_b32_e32 v80, v82
	v_mov_b32_e32 v82, v68
	v_mov_b32_e32 v68, v70
	s_waitcnt vmcnt(3)
	v_mov_b32_e32 v104, v85
	v_mov_b32_e32 v105, v86
	v_mov_b32_e32 v85, v87
	s_waitcnt vmcnt(2)
	v_mov_b32_e32 v86, v89
	v_mov_b32_e32 v87, v90
	v_mov_b32_e32 v89, v91
	v_pk_add_f32 v[84:85], v[104:105], v[84:85]
	v_pk_add_f32 v[86:87], v[86:87], v[88:89]
	v_add_f32_e32 v81, v84, v85
	v_pk_add_f32 v[84:85], v[86:87], v[86:87] op_sel:[0,1] op_sel_hi:[1,0]
	s_waitcnt vmcnt(1)
	v_add_f32_e32 v90, v92, v93
	v_add_f32_e32 v92, v94, v95
	s_waitcnt vmcnt(0)
	v_mov_b32_e32 v95, v96
	v_mov_b32_e32 v91, v98
	v_mov_b32_e32 v93, v99
	v_add_f32_e32 v94, 0, v81
	v_mov_b32_e32 v85, v97
	v_pk_add_f32 v[88:89], v[90:91], v[92:93]
	v_pk_add_f32 v[84:85], v[94:95], v[84:85]
	v_mov_b32_e32 v81, v78
	v_pk_add_f32 v[84:85], v[84:85], v[88:89]
	v_mov_b32_e32 v78, v83
	v_add_f32_e32 v84, v84, v85
	v_mov_b32_e32 v85, v84
	s_nop 1
	v_permlane16_swap_b32_e32 v85, v84
	v_mov_b32_e32 v83, v72
	v_mov_b32_e32 v72, v69
	v_mov_b32_e32 v69, v74
	v_mov_b32_e32 v74, v71
	s_waitcnt lgkmcnt(0)
	v_add_f32_e32 v84, v84, v85
	v_mov_b32_e32 v85, v84
	s_nop 1
	v_permlane32_swap_b32_e32 v85, v84
	s_waitcnt lgkmcnt(0)
	v_add_f32_e32 v70, v84, v85
	v_fmamk_f32 v70, v70, 0x3a000000, v226
	v_mul_f32_e32 v71, 0x4b800000, v70
	v_cmp_gt_f32_e32 vcc, s67, v70
	s_nop 1
	v_cndmask_b32_e32 v70, v70, v71, vcc
	v_rsq_f32_e32 v86, v70
	v_mad_i64_i32 v[70:71], s[36:37], v100, s68, v[116:117]
	v_lshl_add_u64 v[84:85], v[70:71], 0, v[2:3]
	v_mul_f32_e32 v70, 0x45800000, v86
	v_cndmask_b32_e32 v70, v86, v70, vcc
	v_pk_mul_f32 v[86:87], v[102:103], v[70:71] op_sel_hi:[1,0]
	v_pk_mul_f32 v[76:77], v[76:77], v[70:71] op_sel_hi:[1,0]
	v_pk_mul_f32 v[80:81], v[80:81], v[70:71] op_sel_hi:[1,0]
	v_pk_mul_f32 v[78:79], v[78:79], v[70:71] op_sel_hi:[1,0]
	v_pk_mul_f32 v[82:83], v[82:83], v[70:71] op_sel_hi:[1,0]
	v_pk_mul_f32 v[72:73], v[72:73], v[70:71] op_sel_hi:[1,0]
	v_pk_mul_f32 v[68:69], v[68:69], v[70:71] op_sel_hi:[1,0]
	v_pk_mul_f32 v[70:71], v[74:75], v[70:71] op_sel_hi:[1,0]
	v_mul_f32_e32 v74, 0xbfb8aa3b, v87
	v_mul_f32_e32 v93, 0xbfb8aa3b, v71
	v_mul_f32_e32 v75, 0xbfb8aa3b, v77
	v_mul_f32_e32 v88, 0xbfb8aa3b, v81
	v_mul_f32_e32 v89, 0xbfb8aa3b, v79
	v_mul_f32_e32 v90, 0xbfb8aa3b, v83
	v_mul_f32_e32 v91, 0xbfb8aa3b, v73
	v_mul_f32_e32 v92, 0xbfb8aa3b, v69
	v_exp_f32_e32 v93, v93
	v_exp_f32_e32 v74, v74
	v_exp_f32_e32 v75, v75
	v_exp_f32_e32 v88, v88
	v_exp_f32_e32 v89, v89
	v_exp_f32_e32 v90, v90
	v_exp_f32_e32 v91, v91
	v_exp_f32_e32 v92, v92
	v_add_f32_e32 v93, 1.0, v93
	v_add_f32_e32 v74, 1.0, v74
	v_add_f32_e32 v75, 1.0, v75
	v_add_f32_e32 v88, 1.0, v88
	v_add_f32_e32 v89, 1.0, v89
	v_add_f32_e32 v90, 1.0, v90
	v_add_f32_e32 v91, 1.0, v91
	v_add_f32_e32 v92, 1.0, v92
	v_rcp_f32_e32 v93, v93
	v_rcp_f32_e32 v74, v74
	v_rcp_f32_e32 v75, v75
	v_rcp_f32_e32 v88, v88
	v_rcp_f32_e32 v89, v89
	v_rcp_f32_e32 v90, v90
	v_rcp_f32_e32 v91, v91
	v_rcp_f32_e32 v92, v92
	v_mul_f32_e32 v71, v71, v93
	v_mul_f32_e32 v74, v87, v74
	v_mul_f32_e32 v75, v77, v75
	v_mul_f32_e32 v77, v81, v88
	v_mul_f32_e32 v79, v79, v89
	v_mul_f32_e32 v81, v83, v90
	v_mul_f32_e32 v73, v73, v91
	v_mul_f32_e32 v69, v69, v92
	v_mul_f32_e32 v71, v70, v71
	v_mul_f32_e32 v74, v86, v74
	v_mul_f32_e32 v75, v76, v75
	v_mul_f32_e32 v76, v80, v77
	v_mul_f32_e32 v77, v78, v79
	v_mul_f32_e32 v78, v82, v81
	v_mul_f32_e32 v72, v72, v73
	v_mul_f32_e32 v73, v68, v69
	v_cvt_pk_bf16_f32 v68, v74, v75
	v_cvt_pk_bf16_f32 v69, v76, v77
	v_cvt_pk_bf16_f32 v70, v78, v72
	v_cvt_pk_bf16_f32 v71, v73, v71
	global_store_dwordx4 v[84:85], v[68:71], off
	s_and_b64 vcc, exec, s[8:9]
	s_cbranch_vccz .LBB0_1057
	s_andn2_b64 vcc, exec, s[24:25]
	s_mov_b64 s[8:9], -1
	s_cbranch_vccnz .LBB0_1036
	s_branch .LBB0_1058
.LBB0_1057:
	v_add_u32_e32 v84, 0x80, v132
	v_ashrrev_i32_e32 v85, 31, v84
	v_lshlrev_b64 v[68:69], 8, v[84:85]
	v_lshl_add_u64 v[80:81], v[204:205], 0, v[68:69]
	global_load_dwordx4 v[68:71], v[80:81], off
	global_load_dwordx4 v[72:75], v[80:81], off offset:16
	global_load_dwordx4 v[76:79], v[80:81], off offset:32
	s_nop 0
	global_load_dwordx4 v[80:83], v[80:81], off offset:48
	v_mov_b32_e32 v86, v64
	v_mov_b32_e32 v87, v56
	v_mov_b32_e32 v56, v65
	v_mov_b32_e32 v64, v66
	v_mov_b32_e32 v65, v58
	v_mov_b32_e32 v58, v67
	v_mov_b32_e32 v66, v60
	v_mov_b32_e32 v67, v52
	v_mov_b32_e32 v52, v61
	s_waitcnt vmcnt(3)
	v_mov_b32_e32 v60, v69
	v_mov_b32_e32 v61, v70
	v_mov_b32_e32 v69, v71
	s_waitcnt vmcnt(2)
	v_mov_b32_e32 v70, v73
	v_mov_b32_e32 v71, v74
	v_mov_b32_e32 v73, v75
	v_pk_add_f32 v[60:61], v[60:61], v[68:69]
	v_pk_add_f32 v[68:69], v[70:71], v[72:73]
	v_add_f32_e32 v72, v60, v61
	v_pk_add_f32 v[60:61], v[68:69], v[68:69] op_sel:[0,1] op_sel_hi:[1,0]
	s_waitcnt vmcnt(1)
	v_add_f32_e32 v74, v76, v77
	v_add_f32_e32 v76, v78, v79
	s_waitcnt vmcnt(0)
	v_mov_b32_e32 v79, v80
	v_mov_b32_e32 v75, v82
	v_mov_b32_e32 v77, v83
	v_add_f32_e32 v78, 0, v72
	v_mov_b32_e32 v61, v81
	v_pk_add_f32 v[70:71], v[74:75], v[76:77]
	v_pk_add_f32 v[60:61], v[78:79], v[60:61]
	v_mov_b32_e32 v69, v54
	v_pk_add_f32 v[60:61], v[60:61], v[70:71]
	v_mov_b32_e32 v54, v63
	v_add_f32_e32 v70, v60, v61
	v_mov_b32_e32 v71, v70
	s_nop 1
	v_permlane16_swap_b32_e32 v71, v70
	v_mov_b32_e32 v68, v62
	v_mov_b64_e32 v[60:61], s[12:13]
	v_mad_i64_i32 v[62:63], s[8:9], v84, s68, v[60:61]
	s_waitcnt lgkmcnt(0)
	v_add_f32_e32 v72, v70, v71
	v_mov_b32_e32 v73, v72
	s_nop 1
	v_permlane32_swap_b32_e32 v73, v72
	v_add_u32_e32 v70, 0x90, v132
	v_ashrrev_i32_e32 v71, 31, v70
	v_lshl_add_u64 v[62:63], v[62:63], 0, v[2:3]
	s_waitcnt lgkmcnt(0)
	v_add_f32_e32 v72, v72, v73
	v_fmamk_f32 v72, v72, 0x3a000000, v226
	v_mul_f32_e32 v73, 0x4b800000, v72
	v_cmp_gt_f32_e32 vcc, s67, v72
	s_nop 1
	v_cndmask_b32_e32 v72, v72, v73, vcc
	v_rsq_f32_e32 v74, v72
	v_lshlrev_b64 v[72:73], 8, v[70:71]
	v_lshl_add_u64 v[72:73], v[204:205], 0, v[72:73]
	v_mul_f32_e32 v71, 0x45800000, v74
	v_cndmask_b32_e32 v74, v74, v71, vcc
	v_pk_mul_f32 v[54:55], v[54:55], v[74:75] op_sel_hi:[1,0]
	v_pk_mul_f32 v[76:77], v[86:87], v[74:75] op_sel_hi:[1,0]
	v_pk_mul_f32 v[56:57], v[56:57], v[74:75] op_sel_hi:[1,0]
	v_pk_mul_f32 v[64:65], v[64:65], v[74:75] op_sel_hi:[1,0]
	v_pk_mul_f32 v[58:59], v[58:59], v[74:75] op_sel_hi:[1,0]
	v_pk_mul_f32 v[66:67], v[66:67], v[74:75] op_sel_hi:[1,0]
	v_pk_mul_f32 v[52:53], v[52:53], v[74:75] op_sel_hi:[1,0]
	v_pk_mul_f32 v[68:69], v[68:69], v[74:75] op_sel_hi:[1,0]
	v_mul_f32_e32 v82, 0xbfb8aa3b, v55
	v_mul_f32_e32 v71, 0xbfb8aa3b, v77
	v_mul_f32_e32 v74, 0xbfb8aa3b, v57
	v_mul_f32_e32 v75, 0xbfb8aa3b, v65
	v_mul_f32_e32 v78, 0xbfb8aa3b, v59
	v_mul_f32_e32 v79, 0xbfb8aa3b, v67
	v_mul_f32_e32 v80, 0xbfb8aa3b, v53
	v_mul_f32_e32 v81, 0xbfb8aa3b, v69
	v_exp_f32_e32 v82, v82
	v_exp_f32_e32 v71, v71
	v_exp_f32_e32 v74, v74
	v_exp_f32_e32 v75, v75
	v_exp_f32_e32 v78, v78
	v_exp_f32_e32 v79, v79
	v_exp_f32_e32 v80, v80
	v_exp_f32_e32 v81, v81
	v_add_f32_e32 v82, 1.0, v82
	v_add_f32_e32 v71, 1.0, v71
	v_add_f32_e32 v74, 1.0, v74
	v_add_f32_e32 v75, 1.0, v75
	v_add_f32_e32 v78, 1.0, v78
	v_add_f32_e32 v79, 1.0, v79
	v_add_f32_e32 v80, 1.0, v80
	v_add_f32_e32 v81, 1.0, v81
	v_rcp_f32_e32 v82, v82
	v_rcp_f32_e32 v71, v71
	v_rcp_f32_e32 v74, v74
	v_rcp_f32_e32 v75, v75
	v_rcp_f32_e32 v78, v78
	v_rcp_f32_e32 v79, v79
	v_rcp_f32_e32 v80, v80
	v_rcp_f32_e32 v81, v81
	v_mul_f32_e32 v55, v55, v82
	v_mul_f32_e32 v71, v77, v71
	v_mul_f32_e32 v57, v57, v74
	v_mul_f32_e32 v65, v65, v75
	v_mul_f32_e32 v59, v59, v78
	v_mul_f32_e32 v67, v67, v79
	v_mul_f32_e32 v53, v53, v80
	v_mul_f32_e32 v69, v69, v81
	v_mul_f32_e32 v55, v54, v55
	v_mul_f32_e32 v71, v76, v71
	v_mul_f32_e32 v56, v56, v57
	v_mul_f32_e32 v57, v64, v65
	v_mul_f32_e32 v58, v58, v59
	v_mul_f32_e32 v59, v66, v67
	v_mul_f32_e32 v64, v52, v53
	v_mul_f32_e32 v65, v68, v69
	v_cvt_pk_bf16_f32 v52, v71, v56
	v_cvt_pk_bf16_f32 v53, v57, v58
	v_cvt_pk_bf16_f32 v54, v59, v64
	v_cvt_pk_bf16_f32 v55, v65, v55
	global_store_dwordx4 v[62:63], v[52:55], off
	global_load_dwordx4 v[52:55], v[72:73], off
	global_load_dwordx4 v[56:59], v[72:73], off offset:16
	global_load_dwordx4 v[62:65], v[72:73], off offset:32
	global_load_dwordx4 v[66:69], v[72:73], off offset:48
	v_mov_b32_e32 v73, v40
	v_mov_b32_e32 v40, v49
	v_mov_b32_e32 v49, v42
	v_mov_b32_e32 v42, v51
	v_mov_b32_e32 v51, v36
	v_mov_b32_e32 v72, v48
	v_mov_b32_e32 v48, v50
	v_mov_b32_e32 v50, v44
	v_mov_b32_e32 v44, v46
	s_waitcnt vmcnt(3)
	v_mov_b32_e32 v74, v53
	v_mov_b32_e32 v75, v54
	v_mov_b32_e32 v53, v55
	s_waitcnt vmcnt(2)
	v_mov_b32_e32 v54, v57
	v_mov_b32_e32 v55, v58
	v_mov_b32_e32 v57, v59
	v_pk_add_f32 v[52:53], v[74:75], v[52:53]
	v_pk_add_f32 v[54:55], v[54:55], v[56:57]
	v_add_f32_e32 v36, v52, v53
	v_pk_add_f32 v[52:53], v[54:55], v[54:55] op_sel:[0,1] op_sel_hi:[1,0]
	s_waitcnt vmcnt(1)
	v_add_f32_e32 v58, v62, v63
	v_add_f32_e32 v62, v64, v65
	s_waitcnt vmcnt(0)
	v_mov_b32_e32 v65, v66
	v_mov_b32_e32 v59, v68
	v_mov_b32_e32 v63, v69
	v_add_f32_e32 v64, 0, v36
	v_mov_b32_e32 v53, v67
	v_pk_add_f32 v[56:57], v[58:59], v[62:63]
	v_pk_add_f32 v[52:53], v[64:65], v[52:53]
	v_mov_b32_e32 v36, v45
	v_pk_add_f32 v[52:53], v[52:53], v[56:57]
	v_mov_b32_e32 v45, v38
	v_add_f32_e32 v52, v52, v53
	v_mov_b32_e32 v53, v52
	s_nop 1
	v_permlane16_swap_b32_e32 v53, v52
	v_mov_b32_e32 v38, v47
	v_mad_i64_i32 v[46:47], s[8:9], v70, s68, v[60:61]
	v_lshl_add_u64 v[46:47], v[46:47], 0, v[2:3]
	s_waitcnt lgkmcnt(0)
	v_add_f32_e32 v54, v52, v53
	v_mov_b32_e32 v55, v54
	s_nop 1
	v_permlane32_swap_b32_e32 v55, v54
	v_add_u32_e32 v52, 0xa0, v132
	v_ashrrev_i32_e32 v53, 31, v52
	s_waitcnt lgkmcnt(0)
	v_add_f32_e32 v54, v54, v55
	v_fmamk_f32 v54, v54, 0x3a000000, v226
	v_mul_f32_e32 v55, 0x4b800000, v54
	v_cmp_gt_f32_e32 vcc, s67, v54
	s_nop 1
	v_cndmask_b32_e32 v54, v54, v55, vcc
	v_rsq_f32_e32 v56, v54
	v_lshlrev_b64 v[54:55], 8, v[52:53]
	v_lshl_add_u64 v[54:55], v[204:205], 0, v[54:55]
	v_mul_f32_e32 v53, 0x45800000, v56
	v_cndmask_b32_e32 v56, v56, v53, vcc
	v_pk_mul_f32 v[38:39], v[38:39], v[56:57] op_sel_hi:[1,0]
	v_pk_mul_f32 v[58:59], v[72:73], v[56:57] op_sel_hi:[1,0]
	v_pk_mul_f32 v[40:41], v[40:41], v[56:57] op_sel_hi:[1,0]
	v_pk_mul_f32 v[48:49], v[48:49], v[56:57] op_sel_hi:[1,0]
	v_pk_mul_f32 v[42:43], v[42:43], v[56:57] op_sel_hi:[1,0]
	v_pk_mul_f32 v[50:51], v[50:51], v[56:57] op_sel_hi:[1,0]
	v_pk_mul_f32 v[36:37], v[36:37], v[56:57] op_sel_hi:[1,0]
	v_pk_mul_f32 v[44:45], v[44:45], v[56:57] op_sel_hi:[1,0]
	v_mul_f32_e32 v66, 0xbfb8aa3b, v39
	v_mul_f32_e32 v53, 0xbfb8aa3b, v59
	v_mul_f32_e32 v56, 0xbfb8aa3b, v41
	v_mul_f32_e32 v57, 0xbfb8aa3b, v49
	v_mul_f32_e32 v62, 0xbfb8aa3b, v43
	v_mul_f32_e32 v63, 0xbfb8aa3b, v51
	v_mul_f32_e32 v64, 0xbfb8aa3b, v37
	v_mul_f32_e32 v65, 0xbfb8aa3b, v45
	v_exp_f32_e32 v66, v66
	v_exp_f32_e32 v53, v53
	v_exp_f32_e32 v56, v56
	v_exp_f32_e32 v57, v57
	v_exp_f32_e32 v62, v62
	v_exp_f32_e32 v63, v63
	v_exp_f32_e32 v64, v64
	v_exp_f32_e32 v65, v65
	v_add_f32_e32 v66, 1.0, v66
	v_add_f32_e32 v53, 1.0, v53
	v_add_f32_e32 v56, 1.0, v56
	v_add_f32_e32 v57, 1.0, v57
	v_add_f32_e32 v62, 1.0, v62
	v_add_f32_e32 v63, 1.0, v63
	v_add_f32_e32 v64, 1.0, v64
	v_add_f32_e32 v65, 1.0, v65
	v_rcp_f32_e32 v66, v66
	v_rcp_f32_e32 v53, v53
	v_rcp_f32_e32 v56, v56
	v_rcp_f32_e32 v57, v57
	v_rcp_f32_e32 v62, v62
	v_rcp_f32_e32 v63, v63
	v_rcp_f32_e32 v64, v64
	v_rcp_f32_e32 v65, v65
	v_mul_f32_e32 v39, v39, v66
	v_mul_f32_e32 v53, v59, v53
	v_mul_f32_e32 v41, v41, v56
	v_mul_f32_e32 v49, v49, v57
	v_mul_f32_e32 v43, v43, v62
	v_mul_f32_e32 v51, v51, v63
	v_mul_f32_e32 v37, v37, v64
	v_mul_f32_e32 v45, v45, v65
	v_mul_f32_e32 v39, v38, v39
	v_mul_f32_e32 v53, v58, v53
	v_mul_f32_e32 v40, v40, v41
	v_mul_f32_e32 v41, v48, v49
	v_mul_f32_e32 v42, v42, v43
	v_mul_f32_e32 v43, v50, v51
	v_mul_f32_e32 v48, v36, v37
	v_mul_f32_e32 v44, v44, v45
	v_cvt_pk_bf16_f32 v36, v53, v40
	v_cvt_pk_bf16_f32 v37, v41, v42
	v_cvt_pk_bf16_f32 v38, v43, v48
	v_cvt_pk_bf16_f32 v39, v44, v39
	global_store_dwordx4 v[46:47], v[36:39], off
	global_load_dwordx4 v[36:39], v[54:55], off
	global_load_dwordx4 v[40:43], v[54:55], off offset:16
	global_load_dwordx4 v[44:47], v[54:55], off offset:32
	global_load_dwordx4 v[48:51], v[54:55], off offset:48
	v_mov_b32_e32 v55, v24
	v_mov_b32_e32 v24, v33
	v_mov_b32_e32 v33, v26
	v_mov_b32_e32 v26, v35
	v_mov_b32_e32 v35, v20
	v_mov_b32_e32 v54, v32
	v_mov_b32_e32 v32, v34
	v_mov_b32_e32 v34, v28
	v_mov_b32_e32 v28, v30
	s_waitcnt vmcnt(3)
	v_mov_b32_e32 v56, v37
	v_mov_b32_e32 v57, v38
	v_mov_b32_e32 v37, v39
	s_waitcnt vmcnt(2)
	v_mov_b32_e32 v38, v41
	v_mov_b32_e32 v39, v42
	v_mov_b32_e32 v41, v43
	v_pk_add_f32 v[36:37], v[56:57], v[36:37]
	v_pk_add_f32 v[38:39], v[38:39], v[40:41]
	v_add_f32_e32 v20, v36, v37
	v_pk_add_f32 v[36:37], v[38:39], v[38:39] op_sel:[0,1] op_sel_hi:[1,0]
	s_waitcnt vmcnt(1)
	v_add_f32_e32 v42, v44, v45
	v_add_f32_e32 v44, v46, v47
	s_waitcnt vmcnt(0)
	v_mov_b32_e32 v47, v48
	v_mov_b32_e32 v43, v50
	v_mov_b32_e32 v45, v51
	v_add_f32_e32 v46, 0, v20
	v_mov_b32_e32 v37, v49
	v_pk_add_f32 v[40:41], v[42:43], v[44:45]
	v_pk_add_f32 v[36:37], v[46:47], v[36:37]
	v_mov_b32_e32 v20, v29
	v_pk_add_f32 v[36:37], v[36:37], v[40:41]
	v_mov_b32_e32 v29, v22
	v_add_f32_e32 v36, v36, v37
	v_mov_b32_e32 v37, v36
	s_nop 1
	v_permlane16_swap_b32_e32 v37, v36
	v_mov_b32_e32 v22, v31
	v_mad_i64_i32 v[30:31], s[8:9], v52, s68, v[60:61]
	v_lshl_add_u64 v[30:31], v[30:31], 0, v[2:3]
	s_waitcnt lgkmcnt(0)
	v_add_f32_e32 v38, v36, v37
	v_mov_b32_e32 v39, v38
	s_nop 1
	v_permlane32_swap_b32_e32 v39, v38
	v_add_u32_e32 v36, 0xb0, v132
	v_ashrrev_i32_e32 v37, 31, v36
	s_waitcnt lgkmcnt(0)
	v_add_f32_e32 v38, v38, v39
	v_fmamk_f32 v38, v38, 0x3a000000, v226
	v_mul_f32_e32 v39, 0x4b800000, v38
	v_cmp_gt_f32_e32 vcc, s67, v38
	s_nop 1
	v_cndmask_b32_e32 v38, v38, v39, vcc
	v_rsq_f32_e32 v40, v38
	v_lshlrev_b64 v[38:39], 8, v[36:37]
	v_lshl_add_u64 v[38:39], v[204:205], 0, v[38:39]
	v_mul_f32_e32 v37, 0x45800000, v40
	v_cndmask_b32_e32 v40, v40, v37, vcc
	v_pk_mul_f32 v[22:23], v[22:23], v[40:41] op_sel_hi:[1,0]
	v_pk_mul_f32 v[42:43], v[54:55], v[40:41] op_sel_hi:[1,0]
	v_pk_mul_f32 v[24:25], v[24:25], v[40:41] op_sel_hi:[1,0]
	v_pk_mul_f32 v[32:33], v[32:33], v[40:41] op_sel_hi:[1,0]
	v_pk_mul_f32 v[26:27], v[26:27], v[40:41] op_sel_hi:[1,0]
	v_pk_mul_f32 v[34:35], v[34:35], v[40:41] op_sel_hi:[1,0]
	v_pk_mul_f32 v[20:21], v[20:21], v[40:41] op_sel_hi:[1,0]
	v_pk_mul_f32 v[28:29], v[28:29], v[40:41] op_sel_hi:[1,0]
	v_mul_f32_e32 v48, 0xbfb8aa3b, v23
	v_mul_f32_e32 v37, 0xbfb8aa3b, v43
	v_mul_f32_e32 v40, 0xbfb8aa3b, v25
	v_mul_f32_e32 v41, 0xbfb8aa3b, v33
	v_mul_f32_e32 v44, 0xbfb8aa3b, v27
	v_mul_f32_e32 v45, 0xbfb8aa3b, v35
	v_mul_f32_e32 v46, 0xbfb8aa3b, v21
	v_mul_f32_e32 v47, 0xbfb8aa3b, v29
	v_exp_f32_e32 v48, v48
	v_exp_f32_e32 v37, v37
	v_exp_f32_e32 v40, v40
	v_exp_f32_e32 v41, v41
	v_exp_f32_e32 v44, v44
	v_exp_f32_e32 v45, v45
	v_exp_f32_e32 v46, v46
	v_exp_f32_e32 v47, v47
	v_add_f32_e32 v48, 1.0, v48
	v_add_f32_e32 v37, 1.0, v37
	v_add_f32_e32 v40, 1.0, v40
	v_add_f32_e32 v41, 1.0, v41
	v_add_f32_e32 v44, 1.0, v44
	v_add_f32_e32 v45, 1.0, v45
	v_add_f32_e32 v46, 1.0, v46
	v_add_f32_e32 v47, 1.0, v47
	v_rcp_f32_e32 v48, v48
	v_rcp_f32_e32 v37, v37
	v_rcp_f32_e32 v40, v40
	v_rcp_f32_e32 v41, v41
	v_rcp_f32_e32 v44, v44
	v_rcp_f32_e32 v45, v45
	v_rcp_f32_e32 v46, v46
	v_rcp_f32_e32 v47, v47
	v_mul_f32_e32 v23, v23, v48
	v_mul_f32_e32 v37, v43, v37
	v_mul_f32_e32 v25, v25, v40
	v_mul_f32_e32 v33, v33, v41
	v_mul_f32_e32 v27, v27, v44
	v_mul_f32_e32 v35, v35, v45
	v_mul_f32_e32 v21, v21, v46
	v_mul_f32_e32 v29, v29, v47
	v_mul_f32_e32 v23, v22, v23
	v_mul_f32_e32 v37, v42, v37
	v_mul_f32_e32 v24, v24, v25
	v_mul_f32_e32 v25, v32, v33
	v_mul_f32_e32 v26, v26, v27
	v_mul_f32_e32 v27, v34, v35
	v_mul_f32_e32 v32, v20, v21
	v_mul_f32_e32 v28, v28, v29
	v_cvt_pk_bf16_f32 v20, v37, v24
	v_cvt_pk_bf16_f32 v21, v25, v26
	v_cvt_pk_bf16_f32 v22, v27, v32
	v_cvt_pk_bf16_f32 v23, v28, v23
	global_store_dwordx4 v[30:31], v[20:23], off
	global_load_dwordx4 v[20:23], v[38:39], off
	global_load_dwordx4 v[24:27], v[38:39], off offset:16
	global_load_dwordx4 v[28:31], v[38:39], off offset:32
	global_load_dwordx4 v[32:35], v[38:39], off offset:48
	v_mov_b32_e32 v38, v16
	v_mov_b32_e32 v39, v8
	v_mov_b32_e32 v8, v17
	s_waitcnt vmcnt(3)
	v_mov_b32_e32 v16, v21
	v_mov_b32_e32 v17, v22
	v_mov_b32_e32 v21, v23
	s_waitcnt vmcnt(2)
	v_mov_b32_e32 v22, v25
	v_mov_b32_e32 v23, v26
	v_mov_b32_e32 v25, v27
	v_pk_add_f32 v[16:17], v[16:17], v[20:21]
	v_pk_add_f32 v[20:21], v[22:23], v[24:25]
	v_add_f32_e32 v24, v16, v17
	v_pk_add_f32 v[16:17], v[20:21], v[20:21] op_sel:[0,1] op_sel_hi:[1,0]
	s_waitcnt vmcnt(1)
	v_add_f32_e32 v26, v28, v29
	v_add_f32_e32 v28, v30, v31
	s_waitcnt vmcnt(0)
	v_mov_b32_e32 v31, v32
	v_mov_b32_e32 v27, v34
	v_mov_b32_e32 v29, v35
	v_add_f32_e32 v30, 0, v24
	v_mov_b32_e32 v17, v33
	v_pk_add_f32 v[22:23], v[26:27], v[28:29]
	v_pk_add_f32 v[16:17], v[30:31], v[16:17]
	s_nop 0
	v_pk_add_f32 v[16:17], v[16:17], v[22:23]
	s_nop 0
	v_add_f32_e32 v20, v16, v17
	v_mov_b32_e32 v1, v20
	s_nop 1
	v_permlane16_swap_b32_e32 v1, v20
	v_mov_b32_e32 v17, v10
	v_mov_b32_e32 v10, v19
	v_mov_b32_e32 v19, v4
	v_mov_b32_e32 v4, v13
	s_waitcnt lgkmcnt(0)
	v_add_f32_e32 v1, v20, v1
	v_mov_b32_e32 v20, v1
	s_nop 1
	v_permlane32_swap_b32_e32 v20, v1
	v_mov_b32_e32 v13, v6
	v_mov_b32_e32 v16, v18
	v_mov_b32_e32 v18, v12
	v_mov_b32_e32 v12, v14
	s_waitcnt lgkmcnt(0)
	v_add_f32_e32 v1, v1, v20
	v_fmamk_f32 v1, v1, 0x3a000000, v226
	v_mul_f32_e32 v6, 0x4b800000, v1
	v_cmp_gt_f32_e32 vcc, s67, v1
	s_nop 1
	v_cndmask_b32_e32 v1, v1, v6, vcc
	v_rsq_f32_e32 v1, v1
	v_mov_b32_e32 v6, v15
	v_mad_i64_i32 v[14:15], s[8:9], v36, s68, v[60:61]
	v_mul_f32_e32 v20, 0x45800000, v1
	v_cndmask_b32_e32 v20, v1, v20, vcc
	v_pk_mul_f32 v[6:7], v[6:7], v[20:21] op_sel_hi:[1,0]
	v_pk_mul_f32 v[22:23], v[38:39], v[20:21] op_sel_hi:[1,0]
	v_pk_mul_f32 v[8:9], v[8:9], v[20:21] op_sel_hi:[1,0]
	v_pk_mul_f32 v[16:17], v[16:17], v[20:21] op_sel_hi:[1,0]
	v_pk_mul_f32 v[10:11], v[10:11], v[20:21] op_sel_hi:[1,0]
	v_pk_mul_f32 v[18:19], v[18:19], v[20:21] op_sel_hi:[1,0]
	v_pk_mul_f32 v[4:5], v[4:5], v[20:21] op_sel_hi:[1,0]
	v_pk_mul_f32 v[12:13], v[12:13], v[20:21] op_sel_hi:[1,0]
	v_mul_f32_e32 v28, 0xbfb8aa3b, v7
	v_mul_f32_e32 v1, 0xbfb8aa3b, v23
	v_mul_f32_e32 v20, 0xbfb8aa3b, v9
	v_mul_f32_e32 v21, 0xbfb8aa3b, v17
	v_mul_f32_e32 v24, 0xbfb8aa3b, v11
	v_mul_f32_e32 v25, 0xbfb8aa3b, v19
	v_mul_f32_e32 v26, 0xbfb8aa3b, v5
	v_mul_f32_e32 v27, 0xbfb8aa3b, v13
	v_exp_f32_e32 v28, v28
	v_exp_f32_e32 v1, v1
	v_exp_f32_e32 v20, v20
	v_exp_f32_e32 v21, v21
	v_exp_f32_e32 v24, v24
	v_exp_f32_e32 v25, v25
	v_exp_f32_e32 v26, v26
	v_exp_f32_e32 v27, v27
	v_add_f32_e32 v28, 1.0, v28
	v_add_f32_e32 v1, 1.0, v1
	v_add_f32_e32 v20, 1.0, v20
	v_add_f32_e32 v21, 1.0, v21
	v_add_f32_e32 v24, 1.0, v24
	v_add_f32_e32 v25, 1.0, v25
	v_add_f32_e32 v26, 1.0, v26
	v_add_f32_e32 v27, 1.0, v27
	v_rcp_f32_e32 v28, v28
	v_rcp_f32_e32 v1, v1
	v_rcp_f32_e32 v20, v20
	v_rcp_f32_e32 v21, v21
	v_rcp_f32_e32 v24, v24
	v_rcp_f32_e32 v25, v25
	v_rcp_f32_e32 v26, v26
	v_rcp_f32_e32 v27, v27
	v_mul_f32_e32 v7, v7, v28
	v_mul_f32_e32 v1, v23, v1
	v_mul_f32_e32 v9, v9, v20
	v_mul_f32_e32 v17, v17, v21
	v_mul_f32_e32 v11, v11, v24
	v_mul_f32_e32 v19, v19, v25
	v_mul_f32_e32 v5, v5, v26
	v_mul_f32_e32 v13, v13, v27
	v_mul_f32_e32 v7, v6, v7
	v_lshl_add_u64 v[2:3], v[14:15], 0, v[2:3]
	v_mul_f32_e32 v1, v22, v1
	v_mul_f32_e32 v8, v8, v9
	v_mul_f32_e32 v9, v16, v17
	v_mul_f32_e32 v10, v10, v11
	v_mul_f32_e32 v11, v18, v19
	v_mul_f32_e32 v16, v4, v5
	v_mul_f32_e32 v12, v12, v13
	v_cvt_pk_bf16_f32 v4, v1, v8
	v_cvt_pk_bf16_f32 v5, v9, v10
	v_cvt_pk_bf16_f32 v6, v11, v16
	v_cvt_pk_bf16_f32 v7, v12, v7
	global_store_dwordx4 v[2:3], v[4:7], off
	s_andn2_b64 vcc, exec, s[24:25]
	s_mov_b64 s[8:9], -1
	s_cbranch_vccnz .LBB0_1036

.LBB0_1140:
	v_lshl_add_u32 v146, s65, 8, v148
	v_lshl_or_b32 v144, s12, 8, v150
	v_ashrrev_i32_e32 v147, 31, v146
	v_ashrrev_i32_e32 v145, 31, v144
	v_lshlrev_b64 v[156:157], 11, v[146:147]
	v_lshl_add_u64 v[156:157], v[156:157], 0, v[144:145]
	v_lshlrev_b64 v[160:161], 1, v[156:157]
	v_lshl_add_u64 v[156:157], s[18:19], 0, v[160:161]
	global_load_dwordx4 v[156:159], v[156:157], off
	v_lshl_add_u64 v[162:163], s[16:17], 0, v[160:161]
	v_or_b32_e32 v160, 0x100, v160
	v_lshl_add_u64 v[164:165], s[18:19], 0, v[160:161]
	v_xor_b32_e32 v155, 32, v154
	s_lshl_b32 s30, s12, 2
	s_ashr_i32 s31, s30, 31
	s_waitcnt vmcnt(0)
	v_lshlrev_b32_e32 v166, 16, v156
	v_and_b32_e32 v167, 0xffff0000, v156
	v_lshlrev_b32_e32 v156, 16, v157
	v_and_b32_e32 v157, 0xffff0000, v157
	v_lshlrev_b32_e32 v168, 16, v158
	v_and_b32_e32 v169, 0xffff0000, v158
	v_lshlrev_b32_e32 v158, 16, v159
	v_and_b32_e32 v159, 0xffff0000, v159
	v_pk_add_f32 v[126:127], v[126:127], v[156:157]
	v_pk_add_f32 v[166:167], v[124:125], v[166:167]
	v_pk_add_f32 v[170:171], v[122:123], v[158:159]
	v_pk_add_f32 v[168:169], v[120:121], v[168:169]
	v_cvt_pk_bf16_f32 v122, v166, v167
	v_cvt_pk_bf16_f32 v123, v126, v127
	v_mul_f32_e32 v127, v127, v127
	v_cvt_pk_bf16_f32 v124, v168, v169
	v_cvt_pk_bf16_f32 v125, v170, v171
	global_load_dwordx4 v[156:159], v[164:165], off
	v_mul_f32_e32 v164, v167, v167
	v_mul_f32_e32 v165, v169, v169
	v_mul_f32_e32 v167, v171, v171
	v_fmac_f32_e32 v164, v166, v166
	v_fmac_f32_e32 v127, v126, v126
	v_fmac_f32_e32 v165, v168, v168
	v_fmac_f32_e32 v167, v170, v170
	v_add_f32_e32 v126, v164, v127
	v_add_f32_e32 v127, v165, v167
	v_add_f32_e32 v166, v126, v127
	v_and_b32_e32 v121, 64, v154
	v_xor_b32_e32 v120, 16, v154
	v_add_u32_e32 v121, 64, v121
	v_cmp_lt_i32_e32 vcc, v120, v121
	global_store_dwordx4 v[162:163], v[122:125], off
	s_waitcnt vmcnt(1)
	v_lshlrev_b32_e32 v126, 16, v156
	v_and_b32_e32 v127, 0xffff0000, v156
	v_lshlrev_b32_e32 v156, 16, v157
	v_and_b32_e32 v157, 0xffff0000, v157
	v_lshlrev_b32_e32 v164, 16, v158
	v_and_b32_e32 v165, 0xffff0000, v158
	v_lshlrev_b32_e32 v158, 16, v159
	v_and_b32_e32 v159, 0xffff0000, v159
	v_pk_add_f32 v[118:119], v[118:119], v[156:157]
	v_pk_add_f32 v[116:117], v[116:117], v[126:127]
	v_pk_add_f32 v[126:127], v[114:115], v[158:159]
	v_pk_add_f32 v[156:157], v[112:113], v[164:165]
	v_mul_f32_e32 v112, v117, v117
	v_mul_f32_e32 v113, v119, v119
	v_mul_f32_e32 v114, v157, v157
	v_mul_f32_e32 v115, v127, v127
	v_fmac_f32_e32 v112, v116, v116
	v_fmac_f32_e32 v113, v118, v118
	v_fmac_f32_e32 v114, v156, v156
	v_fmac_f32_e32 v115, v126, v126
	v_add_f32_e32 v112, v112, v113
	v_add_f32_e32 v113, v114, v115
	v_cndmask_b32_e32 v120, v154, v120, vcc
	v_add_f32_e32 v112, v112, v113
	v_lshlrev_b32_e32 v120, 2, v120
	v_add_f32_e32 v112, v166, v112
	v_mov_b32_e32 v113, v112
	s_nop 1
	v_permlane16_swap_b32_e32 v113, v112
	v_cmp_lt_i32_e32 vcc, v155, v121
	v_lshl_add_u64 v[122:123], s[16:17], 0, v[160:161]
	v_cvt_pk_bf16_f32 v116, v116, v117
	v_cvt_pk_bf16_f32 v117, v118, v119
	s_waitcnt lgkmcnt(0)
	v_add_f32_e32 v112, v112, v113
	v_cndmask_b32_e32 v114, v154, v155, vcc
	v_lshlrev_b32_e32 v114, 2, v114
	v_mov_b32_e32 v113, v112
	s_nop 1
	v_permlane32_swap_b32_e32 v113, v112
	v_cvt_pk_bf16_f32 v118, v156, v157
	v_cvt_pk_bf16_f32 v119, v126, v127
	global_store_dwordx4 v[122:123], v[116:119], off
	s_and_saveexec_b64 s[34:35], s[6:7]
	s_cbranch_execz .LBB0_1142
	s_waitcnt lgkmcnt(0)
	v_add_f32_e32 v115, v112, v113
	v_lshlrev_b64 v[112:113], 7, v[146:147]
	v_lshl_add_u64 v[112:113], s[20:21], 0, v[112:113]
	v_lshl_add_u64 v[112:113], s[30:31], 2, v[112:113]
	s_lshl_b32 s12, s57, 2
	v_lshl_add_u64 v[112:113], v[112:113], 0, s[12:13]
	global_store_dword v[112:113], v115, off
.LBB0_1142:
	s_or_b64 exec, exec, s[34:35]
	v_or_b32_e32 v112, 16, v146
	s_waitcnt lgkmcnt(0)
	v_ashrrev_i32_e32 v113, 31, v112
	v_lshlrev_b64 v[116:117], 11, v[112:113]
	v_lshl_add_u64 v[116:117], v[116:117], 0, v[144:145]
	v_lshlrev_b64 v[122:123], 1, v[116:117]
	v_lshl_add_u64 v[116:117], s[18:19], 0, v[122:123]
	global_load_dwordx4 v[116:119], v[116:117], off
	v_lshl_add_u64 v[124:125], s[16:17], 0, v[122:123]
	v_or_b32_e32 v122, 0x100, v122
	v_lshl_add_u64 v[126:127], s[18:19], 0, v[122:123]
	s_waitcnt vmcnt(0)
	v_lshlrev_b32_e32 v156, 16, v116
	v_and_b32_e32 v157, 0xffff0000, v116
	v_lshlrev_b32_e32 v116, 16, v117
	v_and_b32_e32 v117, 0xffff0000, v117
	v_lshlrev_b32_e32 v158, 16, v118
	v_and_b32_e32 v159, 0xffff0000, v118
	v_lshlrev_b32_e32 v118, 16, v119
	v_and_b32_e32 v119, 0xffff0000, v119
	v_pk_add_f32 v[116:117], v[110:111], v[116:117]
	v_pk_add_f32 v[156:157], v[108:109], v[156:157]
	v_pk_add_f32 v[118:119], v[106:107], v[118:119]
	v_pk_add_f32 v[158:159], v[104:105], v[158:159]
	v_cvt_pk_bf16_f32 v104, v156, v157
	v_cvt_pk_bf16_f32 v105, v116, v117
	v_mul_f32_e32 v115, v157, v157
	v_cvt_pk_bf16_f32 v106, v158, v159
	v_cvt_pk_bf16_f32 v107, v118, v119
	global_load_dwordx4 v[108:111], v[126:127], off
	v_mul_f32_e32 v117, v117, v117
	v_mul_f32_e32 v121, v159, v159
	v_mul_f32_e32 v119, v119, v119
	v_fmac_f32_e32 v115, v156, v156
	v_fmac_f32_e32 v117, v116, v116
	v_fmac_f32_e32 v121, v158, v158
	v_fmac_f32_e32 v119, v118, v118
	v_add_f32_e32 v115, v115, v117
	v_add_f32_e32 v116, v121, v119
	v_add_f32_e32 v115, v115, v116
	global_store_dwordx4 v[124:125], v[104:107], off
	s_waitcnt vmcnt(1)
	v_lshlrev_b32_e32 v116, 16, v108
	v_and_b32_e32 v117, 0xffff0000, v108
	v_lshlrev_b32_e32 v108, 16, v109
	v_and_b32_e32 v109, 0xffff0000, v109
	v_lshlrev_b32_e32 v118, 16, v110
	v_and_b32_e32 v119, 0xffff0000, v110
	v_lshlrev_b32_e32 v110, 16, v111
	v_and_b32_e32 v111, 0xffff0000, v111
	v_pk_add_f32 v[102:103], v[102:103], v[108:109]
	v_pk_add_f32 v[100:101], v[100:101], v[116:117]
	v_pk_add_f32 v[108:109], v[98:99], v[110:111]
	v_pk_add_f32 v[110:111], v[96:97], v[118:119]
	v_mul_f32_e32 v96, v101, v101
	v_mul_f32_e32 v97, v103, v103
	v_mul_f32_e32 v98, v111, v111
	v_mul_f32_e32 v99, v109, v109
	v_fmac_f32_e32 v96, v100, v100
	v_fmac_f32_e32 v97, v102, v102
	v_fmac_f32_e32 v98, v110, v110
	v_fmac_f32_e32 v99, v108, v108
	v_add_f32_e32 v96, v96, v97
	v_add_f32_e32 v97, v98, v99
	v_add_f32_e32 v96, v96, v97
	v_add_f32_e32 v96, v115, v96
	v_mov_b32_e32 v97, v96
	s_nop 1
	v_permlane16_swap_b32_e32 v97, v96
	v_cvt_pk_bf16_f32 v98, v100, v101
	v_cvt_pk_bf16_f32 v99, v102, v103
	v_lshl_add_u64 v[102:103], s[16:17], 0, v[122:123]
	v_cvt_pk_bf16_f32 v100, v110, v111
	s_waitcnt lgkmcnt(0)
	v_add_f32_e32 v96, v96, v97
	v_mov_b32_e32 v97, v96
	s_nop 1
	v_permlane32_swap_b32_e32 v97, v96
	v_cvt_pk_bf16_f32 v101, v108, v109
	global_store_dwordx4 v[102:103], v[98:101], off
	s_and_saveexec_b64 s[34:35], s[6:7]
	s_cbranch_execz .LBB0_1144
	s_waitcnt lgkmcnt(0)
	v_add_f32_e32 v98, v96, v97
	v_lshlrev_b64 v[96:97], 7, v[112:113]
	v_lshl_add_u64 v[96:97], s[20:21], 0, v[96:97]
	v_lshl_add_u64 v[96:97], s[30:31], 2, v[96:97]
	s_lshl_b32 s12, s57, 2
	v_lshl_add_u64 v[96:97], v[96:97], 0, s[12:13]
	global_store_dword v[96:97], v98, off
.LBB0_1144:
	s_or_b64 exec, exec, s[34:35]
	v_or_b32_e32 v96, 32, v146
	s_waitcnt lgkmcnt(0)
	v_ashrrev_i32_e32 v97, 31, v96
	v_lshlrev_b64 v[98:99], 11, v[96:97]
	v_lshl_add_u64 v[98:99], v[98:99], 0, v[144:145]
	v_lshlrev_b64 v[102:103], 1, v[98:99]
	v_lshl_add_u64 v[98:99], s[18:19], 0, v[102:103]
	global_load_dwordx4 v[98:101], v[98:99], off
	v_lshl_add_u64 v[104:105], s[16:17], 0, v[102:103]
	v_or_b32_e32 v102, 0x100, v102
	v_lshl_add_u64 v[106:107], s[18:19], 0, v[102:103]
	s_waitcnt vmcnt(0)
	v_lshlrev_b32_e32 v108, 16, v98
	v_and_b32_e32 v109, 0xffff0000, v98
	v_lshlrev_b32_e32 v98, 16, v99
	v_and_b32_e32 v99, 0xffff0000, v99
	v_lshlrev_b32_e32 v110, 16, v100
	v_and_b32_e32 v111, 0xffff0000, v100
	v_lshlrev_b32_e32 v100, 16, v101
	v_and_b32_e32 v101, 0xffff0000, v101
	v_pk_add_f32 v[98:99], v[94:95], v[98:99]
	v_pk_add_f32 v[108:109], v[92:93], v[108:109]
	v_pk_add_f32 v[100:101], v[90:91], v[100:101]
	v_pk_add_f32 v[110:111], v[88:89], v[110:111]
	v_cvt_pk_bf16_f32 v88, v108, v109
	v_cvt_pk_bf16_f32 v89, v98, v99
	v_mul_f32_e32 v99, v99, v99
	v_cvt_pk_bf16_f32 v90, v110, v111
	v_cvt_pk_bf16_f32 v91, v100, v101
	global_load_dwordx4 v[92:95], v[106:107], off
	v_mul_f32_e32 v106, v109, v109
	v_mul_f32_e32 v107, v111, v111
	v_mul_f32_e32 v101, v101, v101
	v_fmac_f32_e32 v106, v108, v108
	v_fmac_f32_e32 v99, v98, v98
	v_fmac_f32_e32 v107, v110, v110
	v_fmac_f32_e32 v101, v100, v100
	v_add_f32_e32 v98, v106, v99
	v_add_f32_e32 v99, v107, v101
	v_add_f32_e32 v106, v98, v99
	global_store_dwordx4 v[104:105], v[88:91], off
	s_waitcnt vmcnt(1)
	v_lshlrev_b32_e32 v98, 16, v92
	v_and_b32_e32 v99, 0xffff0000, v92
	v_lshlrev_b32_e32 v92, 16, v93
	v_and_b32_e32 v93, 0xffff0000, v93
	v_lshlrev_b32_e32 v100, 16, v94
	v_and_b32_e32 v101, 0xffff0000, v94
	v_lshlrev_b32_e32 v94, 16, v95
	v_and_b32_e32 v95, 0xffff0000, v95
	v_pk_add_f32 v[86:87], v[86:87], v[92:93]
	v_pk_add_f32 v[84:85], v[84:85], v[98:99]
	v_pk_add_f32 v[92:93], v[82:83], v[94:95]
	v_pk_add_f32 v[94:95], v[80:81], v[100:101]
	v_mul_f32_e32 v80, v85, v85
	v_mul_f32_e32 v81, v87, v87
	v_mul_f32_e32 v82, v95, v95
	v_mul_f32_e32 v83, v93, v93
	v_fmac_f32_e32 v80, v84, v84
	v_fmac_f32_e32 v81, v86, v86
	v_fmac_f32_e32 v82, v94, v94
	v_fmac_f32_e32 v83, v92, v92
	v_add_f32_e32 v80, v80, v81
	v_add_f32_e32 v81, v82, v83
	v_add_f32_e32 v80, v80, v81
	v_add_f32_e32 v80, v106, v80
	v_mov_b32_e32 v81, v80
	s_nop 1
	v_permlane16_swap_b32_e32 v81, v80
	v_cvt_pk_bf16_f32 v82, v84, v85
	v_cvt_pk_bf16_f32 v83, v86, v87
	v_lshl_add_u64 v[86:87], s[16:17], 0, v[102:103]
	v_cvt_pk_bf16_f32 v84, v94, v95
	s_waitcnt lgkmcnt(0)
	v_add_f32_e32 v80, v80, v81
	v_mov_b32_e32 v81, v80
	s_nop 1
	v_permlane32_swap_b32_e32 v81, v80
	v_cvt_pk_bf16_f32 v85, v92, v93
	global_store_dwordx4 v[86:87], v[82:85], off
	s_and_saveexec_b64 s[34:35], s[6:7]
	s_cbranch_execz .LBB0_1146
	s_waitcnt lgkmcnt(0)
	v_add_f32_e32 v82, v80, v81
	v_lshlrev_b64 v[80:81], 7, v[96:97]
	v_lshl_add_u64 v[80:81], s[20:21], 0, v[80:81]
	v_lshl_add_u64 v[80:81], s[30:31], 2, v[80:81]
	s_lshl_b32 s12, s57, 2
	v_lshl_add_u64 v[80:81], v[80:81], 0, s[12:13]
	global_store_dword v[80:81], v82, off
.LBB0_1146:
	s_or_b64 exec, exec, s[34:35]
	v_or_b32_e32 v80, 48, v146
	s_waitcnt lgkmcnt(0)
	v_ashrrev_i32_e32 v81, 31, v80
	v_lshlrev_b64 v[82:83], 11, v[80:81]
	v_lshl_add_u64 v[82:83], v[82:83], 0, v[144:145]
	v_lshlrev_b64 v[86:87], 1, v[82:83]
	v_lshl_add_u64 v[82:83], s[18:19], 0, v[86:87]
	global_load_dwordx4 v[82:85], v[82:83], off
	v_lshl_add_u64 v[88:89], s[16:17], 0, v[86:87]
	v_or_b32_e32 v86, 0x100, v86
	v_lshl_add_u64 v[90:91], s[18:19], 0, v[86:87]
	s_waitcnt vmcnt(0)
	v_lshlrev_b32_e32 v92, 16, v82
	v_and_b32_e32 v93, 0xffff0000, v82
	v_lshlrev_b32_e32 v82, 16, v83
	v_and_b32_e32 v83, 0xffff0000, v83
	v_lshlrev_b32_e32 v94, 16, v84
	v_and_b32_e32 v95, 0xffff0000, v84
	v_lshlrev_b32_e32 v84, 16, v85
	v_and_b32_e32 v85, 0xffff0000, v85
	v_pk_add_f32 v[82:83], v[78:79], v[82:83]
	v_pk_add_f32 v[92:93], v[76:77], v[92:93]
	v_pk_add_f32 v[84:85], v[74:75], v[84:85]
	v_pk_add_f32 v[94:95], v[72:73], v[94:95]
	v_cvt_pk_bf16_f32 v72, v92, v93
	v_cvt_pk_bf16_f32 v73, v82, v83
	v_mul_f32_e32 v83, v83, v83
	v_cvt_pk_bf16_f32 v74, v94, v95
	v_cvt_pk_bf16_f32 v75, v84, v85
	global_load_dwordx4 v[76:79], v[90:91], off
	v_mul_f32_e32 v90, v93, v93
	v_mul_f32_e32 v91, v95, v95
	v_mul_f32_e32 v85, v85, v85
	v_fmac_f32_e32 v90, v92, v92
	v_fmac_f32_e32 v83, v82, v82
	v_fmac_f32_e32 v91, v94, v94
	v_fmac_f32_e32 v85, v84, v84
	v_add_f32_e32 v82, v90, v83
	v_add_f32_e32 v83, v91, v85
	v_add_f32_e32 v90, v82, v83
	global_store_dwordx4 v[88:89], v[72:75], off
	s_waitcnt vmcnt(1)
	v_lshlrev_b32_e32 v82, 16, v76
	v_and_b32_e32 v83, 0xffff0000, v76
	v_lshlrev_b32_e32 v76, 16, v77
	v_and_b32_e32 v77, 0xffff0000, v77
	v_lshlrev_b32_e32 v84, 16, v78
	v_and_b32_e32 v85, 0xffff0000, v78
	v_lshlrev_b32_e32 v78, 16, v79
	v_and_b32_e32 v79, 0xffff0000, v79
	v_pk_add_f32 v[70:71], v[70:71], v[76:77]
	v_pk_add_f32 v[68:69], v[68:69], v[82:83]
	v_pk_add_f32 v[76:77], v[66:67], v[78:79]
	v_pk_add_f32 v[78:79], v[64:65], v[84:85]
	v_mul_f32_e32 v64, v69, v69
	v_mul_f32_e32 v65, v71, v71
	v_mul_f32_e32 v66, v79, v79
	v_mul_f32_e32 v67, v77, v77
	v_fmac_f32_e32 v64, v68, v68
	v_fmac_f32_e32 v65, v70, v70
	v_fmac_f32_e32 v66, v78, v78
	v_fmac_f32_e32 v67, v76, v76
	v_add_f32_e32 v64, v64, v65
	v_add_f32_e32 v65, v66, v67
	v_add_f32_e32 v64, v64, v65
	v_add_f32_e32 v64, v90, v64
	v_mov_b32_e32 v65, v64
	s_nop 1
	v_permlane16_swap_b32_e32 v65, v64
	v_cvt_pk_bf16_f32 v66, v68, v69
	v_cvt_pk_bf16_f32 v67, v70, v71
	v_lshl_add_u64 v[70:71], s[16:17], 0, v[86:87]
	v_cvt_pk_bf16_f32 v68, v78, v79
	s_waitcnt lgkmcnt(0)
	v_add_f32_e32 v64, v64, v65
	v_mov_b32_e32 v65, v64
	s_nop 1
	v_permlane32_swap_b32_e32 v65, v64
	v_cvt_pk_bf16_f32 v69, v76, v77
	global_store_dwordx4 v[70:71], v[66:69], off
	s_and_saveexec_b64 s[34:35], s[6:7]
	s_cbranch_execz .LBB0_1148
	s_waitcnt lgkmcnt(0)
	v_add_f32_e32 v66, v64, v65
	v_lshlrev_b64 v[64:65], 7, v[80:81]
	v_lshl_add_u64 v[64:65], s[20:21], 0, v[64:65]
	v_lshl_add_u64 v[64:65], s[30:31], 2, v[64:65]
	s_lshl_b32 s12, s57, 2
	v_lshl_add_u64 v[64:65], v[64:65], 0, s[12:13]
	global_store_dword v[64:65], v66, off
.LBB0_1148:
	s_or_b64 exec, exec, s[34:35]
	v_add_u32_e32 v64, 0x80, v146
	s_waitcnt lgkmcnt(0)
	v_ashrrev_i32_e32 v65, 31, v64
	v_lshlrev_b64 v[66:67], 11, v[64:65]
	v_lshl_add_u64 v[66:67], v[66:67], 0, v[144:145]
	v_lshlrev_b64 v[70:71], 1, v[66:67]
	v_lshl_add_u64 v[66:67], s[18:19], 0, v[70:71]
	global_load_dwordx4 v[66:69], v[66:67], off
	v_lshl_add_u64 v[72:73], s[16:17], 0, v[70:71]
	v_or_b32_e32 v70, 0x100, v70
	v_lshl_add_u64 v[74:75], s[18:19], 0, v[70:71]
	s_waitcnt vmcnt(0)
	v_lshlrev_b32_e32 v76, 16, v66
	v_and_b32_e32 v77, 0xffff0000, v66
	v_lshlrev_b32_e32 v66, 16, v67
	v_and_b32_e32 v67, 0xffff0000, v67
	v_lshlrev_b32_e32 v78, 16, v68
	v_and_b32_e32 v79, 0xffff0000, v68
	v_lshlrev_b32_e32 v68, 16, v69
	v_and_b32_e32 v69, 0xffff0000, v69
	v_pk_add_f32 v[66:67], v[62:63], v[66:67]
	v_pk_add_f32 v[76:77], v[60:61], v[76:77]
	v_pk_add_f32 v[68:69], v[58:59], v[68:69]
	v_pk_add_f32 v[78:79], v[56:57], v[78:79]
	v_cvt_pk_bf16_f32 v56, v76, v77
	v_cvt_pk_bf16_f32 v57, v66, v67
	v_mul_f32_e32 v67, v67, v67
	v_cvt_pk_bf16_f32 v58, v78, v79
	v_cvt_pk_bf16_f32 v59, v68, v69
	global_load_dwordx4 v[60:63], v[74:75], off
	v_mul_f32_e32 v74, v77, v77
	v_mul_f32_e32 v75, v79, v79
	v_mul_f32_e32 v69, v69, v69
	v_fmac_f32_e32 v74, v76, v76
	v_fmac_f32_e32 v67, v66, v66
	v_fmac_f32_e32 v75, v78, v78
	v_fmac_f32_e32 v69, v68, v68
	v_add_f32_e32 v66, v74, v67
	v_add_f32_e32 v67, v75, v69
	v_add_f32_e32 v74, v66, v67
	global_store_dwordx4 v[72:73], v[56:59], off
	s_waitcnt vmcnt(1)
	v_lshlrev_b32_e32 v66, 16, v60
	v_and_b32_e32 v67, 0xffff0000, v60
	v_lshlrev_b32_e32 v60, 16, v61
	v_and_b32_e32 v61, 0xffff0000, v61
	v_lshlrev_b32_e32 v68, 16, v62
	v_and_b32_e32 v69, 0xffff0000, v62
	v_lshlrev_b32_e32 v62, 16, v63
	v_and_b32_e32 v63, 0xffff0000, v63
	v_pk_add_f32 v[54:55], v[54:55], v[60:61]
	v_pk_add_f32 v[52:53], v[52:53], v[66:67]
	v_pk_add_f32 v[60:61], v[50:51], v[62:63]
	v_pk_add_f32 v[62:63], v[48:49], v[68:69]
	v_mul_f32_e32 v48, v53, v53
	v_mul_f32_e32 v49, v55, v55
	v_mul_f32_e32 v50, v63, v63
	v_mul_f32_e32 v51, v61, v61
	v_fmac_f32_e32 v48, v52, v52
	v_fmac_f32_e32 v49, v54, v54
	v_fmac_f32_e32 v50, v62, v62
	v_fmac_f32_e32 v51, v60, v60
	v_add_f32_e32 v48, v48, v49
	v_add_f32_e32 v49, v50, v51
	v_add_f32_e32 v48, v48, v49
	v_add_f32_e32 v48, v74, v48
	v_mov_b32_e32 v49, v48
	s_nop 1
	v_permlane16_swap_b32_e32 v49, v48
	v_cvt_pk_bf16_f32 v50, v52, v53
	v_cvt_pk_bf16_f32 v51, v54, v55
	v_lshl_add_u64 v[54:55], s[16:17], 0, v[70:71]
	v_cvt_pk_bf16_f32 v52, v62, v63
	s_waitcnt lgkmcnt(0)
	v_add_f32_e32 v48, v48, v49
	v_mov_b32_e32 v49, v48
	s_nop 1
	v_permlane32_swap_b32_e32 v49, v48
	v_cvt_pk_bf16_f32 v53, v60, v61
	global_store_dwordx4 v[54:55], v[50:53], off
	s_and_saveexec_b64 s[34:35], s[6:7]
	s_cbranch_execz .LBB0_1150
	s_waitcnt lgkmcnt(0)
	v_add_f32_e32 v50, v48, v49
	v_lshlrev_b64 v[48:49], 7, v[64:65]
	v_lshl_add_u64 v[48:49], s[20:21], 0, v[48:49]
	v_lshl_add_u64 v[48:49], s[30:31], 2, v[48:49]
	s_lshl_b32 s12, s57, 2
	v_lshl_add_u64 v[48:49], v[48:49], 0, s[12:13]
	global_store_dword v[48:49], v50, off
.LBB0_1150:
	s_or_b64 exec, exec, s[34:35]
	v_add_u32_e32 v48, 0x90, v146
	s_waitcnt lgkmcnt(0)
	v_ashrrev_i32_e32 v49, 31, v48
	v_lshlrev_b64 v[50:51], 11, v[48:49]
	v_lshl_add_u64 v[50:51], v[50:51], 0, v[144:145]
	v_lshlrev_b64 v[54:55], 1, v[50:51]
	v_lshl_add_u64 v[50:51], s[18:19], 0, v[54:55]
	global_load_dwordx4 v[50:53], v[50:51], off
	v_lshl_add_u64 v[56:57], s[16:17], 0, v[54:55]
	v_or_b32_e32 v54, 0x100, v54
	v_lshl_add_u64 v[58:59], s[18:19], 0, v[54:55]
	s_waitcnt vmcnt(0)
	v_lshlrev_b32_e32 v60, 16, v50
	v_and_b32_e32 v61, 0xffff0000, v50
	v_lshlrev_b32_e32 v50, 16, v51
	v_and_b32_e32 v51, 0xffff0000, v51
	v_lshlrev_b32_e32 v62, 16, v52
	v_and_b32_e32 v63, 0xffff0000, v52
	v_lshlrev_b32_e32 v52, 16, v53
	v_and_b32_e32 v53, 0xffff0000, v53
	v_pk_add_f32 v[50:51], v[46:47], v[50:51]
	v_pk_add_f32 v[60:61], v[44:45], v[60:61]
	v_pk_add_f32 v[52:53], v[42:43], v[52:53]
	v_pk_add_f32 v[62:63], v[40:41], v[62:63]
	v_cvt_pk_bf16_f32 v40, v60, v61
	v_cvt_pk_bf16_f32 v41, v50, v51
	v_mul_f32_e32 v51, v51, v51
	v_cvt_pk_bf16_f32 v42, v62, v63
	v_cvt_pk_bf16_f32 v43, v52, v53
	global_load_dwordx4 v[44:47], v[58:59], off
	v_mul_f32_e32 v58, v61, v61
	v_mul_f32_e32 v59, v63, v63
	v_mul_f32_e32 v53, v53, v53
	v_fmac_f32_e32 v58, v60, v60
	v_fmac_f32_e32 v51, v50, v50
	v_fmac_f32_e32 v59, v62, v62
	v_fmac_f32_e32 v53, v52, v52
	v_add_f32_e32 v50, v58, v51
	v_add_f32_e32 v51, v59, v53
	v_add_f32_e32 v58, v50, v51
	global_store_dwordx4 v[56:57], v[40:43], off
	s_waitcnt vmcnt(1)
	v_lshlrev_b32_e32 v50, 16, v44
	v_and_b32_e32 v51, 0xffff0000, v44
	v_lshlrev_b32_e32 v44, 16, v45
	v_and_b32_e32 v45, 0xffff0000, v45
	v_lshlrev_b32_e32 v52, 16, v46
	v_and_b32_e32 v53, 0xffff0000, v46
	v_lshlrev_b32_e32 v46, 16, v47
	v_and_b32_e32 v47, 0xffff0000, v47
	v_pk_add_f32 v[38:39], v[38:39], v[44:45]
	v_pk_add_f32 v[36:37], v[36:37], v[50:51]
	v_pk_add_f32 v[44:45], v[34:35], v[46:47]
	v_pk_add_f32 v[46:47], v[32:33], v[52:53]
	v_mul_f32_e32 v32, v37, v37
	v_mul_f32_e32 v33, v39, v39
	v_mul_f32_e32 v34, v47, v47
	v_mul_f32_e32 v35, v45, v45
	v_fmac_f32_e32 v32, v36, v36
	v_fmac_f32_e32 v33, v38, v38
	v_fmac_f32_e32 v34, v46, v46
	v_fmac_f32_e32 v35, v44, v44
	v_add_f32_e32 v32, v32, v33
	v_add_f32_e32 v33, v34, v35
	v_add_f32_e32 v32, v32, v33
	v_add_f32_e32 v32, v58, v32
	v_mov_b32_e32 v33, v32
	s_nop 1
	v_permlane16_swap_b32_e32 v33, v32
	v_cvt_pk_bf16_f32 v34, v36, v37
	v_cvt_pk_bf16_f32 v35, v38, v39
	v_lshl_add_u64 v[38:39], s[16:17], 0, v[54:55]
	v_cvt_pk_bf16_f32 v36, v46, v47
	s_waitcnt lgkmcnt(0)
	v_add_f32_e32 v32, v32, v33
	v_mov_b32_e32 v33, v32
	s_nop 1
	v_permlane32_swap_b32_e32 v33, v32
	v_cvt_pk_bf16_f32 v37, v44, v45
	global_store_dwordx4 v[38:39], v[34:37], off
	s_and_saveexec_b64 s[34:35], s[6:7]
	s_cbranch_execz .LBB0_1152
	s_waitcnt lgkmcnt(0)
	v_add_f32_e32 v34, v32, v33
	v_lshlrev_b64 v[32:33], 7, v[48:49]
	v_lshl_add_u64 v[32:33], s[20:21], 0, v[32:33]
	v_lshl_add_u64 v[32:33], s[30:31], 2, v[32:33]
	s_lshl_b32 s12, s57, 2
	v_lshl_add_u64 v[32:33], v[32:33], 0, s[12:13]
	global_store_dword v[32:33], v34, off
.LBB0_1152:
	s_or_b64 exec, exec, s[34:35]
	v_add_u32_e32 v32, 0xa0, v146
	s_waitcnt lgkmcnt(0)
	v_ashrrev_i32_e32 v33, 31, v32
	v_lshlrev_b64 v[34:35], 11, v[32:33]
	v_lshl_add_u64 v[34:35], v[34:35], 0, v[144:145]
	v_lshlrev_b64 v[38:39], 1, v[34:35]
	v_lshl_add_u64 v[34:35], s[18:19], 0, v[38:39]
	global_load_dwordx4 v[34:37], v[34:35], off
	v_lshl_add_u64 v[40:41], s[16:17], 0, v[38:39]
	v_or_b32_e32 v38, 0x100, v38
	v_lshl_add_u64 v[42:43], s[18:19], 0, v[38:39]
	s_waitcnt vmcnt(0)
	v_lshlrev_b32_e32 v44, 16, v34
	v_and_b32_e32 v45, 0xffff0000, v34
	v_lshlrev_b32_e32 v34, 16, v35
	v_and_b32_e32 v35, 0xffff0000, v35
	v_lshlrev_b32_e32 v46, 16, v36
	v_and_b32_e32 v47, 0xffff0000, v36
	v_lshlrev_b32_e32 v36, 16, v37
	v_and_b32_e32 v37, 0xffff0000, v37
	v_pk_add_f32 v[34:35], v[30:31], v[34:35]
	v_pk_add_f32 v[44:45], v[28:29], v[44:45]
	v_pk_add_f32 v[36:37], v[26:27], v[36:37]
	v_pk_add_f32 v[46:47], v[24:25], v[46:47]
	v_cvt_pk_bf16_f32 v24, v44, v45
	v_cvt_pk_bf16_f32 v25, v34, v35
	v_mul_f32_e32 v35, v35, v35
	v_cvt_pk_bf16_f32 v26, v46, v47
	v_cvt_pk_bf16_f32 v27, v36, v37
	global_load_dwordx4 v[28:31], v[42:43], off
	v_mul_f32_e32 v42, v45, v45
	v_mul_f32_e32 v43, v47, v47
	v_mul_f32_e32 v37, v37, v37
	v_fmac_f32_e32 v42, v44, v44
	v_fmac_f32_e32 v35, v34, v34
	v_fmac_f32_e32 v43, v46, v46
	v_fmac_f32_e32 v37, v36, v36
	v_add_f32_e32 v34, v42, v35
	v_add_f32_e32 v35, v43, v37
	v_add_f32_e32 v42, v34, v35
	global_store_dwordx4 v[40:41], v[24:27], off
	s_waitcnt vmcnt(1)
	v_lshlrev_b32_e32 v34, 16, v28
	v_and_b32_e32 v35, 0xffff0000, v28
	v_lshlrev_b32_e32 v28, 16, v29
	v_and_b32_e32 v29, 0xffff0000, v29
	v_lshlrev_b32_e32 v36, 16, v30
	v_and_b32_e32 v37, 0xffff0000, v30
	v_lshlrev_b32_e32 v30, 16, v31
	v_and_b32_e32 v31, 0xffff0000, v31
	v_pk_add_f32 v[22:23], v[22:23], v[28:29]
	v_pk_add_f32 v[20:21], v[20:21], v[34:35]
	v_pk_add_f32 v[28:29], v[18:19], v[30:31]
	v_pk_add_f32 v[30:31], v[16:17], v[36:37]
	v_mul_f32_e32 v16, v21, v21
	v_mul_f32_e32 v17, v23, v23
	v_mul_f32_e32 v18, v31, v31
	v_mul_f32_e32 v19, v29, v29
	v_fmac_f32_e32 v16, v20, v20
	v_fmac_f32_e32 v17, v22, v22
	v_fmac_f32_e32 v18, v30, v30
	v_fmac_f32_e32 v19, v28, v28
	v_add_f32_e32 v16, v16, v17
	v_add_f32_e32 v17, v18, v19
	v_add_f32_e32 v16, v16, v17
	v_add_f32_e32 v16, v42, v16
	v_mov_b32_e32 v17, v16
	s_nop 1
	v_permlane16_swap_b32_e32 v17, v16
	v_cvt_pk_bf16_f32 v18, v20, v21
	v_cvt_pk_bf16_f32 v19, v22, v23
	v_lshl_add_u64 v[22:23], s[16:17], 0, v[38:39]
	v_cvt_pk_bf16_f32 v20, v30, v31
	s_waitcnt lgkmcnt(0)
	v_add_f32_e32 v16, v16, v17
	v_mov_b32_e32 v17, v16
	s_nop 1
	v_permlane32_swap_b32_e32 v17, v16
	v_cvt_pk_bf16_f32 v21, v28, v29
	global_store_dwordx4 v[22:23], v[18:21], off
	s_and_saveexec_b64 s[34:35], s[6:7]
	s_cbranch_execz .LBB0_1154
	s_waitcnt lgkmcnt(0)
	v_add_f32_e32 v18, v16, v17
	v_lshlrev_b64 v[16:17], 7, v[32:33]
	v_lshl_add_u64 v[16:17], s[20:21], 0, v[16:17]
	v_lshl_add_u64 v[16:17], s[30:31], 2, v[16:17]
	s_lshl_b32 s12, s57, 2
	v_lshl_add_u64 v[16:17], v[16:17], 0, s[12:13]
	global_store_dword v[16:17], v18, off
.LBB0_1154:
	s_or_b64 exec, exec, s[34:35]
	v_add_u32_e32 v16, 0xb0, v146
	s_waitcnt lgkmcnt(0)
	v_ashrrev_i32_e32 v17, 31, v16
	v_lshlrev_b64 v[18:19], 11, v[16:17]
	v_lshl_add_u64 v[18:19], v[18:19], 0, v[144:145]
	v_lshlrev_b64 v[22:23], 1, v[18:19]
	v_lshl_add_u64 v[18:19], s[18:19], 0, v[22:23]
	global_load_dwordx4 v[18:21], v[18:19], off
	v_lshl_add_u64 v[24:25], s[16:17], 0, v[22:23]
	v_or_b32_e32 v22, 0x100, v22
	v_lshl_add_u64 v[26:27], s[18:19], 0, v[22:23]
	s_waitcnt vmcnt(0)
	v_lshlrev_b32_e32 v28, 16, v18
	v_and_b32_e32 v29, 0xffff0000, v18
	v_lshlrev_b32_e32 v18, 16, v19
	v_and_b32_e32 v19, 0xffff0000, v19
	v_lshlrev_b32_e32 v30, 16, v20
	v_and_b32_e32 v31, 0xffff0000, v20
	v_lshlrev_b32_e32 v20, 16, v21
	v_and_b32_e32 v21, 0xffff0000, v21
	v_pk_add_f32 v[18:19], v[14:15], v[18:19]
	v_pk_add_f32 v[28:29], v[12:13], v[28:29]
	v_pk_add_f32 v[20:21], v[10:11], v[20:21]
	v_pk_add_f32 v[30:31], v[8:9], v[30:31]
	v_cvt_pk_bf16_f32 v8, v28, v29
	v_cvt_pk_bf16_f32 v9, v18, v19
	v_mul_f32_e32 v19, v19, v19
	v_cvt_pk_bf16_f32 v10, v30, v31
	v_cvt_pk_bf16_f32 v11, v20, v21
	global_load_dwordx4 v[12:15], v[26:27], off
	v_mul_f32_e32 v26, v29, v29
	v_mul_f32_e32 v27, v31, v31
	v_mul_f32_e32 v21, v21, v21
	v_fmac_f32_e32 v26, v28, v28
	v_fmac_f32_e32 v19, v18, v18
	v_fmac_f32_e32 v27, v30, v30
	v_fmac_f32_e32 v21, v20, v20
	v_add_f32_e32 v18, v26, v19
	v_add_f32_e32 v19, v27, v21
	v_add_f32_e32 v26, v18, v19
	global_store_dwordx4 v[24:25], v[8:11], off
	s_waitcnt vmcnt(1)
	v_lshlrev_b32_e32 v18, 16, v12
	v_and_b32_e32 v19, 0xffff0000, v12
	v_lshlrev_b32_e32 v12, 16, v13
	v_and_b32_e32 v13, 0xffff0000, v13
	v_lshlrev_b32_e32 v20, 16, v14
	v_and_b32_e32 v21, 0xffff0000, v14
	v_lshlrev_b32_e32 v14, 16, v15
	v_and_b32_e32 v15, 0xffff0000, v15
	v_pk_add_f32 v[6:7], v[6:7], v[12:13]
	v_pk_add_f32 v[4:5], v[4:5], v[18:19]
	v_pk_add_f32 v[12:13], v[2:3], v[14:15]
	v_pk_add_f32 v[14:15], v[0:1], v[20:21]
	v_mul_f32_e32 v0, v5, v5
	v_mul_f32_e32 v1, v7, v7
	v_mul_f32_e32 v2, v15, v15
	v_mul_f32_e32 v3, v13, v13
	v_fmac_f32_e32 v0, v4, v4
	v_fmac_f32_e32 v1, v6, v6
	v_fmac_f32_e32 v2, v14, v14
	v_fmac_f32_e32 v3, v12, v12
	v_add_f32_e32 v0, v0, v1
	v_add_f32_e32 v1, v2, v3
	v_add_f32_e32 v0, v0, v1
	v_add_f32_e32 v0, v26, v0
	v_mov_b32_e32 v1, v0
	s_nop 1
	v_permlane16_swap_b32_e32 v1, v0
	v_cvt_pk_bf16_f32 v2, v4, v5
	v_cvt_pk_bf16_f32 v3, v6, v7
	v_lshl_add_u64 v[6:7], s[16:17], 0, v[22:23]
	v_cvt_pk_bf16_f32 v4, v14, v15
	s_waitcnt lgkmcnt(0)
	v_add_f32_e32 v0, v0, v1
	v_mov_b32_e32 v1, v0
	s_nop 1
	v_permlane32_swap_b32_e32 v1, v0
	v_cvt_pk_bf16_f32 v5, v12, v13
	global_store_dwordx4 v[6:7], v[2:5], off
	s_and_saveexec_b64 s[34:35], s[6:7]
	s_cbranch_execz .LBB0_1156
	s_waitcnt lgkmcnt(0)
	v_add_f32_e32 v2, v0, v1
	v_lshlrev_b64 v[0:1], 7, v[16:17]
	v_lshl_add_u64 v[0:1], s[20:21], 0, v[0:1]
	v_lshl_add_u64 v[0:1], s[30:31], 2, v[0:1]
	s_lshl_b32 s12, s57, 2
	v_lshl_add_u64 v[0:1], v[0:1], 0, s[12:13]
	global_store_dword v[0:1], v2, off

.LBB0_1234:
	s_add_u32 s4, s8, 0x200000
	s_addc_u32 s5, s9, 0
	s_add_u32 s2, s8, 0x19000000
	s_addc_u32 s3, s9, 0
	s_lshl_b32 s1, s14, 8
	s_add_i32 s1, s1, s52
	v_or_b32_e32 v150, s1, v149
	v_ashrrev_i32_e32 v151, 31, v150
	v_lshlrev_b64 v[134:135], 7, v[150:151]
	v_mov_b32_e32 v131, 0
	v_lshl_add_u64 v[128:129], s[4:5], 0, v[134:135]
	v_lshlrev_b32_e32 v130, 5, v148
	v_lshl_add_u64 v[128:129], v[128:129], 0, v[130:131]
	s_barrier
	global_load_dwordx4 v[136:139], v[128:129], off
	global_load_dwordx4 v[142:145], v[128:129], off offset:16
	s_lshl_b32 s0, s44, 5
	s_lshl_b32 s1, s15, 8
	s_or_b32 s0, s1, s0
	v_lshl_or_b32 v128, v148, 3, s0
	v_ashrrev_i32_e32 v129, 31, v128
	v_lshlrev_b64 v[132:133], 11, v[150:151]
	v_lshl_add_u64 v[132:133], v[132:133], 0, v[128:129]
	v_lshlrev_b64 v[146:147], 1, v[132:133]
	v_lshl_add_u64 v[140:141], s[12:13], 0, v[146:147]
	global_load_dwordx4 v[152:155], v[140:141], off
	v_lshl_add_u64 v[140:141], s[2:3], 0, v[146:147]
	global_load_dwordx4 v[156:159], v[140:141], off
	v_or_b32_e32 v146, 0x100, v146
	v_lshl_add_u64 v[160:161], s[12:13], 0, v[146:147]
	v_lshl_add_u64 v[146:147], s[2:3], 0, v[146:147]
	global_load_dwordx4 v[160:163], v[160:161], off
	s_nop 0
	global_load_dwordx4 v[164:167], v[146:147], off
	v_mbcnt_hi_u32_b32 v130, -1, v254
	v_and_b32_e32 v149, 64, v130
	v_xor_b32_e32 v141, 16, v130
	v_add_u32_e32 v149, 64, v149
	v_xor_b32_e32 v151, 32, v130
	v_cmp_lt_i32_e32 vcc, v141, v149
	v_mov_b32_e32 v140, 0x358637bd
	s_mov_b32 s18, 0x800000
	v_cndmask_b32_e32 v141, v130, v141, vcc
	v_cmp_lt_i32_e32 vcc, v151, v149
	v_lshlrev_b32_e32 v195, 2, v141
	s_lshl_b32 s14, s15, 2
	v_cndmask_b32_e32 v130, v130, v151, vcc
	v_lshlrev_b32_e32 v194, 2, v130
	s_mov_b32 s1, 0
	s_ashr_i32 s15, s14, 31
	s_waitcnt vmcnt(0)
	v_mov_b32_e32 v146, v136
	v_mov_b32_e32 v147, v142
	v_mov_b32_e32 v142, v137
	v_mov_b32_e32 v136, v138
	v_mov_b32_e32 v137, v144
	v_mov_b32_e32 v144, v139
	v_pk_add_f32 v[138:139], v[146:147], v[142:143]
	v_pk_add_f32 v[136:137], v[136:137], v[144:145]
	v_lshlrev_b32_e32 v142, 16, v152
	v_pk_add_f32 v[136:137], v[138:139], v[136:137]
	v_and_b32_e32 v143, 0xffff0000, v152
	v_add_f32_e32 v130, 0, v136
	v_add_f32_e32 v130, v130, v137
	v_mov_b32_e32 v139, v130
	s_nop 1
	v_permlane16_swap_b32_e32 v139, v130
	v_lshlrev_b32_e32 v146, 16, v153
	v_and_b32_e32 v147, 0xffff0000, v153
	v_lshlrev_b32_e32 v152, 16, v158
	v_and_b32_e32 v153, 0xffff0000, v158
	s_waitcnt lgkmcnt(0)
	v_add_f32_e32 v130, v130, v139
	v_mov_b32_e32 v141, v130
	s_nop 1
	v_permlane32_swap_b32_e32 v141, v130
	v_lshlrev_b32_e32 v136, 16, v157
	v_and_b32_e32 v137, 0xffff0000, v157
	v_lshlrev_b32_e32 v138, 16, v154
	v_and_b32_e32 v139, 0xffff0000, v154
	s_waitcnt lgkmcnt(0)
	v_add_f32_e32 v130, v130, v141
	v_fmamk_f32 v130, v130, 0x3a000000, v140
	v_mul_f32_e32 v141, 0x4b800000, v130
	v_cmp_gt_f32_e32 vcc, s18, v130
	v_lshlrev_b32_e32 v144, 16, v156
	v_and_b32_e32 v145, 0xffff0000, v156
	v_cndmask_b32_e32 v130, v130, v141, vcc
	v_rsq_f32_e32 v130, v130
	v_lshlrev_b32_e32 v154, 16, v155
	v_and_b32_e32 v155, 0xffff0000, v155
	v_lshlrev_b32_e32 v156, 16, v159
	v_mul_f32_e32 v141, 0x45800000, v130
	v_cndmask_b32_e32 v130, v130, v141, vcc
	v_mul_f32_e32 v124, v124, v130
	v_mul_f32_e32 v125, v125, v130
	v_mul_f32_e32 v126, v126, v130
	v_mul_f32_e32 v127, v127, v130
	v_mul_f32_e32 v120, v120, v130
	v_mul_f32_e32 v121, v121, v130
	v_mul_f32_e32 v122, v122, v130
	v_mul_f32_e32 v123, v123, v130
	v_mul_f32_e32 v124, 0xbfb8aa3b, v124
	v_mul_f32_e32 v125, 0xbfb8aa3b, v125
	v_mul_f32_e32 v126, 0xbfb8aa3b, v126
	v_mul_f32_e32 v127, 0xbfb8aa3b, v127
	v_mul_f32_e32 v120, 0xbfb8aa3b, v120
	v_mul_f32_e32 v121, 0xbfb8aa3b, v121
	v_mul_f32_e32 v116, v116, v130
	v_mul_f32_e32 v117, v117, v130
	v_mul_f32_e32 v122, 0xbfb8aa3b, v122
	v_mul_f32_e32 v123, 0xbfb8aa3b, v123
	v_exp_f32_e32 v124, v124
	v_exp_f32_e32 v125, v125
	v_exp_f32_e32 v126, v126
	v_exp_f32_e32 v127, v127
	v_exp_f32_e32 v120, v120
	v_exp_f32_e32 v121, v121
	v_mul_f32_e32 v116, 0xbfb8aa3b, v116
	v_mul_f32_e32 v117, 0xbfb8aa3b, v117
	v_mul_f32_e32 v118, v118, v130
	v_mul_f32_e32 v119, v119, v130
	v_exp_f32_e32 v122, v122
	v_exp_f32_e32 v123, v123
	v_exp_f32_e32 v116, v116
	v_exp_f32_e32 v117, v117
	v_mul_f32_e32 v118, 0xbfb8aa3b, v118
	v_mul_f32_e32 v119, 0xbfb8aa3b, v119
	v_exp_f32_e32 v118, v118
	v_exp_f32_e32 v119, v119
	v_add_f32_e32 v124, 1.0, v124
	v_add_f32_e32 v125, 1.0, v125
	v_add_f32_e32 v126, 1.0, v126
	v_add_f32_e32 v127, 1.0, v127
	v_add_f32_e32 v141, 1.0, v120
	v_add_f32_e32 v149, 1.0, v121
	v_mul_f32_e32 v112, v112, v130
	v_add_f32_e32 v151, 1.0, v122
	v_add_f32_e32 v158, 1.0, v123
	v_rcp_f32_e32 v120, v124
	v_rcp_f32_e32 v121, v125
	v_rcp_f32_e32 v122, v126
	v_rcp_f32_e32 v123, v127
	v_rcp_f32_e32 v124, v141
	v_rcp_f32_e32 v125, v149
	v_add_f32_e32 v116, 1.0, v116
	v_add_f32_e32 v117, 1.0, v117
	v_mul_f32_e32 v112, 0xbfb8aa3b, v112
	v_rcp_f32_e32 v116, v116
	v_rcp_f32_e32 v117, v117
	v_add_f32_e32 v118, 1.0, v118
	v_add_f32_e32 v119, 1.0, v119
	v_exp_f32_e32 v141, v112
	v_mul_f32_e32 v112, v113, v130
	v_rcp_f32_e32 v118, v118
	v_rcp_f32_e32 v119, v119
	v_mul_f32_e32 v112, 0xbfb8aa3b, v112
	v_exp_f32_e32 v149, v112
	v_pk_fma_f32 v[122:123], v[122:123], v[136:137], v[146:147]
	v_pk_fma_f32 v[124:125], v[124:125], v[152:153], v[138:139]
	v_lshlrev_b32_e32 v146, 16, v160
	v_and_b32_e32 v147, 0xffff0000, v160
	v_lshlrev_b32_e32 v152, 16, v164
	v_and_b32_e32 v153, 0xffff0000, v164
	v_mul_f32_e32 v114, v114, v130
	v_pk_fma_f32 v[116:117], v[116:117], v[152:153], v[146:147]
	v_lshlrev_b32_e32 v146, 16, v161
	v_and_b32_e32 v147, 0xffff0000, v161
	v_lshlrev_b32_e32 v152, 16, v165
	v_and_b32_e32 v153, 0xffff0000, v165
	v_mul_f32_e32 v114, 0xbfb8aa3b, v114
	v_pk_fma_f32 v[112:113], v[118:119], v[152:153], v[146:147]
	v_add_f32_e32 v118, 1.0, v141
	v_exp_f32_e32 v141, v114
	v_mul_f32_e32 v114, v115, v130
	v_add_f32_e32 v119, 1.0, v149
	v_mul_f32_e32 v114, 0xbfb8aa3b, v114
	v_rcp_f32_e32 v118, v118
	v_rcp_f32_e32 v119, v119
	v_exp_f32_e32 v130, v114
	v_lshlrev_b32_e32 v146, 16, v162
	v_and_b32_e32 v147, 0xffff0000, v162
	v_lshlrev_b32_e32 v152, 16, v166
	v_and_b32_e32 v153, 0xffff0000, v166
	v_pk_fma_f32 v[114:115], v[118:119], v[152:153], v[146:147]
	v_add_f32_e32 v118, 1.0, v141
	v_add_f32_e32 v119, 1.0, v130
	v_rcp_f32_e32 v118, v118
	v_rcp_f32_e32 v119, v119
	v_rcp_f32_e32 v126, v151
	v_rcp_f32_e32 v127, v158
	v_lshlrev_b32_e32 v146, 16, v163
	v_and_b32_e32 v147, 0xffff0000, v163
	v_lshlrev_b32_e32 v152, 16, v167
	v_and_b32_e32 v153, 0xffff0000, v167
	v_and_b32_e32 v157, 0xffff0000, v159
	v_pk_fma_f32 v[118:119], v[118:119], v[152:153], v[146:147]
	v_pk_fma_f32 v[126:127], v[126:127], v[156:157], v[154:155]
	v_pk_mul_f32 v[154:155], v[114:115], v[114:115]
	v_pk_mul_f32 v[156:157], v[118:119], v[118:119]
	v_pk_mul_f32 v[146:147], v[116:117], v[116:117]
	v_pk_mul_f32 v[152:153], v[112:113], v[112:113]
	v_add_f32_e32 v130, v156, v157
	v_add_f32_e32 v141, v154, v155
	v_pk_fma_f32 v[120:121], v[120:121], v[144:145], v[142:143]
	v_add_f32_e32 v130, v141, v130
	v_add_f32_e32 v141, v152, v153
	v_add_f32_e32 v146, v146, v147
	v_pk_mul_f32 v[136:137], v[120:121], v[120:121]
	v_pk_mul_f32 v[138:139], v[122:123], v[122:123]
	v_pk_mul_f32 v[142:143], v[124:125], v[124:125]
	v_pk_mul_f32 v[144:145], v[126:127], v[126:127]
	v_add_f32_e32 v141, v146, v141
	v_add_f32_e32 v130, v141, v130
	v_add_f32_e32 v141, v144, v145
	v_add_f32_e32 v142, v142, v143
	v_add_f32_e32 v138, v138, v139
	v_add_f32_e32 v136, v136, v137
	v_add_f32_e32 v141, v142, v141
	v_add_f32_e32 v136, v136, v138
	v_add_f32_e32 v136, v136, v141
	v_add_f32_e32 v136, v136, v130
	v_mov_b32_e32 v137, v136
	s_nop 1
	v_permlane16_swap_b32_e32 v137, v136
	v_lshlrev_b32_e32 v130, 1, v148
	v_cmp_eq_u32_e32 vcc, 0, v148
	s_waitcnt lgkmcnt(0)
	v_add_f32_e32 v136, v136, v137
	v_mov_b32_e32 v137, v136
	s_nop 1
	v_permlane32_swap_b32_e32 v137, v136
	s_and_saveexec_b64 s[16:17], vcc
	s_cbranch_execz .LBB0_1236
	s_waitcnt lgkmcnt(0)
	v_add_f32_e32 v138, v136, v137
	v_lshl_add_u64 v[136:137], s[8:9], 0, v[134:135]
	v_lshl_add_u64 v[136:137], s[14:15], 2, v[136:137]
	s_lshl_b32 s0, s44, 2
	v_lshl_add_u64 v[136:137], v[136:137], 0, s[0:1]
	global_store_dword v[136:137], v138, off
.LBB0_1236:
	s_or_b64 exec, exec, s[16:17]
	v_or_b32_e32 v136, 16, v150
	s_waitcnt lgkmcnt(0)
	v_ashrrev_i32_e32 v137, 31, v136
	v_lshlrev_b64 v[138:139], 7, v[136:137]
	v_lshl_add_u64 v[142:143], s[4:5], 0, v[138:139]
	v_lshlrev_b32_e32 v130, 4, v130
	v_lshl_add_u64 v[146:147], v[142:143], 0, v[130:131]
	global_load_dwordx4 v[142:145], v[146:147], off
	s_nop 0
	global_load_dwordx4 v[146:149], v[146:147], off offset:16
	v_lshlrev_b64 v[136:137], 11, v[136:137]
	v_lshl_add_u64 v[136:137], v[136:137], 0, v[128:129]
	v_lshlrev_b64 v[164:165], 1, v[136:137]
	v_lshl_add_u64 v[152:153], s[12:13], 0, v[164:165]
	v_lshl_add_u64 v[156:157], s[2:3], 0, v[164:165]
	global_load_dwordx4 v[152:155], v[152:153], off
	v_or_b32_e32 v164, 0x100, v164
	global_load_dwordx4 v[156:159], v[156:157], off
	v_lshl_add_u64 v[160:161], s[12:13], 0, v[164:165]
	v_lshl_add_u64 v[164:165], s[2:3], 0, v[164:165]
	global_load_dwordx4 v[160:163], v[160:161], off
	s_waitcnt vmcnt(4)
	v_mov_b32_e32 v168, v142
	global_load_dwordx4 v[164:167], v[164:165], off
	s_waitcnt vmcnt(4)
	v_mov_b32_e32 v169, v146
	v_mov_b32_e32 v146, v143
	v_mov_b32_e32 v142, v144
	v_mov_b32_e32 v143, v148
	v_mov_b32_e32 v148, v145
	v_pk_add_f32 v[144:145], v[168:169], v[146:147]
	v_pk_add_f32 v[142:143], v[142:143], v[148:149]
	s_waitcnt vmcnt(3)
	v_lshlrev_b32_e32 v146, 16, v152
	v_pk_add_f32 v[142:143], v[144:145], v[142:143]
	v_and_b32_e32 v147, 0xffff0000, v152
	v_add_f32_e32 v131, 0, v142
	v_add_f32_e32 v131, v131, v143
	v_mov_b32_e32 v141, v131
	s_nop 1
	v_permlane16_swap_b32_e32 v141, v131
	s_waitcnt vmcnt(2)
	v_lshlrev_b32_e32 v148, 16, v156
	v_and_b32_e32 v149, 0xffff0000, v156
	v_lshlrev_b32_e32 v168, 16, v154
	v_and_b32_e32 v169, 0xffff0000, v154
	s_waitcnt lgkmcnt(0)
	v_add_f32_e32 v131, v131, v141
	v_mov_b32_e32 v141, v131
	s_nop 1
	v_permlane32_swap_b32_e32 v141, v131
	v_lshlrev_b32_e32 v142, 16, v158
	v_and_b32_e32 v143, 0xffff0000, v158
	v_lshlrev_b32_e32 v144, 16, v155
	v_and_b32_e32 v145, 0xffff0000, v155
	s_waitcnt lgkmcnt(0)
	v_add_f32_e32 v131, v131, v141
	v_fmac_f32_e32 v140, 0x3a000000, v131
	v_mul_f32_e32 v131, 0x4b800000, v140
	v_cmp_gt_f32_e64 s[0:1], s18, v140
	v_lshlrev_b32_e32 v154, 16, v159
	v_and_b32_e32 v155, 0xffff0000, v159
	v_cndmask_b32_e64 v131, v140, v131, s[0:1]
	v_rsq_f32_e32 v131, v131
	s_waitcnt vmcnt(1)
	v_lshlrev_b32_e32 v158, 16, v160
	v_and_b32_e32 v159, 0xffff0000, v160
	v_lshlrev_b32_e32 v152, 16, v153
	v_mul_f32_e32 v151, 0x45800000, v131
	v_cndmask_b32_e64 v131, v131, v151, s[0:1]
	v_mul_f32_e32 v108, v108, v131
	v_mul_f32_e32 v109, v109, v131
	v_mul_f32_e32 v100, v100, v131
	v_mul_f32_e32 v101, v101, v131
	v_mul_f32_e32 v108, 0xbfb8aa3b, v108
	v_mul_f32_e32 v109, 0xbfb8aa3b, v109
	v_mul_f32_e32 v100, 0xbfb8aa3b, v100
	v_mul_f32_e32 v101, 0xbfb8aa3b, v101
	v_exp_f32_e32 v108, v108
	v_exp_f32_e32 v109, v109
	v_exp_f32_e32 v100, v100
	v_exp_f32_e32 v101, v101
	v_add_f32_e32 v108, 1.0, v108
	v_add_f32_e32 v109, 1.0, v109
	v_add_f32_e32 v172, 1.0, v100
	v_add_f32_e32 v173, 1.0, v101
	v_rcp_f32_e32 v100, v108
	v_rcp_f32_e32 v101, v109
	v_mul_f32_e32 v110, v110, v131
	v_mul_f32_e32 v111, v111, v131
	v_mul_f32_e32 v106, v106, v131
	v_mul_f32_e32 v107, v107, v131
	v_mul_f32_e32 v104, v104, v131
	v_mul_f32_e32 v105, v105, v131
	v_mul_f32_e32 v110, 0xbfb8aa3b, v110
	v_mul_f32_e32 v111, 0xbfb8aa3b, v111
	v_mul_f32_e32 v106, 0xbfb8aa3b, v106
	v_mul_f32_e32 v107, 0xbfb8aa3b, v107
	v_mul_f32_e32 v104, 0xbfb8aa3b, v104
	v_mul_f32_e32 v105, 0xbfb8aa3b, v105
	v_exp_f32_e32 v110, v110
	v_exp_f32_e32 v111, v111
	v_exp_f32_e32 v106, v106
	v_exp_f32_e32 v107, v107
	v_mul_f32_e32 v102, v102, v131
	v_exp_f32_e32 v104, v104
	v_exp_f32_e32 v105, v105
	v_pk_fma_f32 v[108:109], v[100:101], v[148:149], v[146:147]
	v_mul_f32_e32 v100, v103, v131
	v_mul_f32_e32 v102, 0xbfb8aa3b, v102
	v_mul_f32_e32 v100, 0xbfb8aa3b, v100
	v_exp_f32_e32 v102, v102
	v_exp_f32_e32 v103, v100
	s_waitcnt vmcnt(0)
	v_lshlrev_b32_e32 v140, 16, v164
	v_and_b32_e32 v141, 0xffff0000, v164
	v_add_f32_e32 v110, 1.0, v110
	v_add_f32_e32 v111, 1.0, v111
	v_add_f32_e32 v164, 1.0, v106
	v_add_f32_e32 v171, 1.0, v107
	v_add_f32_e32 v151, 1.0, v104
	v_add_f32_e32 v160, 1.0, v105
	v_rcp_f32_e32 v104, v110
	v_rcp_f32_e32 v105, v111
	v_rcp_f32_e32 v170, v164
	v_rcp_f32_e32 v171, v171
	v_mul_f32_e32 v96, v96, v131
	v_mul_f32_e32 v96, 0xbfb8aa3b, v96
	v_rcp_f32_e32 v106, v151
	v_rcp_f32_e32 v172, v172
	v_rcp_f32_e32 v173, v173
	v_add_f32_e32 v102, 1.0, v102
	v_add_f32_e32 v103, 1.0, v103
	v_exp_f32_e32 v151, v96
	v_mul_f32_e32 v96, v97, v131
	v_and_b32_e32 v153, 0xffff0000, v153
	v_lshlrev_b32_e32 v156, 16, v157
	v_and_b32_e32 v157, 0xffff0000, v157
	v_rcp_f32_e32 v102, v102
	v_rcp_f32_e32 v103, v103
	v_mul_f32_e32 v96, 0xbfb8aa3b, v96
	v_pk_fma_f32 v[110:111], v[104:105], v[156:157], v[152:153]
	v_pk_fma_f32 v[104:105], v[170:171], v[154:155], v[144:145]
	v_exp_f32_e32 v154, v96
	v_mul_f32_e32 v98, v98, v131
	v_pk_fma_f32 v[100:101], v[172:173], v[140:141], v[158:159]
	v_lshlrev_b32_e32 v140, 16, v161
	v_and_b32_e32 v141, 0xffff0000, v161
	v_lshlrev_b32_e32 v152, 16, v165
	v_and_b32_e32 v153, 0xffff0000, v165
	v_mul_f32_e32 v98, 0xbfb8aa3b, v98
	v_pk_fma_f32 v[96:97], v[102:103], v[152:153], v[140:141]
	v_add_f32_e32 v102, 1.0, v151
	v_exp_f32_e32 v151, v98
	v_mul_f32_e32 v98, v99, v131
	v_add_f32_e32 v103, 1.0, v154
	v_mul_f32_e32 v98, 0xbfb8aa3b, v98
	v_rcp_f32_e32 v102, v102
	v_rcp_f32_e32 v103, v103
	v_exp_f32_e32 v131, v98
	v_lshlrev_b32_e32 v140, 16, v162
	v_and_b32_e32 v141, 0xffff0000, v162
	v_lshlrev_b32_e32 v152, 16, v166
	v_and_b32_e32 v153, 0xffff0000, v166
	v_pk_fma_f32 v[98:99], v[102:103], v[152:153], v[140:141]
	v_add_f32_e32 v102, 1.0, v151
	v_add_f32_e32 v103, 1.0, v131
	v_rcp_f32_e32 v102, v102
	v_rcp_f32_e32 v103, v103
	v_rcp_f32_e32 v107, v160
	v_lshlrev_b32_e32 v140, 16, v163
	v_and_b32_e32 v141, 0xffff0000, v163
	v_lshlrev_b32_e32 v152, 16, v167
	v_and_b32_e32 v153, 0xffff0000, v167
	v_pk_fma_f32 v[102:103], v[102:103], v[152:153], v[140:141]
	v_pk_mul_f32 v[154:155], v[98:99], v[98:99]
	v_pk_mul_f32 v[156:157], v[102:103], v[102:103]
	v_pk_mul_f32 v[140:141], v[100:101], v[100:101]
	v_pk_mul_f32 v[152:153], v[96:97], v[96:97]
	v_add_f32_e32 v131, v156, v157
	v_add_f32_e32 v151, v154, v155
	v_pk_fma_f32 v[106:107], v[106:107], v[142:143], v[168:169]
	v_add_f32_e32 v131, v151, v131
	v_add_f32_e32 v151, v152, v153
	v_add_f32_e32 v140, v140, v141
	v_pk_mul_f32 v[146:147], v[106:107], v[106:107]
	v_pk_mul_f32 v[148:149], v[104:105], v[104:105]
	v_add_f32_e32 v140, v140, v151
	v_pk_mul_f32 v[142:143], v[108:109], v[108:109]
	v_pk_mul_f32 v[144:145], v[110:111], v[110:111]
	v_add_f32_e32 v131, v140, v131
	v_add_f32_e32 v140, v148, v149
	v_add_f32_e32 v141, v146, v147
	v_add_f32_e32 v140, v141, v140
	v_add_f32_e32 v141, v144, v145
	v_add_f32_e32 v142, v142, v143
	v_add_f32_e32 v141, v142, v141
	v_add_f32_e32 v140, v141, v140
	v_add_f32_e32 v131, v140, v131
	v_mov_b32_e32 v140, v131
	s_nop 1
	v_permlane16_swap_b32_e32 v140, v131
	s_waitcnt lgkmcnt(0)
	v_add_f32_e32 v131, v131, v140
	v_mov_b32_e32 v140, v131
	s_nop 1
	v_permlane32_swap_b32_e32 v140, v131
	s_and_saveexec_b64 s[0:1], vcc
	s_cbranch_execz .LBB0_1238
	s_waitcnt lgkmcnt(0)
	v_add_f32_e32 v131, v131, v140
	v_lshl_add_u64 v[140:141], s[8:9], 0, v[138:139]
	v_lshl_add_u64 v[140:141], s[14:15], 2, v[140:141]
	s_lshl_b32 s16, s44, 2
	s_mov_b32 s17, 0
	v_lshl_add_u64 v[140:141], v[140:141], 0, s[16:17]
	global_store_dword v[140:141], v131, off
.LBB0_1238:
	s_or_b64 exec, exec, s[0:1]
	s_waitcnt lgkmcnt(0)
	v_or_b32_e32 v140, 32, v150
	v_ashrrev_i32_e32 v141, 31, v140
	v_lshlrev_b64 v[142:143], 7, v[140:141]
	v_lshl_add_u64 v[144:145], s[4:5], 0, v[142:143]
	v_mov_b32_e32 v131, 0
	v_lshl_add_u64 v[148:149], v[144:145], 0, v[130:131]
	global_load_dwordx4 v[144:147], v[148:149], off
	global_load_dwordx4 v[152:155], v[148:149], off offset:16
	v_lshlrev_b64 v[140:141], 11, v[140:141]
	v_lshl_add_u64 v[140:141], v[140:141], 0, v[128:129]
	v_lshlrev_b64 v[148:149], 1, v[140:141]
	v_lshl_add_u64 v[156:157], s[12:13], 0, v[148:149]
	v_lshl_add_u64 v[160:161], s[2:3], 0, v[148:149]
	v_or_b32_e32 v148, 0x100, v148
	v_lshl_add_u64 v[164:165], s[12:13], 0, v[148:149]
	global_load_dwordx4 v[156:159], v[156:157], off
	v_lshl_add_u64 v[148:149], s[2:3], 0, v[148:149]
	global_load_dwordx4 v[160:163], v[160:161], off
	s_mov_b32 s17, 0
	global_load_dwordx4 v[164:167], v[164:165], off
	s_waitcnt vmcnt(4)
	v_mov_b32_e32 v172, v144
	global_load_dwordx4 v[168:171], v[148:149], off
	s_waitcnt vmcnt(4)
	v_mov_b32_e32 v173, v152
	v_mov_b32_e32 v152, v145
	v_mov_b32_e32 v144, v146
	v_mov_b32_e32 v145, v154
	v_mov_b32_e32 v154, v147
	v_pk_add_f32 v[146:147], v[172:173], v[152:153]
	v_pk_add_f32 v[144:145], v[144:145], v[154:155]
	v_mov_b32_e32 v148, 0x358637bd
	v_pk_add_f32 v[144:145], v[146:147], v[144:145]
	s_waitcnt vmcnt(3)
	v_lshlrev_b32_e32 v172, 16, v158
	v_add_f32_e32 v144, 0, v144
	v_add_f32_e32 v147, v144, v145
	v_mov_b32_e32 v149, v147
	s_nop 1
	v_permlane16_swap_b32_e32 v149, v147
	v_and_b32_e32 v173, 0xffff0000, v158
	s_waitcnt vmcnt(2)
	v_lshlrev_b32_e32 v144, 16, v162
	v_and_b32_e32 v145, 0xffff0000, v162
	v_lshlrev_b32_e32 v146, 16, v159
	s_waitcnt lgkmcnt(0)
	v_add_f32_e32 v149, v147, v149
	v_mov_b32_e32 v151, v149
	s_nop 1
	v_permlane32_swap_b32_e32 v151, v149
	v_and_b32_e32 v147, 0xffff0000, v159
	v_lshlrev_b32_e32 v158, 16, v163
	v_and_b32_e32 v159, 0xffff0000, v163
	s_waitcnt vmcnt(1)
	v_lshlrev_b32_e32 v162, 16, v164
	s_waitcnt lgkmcnt(0)
	v_add_f32_e32 v149, v149, v151
	v_fmamk_f32 v149, v149, 0x3a000000, v148
	v_mul_f32_e32 v151, 0x4b800000, v149
	v_cmp_gt_f32_e64 s[0:1], s18, v149
	v_and_b32_e32 v163, 0xffff0000, v164
	v_lshlrev_b32_e32 v152, 16, v156
	v_cndmask_b32_e64 v149, v149, v151, s[0:1]
	v_rsq_f32_e32 v149, v149
	v_and_b32_e32 v153, 0xffff0000, v156
	v_lshlrev_b32_e32 v154, 16, v160
	v_and_b32_e32 v155, 0xffff0000, v160
	v_mul_f32_e32 v151, 0x45800000, v149
	v_cndmask_b32_e64 v149, v149, v151, s[0:1]
	v_mul_f32_e32 v92, v92, v149
	v_mul_f32_e32 v93, v93, v149
	v_mul_f32_e32 v94, v94, v149
	v_mul_f32_e32 v95, v95, v149
	v_mul_f32_e32 v88, v88, v149
	v_mul_f32_e32 v89, v89, v149
	v_mul_f32_e32 v84, v84, v149
	v_mul_f32_e32 v85, v85, v149
	v_mul_f32_e32 v92, 0xbfb8aa3b, v92
	v_mul_f32_e32 v93, 0xbfb8aa3b, v93
	v_mul_f32_e32 v94, 0xbfb8aa3b, v94
	v_mul_f32_e32 v95, 0xbfb8aa3b, v95
	v_mul_f32_e32 v88, 0xbfb8aa3b, v88
	v_mul_f32_e32 v89, 0xbfb8aa3b, v89
	v_mul_f32_e32 v84, 0xbfb8aa3b, v84
	v_mul_f32_e32 v85, 0xbfb8aa3b, v85
	v_exp_f32_e32 v92, v92
	v_exp_f32_e32 v93, v93
	v_exp_f32_e32 v94, v94
	v_exp_f32_e32 v95, v95
	v_exp_f32_e32 v88, v88
	v_exp_f32_e32 v89, v89
	v_exp_f32_e32 v84, v84
	v_exp_f32_e32 v85, v85
	v_mul_f32_e32 v90, v90, v149
	v_mul_f32_e32 v91, v91, v149
	v_mul_f32_e32 v90, 0xbfb8aa3b, v90
	v_mul_f32_e32 v91, 0xbfb8aa3b, v91
	v_exp_f32_e32 v90, v90
	v_exp_f32_e32 v91, v91
	v_add_f32_e32 v92, 1.0, v92
	v_add_f32_e32 v93, 1.0, v93
	v_add_f32_e32 v94, 1.0, v94
	v_add_f32_e32 v95, 1.0, v95
	v_add_f32_e32 v151, 1.0, v88
	v_add_f32_e32 v164, 1.0, v89
	v_add_f32_e32 v179, 1.0, v85
	v_rcp_f32_e32 v85, v93
	v_rcp_f32_e32 v88, v94
	v_rcp_f32_e32 v89, v95
	v_rcp_f32_e32 v94, v151
	v_rcp_f32_e32 v95, v164
	v_mul_f32_e32 v86, v86, v149
	s_waitcnt vmcnt(0)
	v_lshlrev_b32_e32 v174, 16, v168
	v_and_b32_e32 v175, 0xffff0000, v168
	v_add_f32_e32 v168, 1.0, v84
	v_rcp_f32_e32 v84, v92
	v_add_f32_e32 v90, 1.0, v90
	v_add_f32_e32 v91, 1.0, v91
	v_mul_f32_e32 v86, 0xbfb8aa3b, v86
	v_rcp_f32_e32 v176, v90
	v_rcp_f32_e32 v177, v91
	v_pk_fma_f32 v[90:91], v[84:85], v[154:155], v[152:153]
	v_pk_fma_f32 v[84:85], v[94:95], v[144:145], v[172:173]
	v_exp_f32_e32 v94, v86
	v_mul_f32_e32 v86, v87, v149
	v_mul_f32_e32 v86, 0xbfb8aa3b, v86
	v_exp_f32_e32 v95, v86
	v_mul_f32_e32 v80, v80, v149
	v_mul_f32_e32 v80, 0xbfb8aa3b, v80
	v_add_f32_e32 v94, 1.0, v94
	v_add_f32_e32 v95, 1.0, v95
	v_exp_f32_e32 v151, v80
	v_mul_f32_e32 v80, v81, v149
	v_lshlrev_b32_e32 v156, 16, v157
	v_and_b32_e32 v157, 0xffff0000, v157
	v_lshlrev_b32_e32 v160, 16, v161
	v_and_b32_e32 v161, 0xffff0000, v161
	v_rcp_f32_e32 v94, v94
	v_rcp_f32_e32 v95, v95
	v_mul_f32_e32 v80, 0xbfb8aa3b, v80
	v_pk_fma_f32 v[92:93], v[88:89], v[160:161], v[156:157]
	v_exp_f32_e32 v160, v80
	v_mul_f32_e32 v82, v82, v149
	v_pk_fma_f32 v[88:89], v[176:177], v[158:159], v[146:147]
	v_lshlrev_b32_e32 v156, 16, v165
	v_and_b32_e32 v157, 0xffff0000, v165
	v_lshlrev_b32_e32 v158, 16, v169
	v_and_b32_e32 v159, 0xffff0000, v169
	v_mul_f32_e32 v82, 0xbfb8aa3b, v82
	v_pk_fma_f32 v[80:81], v[94:95], v[158:159], v[156:157]
	v_add_f32_e32 v94, 1.0, v151
	v_exp_f32_e32 v151, v82
	v_mul_f32_e32 v82, v83, v149
	v_add_f32_e32 v95, 1.0, v160
	v_mul_f32_e32 v82, 0xbfb8aa3b, v82
	v_rcp_f32_e32 v94, v94
	v_rcp_f32_e32 v95, v95
	v_exp_f32_e32 v149, v82
	v_lshlrev_b32_e32 v156, 16, v166
	v_and_b32_e32 v157, 0xffff0000, v166
	v_lshlrev_b32_e32 v158, 16, v170
	v_and_b32_e32 v159, 0xffff0000, v170
	v_pk_fma_f32 v[82:83], v[94:95], v[158:159], v[156:157]
	v_add_f32_e32 v94, 1.0, v151
	v_add_f32_e32 v95, 1.0, v149
	v_rcp_f32_e32 v94, v94
	v_rcp_f32_e32 v95, v95
	v_rcp_f32_e32 v178, v168
	v_rcp_f32_e32 v179, v179
	v_lshlrev_b32_e32 v156, 16, v167
	v_and_b32_e32 v157, 0xffff0000, v167
	v_lshlrev_b32_e32 v158, 16, v171
	v_and_b32_e32 v159, 0xffff0000, v171
	v_pk_fma_f32 v[94:95], v[94:95], v[158:159], v[156:157]
	v_pk_fma_f32 v[86:87], v[178:179], v[174:175], v[162:163]
	v_pk_mul_f32 v[160:161], v[82:83], v[82:83]
	v_pk_mul_f32 v[162:163], v[94:95], v[94:95]
	v_pk_mul_f32 v[156:157], v[86:87], v[86:87]
	v_pk_mul_f32 v[158:159], v[80:81], v[80:81]
	v_add_f32_e32 v149, v162, v163
	v_add_f32_e32 v151, v160, v161
	v_add_f32_e32 v149, v151, v149
	v_add_f32_e32 v151, v158, v159
	v_add_f32_e32 v156, v156, v157
	v_pk_mul_f32 v[144:145], v[90:91], v[90:91]
	v_pk_mul_f32 v[146:147], v[92:93], v[92:93]
	v_pk_mul_f32 v[152:153], v[84:85], v[84:85]
	v_pk_mul_f32 v[154:155], v[88:89], v[88:89]
	v_add_f32_e32 v151, v156, v151
	v_add_f32_e32 v149, v151, v149
	v_add_f32_e32 v151, v154, v155
	v_add_f32_e32 v152, v152, v153
	v_add_f32_e32 v146, v146, v147
	v_add_f32_e32 v144, v144, v145
	v_add_f32_e32 v151, v152, v151
	v_add_f32_e32 v144, v144, v146
	v_add_f32_e32 v144, v144, v151
	v_add_f32_e32 v144, v144, v149
	v_mov_b32_e32 v145, v144
	s_nop 1
	v_permlane16_swap_b32_e32 v145, v144
	s_waitcnt lgkmcnt(0)
	v_add_f32_e32 v144, v144, v145
	v_mov_b32_e32 v145, v144
	s_nop 1
	v_permlane32_swap_b32_e32 v145, v144
	s_and_saveexec_b64 s[0:1], vcc
	s_cbranch_execz .LBB0_1240
	s_waitcnt lgkmcnt(0)
	v_add_f32_e32 v146, v144, v145
	v_lshl_add_u64 v[144:145], s[8:9], 0, v[142:143]
	v_lshl_add_u64 v[144:145], s[14:15], 2, v[144:145]
	s_lshl_b32 s16, s44, 2
	v_lshl_add_u64 v[144:145], v[144:145], 0, s[16:17]
	global_store_dword v[144:145], v146, off
.LBB0_1240:
	s_or_b64 exec, exec, s[0:1]
	v_or_b32_e32 v144, 48, v150
	s_waitcnt lgkmcnt(0)
	v_ashrrev_i32_e32 v145, 31, v144
	v_lshlrev_b64 v[146:147], 7, v[144:145]
	v_lshl_add_u64 v[152:153], s[4:5], 0, v[146:147]
	v_lshl_add_u64 v[156:157], v[152:153], 0, v[130:131]
	global_load_dwordx4 v[152:155], v[156:157], off
	s_nop 0
	global_load_dwordx4 v[156:159], v[156:157], off offset:16
	v_lshlrev_b64 v[144:145], 11, v[144:145]
	v_lshl_add_u64 v[144:145], v[144:145], 0, v[128:129]
	v_lshlrev_b64 v[172:173], 1, v[144:145]
	v_lshl_add_u64 v[160:161], s[12:13], 0, v[172:173]
	v_lshl_add_u64 v[164:165], s[2:3], 0, v[172:173]
	v_or_b32_e32 v172, 0x100, v172
	v_lshl_add_u64 v[168:169], s[12:13], 0, v[172:173]
	global_load_dwordx4 v[160:163], v[160:161], off
	v_lshl_add_u64 v[172:173], s[2:3], 0, v[172:173]
	global_load_dwordx4 v[164:167], v[164:165], off
	s_waitcnt vmcnt(3)
	v_mov_b32_e32 v176, v152
	global_load_dwordx4 v[168:171], v[168:169], off
	s_waitcnt vmcnt(3)
	v_mov_b32_e32 v177, v156
	global_load_dwordx4 v[172:175], v[172:173], off
	v_mov_b32_e32 v156, v153
	v_mov_b32_e32 v152, v154
	v_mov_b32_e32 v153, v158
	v_mov_b32_e32 v158, v155
	v_pk_add_f32 v[154:155], v[176:177], v[156:157]
	v_pk_add_f32 v[152:153], v[152:153], v[158:159]
	s_waitcnt vmcnt(3)
	v_lshlrev_b32_e32 v176, 16, v162
	v_pk_add_f32 v[152:153], v[154:155], v[152:153]
	v_and_b32_e32 v177, 0xffff0000, v162
	v_add_f32_e32 v131, 0, v152
	v_add_f32_e32 v131, v131, v153
	v_mov_b32_e32 v149, v131
	s_nop 1
	v_permlane16_swap_b32_e32 v149, v131
	s_waitcnt vmcnt(2)
	v_lshlrev_b32_e32 v152, 16, v166
	v_and_b32_e32 v153, 0xffff0000, v166
	v_lshlrev_b32_e32 v154, 16, v163
	v_and_b32_e32 v155, 0xffff0000, v163
	s_waitcnt lgkmcnt(0)
	v_add_f32_e32 v131, v131, v149
	v_mov_b32_e32 v149, v131
	s_nop 1
	v_permlane32_swap_b32_e32 v149, v131
	v_lshlrev_b32_e32 v162, 16, v167
	v_and_b32_e32 v163, 0xffff0000, v167
	v_lshlrev_b32_e32 v156, 16, v160
	v_and_b32_e32 v157, 0xffff0000, v160
	s_waitcnt lgkmcnt(0)
	v_add_f32_e32 v131, v131, v149
	v_fmac_f32_e32 v148, 0x3a000000, v131
	v_mul_f32_e32 v131, 0x4b800000, v148
	v_cmp_gt_f32_e64 s[0:1], s18, v148
	v_lshlrev_b32_e32 v158, 16, v164
	v_and_b32_e32 v159, 0xffff0000, v164
	v_cndmask_b32_e64 v131, v148, v131, s[0:1]
	v_rsq_f32_e32 v131, v131
	v_lshlrev_b32_e32 v160, 16, v161
	v_and_b32_e32 v161, 0xffff0000, v161
	v_lshlrev_b32_e32 v164, 16, v165
	v_mul_f32_e32 v151, 0x45800000, v131
	v_cndmask_b32_e64 v131, v131, v151, s[0:1]
	v_mul_f32_e32 v76, v76, v131
	v_mul_f32_e32 v77, v77, v131
	v_mul_f32_e32 v78, v78, v131
	v_mul_f32_e32 v79, v79, v131
	v_mul_f32_e32 v68, v68, v131
	v_mul_f32_e32 v69, v69, v131
	v_mul_f32_e32 v151, v71, v131
	v_mul_f32_e32 v71, 0xbfb8aa3b, v76
	v_mul_f32_e32 v76, 0xbfb8aa3b, v77
	v_mul_f32_e32 v77, 0xbfb8aa3b, v78
	v_mul_f32_e32 v78, 0xbfb8aa3b, v79
	v_mul_f32_e32 v68, 0xbfb8aa3b, v68
	v_mul_f32_e32 v69, 0xbfb8aa3b, v69
	v_exp_f32_e32 v71, v71
	v_exp_f32_e32 v76, v76
	v_exp_f32_e32 v77, v77
	v_exp_f32_e32 v78, v78
	v_exp_f32_e32 v68, v68
	v_exp_f32_e32 v69, v69
	v_mul_f32_e32 v70, v70, v131
	v_mul_f32_e32 v70, 0xbfb8aa3b, v70
	v_mul_f32_e32 v74, v74, v131
	v_mul_f32_e32 v75, v75, v131
	v_add_f32_e32 v79, 1.0, v69
	v_mul_f32_e32 v74, 0xbfb8aa3b, v74
	v_mul_f32_e32 v75, 0xbfb8aa3b, v75
	v_exp_f32_e32 v74, v74
	v_exp_f32_e32 v75, v75
	v_and_b32_e32 v165, 0xffff0000, v165
	v_rcp_f32_e32 v179, v79
	v_add_f32_e32 v74, 1.0, v74
	v_add_f32_e32 v75, 1.0, v75
	v_rcp_f32_e32 v74, v74
	v_rcp_f32_e32 v75, v75
	v_mul_f32_e32 v64, v64, v131
	v_mul_f32_e32 v64, 0xbfb8aa3b, v64
	v_mul_f32_e32 v66, v66, v131
	v_pk_fma_f32 v[74:75], v[74:75], v[162:163], v[154:155]
	v_mul_f32_e32 v66, 0xbfb8aa3b, v66
	v_mul_f32_e32 v72, v72, v131
	v_mul_f32_e32 v73, v73, v131
	v_mul_f32_e32 v72, 0xbfb8aa3b, v72
	s_waitcnt vmcnt(1)
	v_lshlrev_b32_e32 v166, 16, v168
	v_and_b32_e32 v167, 0xffff0000, v168
	v_exp_f32_e32 v168, v70
	v_add_f32_e32 v70, 1.0, v71
	v_add_f32_e32 v71, 1.0, v76
	v_add_f32_e32 v76, 1.0, v77
	v_add_f32_e32 v77, 1.0, v78
	v_add_f32_e32 v78, 1.0, v68
	v_rcp_f32_e32 v68, v70
	v_rcp_f32_e32 v69, v71
	v_rcp_f32_e32 v70, v76
	v_rcp_f32_e32 v71, v77
	v_rcp_f32_e32 v178, v78
	v_pk_fma_f32 v[76:77], v[68:69], v[158:159], v[156:157]
	v_mul_f32_e32 v68, 0xbfb8aa3b, v151
	v_pk_fma_f32 v[78:79], v[70:71], v[164:165], v[160:161]
	v_exp_f32_e32 v71, v68
	v_add_f32_e32 v70, 1.0, v168
	v_exp_f32_e32 v151, v64
	v_mul_f32_e32 v64, v65, v131
	v_add_f32_e32 v71, 1.0, v71
	v_rcp_f32_e32 v70, v70
	v_rcp_f32_e32 v71, v71
	v_mul_f32_e32 v64, 0xbfb8aa3b, v64
	v_exp_f32_e32 v162, v64
	s_waitcnt vmcnt(0)
	v_lshlrev_b32_e32 v148, 16, v172
	v_and_b32_e32 v149, 0xffff0000, v172
	v_pk_fma_f32 v[68:69], v[178:179], v[148:149], v[166:167]
	v_lshlrev_b32_e32 v148, 16, v169
	v_and_b32_e32 v149, 0xffff0000, v169
	v_lshlrev_b32_e32 v160, 16, v173
	v_and_b32_e32 v161, 0xffff0000, v173
	v_pk_fma_f32 v[64:65], v[70:71], v[160:161], v[148:149]
	v_add_f32_e32 v70, 1.0, v151
	v_exp_f32_e32 v151, v66
	v_mul_f32_e32 v66, v67, v131
	v_add_f32_e32 v71, 1.0, v162
	v_mul_f32_e32 v66, 0xbfb8aa3b, v66
	v_rcp_f32_e32 v70, v70
	v_rcp_f32_e32 v71, v71
	v_exp_f32_e32 v131, v66
	v_mul_f32_e32 v73, 0xbfb8aa3b, v73
	v_exp_f32_e32 v72, v72
	v_exp_f32_e32 v73, v73
	v_lshlrev_b32_e32 v148, 16, v170
	v_and_b32_e32 v149, 0xffff0000, v170
	v_lshlrev_b32_e32 v160, 16, v174
	v_and_b32_e32 v161, 0xffff0000, v174
	v_pk_fma_f32 v[66:67], v[70:71], v[160:161], v[148:149]
	v_add_f32_e32 v70, 1.0, v151
	v_add_f32_e32 v71, 1.0, v131
	v_rcp_f32_e32 v70, v70
	v_rcp_f32_e32 v71, v71
	v_add_f32_e32 v72, 1.0, v72
	v_add_f32_e32 v73, 1.0, v73
	v_rcp_f32_e32 v72, v72
	v_rcp_f32_e32 v73, v73
	v_lshlrev_b32_e32 v148, 16, v171
	v_and_b32_e32 v149, 0xffff0000, v171
	v_lshlrev_b32_e32 v160, 16, v175
	v_and_b32_e32 v161, 0xffff0000, v175
	v_pk_fma_f32 v[70:71], v[70:71], v[160:161], v[148:149]
	v_pk_mul_f32 v[162:163], v[66:67], v[66:67]
	v_pk_mul_f32 v[164:165], v[70:71], v[70:71]
	v_pk_mul_f32 v[148:149], v[68:69], v[68:69]
	v_pk_mul_f32 v[160:161], v[64:65], v[64:65]
	v_add_f32_e32 v131, v164, v165
	v_add_f32_e32 v151, v162, v163
	v_pk_fma_f32 v[72:73], v[72:73], v[152:153], v[176:177]
	v_add_f32_e32 v131, v151, v131
	v_add_f32_e32 v151, v160, v161
	v_add_f32_e32 v148, v148, v149
	v_pk_mul_f32 v[156:157], v[72:73], v[72:73]
	v_pk_mul_f32 v[158:159], v[74:75], v[74:75]
	v_add_f32_e32 v148, v148, v151
	v_pk_mul_f32 v[152:153], v[76:77], v[76:77]
	v_pk_mul_f32 v[154:155], v[78:79], v[78:79]
	v_add_f32_e32 v131, v148, v131
	v_add_f32_e32 v148, v158, v159
	v_add_f32_e32 v149, v156, v157
	v_add_f32_e32 v148, v149, v148
	v_add_f32_e32 v149, v154, v155
	v_add_f32_e32 v151, v152, v153
	v_add_f32_e32 v149, v151, v149
	v_add_f32_e32 v148, v149, v148
	v_add_f32_e32 v131, v148, v131
	v_mov_b32_e32 v148, v131
	s_nop 1
	v_permlane16_swap_b32_e32 v148, v131
	s_waitcnt lgkmcnt(0)
	v_add_f32_e32 v131, v131, v148
	v_mov_b32_e32 v148, v131
	s_nop 1
	v_permlane32_swap_b32_e32 v148, v131
	s_and_saveexec_b64 s[0:1], vcc
	s_cbranch_execz .LBB0_1242
	s_waitcnt lgkmcnt(0)
	v_add_f32_e32 v131, v131, v148
	v_lshl_add_u64 v[148:149], s[8:9], 0, v[146:147]
	v_lshl_add_u64 v[148:149], s[14:15], 2, v[148:149]
	s_lshl_b32 s16, s44, 2
	v_lshl_add_u64 v[148:149], v[148:149], 0, s[16:17]
	global_store_dword v[148:149], v131, off
.LBB0_1242:
	s_or_b64 exec, exec, s[0:1]
	v_add_u32_e32 v154, 0x80, v150
	v_ashrrev_i32_e32 v155, 31, v154
	v_lshlrev_b64 v[152:153], 7, v[154:155]
	s_waitcnt lgkmcnt(0)
	v_lshl_add_u64 v[148:149], s[4:5], 0, v[152:153]
	v_mov_b32_e32 v131, 0
	v_lshl_add_u64 v[148:149], v[148:149], 0, v[130:131]
	global_load_dwordx4 v[156:159], v[148:149], off
	global_load_dwordx4 v[160:163], v[148:149], off offset:16
	v_lshlrev_b64 v[148:149], 11, v[154:155]
	v_lshl_add_u64 v[148:149], v[148:149], 0, v[128:129]
	v_lshlrev_b64 v[176:177], 1, v[148:149]
	v_lshl_add_u64 v[164:165], s[12:13], 0, v[176:177]
	v_lshl_add_u64 v[168:169], s[2:3], 0, v[176:177]
	global_load_dwordx4 v[164:167], v[164:165], off
	v_or_b32_e32 v176, 0x100, v176
	global_load_dwordx4 v[168:171], v[168:169], off
	v_lshl_add_u64 v[172:173], s[12:13], 0, v[176:177]
	global_load_dwordx4 v[172:175], v[172:173], off
	v_lshl_add_u64 v[176:177], s[2:3], 0, v[176:177]
	global_load_dwordx4 v[176:179], v[176:177], off
	v_mov_b32_e32 v151, 0x358637bd
	s_waitcnt vmcnt(5)
	v_mov_b32_e32 v180, v156
	s_waitcnt vmcnt(4)
	v_mov_b32_e32 v181, v160
	v_mov_b32_e32 v160, v157
	v_mov_b32_e32 v156, v158
	v_mov_b32_e32 v157, v162
	v_mov_b32_e32 v162, v159
	v_pk_add_f32 v[158:159], v[180:181], v[160:161]
	v_pk_add_f32 v[156:157], v[156:157], v[162:163]
	s_waitcnt vmcnt(3)
	v_lshlrev_b32_e32 v180, 16, v166
	v_pk_add_f32 v[156:157], v[158:159], v[156:157]
	v_and_b32_e32 v181, 0xffff0000, v166
	v_add_f32_e32 v155, 0, v156
	v_add_f32_e32 v155, v155, v157
	v_mov_b32_e32 v159, v155
	s_nop 1
	v_permlane16_swap_b32_e32 v159, v155
	v_lshlrev_b32_e32 v158, 16, v167
	s_waitcnt vmcnt(2)
	v_lshlrev_b32_e32 v166, 16, v171
	v_lshlrev_b32_e32 v156, 16, v170
	v_and_b32_e32 v157, 0xffff0000, v170
	s_waitcnt lgkmcnt(0)
	v_add_f32_e32 v155, v155, v159
	v_mov_b32_e32 v182, v155
	s_nop 1
	v_permlane32_swap_b32_e32 v182, v155
	v_and_b32_e32 v159, 0xffff0000, v167
	v_and_b32_e32 v167, 0xffff0000, v171
	s_waitcnt vmcnt(1)
	v_lshlrev_b32_e32 v170, 16, v172
	s_waitcnt vmcnt(0)
	v_and_b32_e32 v183, 0xffff0000, v176
	s_waitcnt lgkmcnt(0)
	v_add_f32_e32 v155, v155, v182
	v_fmamk_f32 v155, v155, 0x3a000000, v151
	v_mul_f32_e32 v171, 0x4b800000, v155
	v_cmp_gt_f32_e64 s[0:1], s18, v155
	v_lshlrev_b32_e32 v182, 16, v176
	v_lshlrev_b32_e32 v160, 16, v164
	v_cndmask_b32_e64 v155, v155, v171, s[0:1]
	v_rsq_f32_e32 v155, v155
	v_and_b32_e32 v171, 0xffff0000, v172
	v_and_b32_e32 v161, 0xffff0000, v164
	v_lshlrev_b32_e32 v162, 16, v168
	v_mul_f32_e32 v172, 0x45800000, v155
	v_cndmask_b32_e64 v155, v155, v172, s[0:1]
	v_mul_f32_e32 v60, v60, v155
	v_mul_f32_e32 v61, v61, v155
	v_mul_f32_e32 v62, v62, v155
	v_mul_f32_e32 v63, v63, v155
	v_mul_f32_e32 v56, v56, v155
	v_mul_f32_e32 v57, v57, v155
	v_mul_f32_e32 v52, v52, v155
	v_mul_f32_e32 v53, v53, v155
	v_mul_f32_e32 v60, 0xbfb8aa3b, v60
	v_mul_f32_e32 v61, 0xbfb8aa3b, v61
	v_mul_f32_e32 v62, 0xbfb8aa3b, v62
	v_mul_f32_e32 v63, 0xbfb8aa3b, v63
	v_mul_f32_e32 v56, 0xbfb8aa3b, v56
	v_mul_f32_e32 v57, 0xbfb8aa3b, v57
	v_mul_f32_e32 v52, 0xbfb8aa3b, v52
	v_mul_f32_e32 v53, 0xbfb8aa3b, v53
	v_exp_f32_e32 v60, v60
	v_exp_f32_e32 v61, v61
	v_exp_f32_e32 v62, v62
	v_exp_f32_e32 v63, v63
	v_exp_f32_e32 v56, v56
	v_exp_f32_e32 v57, v57
	v_exp_f32_e32 v52, v52
	v_exp_f32_e32 v53, v53
	v_mul_f32_e32 v58, v58, v155
	v_mul_f32_e32 v59, v59, v155
	v_mul_f32_e32 v58, 0xbfb8aa3b, v58
	v_mul_f32_e32 v59, 0xbfb8aa3b, v59
	v_exp_f32_e32 v58, v58
	v_exp_f32_e32 v59, v59
	v_add_f32_e32 v60, 1.0, v60
	v_add_f32_e32 v61, 1.0, v61
	v_add_f32_e32 v62, 1.0, v62
	v_add_f32_e32 v63, 1.0, v63
	v_add_f32_e32 v172, 1.0, v56
	v_add_f32_e32 v176, 1.0, v57
	v_add_f32_e32 v186, 1.0, v52
	v_add_f32_e32 v187, 1.0, v53
	v_rcp_f32_e32 v52, v60
	v_rcp_f32_e32 v53, v61
	v_rcp_f32_e32 v56, v62
	v_rcp_f32_e32 v57, v63
	v_rcp_f32_e32 v62, v172
	v_rcp_f32_e32 v63, v176
	v_mul_f32_e32 v54, v54, v155
	v_and_b32_e32 v163, 0xffff0000, v168
	v_add_f32_e32 v58, 1.0, v58
	v_add_f32_e32 v59, 1.0, v59
	v_mul_f32_e32 v54, 0xbfb8aa3b, v54
	v_rcp_f32_e32 v184, v58
	v_rcp_f32_e32 v185, v59
	v_pk_fma_f32 v[58:59], v[52:53], v[162:163], v[160:161]
	v_pk_fma_f32 v[52:53], v[62:63], v[156:157], v[180:181]
	v_exp_f32_e32 v62, v54
	v_mul_f32_e32 v54, v55, v155
	v_mul_f32_e32 v54, 0xbfb8aa3b, v54
	v_exp_f32_e32 v63, v54
	v_mul_f32_e32 v48, v48, v155
	v_lshlrev_b32_e32 v164, 16, v165
	v_and_b32_e32 v165, 0xffff0000, v165
	v_lshlrev_b32_e32 v168, 16, v169
	v_and_b32_e32 v169, 0xffff0000, v169
	v_mul_f32_e32 v48, 0xbfb8aa3b, v48
	v_pk_fma_f32 v[60:61], v[56:57], v[168:169], v[164:165]
	v_add_f32_e32 v62, 1.0, v62
	v_add_f32_e32 v63, 1.0, v63
	v_exp_f32_e32 v168, v48
	v_mul_f32_e32 v48, v49, v155
	v_rcp_f32_e32 v62, v62
	v_rcp_f32_e32 v63, v63
	v_mul_f32_e32 v48, 0xbfb8aa3b, v48
	v_exp_f32_e32 v169, v48
	v_mul_f32_e32 v50, v50, v155
	v_pk_fma_f32 v[56:57], v[184:185], v[166:167], v[158:159]
	v_lshlrev_b32_e32 v164, 16, v173
	v_and_b32_e32 v165, 0xffff0000, v173
	v_lshlrev_b32_e32 v166, 16, v177
	v_and_b32_e32 v167, 0xffff0000, v177
	v_mul_f32_e32 v50, 0xbfb8aa3b, v50
	v_pk_fma_f32 v[48:49], v[62:63], v[166:167], v[164:165]
	v_add_f32_e32 v62, 1.0, v168
	v_exp_f32_e32 v168, v50
	v_mul_f32_e32 v50, v51, v155
	v_add_f32_e32 v63, 1.0, v169
	v_mul_f32_e32 v50, 0xbfb8aa3b, v50
	v_rcp_f32_e32 v62, v62
	v_rcp_f32_e32 v63, v63
	v_exp_f32_e32 v155, v50
	v_lshlrev_b32_e32 v164, 16, v174
	v_and_b32_e32 v165, 0xffff0000, v174
	v_lshlrev_b32_e32 v166, 16, v178
	v_and_b32_e32 v167, 0xffff0000, v178
	v_pk_fma_f32 v[50:51], v[62:63], v[166:167], v[164:165]
	v_add_f32_e32 v62, 1.0, v168
	v_add_f32_e32 v63, 1.0, v155
	v_rcp_f32_e32 v186, v186
	v_rcp_f32_e32 v187, v187
	v_rcp_f32_e32 v62, v62
	v_rcp_f32_e32 v63, v63
	v_lshlrev_b32_e32 v164, 16, v175
	v_and_b32_e32 v165, 0xffff0000, v175
	v_lshlrev_b32_e32 v166, 16, v179
	v_and_b32_e32 v167, 0xffff0000, v179
	v_pk_fma_f32 v[54:55], v[186:187], v[182:183], v[170:171]
	v_pk_fma_f32 v[62:63], v[62:63], v[166:167], v[164:165]
	v_pk_mul_f32 v[156:157], v[58:59], v[58:59]
	v_pk_mul_f32 v[158:159], v[60:61], v[60:61]
	v_pk_mul_f32 v[160:161], v[52:53], v[52:53]
	v_pk_mul_f32 v[162:163], v[56:57], v[56:57]
	v_pk_mul_f32 v[164:165], v[54:55], v[54:55]
	v_pk_mul_f32 v[166:167], v[48:49], v[48:49]
	v_pk_mul_f32 v[168:169], v[50:51], v[50:51]
	v_pk_mul_f32 v[170:171], v[62:63], v[62:63]
	v_add_f32_e32 v168, v168, v169
	v_add_f32_e32 v155, v170, v171
	v_add_f32_e32 v166, v166, v167
	v_add_f32_e32 v164, v164, v165
	v_add_f32_e32 v162, v162, v163
	v_add_f32_e32 v160, v160, v161
	v_add_f32_e32 v158, v158, v159
	v_add_f32_e32 v156, v156, v157
	v_add_f32_e32 v155, v168, v155
	v_add_f32_e32 v164, v164, v166
	v_add_f32_e32 v160, v160, v162
	v_add_f32_e32 v156, v156, v158
	v_add_f32_e32 v155, v164, v155
	v_add_f32_e32 v156, v156, v160
	v_add_f32_e32 v155, v156, v155
	v_mov_b32_e32 v156, v155
	s_nop 1
	v_permlane16_swap_b32_e32 v156, v155
	s_waitcnt lgkmcnt(0)
	v_add_f32_e32 v155, v155, v156
	v_mov_b32_e32 v156, v155
	s_nop 1
	v_permlane32_swap_b32_e32 v156, v155
	s_and_saveexec_b64 s[0:1], vcc
	s_cbranch_execz .LBB0_1244
	s_waitcnt lgkmcnt(0)
	v_add_f32_e32 v155, v155, v156
	v_lshl_add_u64 v[156:157], s[8:9], 0, v[152:153]
	v_lshl_add_u64 v[156:157], s[14:15], 2, v[156:157]
	s_lshl_b32 s16, s44, 2
	v_lshl_add_u64 v[156:157], v[156:157], 0, s[16:17]
	global_store_dword v[156:157], v155, off
.LBB0_1244:
	s_or_b64 exec, exec, s[0:1]
	v_add_u32_e32 v166, 0x90, v150
	v_ashrrev_i32_e32 v167, 31, v166
	v_lshlrev_b64 v[164:165], 7, v[166:167]
	s_waitcnt lgkmcnt(0)
	v_lshl_add_u64 v[156:157], s[4:5], 0, v[164:165]
	v_lshl_add_u64 v[160:161], v[156:157], 0, v[130:131]
	global_load_dwordx4 v[156:159], v[160:161], off
	s_nop 0
	global_load_dwordx4 v[160:163], v[160:161], off offset:16
	v_lshlrev_b64 v[166:167], 11, v[166:167]
	v_lshl_add_u64 v[166:167], v[166:167], 0, v[128:129]
	v_lshlrev_b64 v[178:179], 1, v[166:167]
	v_lshl_add_u64 v[166:167], s[12:13], 0, v[178:179]
	v_lshl_add_u64 v[170:171], s[2:3], 0, v[178:179]
	global_load_dwordx4 v[166:169], v[166:167], off
	v_or_b32_e32 v178, 0x100, v178
	global_load_dwordx4 v[170:173], v[170:171], off
	v_lshl_add_u64 v[174:175], s[12:13], 0, v[178:179]
	v_lshl_add_u64 v[178:179], s[2:3], 0, v[178:179]
	global_load_dwordx4 v[174:177], v[174:175], off
	s_waitcnt vmcnt(4)
	v_mov_b32_e32 v182, v156
	global_load_dwordx4 v[178:181], v[178:179], off
	s_waitcnt vmcnt(4)
	v_mov_b32_e32 v183, v160
	v_mov_b32_e32 v160, v157
	v_mov_b32_e32 v156, v158
	v_mov_b32_e32 v157, v162
	v_mov_b32_e32 v162, v159
	v_pk_add_f32 v[158:159], v[182:183], v[160:161]
	v_pk_add_f32 v[156:157], v[156:157], v[162:163]
	s_waitcnt vmcnt(3)
	v_lshlrev_b32_e32 v182, 16, v168
	v_pk_add_f32 v[156:157], v[158:159], v[156:157]
	v_and_b32_e32 v183, 0xffff0000, v168
	v_add_f32_e32 v131, 0, v156
	v_add_f32_e32 v131, v131, v157
	v_mov_b32_e32 v155, v131
	s_nop 1
	v_permlane16_swap_b32_e32 v155, v131
	s_waitcnt vmcnt(2)
	v_lshlrev_b32_e32 v156, 16, v172
	v_and_b32_e32 v157, 0xffff0000, v172
	v_lshlrev_b32_e32 v160, 16, v166
	v_and_b32_e32 v161, 0xffff0000, v166
	s_waitcnt lgkmcnt(0)
	v_add_f32_e32 v131, v131, v155
	v_mov_b32_e32 v155, v131
	s_nop 1
	v_permlane32_swap_b32_e32 v155, v131
	v_lshlrev_b32_e32 v162, 16, v170
	v_and_b32_e32 v163, 0xffff0000, v170
	v_lshlrev_b32_e32 v168, 16, v169
	v_and_b32_e32 v169, 0xffff0000, v169
	s_waitcnt lgkmcnt(0)
	v_add_f32_e32 v131, v131, v155
	v_fmac_f32_e32 v151, 0x3a000000, v131
	v_mul_f32_e32 v131, 0x4b800000, v151
	v_cmp_gt_f32_e64 s[0:1], s18, v151
	v_lshlrev_b32_e32 v172, 16, v173
	v_and_b32_e32 v173, 0xffff0000, v173
	v_cndmask_b32_e64 v131, v151, v131, s[0:1]
	v_rsq_f32_e32 v131, v131
	s_waitcnt vmcnt(1)
	v_lshlrev_b32_e32 v184, 16, v174
	v_and_b32_e32 v185, 0xffff0000, v174
	v_lshlrev_b32_e32 v166, 16, v167
	v_mul_f32_e32 v151, 0x45800000, v131
	v_cndmask_b32_e64 v131, v131, v151, s[0:1]
	v_mul_f32_e32 v40, v40, v131
	v_mul_f32_e32 v41, v41, v131
	v_mul_f32_e32 v40, 0xbfb8aa3b, v40
	v_mul_f32_e32 v41, 0xbfb8aa3b, v41
	v_exp_f32_e32 v40, v40
	v_exp_f32_e32 v41, v41
	v_mul_f32_e32 v44, v44, v131
	v_mul_f32_e32 v45, v45, v131
	v_mul_f32_e32 v46, v46, v131
	v_mul_f32_e32 v47, v47, v131
	v_mul_f32_e32 v36, v36, v131
	v_mul_f32_e32 v37, v37, v131
	v_mul_f32_e32 v151, v39, v131
	v_mul_f32_e32 v39, 0xbfb8aa3b, v44
	v_mul_f32_e32 v44, 0xbfb8aa3b, v45
	v_mul_f32_e32 v45, 0xbfb8aa3b, v46
	v_mul_f32_e32 v46, 0xbfb8aa3b, v47
	v_mul_f32_e32 v36, 0xbfb8aa3b, v36
	v_mul_f32_e32 v37, 0xbfb8aa3b, v37
	v_exp_f32_e32 v39, v39
	v_exp_f32_e32 v44, v44
	v_exp_f32_e32 v45, v45
	v_exp_f32_e32 v46, v46
	v_exp_f32_e32 v36, v36
	v_exp_f32_e32 v37, v37
	v_add_f32_e32 v40, 1.0, v40
	v_add_f32_e32 v41, 1.0, v41
	v_rcp_f32_e32 v40, v40
	v_rcp_f32_e32 v41, v41
	v_mul_f32_e32 v38, v38, v131
	v_mul_f32_e32 v42, v42, v131
	v_mul_f32_e32 v43, v43, v131
	v_mul_f32_e32 v38, 0xbfb8aa3b, v38
	v_mul_f32_e32 v42, 0xbfb8aa3b, v42
	v_mul_f32_e32 v43, 0xbfb8aa3b, v43
	v_exp_f32_e32 v155, v38
	v_add_f32_e32 v38, 1.0, v39
	v_add_f32_e32 v39, 1.0, v44
	v_add_f32_e32 v44, 1.0, v45
	v_add_f32_e32 v45, 1.0, v46
	v_add_f32_e32 v46, 1.0, v36
	v_add_f32_e32 v47, 1.0, v37
	v_exp_f32_e32 v42, v42
	v_exp_f32_e32 v43, v43
	v_rcp_f32_e32 v36, v38
	v_rcp_f32_e32 v37, v39
	v_rcp_f32_e32 v38, v44
	v_rcp_f32_e32 v39, v45
	v_rcp_f32_e32 v44, v46
	v_rcp_f32_e32 v45, v47
	v_pk_fma_f32 v[46:47], v[40:41], v[156:157], v[182:183]
	v_mul_f32_e32 v40, 0xbfb8aa3b, v151
	v_mul_f32_e32 v32, v32, v131
	v_mul_f32_e32 v33, v33, v131
	v_exp_f32_e32 v41, v40
	v_mul_f32_e32 v32, 0xbfb8aa3b, v32
	v_mul_f32_e32 v33, 0xbfb8aa3b, v33
	v_exp_f32_e32 v32, v32
	v_exp_f32_e32 v33, v33
	v_add_f32_e32 v42, 1.0, v42
	v_add_f32_e32 v43, 1.0, v43
	v_rcp_f32_e32 v42, v42
	v_rcp_f32_e32 v43, v43
	v_add_f32_e32 v40, 1.0, v155
	v_add_f32_e32 v41, 1.0, v41
	v_mul_f32_e32 v34, v34, v131
	v_mul_f32_e32 v35, v35, v131
	v_rcp_f32_e32 v40, v40
	v_rcp_f32_e32 v41, v41
	v_add_f32_e32 v32, 1.0, v32
	v_add_f32_e32 v33, 1.0, v33
	v_mul_f32_e32 v34, 0xbfb8aa3b, v34
	v_mul_f32_e32 v35, 0xbfb8aa3b, v35
	v_rcp_f32_e32 v32, v32
	v_rcp_f32_e32 v33, v33
	v_exp_f32_e32 v34, v34
	v_exp_f32_e32 v35, v35
	v_pk_fma_f32 v[158:159], v[36:37], v[162:163], v[160:161]
	v_pk_fma_f32 v[156:157], v[42:43], v[172:173], v[168:169]
	v_lshlrev_b32_e32 v42, 16, v175
	v_and_b32_e32 v43, 0xffff0000, v175
	s_waitcnt vmcnt(0)
	v_lshlrev_b32_e32 v162, 16, v179
	v_and_b32_e32 v163, 0xffff0000, v179
	v_pk_fma_f32 v[162:163], v[40:41], v[162:163], v[42:43]
	v_lshlrev_b32_e32 v40, 16, v176
	v_and_b32_e32 v41, 0xffff0000, v176
	v_lshlrev_b32_e32 v42, 16, v180
	v_and_b32_e32 v43, 0xffff0000, v180
	v_pk_fma_f32 v[40:41], v[32:33], v[42:43], v[40:41]
	v_add_f32_e32 v32, 1.0, v34
	v_add_f32_e32 v33, 1.0, v35
	v_rcp_f32_e32 v32, v32
	v_rcp_f32_e32 v33, v33
	v_lshlrev_b32_e32 v186, 16, v178
	v_and_b32_e32 v187, 0xffff0000, v178
	v_pk_fma_f32 v[44:45], v[44:45], v[186:187], v[184:185]
	v_lshlrev_b32_e32 v34, 16, v177
	v_and_b32_e32 v35, 0xffff0000, v177
	v_lshlrev_b32_e32 v42, 16, v181
	v_and_b32_e32 v43, 0xffff0000, v181
	v_and_b32_e32 v167, 0xffff0000, v167
	v_lshlrev_b32_e32 v170, 16, v171
	v_and_b32_e32 v171, 0xffff0000, v171
	v_pk_fma_f32 v[42:43], v[32:33], v[42:43], v[34:35]
	v_pk_mul_f32 v[32:33], v[44:45], v[44:45]
	v_pk_mul_f32 v[34:35], v[162:163], v[162:163]
	v_pk_fma_f32 v[160:161], v[38:39], v[170:171], v[166:167]
	v_pk_mul_f32 v[166:167], v[46:47], v[46:47]
	v_pk_mul_f32 v[168:169], v[156:157], v[156:157]
	v_add_f32_e32 v34, v34, v35
	v_add_f32_e32 v32, v32, v33
	v_pk_mul_f32 v[36:37], v[158:159], v[158:159]
	v_pk_mul_f32 v[38:39], v[160:161], v[160:161]
	v_pk_mul_f32 v[170:171], v[40:41], v[40:41]
	v_pk_mul_f32 v[172:173], v[42:43], v[42:43]
	v_add_f32_e32 v32, v32, v34
	v_add_f32_e32 v33, v168, v169
	v_add_f32_e32 v34, v166, v167
	v_add_f32_e32 v131, v172, v173
	v_add_f32_e32 v151, v170, v171
	v_add_f32_e32 v33, v34, v33
	v_add_f32_e32 v34, v38, v39
	v_add_f32_e32 v35, v36, v37
	v_add_f32_e32 v131, v151, v131
	v_add_f32_e32 v34, v35, v34
	v_add_f32_e32 v32, v32, v131
	v_add_f32_e32 v33, v34, v33
	v_add_f32_e32 v32, v33, v32
	v_mov_b32_e32 v33, v32
	s_nop 1
	v_permlane16_swap_b32_e32 v33, v32
	s_waitcnt lgkmcnt(0)
	v_add_f32_e32 v32, v32, v33
	v_mov_b32_e32 v33, v32
	s_nop 1
	v_permlane32_swap_b32_e32 v33, v32
	s_and_saveexec_b64 s[0:1], vcc
	s_cbranch_execz .LBB0_1246
	s_waitcnt lgkmcnt(0)
	v_add_f32_e32 v34, v32, v33
	v_lshl_add_u64 v[32:33], s[8:9], 0, v[164:165]
	v_lshl_add_u64 v[32:33], s[14:15], 2, v[32:33]
	s_lshl_b32 s16, s44, 2
	v_lshl_add_u64 v[32:33], v[32:33], 0, s[16:17]
	global_store_dword v[32:33], v34, off
.LBB0_1246:
	s_or_b64 exec, exec, s[0:1]
	v_add_u32_e32 v34, 0xa0, v150
	v_ashrrev_i32_e32 v35, 31, v34
	s_waitcnt lgkmcnt(0)
	v_lshlrev_b64 v[32:33], 7, v[34:35]
	v_lshl_add_u64 v[36:37], s[4:5], 0, v[32:33]
	v_mov_b32_e32 v131, 0
	v_lshl_add_u64 v[164:165], v[36:37], 0, v[130:131]
	global_load_dwordx4 v[36:39], v[164:165], off
	s_nop 0
	global_load_dwordx4 v[164:167], v[164:165], off offset:16
	v_lshlrev_b64 v[34:35], 11, v[34:35]
	v_lshl_add_u64 v[34:35], v[34:35], 0, v[128:129]
	v_lshlrev_b64 v[34:35], 1, v[34:35]
	v_lshl_add_u64 v[168:169], s[12:13], 0, v[34:35]
	v_lshl_add_u64 v[172:173], s[2:3], 0, v[34:35]
	v_or_b32_e32 v34, 0x100, v34
	v_lshl_add_u64 v[176:177], s[12:13], 0, v[34:35]
	v_lshl_add_u64 v[34:35], s[2:3], 0, v[34:35]
	global_load_dwordx4 v[168:171], v[168:169], off
	s_waitcnt vmcnt(2)
	v_mov_b32_e32 v184, v36
	global_load_dwordx4 v[172:175], v[172:173], off
	s_waitcnt vmcnt(2)
	v_mov_b32_e32 v185, v164
	global_load_dwordx4 v[176:179], v[176:177], off
	v_mov_b32_e32 v164, v37
	global_load_dwordx4 v[180:183], v[34:35], off
	v_mov_b32_e32 v36, v38
	v_mov_b32_e32 v37, v166
	v_mov_b32_e32 v166, v39
	v_pk_add_f32 v[38:39], v[184:185], v[164:165]
	v_pk_add_f32 v[36:37], v[36:37], v[166:167]
	v_mov_b32_e32 v34, 0x358637bd
	v_pk_add_f32 v[36:37], v[38:39], v[36:37]
	s_waitcnt vmcnt(3)
	v_lshlrev_b32_e32 v184, 16, v170
	v_add_f32_e32 v35, 0, v36
	v_add_f32_e32 v35, v35, v37
	v_mov_b32_e32 v39, v35
	s_nop 1
	v_permlane16_swap_b32_e32 v39, v35
	v_and_b32_e32 v185, 0xffff0000, v170
	v_lshlrev_b32_e32 v38, 16, v171
	v_lshlrev_b32_e32 v164, 16, v168
	v_and_b32_e32 v165, 0xffff0000, v168
	s_waitcnt lgkmcnt(0)
	v_add_f32_e32 v35, v35, v39
	v_mov_b32_e32 v151, v35
	s_nop 1
	v_permlane32_swap_b32_e32 v151, v35
	v_and_b32_e32 v39, 0xffff0000, v171
	v_lshlrev_b32_e32 v168, 16, v169
	v_and_b32_e32 v169, 0xffff0000, v169
	s_waitcnt lgkmcnt(0)
	v_add_f32_e32 v35, v35, v151
	v_fmamk_f32 v35, v35, 0x3a000000, v34
	v_mul_f32_e32 v151, 0x4b800000, v35
	v_cmp_gt_f32_e64 s[0:1], s18, v35
	s_waitcnt vmcnt(2)
	v_lshlrev_b32_e32 v166, 16, v172
	v_cndmask_b32_e64 v35, v35, v151, s[0:1]
	v_rsq_f32_e32 v35, v35
	s_waitcnt vmcnt(1)
	v_lshlrev_b32_e32 v186, 16, v176
	v_and_b32_e32 v187, 0xffff0000, v176
	s_waitcnt vmcnt(0)
	v_lshlrev_b32_e32 v188, 16, v180
	v_mul_f32_e32 v151, 0x45800000, v35
	v_cndmask_b32_e64 v35, v35, v151, s[0:1]
	v_mul_f32_e32 v28, v28, v35
	v_mul_f32_e32 v29, v29, v35
	v_mul_f32_e32 v30, v30, v35
	v_mul_f32_e32 v31, v31, v35
	v_mul_f32_e32 v24, v24, v35
	v_mul_f32_e32 v25, v25, v35
	v_mul_f32_e32 v20, v20, v35
	v_mul_f32_e32 v21, v21, v35
	v_mul_f32_e32 v26, v26, v35
	v_mul_f32_e32 v27, v27, v35
	v_mul_f32_e32 v22, v22, v35
	v_mul_f32_e32 v28, 0xbfb8aa3b, v28
	v_mul_f32_e32 v29, 0xbfb8aa3b, v29
	v_mul_f32_e32 v30, 0xbfb8aa3b, v30
	v_mul_f32_e32 v31, 0xbfb8aa3b, v31
	v_mul_f32_e32 v24, 0xbfb8aa3b, v24
	v_mul_f32_e32 v25, 0xbfb8aa3b, v25
	v_mul_f32_e32 v20, 0xbfb8aa3b, v20
	v_mul_f32_e32 v21, 0xbfb8aa3b, v21
	v_mul_f32_e32 v23, v23, v35
	v_mul_f32_e32 v26, 0xbfb8aa3b, v26
	v_mul_f32_e32 v27, 0xbfb8aa3b, v27
	v_exp_f32_e32 v28, v28
	v_exp_f32_e32 v29, v29
	v_exp_f32_e32 v30, v30
	v_exp_f32_e32 v31, v31
	v_exp_f32_e32 v24, v24
	v_exp_f32_e32 v25, v25
	v_exp_f32_e32 v20, v20
	v_exp_f32_e32 v21, v21
	v_mul_f32_e32 v22, 0xbfb8aa3b, v22
	v_mul_f32_e32 v23, 0xbfb8aa3b, v23
	v_mul_f32_e32 v16, v16, v35
	v_mul_f32_e32 v17, v17, v35
	v_exp_f32_e32 v26, v26
	v_exp_f32_e32 v27, v27
	v_exp_f32_e32 v22, v22
	v_exp_f32_e32 v23, v23
	v_mul_f32_e32 v16, 0xbfb8aa3b, v16
	v_mul_f32_e32 v17, 0xbfb8aa3b, v17
	v_exp_f32_e32 v16, v16
	v_exp_f32_e32 v17, v17
	v_and_b32_e32 v189, 0xffff0000, v180
	v_add_f32_e32 v28, 1.0, v28
	v_add_f32_e32 v29, 1.0, v29
	v_add_f32_e32 v30, 1.0, v30
	v_add_f32_e32 v31, 1.0, v31
	v_add_f32_e32 v151, 1.0, v24
	v_add_f32_e32 v155, 1.0, v25
	v_add_f32_e32 v176, 1.0, v20
	v_add_f32_e32 v180, 1.0, v21
	v_add_f32_e32 v170, 1.0, v26
	v_add_f32_e32 v171, 1.0, v27
	v_rcp_f32_e32 v20, v28
	v_rcp_f32_e32 v21, v29
	v_rcp_f32_e32 v24, v30
	v_rcp_f32_e32 v25, v31
	v_rcp_f32_e32 v26, v151
	v_rcp_f32_e32 v27, v155
	v_rcp_f32_e32 v30, v176
	v_rcp_f32_e32 v31, v180
	v_add_f32_e32 v22, 1.0, v22
	v_add_f32_e32 v23, 1.0, v23
	v_mul_f32_e32 v18, v18, v35
	v_mul_f32_e32 v19, v19, v35
	v_rcp_f32_e32 v28, v170
	v_rcp_f32_e32 v29, v171
	v_rcp_f32_e32 v22, v22
	v_rcp_f32_e32 v23, v23
	v_add_f32_e32 v16, 1.0, v16
	v_add_f32_e32 v17, 1.0, v17
	v_mul_f32_e32 v18, 0xbfb8aa3b, v18
	v_mul_f32_e32 v19, 0xbfb8aa3b, v19
	v_rcp_f32_e32 v16, v16
	v_rcp_f32_e32 v17, v17
	v_exp_f32_e32 v18, v18
	v_exp_f32_e32 v19, v19
	v_and_b32_e32 v167, 0xffff0000, v172
	v_lshlrev_b32_e32 v172, 16, v173
	v_and_b32_e32 v173, 0xffff0000, v173
	v_lshlrev_b32_e32 v36, 16, v174
	v_and_b32_e32 v37, 0xffff0000, v174
	v_lshlrev_b32_e32 v174, 16, v175
	v_and_b32_e32 v175, 0xffff0000, v175
	v_pk_fma_f32 v[170:171], v[20:21], v[166:167], v[164:165]
	v_pk_fma_f32 v[172:173], v[24:25], v[172:173], v[168:169]
	v_pk_fma_f32 v[164:165], v[26:27], v[36:37], v[184:185]
	v_pk_fma_f32 v[168:169], v[30:31], v[188:189], v[186:187]
	v_lshlrev_b32_e32 v30, 16, v177
	v_and_b32_e32 v31, 0xffff0000, v177
	v_lshlrev_b32_e32 v36, 16, v181
	v_and_b32_e32 v37, 0xffff0000, v181
	v_pk_fma_f32 v[166:167], v[28:29], v[174:175], v[38:39]
	v_pk_fma_f32 v[174:175], v[22:23], v[36:37], v[30:31]
	v_lshlrev_b32_e32 v22, 16, v178
	v_and_b32_e32 v23, 0xffff0000, v178
	v_lshlrev_b32_e32 v30, 16, v182
	v_and_b32_e32 v31, 0xffff0000, v182
	v_pk_fma_f32 v[176:177], v[16:17], v[30:31], v[22:23]
	v_add_f32_e32 v16, 1.0, v18
	v_add_f32_e32 v17, 1.0, v19
	v_rcp_f32_e32 v16, v16
	v_rcp_f32_e32 v17, v17
	v_lshlrev_b32_e32 v18, 16, v179
	v_and_b32_e32 v19, 0xffff0000, v179
	v_lshlrev_b32_e32 v22, 16, v183
	v_and_b32_e32 v23, 0xffff0000, v183
	v_pk_fma_f32 v[178:179], v[16:17], v[22:23], v[18:19]
	v_pk_mul_f32 v[16:17], v[168:169], v[168:169]
	v_pk_mul_f32 v[18:19], v[174:175], v[174:175]
	v_pk_mul_f32 v[26:27], v[164:165], v[164:165]
	v_pk_mul_f32 v[28:29], v[166:167], v[166:167]
	v_add_f32_e32 v18, v18, v19
	v_add_f32_e32 v16, v16, v17
	v_pk_mul_f32 v[20:21], v[170:171], v[170:171]
	v_pk_mul_f32 v[24:25], v[172:173], v[172:173]
	v_pk_mul_f32 v[22:23], v[176:177], v[176:177]
	v_pk_mul_f32 v[30:31], v[178:179], v[178:179]
	v_add_f32_e32 v16, v16, v18
	v_add_f32_e32 v17, v28, v29
	v_add_f32_e32 v18, v26, v27
	v_add_f32_e32 v30, v30, v31
	v_add_f32_e32 v22, v22, v23
	v_add_f32_e32 v17, v18, v17
	v_add_f32_e32 v18, v24, v25
	v_add_f32_e32 v19, v20, v21
	v_add_f32_e32 v22, v22, v30
	v_add_f32_e32 v18, v19, v18
	v_add_f32_e32 v16, v16, v22
	v_add_f32_e32 v17, v18, v17
	v_add_f32_e32 v16, v17, v16
	v_mov_b32_e32 v17, v16
	s_nop 1
	v_permlane16_swap_b32_e32 v17, v16
	s_waitcnt lgkmcnt(0)
	v_add_f32_e32 v16, v16, v17
	v_mov_b32_e32 v17, v16
	s_nop 1
	v_permlane32_swap_b32_e32 v17, v16
	s_and_saveexec_b64 s[0:1], vcc
	s_cbranch_execz .LBB0_1248
	s_waitcnt lgkmcnt(0)
	v_add_f32_e32 v18, v16, v17
	v_lshl_add_u64 v[16:17], s[8:9], 0, v[32:33]
	v_lshl_add_u64 v[16:17], s[14:15], 2, v[16:17]
	s_lshl_b32 s16, s44, 2
	v_lshl_add_u64 v[16:17], v[16:17], 0, s[16:17]
	global_store_dword v[16:17], v18, off
.LBB0_1248:
	s_or_b64 exec, exec, s[0:1]
	v_add_u32_e32 v26, 0xb0, v150
	v_ashrrev_i32_e32 v27, 31, v26
	s_waitcnt lgkmcnt(0)
	v_lshlrev_b64 v[16:17], 7, v[26:27]
	v_lshl_add_u64 v[18:19], s[4:5], 0, v[16:17]
	v_lshl_add_u64 v[22:23], v[18:19], 0, v[130:131]
	global_load_dwordx4 v[18:21], v[22:23], off
	s_nop 0
	global_load_dwordx4 v[22:25], v[22:23], off offset:16
	v_lshlrev_b64 v[26:27], 11, v[26:27]
	v_lshl_add_u64 v[26:27], v[26:27], 0, v[128:129]
	v_lshlrev_b64 v[150:151], 1, v[26:27]
	v_lshl_add_u64 v[26:27], s[12:13], 0, v[150:151]
	v_lshl_add_u64 v[30:31], s[2:3], 0, v[150:151]
	global_load_dwordx4 v[26:29], v[26:27], off
	v_or_b32_e32 v150, 0x100, v150
	global_load_dwordx4 v[30:33], v[30:31], off
	v_lshl_add_u64 v[36:37], s[12:13], 0, v[150:151]
	global_load_dwordx4 v[36:39], v[36:37], off
	v_lshl_add_u64 v[150:151], s[2:3], 0, v[150:151]
	global_load_dwordx4 v[190:193], v[150:151], off
	s_waitcnt vmcnt(5)
	v_mov_b32_e32 v150, v18
	s_waitcnt vmcnt(4)
	v_mov_b32_e32 v151, v22
	v_mov_b32_e32 v22, v19
	v_mov_b32_e32 v18, v20
	v_mov_b32_e32 v19, v24
	v_mov_b32_e32 v24, v21
	v_pk_add_f32 v[20:21], v[150:151], v[22:23]
	v_pk_add_f32 v[18:19], v[18:19], v[24:25]
	s_waitcnt vmcnt(3)
	v_lshlrev_b32_e32 v150, 16, v28
	v_pk_add_f32 v[18:19], v[20:21], v[18:19]
	v_and_b32_e32 v151, 0xffff0000, v28
	v_add_f32_e32 v18, 0, v18
	v_add_f32_e32 v21, v18, v19
	v_mov_b32_e32 v35, v21
	s_nop 1
	v_permlane16_swap_b32_e32 v35, v21
	v_lshlrev_b32_e32 v20, 16, v29
	s_waitcnt vmcnt(2)
	v_lshlrev_b32_e32 v28, 16, v33
	v_lshlrev_b32_e32 v18, 16, v32
	v_and_b32_e32 v19, 0xffff0000, v32
	s_waitcnt lgkmcnt(0)
	v_add_f32_e32 v35, v21, v35
	v_mov_b32_e32 v131, v35
	s_nop 1
	v_permlane32_swap_b32_e32 v131, v35
	v_and_b32_e32 v21, 0xffff0000, v29
	v_and_b32_e32 v29, 0xffff0000, v33
	s_waitcnt vmcnt(1)
	v_lshlrev_b32_e32 v32, 16, v36
	v_lshlrev_b32_e32 v22, 16, v26
	s_waitcnt lgkmcnt(0)
	v_add_f32_e32 v33, v35, v131
	v_fmac_f32_e32 v34, 0x3a000000, v33
	v_mul_f32_e32 v33, 0x4b800000, v34
	v_cmp_gt_f32_e64 s[0:1], s18, v34
	s_waitcnt vmcnt(0)
	v_and_b32_e32 v35, 0xffff0000, v190
	v_and_b32_e32 v23, 0xffff0000, v26
	v_cndmask_b32_e64 v33, v34, v33, s[0:1]
	v_rsq_f32_e32 v131, v33
	v_and_b32_e32 v33, 0xffff0000, v36
	v_lshlrev_b32_e32 v34, 16, v190
	v_lshlrev_b32_e32 v24, 16, v30
	v_mul_f32_e32 v36, 0x45800000, v131
	v_cndmask_b32_e64 v36, v131, v36, s[0:1]
	v_mul_f32_e32 v12, v12, v36
	v_mul_f32_e32 v13, v13, v36
	v_mul_f32_e32 v14, v14, v36
	v_mul_f32_e32 v15, v15, v36
	v_mul_f32_e32 v4, v4, v36
	v_mul_f32_e32 v8, v8, v36
	v_mul_f32_e32 v9, v9, v36
	v_mul_f32_e32 v5, v5, v36
	v_mul_f32_e32 v131, v7, v36
	v_mul_f32_e32 v7, 0xbfb8aa3b, v12
	v_mul_f32_e32 v12, 0xbfb8aa3b, v13
	v_mul_f32_e32 v13, 0xbfb8aa3b, v14
	v_mul_f32_e32 v14, 0xbfb8aa3b, v15
	v_mul_f32_e32 v4, 0xbfb8aa3b, v4
	v_mul_f32_e32 v8, 0xbfb8aa3b, v8
	v_mul_f32_e32 v9, 0xbfb8aa3b, v9
	v_mul_f32_e32 v5, 0xbfb8aa3b, v5
	v_exp_f32_e32 v7, v7
	v_exp_f32_e32 v12, v12
	v_exp_f32_e32 v13, v13
	v_exp_f32_e32 v14, v14
	v_exp_f32_e32 v4, v4
	v_exp_f32_e32 v8, v8
	v_exp_f32_e32 v9, v9
	v_exp_f32_e32 v5, v5
	v_mul_f32_e32 v6, v6, v36
	v_mul_f32_e32 v6, 0xbfb8aa3b, v6
	v_exp_f32_e32 v15, v6
	v_add_f32_e32 v6, 1.0, v7
	v_add_f32_e32 v7, 1.0, v12
	v_add_f32_e32 v12, 1.0, v13
	v_add_f32_e32 v13, 1.0, v14
	v_add_f32_e32 v14, 1.0, v4
	v_add_f32_e32 v8, 1.0, v8
	v_add_f32_e32 v9, 1.0, v9
	v_add_f32_e32 v155, 1.0, v5
	v_rcp_f32_e32 v4, v6
	v_rcp_f32_e32 v6, v12
	v_rcp_f32_e32 v12, v14
	v_mul_f32_e32 v14, 0xbfb8aa3b, v131
	v_mul_f32_e32 v0, v0, v36
	v_mul_f32_e32 v1, v1, v36
	v_rcp_f32_e32 v5, v7
	v_rcp_f32_e32 v7, v13
	v_rcp_f32_e32 v8, v8
	v_rcp_f32_e32 v9, v9
	v_rcp_f32_e32 v13, v155
	v_exp_f32_e32 v14, v14
	v_mul_f32_e32 v0, 0xbfb8aa3b, v0
	v_mul_f32_e32 v1, 0xbfb8aa3b, v1
	v_exp_f32_e32 v0, v0
	v_exp_f32_e32 v1, v1
	v_mul_f32_e32 v10, v10, v36
	v_mul_f32_e32 v11, v11, v36
	v_pk_fma_f32 v[180:181], v[8:9], v[18:19], v[150:151]
	v_pk_fma_f32 v[150:151], v[12:13], v[34:35], v[32:33]
	v_add_f32_e32 v12, 1.0, v15
	v_add_f32_e32 v13, 1.0, v14
	v_mul_f32_e32 v2, v2, v36
	v_mul_f32_e32 v3, v3, v36
	v_mul_f32_e32 v10, 0xbfb8aa3b, v10
	v_mul_f32_e32 v11, 0xbfb8aa3b, v11
	v_rcp_f32_e32 v12, v12
	v_rcp_f32_e32 v13, v13
	v_add_f32_e32 v0, 1.0, v0
	v_add_f32_e32 v1, 1.0, v1
	v_mul_f32_e32 v2, 0xbfb8aa3b, v2
	v_mul_f32_e32 v3, 0xbfb8aa3b, v3
	v_exp_f32_e32 v10, v10
	v_exp_f32_e32 v11, v11
	v_rcp_f32_e32 v0, v0
	v_rcp_f32_e32 v1, v1
	v_exp_f32_e32 v2, v2
	v_exp_f32_e32 v3, v3
	v_lshlrev_b32_e32 v14, 16, v37
	v_and_b32_e32 v15, 0xffff0000, v37
	v_lshlrev_b32_e32 v18, 16, v191
	v_and_b32_e32 v19, 0xffff0000, v191
	v_pk_fma_f32 v[188:189], v[12:13], v[18:19], v[14:15]
	v_lshlrev_b32_e32 v12, 16, v38
	v_and_b32_e32 v13, 0xffff0000, v38
	v_lshlrev_b32_e32 v14, 16, v192
	v_and_b32_e32 v15, 0xffff0000, v192
	v_add_f32_e32 v10, 1.0, v10
	v_add_f32_e32 v11, 1.0, v11
	v_pk_fma_f32 v[190:191], v[0:1], v[14:15], v[12:13]
	v_add_f32_e32 v0, 1.0, v2
	v_add_f32_e32 v1, 1.0, v3
	v_rcp_f32_e32 v10, v10
	v_rcp_f32_e32 v11, v11
	v_rcp_f32_e32 v0, v0
	v_rcp_f32_e32 v1, v1
	v_lshlrev_b32_e32 v2, 16, v39
	v_and_b32_e32 v3, 0xffff0000, v39
	v_lshlrev_b32_e32 v12, 16, v193
	v_and_b32_e32 v13, 0xffff0000, v193
	v_and_b32_e32 v25, 0xffff0000, v30
	v_lshlrev_b32_e32 v26, 16, v27
	v_and_b32_e32 v27, 0xffff0000, v27
	v_lshlrev_b32_e32 v30, 16, v31
	v_and_b32_e32 v31, 0xffff0000, v31
	v_pk_fma_f32 v[182:183], v[10:11], v[28:29], v[20:21]
	v_pk_fma_f32 v[192:193], v[0:1], v[12:13], v[2:3]
	v_pk_mul_f32 v[0:1], v[150:151], v[150:151]
	v_pk_mul_f32 v[2:3], v[188:189], v[188:189]
	v_pk_fma_f32 v[184:185], v[4:5], v[24:25], v[22:23]
	v_pk_fma_f32 v[186:187], v[6:7], v[30:31], v[26:27]
	v_pk_mul_f32 v[8:9], v[180:181], v[180:181]
	v_pk_mul_f32 v[10:11], v[182:183], v[182:183]
	v_add_f32_e32 v2, v2, v3
	v_add_f32_e32 v0, v0, v1
	v_pk_mul_f32 v[4:5], v[184:185], v[184:185]
	v_pk_mul_f32 v[6:7], v[186:187], v[186:187]
	v_pk_mul_f32 v[12:13], v[190:191], v[190:191]
	v_pk_mul_f32 v[14:15], v[192:193], v[192:193]
	v_add_f32_e32 v0, v0, v2
	v_add_f32_e32 v1, v10, v11
	v_add_f32_e32 v2, v8, v9
	v_add_f32_e32 v14, v14, v15
	v_add_f32_e32 v12, v12, v13
	v_add_f32_e32 v1, v2, v1
	v_add_f32_e32 v2, v6, v7
	v_add_f32_e32 v3, v4, v5
	v_add_f32_e32 v12, v12, v14
	v_add_f32_e32 v2, v3, v2
	v_add_f32_e32 v0, v0, v12
	v_add_f32_e32 v1, v2, v1
	v_add_f32_e32 v0, v1, v0
	v_mov_b32_e32 v1, v0
	s_nop 1
	v_permlane16_swap_b32_e32 v1, v0
	s_waitcnt lgkmcnt(0)
	v_add_f32_e32 v0, v0, v1
	v_mov_b32_e32 v1, v0
	s_nop 1
	v_permlane32_swap_b32_e32 v1, v0
	s_and_saveexec_b64 s[0:1], vcc
	s_cbranch_execz .LBB0_1250
	s_waitcnt lgkmcnt(0)
	v_add_f32_e32 v2, v0, v1
	v_lshl_add_u64 v[0:1], s[8:9], 0, v[16:17]
	v_lshl_add_u64 v[0:1], s[14:15], 2, v[0:1]
	s_lshl_b32 s2, s44, 2
	s_mov_b32 s3, 0
	v_lshl_add_u64 v[0:1], v[0:1], 0, s[2:3]
	global_store_dword v[0:1], v2, off
